# attention: conflict-free K/V LDS swizzle, 3-deep LDS tile ring, static prio for waves 4-7; GEMM epilogue stores write-through sc1
# speedup vs baseline: 1.0222x; 1.0222x over previous
; __device__ __forceinline__ float softplus(float x) {
;     const float e = __expf(-fabsf(x));
;     const float l = e < 0.03125f ? e * (1.f - e * (0.5f - e * (0.33333334f - 0.25f * e))) : __logf(1.f + e);
;     return fmaxf(x, 0.f) + l;
; }
;     __device__ __forceinline__ void operator()(ACC_T, const pg8::Unit& u, int wr, int wc, int fr, int fq) const {
;     ...
;                 const int i0 = 8 * fq; const f32x4 b0 = *(const f32x4*)(dt_bias + i0), b1 = *(const f32x4*)(dt_bias + i0 + 4);
; #pragma unroll
;                 for (int ai = 0; ai < 2; ++ai)
; #pragma unroll
;                     for (int m = 0; m < 4; ++m) { const int row = row0 + ai * 128 + m * 16; f32x4 v0 = acc[ai][0][m][0] + b0, v1 = acc[ai][0][m][1] + b1;
; #pragma unroll
;                         for (int e = 0; e < 4; ++e) { v0[e] = softplus(v0[e]); v1[e] = softplus(v1[e]); }
;                         *(f32x4*)(DT + (unsigned)row * 32u + i0) = v0; *(f32x4*)(DT + (unsigned)row * 32u + i0 + 4) = v1; asm volatile("" ::: "memory"); }
.LBB0_281:
	s_andn2_saveexec_b64 s[8:9], s[8:9]
	v_mov_b32_e32 v173, 0x3eaaaaab
	v_fmamk_f32 v173, v174, 0xbe800000, v173
	v_fma_f32 v173, -v174, v173, 0.5
	v_fma_f32 v173, -v174, v173, 1.0
	v_mul_f32_e32 v173, v174, v173
	s_or_b64 exec, exec, s[8:9]
	v_max_f32_e32 v156, v156, v156
	v_max_f32_e32 v156, 0, v156
	v_add_f32_e32 v174, v156, v0
	v_max_f32_e32 v0, v157, v157
	v_max_f32_e32 v0, 0, v0
	v_add_f32_e32 v175, v0, v168
	v_max_f32_e32 v0, v160, v160
	v_max_f32_e32 v0, 0, v0
	v_add_f32_e32 v176, v0, v170
	v_max_f32_e32 v0, v161, v161
	v_max_f32_e32 v0, 0, v0
	v_add_f32_e32 v177, v0, v172
	v_max_f32_e32 v0, v158, v158
	v_max_f32_e32 v0, 0, v0
	v_add_f32_e32 v156, v0, v153
	v_max_f32_e32 v0, v159, v159
	v_max_f32_e32 v0, 0, v0
	v_add_f32_e32 v157, v0, v169
	v_max_f32_e32 v0, v162, v162
	v_max_f32_e32 v0, 0, v0
	v_add_f32_e32 v158, v0, v171
	v_lshlrev_b32_e32 v0, 5, v150
	v_max_f32_e32 v153, v163, v163
	v_lshl_add_u64 v[160:161], v[0:1], 2, s[86:87]
	v_max_f32_e32 v153, 0, v153
	v_lshl_add_u64 v[160:161], v[154:155], 2, v[160:161]
	v_add_f32_e32 v159, v153, v173
	global_store_dwordx4 v[160:161], v[174:177], off sc1
	global_store_dwordx4 v[160:161], v[156:159], off offset:16 sc1
	s_nop 1
	v_pk_add_f32 v[156:157], v[110:111], v[134:135]
	s_nop 0
	v_mul_f32_e64 v153, |v156|, s36
	v_exp_f32_e32 v158, v153
	s_nop 0
	v_cmp_ngt_f32_e32 vcc, s46, v158
	s_and_saveexec_b64 s[8:9], vcc
	s_xor_b64 s[8:9], exec, s[8:9]
	s_cbranch_execz .LBB0_285
	v_add_f32_e32 v153, 1.0, v158
	v_cmp_gt_f32_e32 vcc, s51, v153
	s_mov_b32 s2, 0x7f800000
	s_nop 0
	v_cndmask_b32_e64 v158, 0, 32, vcc
	v_ldexp_f32 v153, v153, v158
	v_log_f32_e32 v153, v153
	s_nop 0
	v_mul_f32_e32 v158, 0x3f317217, v153
	v_fma_f32 v158, v153, s47, -v158
	v_fmac_f32_e32 v158, 0x3377d1cf, v153
	v_fmac_f32_e32 v158, 0x3f317217, v153
	v_cmp_lt_f32_e64 s[40:41], |v153|, s2
	s_nop 1
	v_cndmask_b32_e64 v153, v153, v158, s[40:41]
	v_mov_b32_e32 v158, 0x41b17218
	v_cndmask_b32_e32 v158, 0, v158, vcc
	v_sub_f32_e32 v153, v153, v158

; __device__ __forceinline__ float softplus(float x) {
;     const float e = __expf(-fabsf(x));
;     const float l = e < 0.03125f ? e * (1.f - e * (0.5f - e * (0.33333334f - 0.25f * e))) : __logf(1.f + e);
;     return fmaxf(x, 0.f) + l;
; }
;     __device__ __forceinline__ void operator()(ACC_T, const pg8::Unit& u, int wr, int wc, int fr, int fq) const {
;     ...
;                 const int i0 = 8 * fq; const f32x4 b0 = *(const f32x4*)(dt_bias + i0), b1 = *(const f32x4*)(dt_bias + i0 + 4);
; #pragma unroll
;                 for (int ai = 0; ai < 2; ++ai)
; #pragma unroll
;                     for (int m = 0; m < 4; ++m) { const int row = row0 + ai * 128 + m * 16; f32x4 v0 = acc[ai][0][m][0] + b0, v1 = acc[ai][0][m][1] + b1;
; #pragma unroll
;                         for (int e = 0; e < 4; ++e) { v0[e] = softplus(v0[e]); v1[e] = softplus(v1[e]); }
;                         *(f32x4*)(DT + (unsigned)row * 32u + i0) = v0; *(f32x4*)(DT + (unsigned)row * 32u + i0 + 4) = v1; asm volatile("" ::: "memory"); }
.LBB0_313:
	s_andn2_saveexec_b64 s[8:9], s[8:9]
	v_mov_b32_e32 v174, 0x3eaaaaab
	v_fmamk_f32 v174, v175, 0xbe800000, v174
	v_fma_f32 v174, -v175, v174, 0.5
	v_fma_f32 v174, -v175, v174, 1.0
	v_mul_f32_e32 v174, v175, v174
	s_or_b64 exec, exec, s[8:9]
	v_max_f32_e32 v156, v156, v156
	v_max_f32_e32 v156, 0, v156
	v_add_f32_e32 v176, v156, v153
	v_max_f32_e32 v153, v157, v157
	v_max_f32_e32 v153, 0, v153
	v_add_f32_e32 v177, v153, v169
	v_max_f32_e32 v153, v160, v160
	v_max_f32_e32 v153, 0, v153
	v_add_f32_e32 v178, v153, v171
	v_max_f32_e32 v153, v161, v161
	v_max_f32_e32 v153, 0, v153
	v_add_f32_e32 v179, v153, v173
	v_max_f32_e32 v153, v158, v158
	v_max_f32_e32 v153, 0, v153
	v_add_f32_e32 v156, v153, v168
	v_max_f32_e32 v153, v159, v159
	v_max_f32_e32 v153, 0, v153
	v_add_f32_e32 v157, v153, v170
	v_max_f32_e32 v153, v162, v162
	v_max_f32_e32 v153, 0, v153
	v_add_u32_e32 v160, 0x200, v0
	v_mov_b32_e32 v161, v1
	v_add_f32_e32 v158, v153, v172
	v_max_f32_e32 v153, v163, v163
	v_lshl_add_u64 v[160:161], v[160:161], 2, s[86:87]
	v_max_f32_e32 v153, 0, v153
	v_lshl_add_u64 v[160:161], v[154:155], 2, v[160:161]
	v_add_f32_e32 v159, v153, v174
	global_store_dwordx4 v[160:161], v[176:179], off sc1
	global_store_dwordx4 v[160:161], v[156:159], off offset:16 sc1
	s_nop 1
	v_pk_add_f32 v[156:157], v[94:95], v[134:135]
	s_nop 0
	v_mul_f32_e64 v153, |v156|, s36
	v_exp_f32_e32 v158, v153
	s_nop 0
	v_cmp_ngt_f32_e32 vcc, s46, v158
	s_and_saveexec_b64 s[8:9], vcc
	s_xor_b64 s[8:9], exec, s[8:9]
	s_cbranch_execz .LBB0_317
	v_add_f32_e32 v153, 1.0, v158
	v_cmp_gt_f32_e32 vcc, s51, v153
	s_mov_b32 s2, 0x7f800000
	s_nop 0
	v_cndmask_b32_e64 v158, 0, 32, vcc
	v_ldexp_f32 v153, v153, v158
	v_log_f32_e32 v153, v153
	s_nop 0
	v_mul_f32_e32 v158, 0x3f317217, v153
	v_fma_f32 v158, v153, s47, -v158
	v_fmac_f32_e32 v158, 0x3377d1cf, v153
	v_fmac_f32_e32 v158, 0x3f317217, v153
	v_cmp_lt_f32_e64 s[40:41], |v153|, s2
	s_nop 1
	v_cndmask_b32_e64 v153, v153, v158, s[40:41]
	v_mov_b32_e32 v158, 0x41b17218
	v_cndmask_b32_e32 v158, 0, v158, vcc
	v_sub_f32_e32 v153, v153, v158

; __device__ __forceinline__ float softplus(float x) {
;     const float e = __expf(-fabsf(x));
;     const float l = e < 0.03125f ? e * (1.f - e * (0.5f - e * (0.33333334f - 0.25f * e))) : __logf(1.f + e);
;     return fmaxf(x, 0.f) + l;
; }
;     __device__ __forceinline__ void operator()(ACC_T, const pg8::Unit& u, int wr, int wc, int fr, int fq) const {
;     ...
;                 const int i0 = 8 * fq; const f32x4 b0 = *(const f32x4*)(dt_bias + i0), b1 = *(const f32x4*)(dt_bias + i0 + 4);
; #pragma unroll
;                 for (int ai = 0; ai < 2; ++ai)
; #pragma unroll
;                     for (int m = 0; m < 4; ++m) { const int row = row0 + ai * 128 + m * 16; f32x4 v0 = acc[ai][0][m][0] + b0, v1 = acc[ai][0][m][1] + b1;
; #pragma unroll
;                         for (int e = 0; e < 4; ++e) { v0[e] = softplus(v0[e]); v1[e] = softplus(v1[e]); }
;                         *(f32x4*)(DT + (unsigned)row * 32u + i0) = v0; *(f32x4*)(DT + (unsigned)row * 32u + i0 + 4) = v1; asm volatile("" ::: "memory"); }
.LBB0_345:
	s_andn2_saveexec_b64 s[8:9], s[8:9]
	v_mov_b32_e32 v174, 0x3eaaaaab
	v_fmamk_f32 v174, v175, 0xbe800000, v174
	v_fma_f32 v174, -v175, v174, 0.5
	v_fma_f32 v174, -v175, v174, 1.0
	v_mul_f32_e32 v174, v175, v174
	s_or_b64 exec, exec, s[8:9]
	v_max_f32_e32 v156, v156, v156
	v_max_f32_e32 v156, 0, v156
	v_add_f32_e32 v176, v156, v153
	v_max_f32_e32 v153, v157, v157
	v_max_f32_e32 v153, 0, v153
	v_add_f32_e32 v177, v153, v169
	v_max_f32_e32 v153, v160, v160
	v_max_f32_e32 v153, 0, v153
	v_add_f32_e32 v178, v153, v171
	v_max_f32_e32 v153, v161, v161
	v_max_f32_e32 v153, 0, v153
	v_add_f32_e32 v179, v153, v173
	v_max_f32_e32 v153, v158, v158
	v_max_f32_e32 v153, 0, v153
	v_add_f32_e32 v156, v153, v168
	v_max_f32_e32 v153, v159, v159
	v_max_f32_e32 v153, 0, v153
	v_add_f32_e32 v157, v153, v170
	v_max_f32_e32 v153, v162, v162
	v_max_f32_e32 v153, 0, v153
	v_add_u32_e32 v160, 0x400, v0
	v_mov_b32_e32 v161, v1
	v_add_f32_e32 v158, v153, v172
	v_max_f32_e32 v153, v163, v163
	v_lshl_add_u64 v[160:161], v[160:161], 2, s[86:87]
	v_max_f32_e32 v153, 0, v153
	v_lshl_add_u64 v[160:161], v[154:155], 2, v[160:161]
	v_add_f32_e32 v159, v153, v174
	global_store_dwordx4 v[160:161], v[176:179], off sc1
	global_store_dwordx4 v[160:161], v[156:159], off offset:16 sc1
	s_nop 1
	v_pk_add_f32 v[156:157], v[78:79], v[134:135]
	s_nop 0
	v_mul_f32_e64 v153, |v156|, s36
	v_exp_f32_e32 v158, v153
	s_nop 0
	v_cmp_ngt_f32_e32 vcc, s46, v158
	s_and_saveexec_b64 s[8:9], vcc
	s_xor_b64 s[8:9], exec, s[8:9]
	s_cbranch_execz .LBB0_349
	v_add_f32_e32 v153, 1.0, v158
	v_cmp_gt_f32_e32 vcc, s51, v153
	s_mov_b32 s2, 0x7f800000
	s_nop 0
	v_cndmask_b32_e64 v158, 0, 32, vcc
	v_ldexp_f32 v153, v153, v158
	v_log_f32_e32 v153, v153
	s_nop 0
	v_mul_f32_e32 v158, 0x3f317217, v153
	v_fma_f32 v158, v153, s47, -v158
	v_fmac_f32_e32 v158, 0x3377d1cf, v153
	v_fmac_f32_e32 v158, 0x3f317217, v153
	v_cmp_lt_f32_e64 s[40:41], |v153|, s2
	s_nop 1
	v_cndmask_b32_e64 v153, v153, v158, s[40:41]
	v_mov_b32_e32 v158, 0x41b17218
	v_cndmask_b32_e32 v158, 0, v158, vcc
	v_sub_f32_e32 v153, v153, v158

; __device__ __forceinline__ float softplus(float x) {
;     const float e = __expf(-fabsf(x));
;     const float l = e < 0.03125f ? e * (1.f - e * (0.5f - e * (0.33333334f - 0.25f * e))) : __logf(1.f + e);
;     return fmaxf(x, 0.f) + l;
; }
;     __device__ __forceinline__ void operator()(ACC_T, const pg8::Unit& u, int wr, int wc, int fr, int fq) const {
;     ...
;                 const int i0 = 8 * fq; const f32x4 b0 = *(const f32x4*)(dt_bias + i0), b1 = *(const f32x4*)(dt_bias + i0 + 4);
; #pragma unroll
;                 for (int ai = 0; ai < 2; ++ai)
; #pragma unroll
;                     for (int m = 0; m < 4; ++m) { const int row = row0 + ai * 128 + m * 16; f32x4 v0 = acc[ai][0][m][0] + b0, v1 = acc[ai][0][m][1] + b1;
; #pragma unroll
;                         for (int e = 0; e < 4; ++e) { v0[e] = softplus(v0[e]); v1[e] = softplus(v1[e]); }
;                         *(f32x4*)(DT + (unsigned)row * 32u + i0) = v0; *(f32x4*)(DT + (unsigned)row * 32u + i0 + 4) = v1; asm volatile("" ::: "memory"); }
.LBB0_377:
	s_andn2_saveexec_b64 s[8:9], s[8:9]
	v_mov_b32_e32 v174, 0x3eaaaaab
	v_fmamk_f32 v174, v175, 0xbe800000, v174
	v_fma_f32 v174, -v175, v174, 0.5
	v_fma_f32 v174, -v175, v174, 1.0
	v_mul_f32_e32 v174, v175, v174
	s_or_b64 exec, exec, s[8:9]
	v_max_f32_e32 v156, v156, v156
	v_max_f32_e32 v156, 0, v156
	v_add_f32_e32 v176, v156, v153
	v_max_f32_e32 v153, v157, v157
	v_max_f32_e32 v153, 0, v153
	v_add_f32_e32 v177, v153, v169
	v_max_f32_e32 v153, v160, v160
	v_max_f32_e32 v153, 0, v153
	v_add_f32_e32 v178, v153, v171
	v_max_f32_e32 v153, v161, v161
	v_max_f32_e32 v153, 0, v153
	v_add_f32_e32 v179, v153, v173
	v_max_f32_e32 v153, v158, v158
	v_max_f32_e32 v153, 0, v153
	v_add_f32_e32 v156, v153, v168
	v_max_f32_e32 v153, v159, v159
	v_max_f32_e32 v153, 0, v153
	v_add_f32_e32 v157, v153, v170
	v_max_f32_e32 v153, v162, v162
	v_max_f32_e32 v153, 0, v153
	v_add_u32_e32 v160, 0x600, v0
	v_mov_b32_e32 v161, v1
	v_add_f32_e32 v158, v153, v172
	v_max_f32_e32 v153, v163, v163
	v_lshl_add_u64 v[160:161], v[160:161], 2, s[86:87]
	v_max_f32_e32 v153, 0, v153
	v_lshl_add_u64 v[160:161], v[154:155], 2, v[160:161]
	v_add_f32_e32 v159, v153, v174
	global_store_dwordx4 v[160:161], v[176:179], off sc1
	global_store_dwordx4 v[160:161], v[156:159], off offset:16 sc1
	s_nop 1
	v_pk_add_f32 v[156:157], v[62:63], v[134:135]
	s_nop 0
	v_mul_f32_e64 v153, |v156|, s36
	v_exp_f32_e32 v158, v153
	s_nop 0
	v_cmp_ngt_f32_e32 vcc, s46, v158
	s_and_saveexec_b64 s[8:9], vcc
	s_xor_b64 s[8:9], exec, s[8:9]
	s_cbranch_execz .LBB0_381
	v_add_f32_e32 v153, 1.0, v158
	v_cmp_gt_f32_e32 vcc, s51, v153
	s_mov_b32 s2, 0x7f800000
	s_nop 0
	v_cndmask_b32_e64 v158, 0, 32, vcc
	v_ldexp_f32 v153, v153, v158
	v_log_f32_e32 v153, v153
	s_nop 0
	v_mul_f32_e32 v158, 0x3f317217, v153
	v_fma_f32 v158, v153, s47, -v158
	v_fmac_f32_e32 v158, 0x3377d1cf, v153
	v_fmac_f32_e32 v158, 0x3f317217, v153
	v_cmp_lt_f32_e64 s[40:41], |v153|, s2
	s_nop 1
	v_cndmask_b32_e64 v153, v153, v158, s[40:41]
	v_mov_b32_e32 v158, 0x41b17218
	v_cndmask_b32_e32 v158, 0, v158, vcc
	v_sub_f32_e32 v153, v153, v158

; __device__ __forceinline__ float softplus(float x) {
;     const float e = __expf(-fabsf(x));
;     const float l = e < 0.03125f ? e * (1.f - e * (0.5f - e * (0.33333334f - 0.25f * e))) : __logf(1.f + e);
;     return fmaxf(x, 0.f) + l;
; }
;     __device__ __forceinline__ void operator()(ACC_T, const pg8::Unit& u, int wr, int wc, int fr, int fq) const {
;     ...
;                 const int i0 = 8 * fq; const f32x4 b0 = *(const f32x4*)(dt_bias + i0), b1 = *(const f32x4*)(dt_bias + i0 + 4);
; #pragma unroll
;                 for (int ai = 0; ai < 2; ++ai)
; #pragma unroll
;                     for (int m = 0; m < 4; ++m) { const int row = row0 + ai * 128 + m * 16; f32x4 v0 = acc[ai][0][m][0] + b0, v1 = acc[ai][0][m][1] + b1;
; #pragma unroll
;                         for (int e = 0; e < 4; ++e) { v0[e] = softplus(v0[e]); v1[e] = softplus(v1[e]); }
;                         *(f32x4*)(DT + (unsigned)row * 32u + i0) = v0; *(f32x4*)(DT + (unsigned)row * 32u + i0 + 4) = v1; asm volatile("" ::: "memory"); }
.LBB0_409:
	s_andn2_saveexec_b64 s[8:9], s[8:9]
	v_mov_b32_e32 v174, 0x3eaaaaab
	v_fmamk_f32 v174, v175, 0xbe800000, v174
	v_fma_f32 v174, -v175, v174, 0.5
	v_fma_f32 v174, -v175, v174, 1.0
	v_mul_f32_e32 v174, v175, v174
	s_or_b64 exec, exec, s[8:9]
	v_max_f32_e32 v156, v156, v156
	v_max_f32_e32 v156, 0, v156
	v_add_f32_e32 v176, v156, v153
	v_max_f32_e32 v153, v157, v157
	v_max_f32_e32 v153, 0, v153
	v_add_f32_e32 v177, v153, v169
	v_max_f32_e32 v153, v160, v160
	v_max_f32_e32 v153, 0, v153
	v_add_f32_e32 v178, v153, v171
	v_max_f32_e32 v153, v161, v161
	v_max_f32_e32 v153, 0, v153
	v_add_f32_e32 v179, v153, v173
	v_max_f32_e32 v153, v158, v158
	v_max_f32_e32 v153, 0, v153
	v_add_f32_e32 v156, v153, v168
	v_max_f32_e32 v153, v159, v159
	v_max_f32_e32 v153, 0, v153
	v_add_f32_e32 v157, v153, v170
	v_max_f32_e32 v153, v162, v162
	v_max_f32_e32 v153, 0, v153
	v_add_u32_e32 v160, 0x1000, v0
	v_mov_b32_e32 v161, v1
	v_add_f32_e32 v158, v153, v172
	v_max_f32_e32 v153, v163, v163
	v_lshl_add_u64 v[160:161], v[160:161], 2, s[86:87]
	v_max_f32_e32 v153, 0, v153
	v_lshl_add_u64 v[160:161], v[154:155], 2, v[160:161]
	v_add_f32_e32 v159, v153, v174
	global_store_dwordx4 v[160:161], v[176:179], off sc1
	global_store_dwordx4 v[160:161], v[156:159], off offset:16 sc1
	s_nop 1
	v_pk_add_f32 v[156:157], v[46:47], v[134:135]
	s_nop 0
	v_mul_f32_e64 v153, |v156|, s36
	v_exp_f32_e32 v158, v153
	s_nop 0
	v_cmp_ngt_f32_e32 vcc, s46, v158
	s_and_saveexec_b64 s[8:9], vcc
	s_xor_b64 s[8:9], exec, s[8:9]
	s_cbranch_execz .LBB0_413
	v_add_f32_e32 v153, 1.0, v158
	v_cmp_gt_f32_e32 vcc, s51, v153
	s_mov_b32 s2, 0x7f800000
	s_nop 0
	v_cndmask_b32_e64 v158, 0, 32, vcc
	v_ldexp_f32 v153, v153, v158
	v_log_f32_e32 v153, v153
	s_nop 0
	v_mul_f32_e32 v158, 0x3f317217, v153
	v_fma_f32 v158, v153, s47, -v158
	v_fmac_f32_e32 v158, 0x3377d1cf, v153
	v_fmac_f32_e32 v158, 0x3f317217, v153
	v_cmp_lt_f32_e64 s[40:41], |v153|, s2
	s_nop 1
	v_cndmask_b32_e64 v153, v153, v158, s[40:41]
	v_mov_b32_e32 v158, 0x41b17218
	v_cndmask_b32_e32 v158, 0, v158, vcc
	v_sub_f32_e32 v153, v153, v158

; __device__ __forceinline__ float softplus(float x) {
;     const float e = __expf(-fabsf(x));
;     const float l = e < 0.03125f ? e * (1.f - e * (0.5f - e * (0.33333334f - 0.25f * e))) : __logf(1.f + e);
;     return fmaxf(x, 0.f) + l;
; }
;     __device__ __forceinline__ void operator()(ACC_T, const pg8::Unit& u, int wr, int wc, int fr, int fq) const {
;     ...
;                 const int i0 = 8 * fq; const f32x4 b0 = *(const f32x4*)(dt_bias + i0), b1 = *(const f32x4*)(dt_bias + i0 + 4);
; #pragma unroll
;                 for (int ai = 0; ai < 2; ++ai)
; #pragma unroll
;                     for (int m = 0; m < 4; ++m) { const int row = row0 + ai * 128 + m * 16; f32x4 v0 = acc[ai][0][m][0] + b0, v1 = acc[ai][0][m][1] + b1;
; #pragma unroll
;                         for (int e = 0; e < 4; ++e) { v0[e] = softplus(v0[e]); v1[e] = softplus(v1[e]); }
;                         *(f32x4*)(DT + (unsigned)row * 32u + i0) = v0; *(f32x4*)(DT + (unsigned)row * 32u + i0 + 4) = v1; asm volatile("" ::: "memory"); }
.LBB0_441:
	s_andn2_saveexec_b64 s[8:9], s[8:9]
	v_mov_b32_e32 v174, 0x3eaaaaab
	v_fmamk_f32 v174, v175, 0xbe800000, v174
	v_fma_f32 v174, -v175, v174, 0.5
	v_fma_f32 v174, -v175, v174, 1.0
	v_mul_f32_e32 v174, v175, v174
	s_or_b64 exec, exec, s[8:9]
	v_max_f32_e32 v156, v156, v156
	v_max_f32_e32 v156, 0, v156
	v_add_f32_e32 v176, v156, v153
	v_max_f32_e32 v153, v157, v157
	v_max_f32_e32 v153, 0, v153
	v_add_f32_e32 v177, v153, v169
	v_max_f32_e32 v153, v160, v160
	v_max_f32_e32 v153, 0, v153
	v_add_f32_e32 v178, v153, v171
	v_max_f32_e32 v153, v161, v161
	v_max_f32_e32 v153, 0, v153
	v_add_f32_e32 v179, v153, v173
	v_max_f32_e32 v153, v158, v158
	v_max_f32_e32 v153, 0, v153
	v_add_f32_e32 v156, v153, v168
	v_max_f32_e32 v153, v159, v159
	v_max_f32_e32 v153, 0, v153
	v_add_f32_e32 v157, v153, v170
	v_max_f32_e32 v153, v162, v162
	v_max_f32_e32 v153, 0, v153
	v_add_u32_e32 v160, 0x1200, v0
	v_mov_b32_e32 v161, v1
	v_add_f32_e32 v158, v153, v172
	v_max_f32_e32 v153, v163, v163
	v_lshl_add_u64 v[160:161], v[160:161], 2, s[86:87]
	v_max_f32_e32 v153, 0, v153
	v_lshl_add_u64 v[160:161], v[154:155], 2, v[160:161]
	v_add_f32_e32 v159, v153, v174
	global_store_dwordx4 v[160:161], v[176:179], off sc1
	global_store_dwordx4 v[160:161], v[156:159], off offset:16 sc1
	s_nop 1
	v_pk_add_f32 v[156:157], v[30:31], v[134:135]
	s_nop 0
	v_mul_f32_e64 v153, |v156|, s36
	v_exp_f32_e32 v158, v153
	s_nop 0
	v_cmp_ngt_f32_e32 vcc, s46, v158
	s_and_saveexec_b64 s[8:9], vcc
	s_xor_b64 s[8:9], exec, s[8:9]
	s_cbranch_execz .LBB0_445
	v_add_f32_e32 v153, 1.0, v158
	v_cmp_gt_f32_e32 vcc, s51, v153
	s_mov_b32 s2, 0x7f800000
	s_nop 0
	v_cndmask_b32_e64 v158, 0, 32, vcc
	v_ldexp_f32 v153, v153, v158
	v_log_f32_e32 v153, v153
	s_nop 0
	v_mul_f32_e32 v158, 0x3f317217, v153
	v_fma_f32 v158, v153, s47, -v158
	v_fmac_f32_e32 v158, 0x3377d1cf, v153
	v_fmac_f32_e32 v158, 0x3f317217, v153
	v_cmp_lt_f32_e64 s[40:41], |v153|, s2
	s_nop 1
	v_cndmask_b32_e64 v153, v153, v158, s[40:41]
	v_mov_b32_e32 v158, 0x41b17218
	v_cndmask_b32_e32 v158, 0, v158, vcc
	v_sub_f32_e32 v153, v153, v158

; __device__ __forceinline__ float softplus(float x) {
;     const float e = __expf(-fabsf(x));
;     const float l = e < 0.03125f ? e * (1.f - e * (0.5f - e * (0.33333334f - 0.25f * e))) : __logf(1.f + e);
;     return fmaxf(x, 0.f) + l;
; }
;     __device__ __forceinline__ void operator()(ACC_T, const pg8::Unit& u, int wr, int wc, int fr, int fq) const {
;     ...
;                 const int i0 = 8 * fq; const f32x4 b0 = *(const f32x4*)(dt_bias + i0), b1 = *(const f32x4*)(dt_bias + i0 + 4);
; #pragma unroll
;                 for (int ai = 0; ai < 2; ++ai)
; #pragma unroll
;                     for (int m = 0; m < 4; ++m) { const int row = row0 + ai * 128 + m * 16; f32x4 v0 = acc[ai][0][m][0] + b0, v1 = acc[ai][0][m][1] + b1;
; #pragma unroll
;                         for (int e = 0; e < 4; ++e) { v0[e] = softplus(v0[e]); v1[e] = softplus(v1[e]); }
;                         *(f32x4*)(DT + (unsigned)row * 32u + i0) = v0; *(f32x4*)(DT + (unsigned)row * 32u + i0 + 4) = v1; asm volatile("" ::: "memory"); }
.LBB0_473:
	s_andn2_saveexec_b64 s[8:9], s[8:9]
	v_mov_b32_e32 v174, 0x3eaaaaab
	v_fmamk_f32 v174, v175, 0xbe800000, v174
	v_fma_f32 v174, -v175, v174, 0.5
	v_fma_f32 v174, -v175, v174, 1.0
	v_mul_f32_e32 v174, v175, v174
	s_or_b64 exec, exec, s[8:9]
	v_max_f32_e32 v156, v156, v156
	v_max_f32_e32 v156, 0, v156
	v_add_f32_e32 v176, v156, v153
	v_max_f32_e32 v153, v157, v157
	v_max_f32_e32 v153, 0, v153
	v_add_f32_e32 v177, v153, v169
	v_max_f32_e32 v153, v160, v160
	v_max_f32_e32 v153, 0, v153
	v_add_f32_e32 v178, v153, v171
	v_max_f32_e32 v153, v161, v161
	v_max_f32_e32 v153, 0, v153
	v_add_f32_e32 v179, v153, v173
	v_max_f32_e32 v153, v158, v158
	v_max_f32_e32 v153, 0, v153
	v_add_f32_e32 v156, v153, v168
	v_max_f32_e32 v153, v159, v159
	v_max_f32_e32 v153, 0, v153
	v_add_f32_e32 v157, v153, v170
	v_max_f32_e32 v153, v162, v162
	v_max_f32_e32 v153, 0, v153
	v_add_f32_e32 v158, v153, v172
	v_max_f32_e32 v153, v163, v163
	v_add_u32_e32 v160, 0x1400, v0
	v_mov_b32_e32 v161, v1
	v_max_f32_e32 v153, 0, v153
	v_lshl_add_u64 v[160:161], v[160:161], 2, s[86:87]
	v_pk_add_f32 v[134:135], v[14:15], v[134:135]
	v_add_f32_e32 v159, v153, v174
	v_lshl_add_u64 v[160:161], v[154:155], 2, v[160:161]
	v_mul_f32_e64 v153, |v134|, s36
	global_store_dwordx4 v[160:161], v[176:179], off sc1
	global_store_dwordx4 v[160:161], v[156:159], off offset:16 sc1
	s_nop 1
	v_exp_f32_e32 v156, v153
	s_nop 0
	v_cmp_ngt_f32_e32 vcc, s46, v156
	s_and_saveexec_b64 s[8:9], vcc
	s_xor_b64 s[8:9], exec, s[8:9]
	s_cbranch_execz .LBB0_477
	v_add_f32_e32 v153, 1.0, v156
	v_cmp_gt_f32_e32 vcc, s51, v153
	s_mov_b32 s2, 0x7f800000
	s_nop 0
	v_cndmask_b32_e64 v156, 0, 32, vcc
	v_ldexp_f32 v153, v153, v156
	v_log_f32_e32 v153, v153
	s_nop 0
	v_mul_f32_e32 v156, 0x3f317217, v153
	v_fma_f32 v156, v153, s47, -v156
	v_fmac_f32_e32 v156, 0x3377d1cf, v153
	v_fmac_f32_e32 v156, 0x3f317217, v153
	v_cmp_lt_f32_e64 s[40:41], |v153|, s2
	s_nop 1
	v_cndmask_b32_e64 v153, v153, v156, s[40:41]
	v_mov_b32_e32 v156, 0x41b17218
	v_cndmask_b32_e32 v156, 0, v156, vcc
	v_sub_f32_e32 v153, v153, v156

; __device__ __forceinline__ float softplus(float x) {
;     const float e = __expf(-fabsf(x));
;     const float l = e < 0.03125f ? e * (1.f - e * (0.5f - e * (0.33333334f - 0.25f * e))) : __logf(1.f + e);
;     return fmaxf(x, 0.f) + l;
; }
;     __device__ __forceinline__ void operator()(ACC_T, const pg8::Unit& u, int wr, int wc, int fr, int fq) const {
;     ...
;                     for (int m = 0; m < 4; ++m) { const int row = row0 + ai * 128 + m * 16; f32x4 v0 = acc[ai][0][m][0] + b0, v1 = acc[ai][0][m][1] + b1;
; #pragma unroll
;                         for (int e = 0; e < 4; ++e) { v0[e] = softplus(v0[e]); v1[e] = softplus(v1[e]); }
;                         *(f32x4*)(DT + (unsigned)row * 32u + i0) = v0; *(f32x4*)(DT + (unsigned)row * 32u + i0 + 4) = v1; asm volatile("" ::: "memory"); }
.LBB0_505:
	s_andn2_saveexec_b64 s[8:9], s[8:9]
	v_mov_b32_e32 v162, 0x3eaaaaab
	v_fmamk_f32 v162, v163, 0xbe800000, v162
	v_fma_f32 v162, -v163, v162, 0.5
	v_fma_f32 v162, -v163, v162, 1.0
	v_mul_f32_e32 v162, v163, v162
	s_or_b64 exec, exec, s[8:9]
	v_max_f32_e32 v135, v135, v135
	v_max_f32_e32 v130, v130, v130
	v_max_f32_e32 v134, v134, v134
	v_max_f32_e32 v135, 0, v135
	v_max_f32_e32 v136, v136, v136
	v_max_f32_e32 v137, v137, v137
	v_max_f32_e32 v130, 0, v130
	v_add_u32_e32 v0, 0x1600, v0
	v_max_f32_e32 v134, 0, v134
	v_add_f32_e32 v135, v135, v157
	v_max_f32_e32 v136, 0, v136
	v_max_f32_e32 v137, 0, v137
	v_add_f32_e32 v130, v130, v156
	v_max_f32_e32 v131, v131, v131
	v_max_f32_e32 v132, v132, v132
	v_max_f32_e32 v133, v133, v133
	v_lshl_add_u64 v[156:157], v[0:1], 2, s[86:87]
	v_add_f32_e32 v134, v134, v153
	v_add_f32_e32 v136, v136, v159
	v_add_f32_e32 v137, v137, v161
	v_max_f32_e32 v131, 0, v131
	v_max_f32_e32 v132, 0, v132
	v_max_f32_e32 v133, 0, v133
	v_lshl_add_u64 v[154:155], v[154:155], 2, v[156:157]
	v_add_f32_e32 v131, v131, v158
	v_add_f32_e32 v132, v132, v160
	v_add_f32_e32 v133, v133, v162
	global_store_dwordx4 v[154:155], v[134:137], off sc1
	global_store_dwordx4 v[154:155], v[130:133], off offset:16 sc1

; __device__ __forceinline__ void st8(bf16_t* p, f32x4 a, f32x4 b) { u32x4 w; w.x = pk2(a[0], a[1]); w.y = pk2(a[2], a[3]); w.z = pk2(b[0], b[1]); w.w = pk2(b[2], b[3]); *(u32x4*)p = w; }
;     __device__ __forceinline__ void operator()(ACC_T, const pg8::Unit& u, int wr, int wc, int fr, int fq) const {
;     ...
;                     for (int m = 0; m < 4; ++m) { const int row = row0 + ai * 128 + m * 16; const f32x4 v0 = acc[ai][0][m][0], v1 = acc[ai][0][m][1];
;                         const f32x4* rp = (const f32x4*)(rope + (unsigned)((tbase + row) * 64 + 8 * g8)); const f32x4 c01 = rp[0], c23 = rp[1];
;                         f32x4 o1, o2;
;                         o1[0] = v0[0] * c01[0] - v1[0] * c01[1]; o2[0] = v0[0] * c01[1] + v1[0] * c01[0];
;                         o1[1] = v0[1] * c01[2] - v1[1] * c01[3]; o2[1] = v0[1] * c01[3] + v1[1] * c01[2];
;                         o1[2] = v0[2] * c23[0] - v1[2] * c23[1]; o2[2] = v0[2] * c23[1] + v1[2] * c23[0];
;                         o1[3] = v0[3] * c23[2] - v1[3] * c23[3]; o2[3] = v0[3] * c23[3] + v1[3] * c23[2];
;                         st8(KR + (unsigned)row * 64u + 8 * g8, o1, o2); asm volatile("" ::: "memory"); }
.LBB0_509:
	s_andn2_b64 vcc, exec, s[8:9]
	s_cbranch_vccnz .LBB0_511
	v_add_u32_e32 v0, s78, v150
	v_lshl_add_u32 v0, v0, 6, v152
	v_lshl_add_u64 v[134:135], v[0:1], 2, s[88:89]
	global_load_dwordx4 v[130:133], v[134:135], off offset:16
	s_nop 0
	global_load_dwordx4 v[134:137], v[134:135], off
	v_ashrrev_i32_e32 v153, 31, v152
	v_lshlrev_b32_e32 v0, 6, v150
	s_waitcnt vmcnt(0)
	v_mov_b32_e32 v155, v136
	v_mov_b32_e32 v136, v135
	v_mov_b32_e32 v154, v134
	v_pk_mul_f32 v[134:135], v[122:123], v[136:137]
	s_nop 0
	v_pk_fma_f32 v[134:135], v[126:127], v[154:155], v[134:135] neg_lo:[0,0,1] neg_hi:[0,0,1]
	v_pk_mul_f32 v[154:155], v[122:123], v[154:155]
	s_nop 0
	v_pk_fma_f32 v[136:137], v[126:127], v[136:137], v[154:155]
	v_mov_b32_e32 v155, v132
	v_mov_b32_e32 v132, v131
	v_mov_b32_e32 v154, v130
	v_pk_mul_f32 v[130:131], v[124:125], v[132:133]
	s_nop 0
	v_pk_fma_f32 v[156:157], v[128:129], v[154:155], v[130:131] neg_lo:[0,0,1] neg_hi:[0,0,1]
	v_pk_mul_f32 v[130:131], v[124:125], v[154:155]
	s_nop 0
	v_pk_fma_f32 v[154:155], v[128:129], v[132:133], v[130:131]
	v_lshl_add_u64 v[132:133], v[0:1], 1, s[84:85]
	v_lshlrev_b64 v[130:131], 1, v[152:153]
	v_add_u32_e32 v153, 16, v150
	v_lshl_add_u64 v[158:159], v[132:133], 0, v[130:131]
	v_cvt_pk_bf16_f32 v132, v134, v135
	v_cvt_pk_bf16_f32 v133, v156, v157
	v_cvt_pk_bf16_f32 v134, v136, v137
	v_cvt_pk_bf16_f32 v135, v154, v155
	v_add_u32_e32 v0, s78, v153
	global_store_dwordx4 v[158:159], v[132:135], off sc1
	v_lshl_add_u32 v0, v0, 6, v152
	v_lshl_add_u64 v[136:137], v[0:1], 2, s[88:89]
	global_load_dwordx4 v[132:135], v[136:137], off offset:16
	global_load_dwordx4 v[154:157], v[136:137], off
	v_lshlrev_b32_e32 v0, 6, v153
	v_add_u32_e32 v153, 32, v150
	s_waitcnt vmcnt(0)
	v_mov_b32_e32 v137, v156
	v_mov_b32_e32 v156, v155
	v_mov_b32_e32 v136, v154
	v_pk_mul_f32 v[154:155], v[106:107], v[156:157]
	s_nop 0
	v_pk_fma_f32 v[154:155], v[110:111], v[136:137], v[154:155] neg_lo:[0,0,1] neg_hi:[0,0,1]
	v_pk_mul_f32 v[136:137], v[106:107], v[136:137]
	s_nop 0
	v_pk_fma_f32 v[136:137], v[110:111], v[156:157], v[136:137]
	v_mov_b32_e32 v157, v134
	v_mov_b32_e32 v134, v133
	v_mov_b32_e32 v156, v132
	v_pk_mul_f32 v[132:133], v[108:109], v[134:135]
	s_nop 0
	v_pk_fma_f32 v[158:159], v[112:113], v[156:157], v[132:133] neg_lo:[0,0,1] neg_hi:[0,0,1]
	v_pk_mul_f32 v[132:133], v[108:109], v[156:157]
	s_nop 0
	v_pk_fma_f32 v[156:157], v[112:113], v[134:135], v[132:133]
	v_lshl_add_u64 v[132:133], v[0:1], 1, s[84:85]
	v_lshl_add_u64 v[160:161], v[132:133], 0, v[130:131]
	v_cvt_pk_bf16_f32 v132, v154, v155
	v_cvt_pk_bf16_f32 v133, v158, v159
	v_cvt_pk_bf16_f32 v134, v136, v137
	v_cvt_pk_bf16_f32 v135, v156, v157
	v_add_u32_e32 v0, s78, v153
	global_store_dwordx4 v[160:161], v[132:135], off sc1
	v_lshl_add_u32 v0, v0, 6, v152
	v_lshl_add_u64 v[136:137], v[0:1], 2, s[88:89]
	global_load_dwordx4 v[132:135], v[136:137], off offset:16
	global_load_dwordx4 v[154:157], v[136:137], off
	v_lshlrev_b32_e32 v0, 6, v153
	v_add_u32_e32 v153, 48, v150
	s_waitcnt vmcnt(0)
	v_mov_b32_e32 v137, v156
	v_mov_b32_e32 v156, v155
	v_mov_b32_e32 v136, v154
	v_pk_mul_f32 v[154:155], v[90:91], v[156:157]
	s_nop 0
	v_pk_fma_f32 v[154:155], v[94:95], v[136:137], v[154:155] neg_lo:[0,0,1] neg_hi:[0,0,1]
	v_pk_mul_f32 v[136:137], v[90:91], v[136:137]
	s_nop 0
	v_pk_fma_f32 v[136:137], v[94:95], v[156:157], v[136:137]
	v_mov_b32_e32 v157, v134
	v_mov_b32_e32 v134, v133
	v_mov_b32_e32 v156, v132
	v_pk_mul_f32 v[132:133], v[92:93], v[134:135]
	s_nop 0
	v_pk_fma_f32 v[158:159], v[96:97], v[156:157], v[132:133] neg_lo:[0,0,1] neg_hi:[0,0,1]
	v_pk_mul_f32 v[132:133], v[92:93], v[156:157]
	s_nop 0
	v_pk_fma_f32 v[156:157], v[96:97], v[134:135], v[132:133]
	v_lshl_add_u64 v[132:133], v[0:1], 1, s[84:85]
	v_lshl_add_u64 v[160:161], v[132:133], 0, v[130:131]
	v_cvt_pk_bf16_f32 v132, v154, v155
	v_cvt_pk_bf16_f32 v133, v158, v159
	v_cvt_pk_bf16_f32 v134, v136, v137
	v_cvt_pk_bf16_f32 v135, v156, v157
	v_add_u32_e32 v0, s78, v153
	global_store_dwordx4 v[160:161], v[132:135], off sc1
	v_lshl_add_u32 v0, v0, 6, v152
	v_lshl_add_u64 v[136:137], v[0:1], 2, s[88:89]
	global_load_dwordx4 v[132:135], v[136:137], off offset:16
	global_load_dwordx4 v[154:157], v[136:137], off
	v_lshlrev_b32_e32 v0, 6, v153
	v_add_u32_e32 v153, 0x80, v150
	s_waitcnt vmcnt(0)
	v_mov_b32_e32 v137, v156
	v_mov_b32_e32 v156, v155
	v_mov_b32_e32 v136, v154
	v_pk_mul_f32 v[154:155], v[74:75], v[156:157]
	s_nop 0
	v_pk_fma_f32 v[154:155], v[78:79], v[136:137], v[154:155] neg_lo:[0,0,1] neg_hi:[0,0,1]
	v_pk_mul_f32 v[136:137], v[74:75], v[136:137]
	s_nop 0
	v_pk_fma_f32 v[136:137], v[78:79], v[156:157], v[136:137]
	v_mov_b32_e32 v157, v134
	v_mov_b32_e32 v134, v133
	v_mov_b32_e32 v156, v132
	v_pk_mul_f32 v[132:133], v[76:77], v[134:135]
	s_nop 0
	v_pk_fma_f32 v[158:159], v[80:81], v[156:157], v[132:133] neg_lo:[0,0,1] neg_hi:[0,0,1]
	v_pk_mul_f32 v[132:133], v[76:77], v[156:157]
	s_nop 0
	v_pk_fma_f32 v[156:157], v[80:81], v[134:135], v[132:133]
	v_lshl_add_u64 v[132:133], v[0:1], 1, s[84:85]
	v_lshl_add_u64 v[160:161], v[132:133], 0, v[130:131]
	v_cvt_pk_bf16_f32 v132, v154, v155
	v_cvt_pk_bf16_f32 v133, v158, v159
	v_cvt_pk_bf16_f32 v134, v136, v137
	v_cvt_pk_bf16_f32 v135, v156, v157
	v_add_u32_e32 v0, s78, v153
	global_store_dwordx4 v[160:161], v[132:135], off sc1
	v_lshl_add_u32 v0, v0, 6, v152
	v_lshl_add_u64 v[136:137], v[0:1], 2, s[88:89]
	global_load_dwordx4 v[132:135], v[136:137], off offset:16
	global_load_dwordx4 v[154:157], v[136:137], off
	v_lshlrev_b32_e32 v0, 6, v153
	v_add_u32_e32 v153, 0x90, v150
	s_waitcnt vmcnt(0)
; __device__ __forceinline__ void st8(bf16_t* p, f32x4 a, f32x4 b) { u32x4 w; w.x = pk2(a[0], a[1]); w.y = pk2(a[2], a[3]); w.z = pk2(b[0], b[1]); w.w = pk2(b[2], b[3]); *(u32x4*)p = w; }
;     __device__ __forceinline__ void operator()(ACC_T, const pg8::Unit& u, int wr, int wc, int fr, int fq) const {
;     ...
;                     for (int m = 0; m < 4; ++m) { const int row = row0 + ai * 128 + m * 16; const f32x4 v0 = acc[ai][0][m][0], v1 = acc[ai][0][m][1];
;                         const f32x4* rp = (const f32x4*)(rope + (unsigned)((tbase + row) * 64 + 8 * g8)); const f32x4 c01 = rp[0], c23 = rp[1];
;                         f32x4 o1, o2;
;                         o1[0] = v0[0] * c01[0] - v1[0] * c01[1]; o2[0] = v0[0] * c01[1] + v1[0] * c01[0];
;                         o1[1] = v0[1] * c01[2] - v1[1] * c01[3]; o2[1] = v0[1] * c01[3] + v1[1] * c01[2];
;                         o1[2] = v0[2] * c23[0] - v1[2] * c23[1]; o2[2] = v0[2] * c23[1] + v1[2] * c23[0];
;                         o1[3] = v0[3] * c23[2] - v1[3] * c23[3]; o2[3] = v0[3] * c23[3] + v1[3] * c23[2];
;                         st8(KR + (unsigned)row * 64u + 8 * g8, o1, o2); asm volatile("" ::: "memory"); }
	v_mov_b32_e32 v137, v156
	v_mov_b32_e32 v156, v155
	v_mov_b32_e32 v136, v154
	v_pk_mul_f32 v[154:155], v[58:59], v[156:157]
	s_nop 0
	v_pk_fma_f32 v[154:155], v[62:63], v[136:137], v[154:155] neg_lo:[0,0,1] neg_hi:[0,0,1]
	v_pk_mul_f32 v[136:137], v[58:59], v[136:137]
	s_nop 0
	v_pk_fma_f32 v[136:137], v[62:63], v[156:157], v[136:137]
	v_mov_b32_e32 v157, v134
	v_mov_b32_e32 v134, v133
	v_mov_b32_e32 v156, v132
	v_pk_mul_f32 v[132:133], v[60:61], v[134:135]
	s_nop 0
	v_pk_fma_f32 v[158:159], v[64:65], v[156:157], v[132:133] neg_lo:[0,0,1] neg_hi:[0,0,1]
	v_pk_mul_f32 v[132:133], v[60:61], v[156:157]
	s_nop 0
	v_pk_fma_f32 v[156:157], v[64:65], v[134:135], v[132:133]
	v_lshl_add_u64 v[132:133], v[0:1], 1, s[84:85]
	v_lshl_add_u64 v[160:161], v[132:133], 0, v[130:131]
	v_cvt_pk_bf16_f32 v132, v154, v155
	v_cvt_pk_bf16_f32 v133, v158, v159
	v_cvt_pk_bf16_f32 v134, v136, v137
	v_cvt_pk_bf16_f32 v135, v156, v157
	v_add_u32_e32 v0, s78, v153
	global_store_dwordx4 v[160:161], v[132:135], off sc1
	v_lshl_add_u32 v0, v0, 6, v152
	v_lshl_add_u64 v[136:137], v[0:1], 2, s[88:89]
	global_load_dwordx4 v[132:135], v[136:137], off offset:16
	global_load_dwordx4 v[154:157], v[136:137], off
	v_lshlrev_b32_e32 v0, 6, v153
	v_add_u32_e32 v153, 0xa0, v150
	s_waitcnt vmcnt(0)
	v_mov_b32_e32 v137, v156
	v_mov_b32_e32 v156, v155
	v_mov_b32_e32 v136, v154
	v_pk_mul_f32 v[154:155], v[42:43], v[156:157]
	s_nop 0
	v_pk_fma_f32 v[154:155], v[46:47], v[136:137], v[154:155] neg_lo:[0,0,1] neg_hi:[0,0,1]
	v_pk_mul_f32 v[136:137], v[42:43], v[136:137]
	s_nop 0
	v_pk_fma_f32 v[136:137], v[46:47], v[156:157], v[136:137]
	v_mov_b32_e32 v157, v134
	v_mov_b32_e32 v134, v133
	v_mov_b32_e32 v156, v132
	v_pk_mul_f32 v[132:133], v[44:45], v[134:135]
	s_nop 0
	v_pk_fma_f32 v[158:159], v[48:49], v[156:157], v[132:133] neg_lo:[0,0,1] neg_hi:[0,0,1]
	v_pk_mul_f32 v[132:133], v[44:45], v[156:157]
	s_nop 0
	v_pk_fma_f32 v[156:157], v[48:49], v[134:135], v[132:133]
	v_lshl_add_u64 v[132:133], v[0:1], 1, s[84:85]
	v_lshl_add_u64 v[160:161], v[132:133], 0, v[130:131]
	v_cvt_pk_bf16_f32 v132, v154, v155
	v_cvt_pk_bf16_f32 v133, v158, v159
	v_cvt_pk_bf16_f32 v134, v136, v137
	v_cvt_pk_bf16_f32 v135, v156, v157
	v_add_u32_e32 v0, s78, v153
	global_store_dwordx4 v[160:161], v[132:135], off sc1
	v_lshl_add_u32 v0, v0, 6, v152
	v_lshl_add_u64 v[136:137], v[0:1], 2, s[88:89]
	global_load_dwordx4 v[132:135], v[136:137], off offset:16
	global_load_dwordx4 v[154:157], v[136:137], off
	v_lshlrev_b32_e32 v0, 6, v153
	v_add_u32_e32 v153, 0xb0, v150
	s_waitcnt vmcnt(0)
	v_mov_b32_e32 v137, v156
	v_mov_b32_e32 v156, v155
	v_mov_b32_e32 v136, v154
	v_pk_mul_f32 v[154:155], v[26:27], v[156:157]
	s_nop 0
	v_pk_fma_f32 v[154:155], v[30:31], v[136:137], v[154:155] neg_lo:[0,0,1] neg_hi:[0,0,1]
	v_pk_mul_f32 v[136:137], v[26:27], v[136:137]
	s_nop 0
	v_pk_fma_f32 v[136:137], v[30:31], v[156:157], v[136:137]
	v_mov_b32_e32 v157, v134
	v_mov_b32_e32 v134, v133
	v_mov_b32_e32 v156, v132
	v_pk_mul_f32 v[132:133], v[28:29], v[134:135]
	s_nop 0
	v_pk_fma_f32 v[158:159], v[32:33], v[156:157], v[132:133] neg_lo:[0,0,1] neg_hi:[0,0,1]
	v_pk_mul_f32 v[132:133], v[28:29], v[156:157]
	s_nop 0
	v_pk_fma_f32 v[156:157], v[32:33], v[134:135], v[132:133]
	v_lshl_add_u64 v[132:133], v[0:1], 1, s[84:85]
	v_lshl_add_u64 v[160:161], v[132:133], 0, v[130:131]
	v_cvt_pk_bf16_f32 v132, v154, v155
	v_cvt_pk_bf16_f32 v133, v158, v159
	v_cvt_pk_bf16_f32 v134, v136, v137
	v_cvt_pk_bf16_f32 v135, v156, v157
	v_add_u32_e32 v0, s78, v153
	global_store_dwordx4 v[160:161], v[132:135], off sc1
	v_lshl_add_u32 v0, v0, 6, v152
	v_lshl_add_u64 v[136:137], v[0:1], 2, s[88:89]
	global_load_dwordx4 v[132:135], v[136:137], off offset:16
	global_load_dwordx4 v[154:157], v[136:137], off
	v_lshlrev_b32_e32 v0, 6, v153
	s_waitcnt vmcnt(0)
	v_mov_b32_e32 v137, v156
	v_mov_b32_e32 v156, v155
	v_mov_b32_e32 v136, v154
	v_pk_mul_f32 v[154:155], v[10:11], v[156:157]
	s_nop 0
	v_pk_fma_f32 v[154:155], v[14:15], v[136:137], v[154:155] neg_lo:[0,0,1] neg_hi:[0,0,1]
	v_pk_mul_f32 v[136:137], v[10:11], v[136:137]
	s_nop 0
	v_pk_fma_f32 v[136:137], v[14:15], v[156:157], v[136:137]
	v_mov_b32_e32 v157, v134
	v_mov_b32_e32 v134, v133
	v_mov_b32_e32 v156, v132
	v_pk_mul_f32 v[132:133], v[12:13], v[134:135]
	s_nop 0
	v_pk_fma_f32 v[132:133], v[16:17], v[156:157], v[132:133] neg_lo:[0,0,1] neg_hi:[0,0,1]
	v_pk_mul_f32 v[156:157], v[12:13], v[156:157]
	s_nop 0
	v_pk_fma_f32 v[134:135], v[16:17], v[134:135], v[156:157]
	v_lshl_add_u64 v[156:157], v[0:1], 1, s[84:85]
	v_lshl_add_u64 v[156:157], v[156:157], 0, v[130:131]
	v_cvt_pk_bf16_f32 v130, v154, v155
	v_cvt_pk_bf16_f32 v131, v132, v133
	v_cvt_pk_bf16_f32 v132, v136, v137
	v_cvt_pk_bf16_f32 v133, v134, v135
	global_store_dwordx4 v[156:157], v[130:133], off sc1

; __device__ __forceinline__ void st8(bf16_t* p, f32x4 a, f32x4 b) { u32x4 w; w.x = pk2(a[0], a[1]); w.y = pk2(a[2], a[3]); w.z = pk2(b[0], b[1]); w.w = pk2(b[2], b[3]); *(u32x4*)p = w; }
; __device__ __forceinline__ float sigm(float x) { return __builtin_amdgcn_rcpf(1.f + __builtin_amdgcn_exp2f(-1.4426950408889634f * x)); }
;     __device__ __forceinline__ void operator()(ACC_T, const pg8::Unit& u, int wr, int wc, int fr, int fq) const {
;     ...
;             bf16_t* O = pn < 30 ? SGA : SGB; const int c0 = ((pn - 26) & 3) * 256;
; #pragma unroll
;             for (int ai = 0; ai < 2; ++ai)
; #pragma unroll
;                 for (int m = 0; m < 4; ++m) { const int row = row0 + ai * 128 + m * 16;
; #pragma unroll
;                     for (int bj = 0; bj < 2; ++bj) { f32x4 v0 = acc[ai][bj][m][0], v1 = acc[ai][bj][m][1];
; #pragma unroll
;                         for (int e = 0; e < 4; ++e) { v0[e] = sigm(v0[e]); v1[e] = sigm(v1[e]); }
;                         st8(O + (unsigned)row * 1024u + c0 + cw + bj * 128, v0, v1); }
;                     asm volatile("" ::: "memory"); }
.LBB0_512:
	s_andn2_b64 vcc, exec, s[8:9]
	s_cbranch_vccnz .LBB0_514
	s_cmp_lt_u32 s96, 30
	s_mov_b32 s2, 0x13600000
	s_cselect_b32 s2, s2, 0x15600000
	s_add_u32 s2, s42, s2
	s_addc_u32 s7, s43, 0
	s_lshl_b32 s8, s96, 8
	v_mul_f32_e32 v133, 0xbfb8aa3b, v122
	s_and_b32 s8, s8, 0x300
	v_exp_f32_e32 v133, v133
	v_mul_f32_e32 v134, 0xbfb8aa3b, v127
	v_mul_f32_e32 v135, 0xbfb8aa3b, v123
	s_xor_b32 s8, s8, 0x200
	v_exp_f32_e32 v134, v134
	v_exp_f32_e32 v135, v135
	s_lshl_b32 s8, s8, 1
	s_add_u32 s8, s2, s8
	s_addc_u32 s9, s7, 0
	v_ashrrev_i32_e32 v153, 31, v152
	v_add_f32_e32 v133, 1.0, v133
	v_lshl_add_u64 v[130:131], v[152:153], 1, s[8:9]
	v_mul_f32_e32 v132, 0xbfb8aa3b, v126
	v_rcp_f32_e32 v153, v133
	v_add_f32_e32 v133, 1.0, v134
	v_add_f32_e32 v134, 1.0, v135
	v_mul_f32_e32 v135, 0xbfb8aa3b, v128
	v_mul_f32_e32 v154, 0xbfb8aa3b, v124
	v_mul_f32_e32 v155, 0xbfb8aa3b, v129
	v_mul_f32_e32 v156, 0xbfb8aa3b, v125
	v_exp_f32_e32 v132, v132
	v_exp_f32_e32 v135, v135
	v_exp_f32_e32 v154, v154
	v_exp_f32_e32 v155, v155
	v_exp_f32_e32 v156, v156
	v_add_f32_e32 v132, 1.0, v132
	v_add_f32_e32 v135, 1.0, v135
	v_add_f32_e32 v154, 1.0, v154
	v_add_f32_e32 v155, 1.0, v155
	v_add_f32_e32 v156, 1.0, v156
	v_rcp_f32_e32 v132, v132
	v_rcp_f32_e32 v133, v133
	v_rcp_f32_e32 v134, v134
	v_rcp_f32_e32 v135, v135
	v_rcp_f32_e32 v154, v154
	v_rcp_f32_e32 v155, v155
	v_rcp_f32_e32 v156, v156
	v_lshlrev_b32_e32 v0, 10, v150
	v_lshl_add_u64 v[136:137], v[0:1], 1, v[130:131]
	v_cvt_pk_bf16_f32 v132, v132, v133
	v_cvt_pk_bf16_f32 v133, v135, v155
	v_cvt_pk_bf16_f32 v134, v153, v134
	v_cvt_pk_bf16_f32 v135, v154, v156
	v_mul_f32_e32 v154, 0xbfb8aa3b, v114
	v_mul_f32_e32 v153, 0xbfb8aa3b, v118
	v_exp_f32_e32 v154, v154
	global_store_dwordx4 v[136:137], v[132:135], off sc1
	v_exp_f32_e32 v153, v153
	v_mul_f32_e32 v155, 0xbfb8aa3b, v121
	v_mul_f32_e32 v134, 0xbfb8aa3b, v119
	v_mul_f32_e32 v135, 0xbfb8aa3b, v115
	v_exp_f32_e32 v134, v134
	v_exp_f32_e32 v135, v135
	v_add_f32_e32 v133, 1.0, v154
	v_add_f32_e32 v132, 1.0, v153
	v_rcp_f32_e32 v153, v133
	v_add_f32_e32 v133, 1.0, v134
	v_add_f32_e32 v134, 1.0, v135
	v_mul_f32_e32 v135, 0xbfb8aa3b, v120
	v_mul_f32_e32 v154, 0xbfb8aa3b, v116
	v_mul_f32_e32 v156, 0xbfb8aa3b, v117
	v_exp_f32_e32 v135, v135
	v_exp_f32_e32 v154, v154
	v_exp_f32_e32 v155, v155
	v_exp_f32_e32 v156, v156
	v_add_f32_e32 v135, 1.0, v135
	v_add_f32_e32 v154, 1.0, v154
	v_add_f32_e32 v155, 1.0, v155
	v_add_f32_e32 v156, 1.0, v156
	v_rcp_f32_e32 v132, v132
	v_rcp_f32_e32 v133, v133
	v_rcp_f32_e32 v134, v134
	v_rcp_f32_e32 v135, v135
	v_rcp_f32_e32 v154, v154
	v_rcp_f32_e32 v155, v155
	v_rcp_f32_e32 v156, v156
	v_cvt_pk_bf16_f32 v132, v132, v133
	v_cvt_pk_bf16_f32 v134, v153, v134
	v_cvt_pk_bf16_f32 v133, v135, v155
	v_cvt_pk_bf16_f32 v135, v154, v156
	global_store_dwordx4 v[136:137], v[132:135], off offset:256 sc1
	v_mul_f32_e32 v154, 0xbfb8aa3b, v108
	v_mul_f32_e32 v155, 0xbfb8aa3b, v113
	v_mul_f32_e32 v134, 0xbfb8aa3b, v110
	v_mul_f32_e32 v135, 0xbfb8aa3b, v106
	v_exp_f32_e32 v134, v134
	v_exp_f32_e32 v135, v135
	v_add_u32_e32 v132, 0x4000, v0
	v_mov_b32_e32 v133, v1
	v_lshl_add_u64 v[136:137], v[132:133], 1, v[130:131]
	v_add_f32_e32 v132, 1.0, v134
	v_add_f32_e32 v133, 1.0, v135
	v_mul_f32_e32 v134, 0xbfb8aa3b, v111
	v_mul_f32_e32 v135, 0xbfb8aa3b, v107
	v_exp_f32_e32 v134, v134
	v_exp_f32_e32 v135, v135
	v_rcp_f32_e32 v153, v133
	v_mul_f32_e32 v156, 0xbfb8aa3b, v109
	v_add_f32_e32 v133, 1.0, v134
	v_add_f32_e32 v134, 1.0, v135
	v_mul_f32_e32 v135, 0xbfb8aa3b, v112
	v_exp_f32_e32 v135, v135
	v_exp_f32_e32 v154, v154
	v_exp_f32_e32 v155, v155
	v_exp_f32_e32 v156, v156
	v_add_f32_e32 v135, 1.0, v135
	v_add_f32_e32 v154, 1.0, v154
	v_add_f32_e32 v155, 1.0, v155
	v_add_f32_e32 v156, 1.0, v156
	v_rcp_f32_e32 v132, v132
	v_rcp_f32_e32 v133, v133
	v_rcp_f32_e32 v134, v134
	v_rcp_f32_e32 v135, v135
	v_rcp_f32_e32 v154, v154
	v_rcp_f32_e32 v155, v155
	v_rcp_f32_e32 v156, v156
	v_cvt_pk_bf16_f32 v132, v132, v133
	v_cvt_pk_bf16_f32 v134, v153, v134
	v_cvt_pk_bf16_f32 v133, v135, v155
	v_cvt_pk_bf16_f32 v135, v154, v156
	v_mul_f32_e32 v154, 0xbfb8aa3b, v98
	v_mul_f32_e32 v153, 0xbfb8aa3b, v102
	v_exp_f32_e32 v154, v154
	global_store_dwordx4 v[136:137], v[132:135], off sc1
	v_exp_f32_e32 v153, v153
	v_mul_f32_e32 v155, 0xbfb8aa3b, v105
	v_mul_f32_e32 v134, 0xbfb8aa3b, v103
	v_mul_f32_e32 v135, 0xbfb8aa3b, v99
	v_exp_f32_e32 v134, v134
	v_exp_f32_e32 v135, v135
	v_add_f32_e32 v133, 1.0, v154
	v_add_f32_e32 v132, 1.0, v153
	v_rcp_f32_e32 v153, v133
	v_add_f32_e32 v133, 1.0, v134
	v_add_f32_e32 v134, 1.0, v135
	v_mul_f32_e32 v135, 0xbfb8aa3b, v104
	v_mul_f32_e32 v154, 0xbfb8aa3b, v100
	v_mul_f32_e32 v156, 0xbfb8aa3b, v101
	v_exp_f32_e32 v135, v135
	v_exp_f32_e32 v154, v154
	v_exp_f32_e32 v155, v155
	v_exp_f32_e32 v156, v156
	v_add_f32_e32 v135, 1.0, v135
	v_add_f32_e32 v154, 1.0, v154
	v_add_f32_e32 v155, 1.0, v155
	v_add_f32_e32 v156, 1.0, v156
	v_rcp_f32_e32 v132, v132
	v_rcp_f32_e32 v133, v133
	v_rcp_f32_e32 v134, v134
	v_rcp_f32_e32 v135, v135
	v_rcp_f32_e32 v154, v154
	v_rcp_f32_e32 v155, v155
	v_rcp_f32_e32 v156, v156
	v_cvt_pk_bf16_f32 v132, v132, v133
	v_cvt_pk_bf16_f32 v134, v153, v134
	v_cvt_pk_bf16_f32 v133, v135, v155
	v_cvt_pk_bf16_f32 v135, v154, v156
	global_store_dwordx4 v[136:137], v[132:135], off offset:256 sc1
	v_mul_f32_e32 v154, 0xbfb8aa3b, v92
	v_mul_f32_e32 v155, 0xbfb8aa3b, v97
	v_mul_f32_e32 v134, 0xbfb8aa3b, v94
	v_mul_f32_e32 v135, 0xbfb8aa3b, v90
	v_exp_f32_e32 v134, v134
	v_exp_f32_e32 v135, v135
	v_add_u32_e32 v132, 0x8000, v0
	v_mov_b32_e32 v133, v1
	v_lshl_add_u64 v[136:137], v[132:133], 1, v[130:131]
	v_add_f32_e32 v132, 1.0, v134
; __device__ __forceinline__ void st8(bf16_t* p, f32x4 a, f32x4 b) { u32x4 w; w.x = pk2(a[0], a[1]); w.y = pk2(a[2], a[3]); w.z = pk2(b[0], b[1]); w.w = pk2(b[2], b[3]); *(u32x4*)p = w; }
; __device__ __forceinline__ float sigm(float x) { return __builtin_amdgcn_rcpf(1.f + __builtin_amdgcn_exp2f(-1.4426950408889634f * x)); }
;     __device__ __forceinline__ void operator()(ACC_T, const pg8::Unit& u, int wr, int wc, int fr, int fq) const {
;     ...
;             bf16_t* O = pn < 30 ? SGA : SGB; const int c0 = ((pn - 26) & 3) * 256;
; #pragma unroll
;             for (int ai = 0; ai < 2; ++ai)
; #pragma unroll
;                 for (int m = 0; m < 4; ++m) { const int row = row0 + ai * 128 + m * 16;
; #pragma unroll
;                     for (int bj = 0; bj < 2; ++bj) { f32x4 v0 = acc[ai][bj][m][0], v1 = acc[ai][bj][m][1];
; #pragma unroll
;                         for (int e = 0; e < 4; ++e) { v0[e] = sigm(v0[e]); v1[e] = sigm(v1[e]); }
;                         st8(O + (unsigned)row * 1024u + c0 + cw + bj * 128, v0, v1); }
;                     asm volatile("" ::: "memory"); }
	v_add_f32_e32 v133, 1.0, v135
	v_mul_f32_e32 v134, 0xbfb8aa3b, v95
	v_mul_f32_e32 v135, 0xbfb8aa3b, v91
	v_exp_f32_e32 v134, v134
	v_exp_f32_e32 v135, v135
	v_rcp_f32_e32 v153, v133
	v_mul_f32_e32 v156, 0xbfb8aa3b, v93
	v_add_f32_e32 v133, 1.0, v134
	v_add_f32_e32 v134, 1.0, v135
	v_mul_f32_e32 v135, 0xbfb8aa3b, v96
	v_exp_f32_e32 v135, v135
	v_exp_f32_e32 v154, v154
	v_exp_f32_e32 v155, v155
	v_exp_f32_e32 v156, v156
	v_add_f32_e32 v135, 1.0, v135
	v_add_f32_e32 v154, 1.0, v154
	v_add_f32_e32 v155, 1.0, v155
	v_add_f32_e32 v156, 1.0, v156
	v_rcp_f32_e32 v132, v132
	v_rcp_f32_e32 v133, v133
	v_rcp_f32_e32 v134, v134
	v_rcp_f32_e32 v135, v135
	v_rcp_f32_e32 v154, v154
	v_rcp_f32_e32 v155, v155
	v_rcp_f32_e32 v156, v156
	v_cvt_pk_bf16_f32 v132, v132, v133
	v_cvt_pk_bf16_f32 v134, v153, v134
	v_cvt_pk_bf16_f32 v133, v135, v155
	v_cvt_pk_bf16_f32 v135, v154, v156
	v_mul_f32_e32 v154, 0xbfb8aa3b, v82
	v_mul_f32_e32 v153, 0xbfb8aa3b, v86
	v_exp_f32_e32 v154, v154
	global_store_dwordx4 v[136:137], v[132:135], off sc1
	v_exp_f32_e32 v153, v153
	v_mul_f32_e32 v155, 0xbfb8aa3b, v89
	v_mul_f32_e32 v134, 0xbfb8aa3b, v87
	v_mul_f32_e32 v135, 0xbfb8aa3b, v83
	v_exp_f32_e32 v134, v134
	v_exp_f32_e32 v135, v135
	v_add_f32_e32 v133, 1.0, v154
	v_add_f32_e32 v132, 1.0, v153
	v_rcp_f32_e32 v153, v133
	v_add_f32_e32 v133, 1.0, v134
	v_add_f32_e32 v134, 1.0, v135
	v_mul_f32_e32 v135, 0xbfb8aa3b, v88
	v_mul_f32_e32 v154, 0xbfb8aa3b, v84
	v_mul_f32_e32 v156, 0xbfb8aa3b, v85
	v_exp_f32_e32 v135, v135
	v_exp_f32_e32 v154, v154
	v_exp_f32_e32 v155, v155
	v_exp_f32_e32 v156, v156
	v_add_f32_e32 v135, 1.0, v135
	v_add_f32_e32 v154, 1.0, v154
	v_add_f32_e32 v155, 1.0, v155
	v_add_f32_e32 v156, 1.0, v156
	v_rcp_f32_e32 v132, v132
	v_rcp_f32_e32 v133, v133
	v_rcp_f32_e32 v134, v134
	v_rcp_f32_e32 v135, v135
	v_rcp_f32_e32 v154, v154
	v_rcp_f32_e32 v155, v155
	v_rcp_f32_e32 v156, v156
	v_cvt_pk_bf16_f32 v132, v132, v133
	v_cvt_pk_bf16_f32 v134, v153, v134
	v_cvt_pk_bf16_f32 v133, v135, v155
	v_cvt_pk_bf16_f32 v135, v154, v156
	global_store_dwordx4 v[136:137], v[132:135], off offset:256 sc1
	v_mul_f32_e32 v154, 0xbfb8aa3b, v76
	v_mul_f32_e32 v155, 0xbfb8aa3b, v81
	v_mul_f32_e32 v134, 0xbfb8aa3b, v78
	v_mul_f32_e32 v135, 0xbfb8aa3b, v74
	v_exp_f32_e32 v134, v134
	v_exp_f32_e32 v135, v135
	v_add_u32_e32 v132, 0xc000, v0
	v_mov_b32_e32 v133, v1
	v_lshl_add_u64 v[136:137], v[132:133], 1, v[130:131]
	v_add_f32_e32 v132, 1.0, v134
	v_add_f32_e32 v133, 1.0, v135
	v_mul_f32_e32 v134, 0xbfb8aa3b, v79
	v_mul_f32_e32 v135, 0xbfb8aa3b, v75
	v_exp_f32_e32 v134, v134
	v_exp_f32_e32 v135, v135
	v_rcp_f32_e32 v153, v133
	v_mul_f32_e32 v156, 0xbfb8aa3b, v77
	v_add_f32_e32 v133, 1.0, v134
	v_add_f32_e32 v134, 1.0, v135
	v_mul_f32_e32 v135, 0xbfb8aa3b, v80
	v_exp_f32_e32 v135, v135
	v_exp_f32_e32 v154, v154
	v_exp_f32_e32 v155, v155
	v_exp_f32_e32 v156, v156
	v_add_f32_e32 v135, 1.0, v135
	v_add_f32_e32 v154, 1.0, v154
	v_add_f32_e32 v155, 1.0, v155
	v_add_f32_e32 v156, 1.0, v156
	v_rcp_f32_e32 v132, v132
	v_rcp_f32_e32 v133, v133
	v_rcp_f32_e32 v134, v134
	v_rcp_f32_e32 v135, v135
	v_rcp_f32_e32 v154, v154
	v_rcp_f32_e32 v155, v155
	v_rcp_f32_e32 v156, v156
	v_cvt_pk_bf16_f32 v132, v132, v133
	v_cvt_pk_bf16_f32 v134, v153, v134
	v_cvt_pk_bf16_f32 v133, v135, v155
	v_cvt_pk_bf16_f32 v135, v154, v156
	v_mul_f32_e32 v154, 0xbfb8aa3b, v66
	v_mul_f32_e32 v153, 0xbfb8aa3b, v70
	v_exp_f32_e32 v154, v154
	global_store_dwordx4 v[136:137], v[132:135], off sc1
	v_exp_f32_e32 v153, v153
	v_mul_f32_e32 v155, 0xbfb8aa3b, v73
	v_mul_f32_e32 v134, 0xbfb8aa3b, v71
	v_mul_f32_e32 v135, 0xbfb8aa3b, v67
	v_exp_f32_e32 v134, v134
	v_exp_f32_e32 v135, v135
	v_add_f32_e32 v133, 1.0, v154
	v_add_f32_e32 v132, 1.0, v153
	v_rcp_f32_e32 v153, v133
	v_add_f32_e32 v133, 1.0, v134
	v_add_f32_e32 v134, 1.0, v135
	v_mul_f32_e32 v135, 0xbfb8aa3b, v72
	v_mul_f32_e32 v154, 0xbfb8aa3b, v68
	v_mul_f32_e32 v156, 0xbfb8aa3b, v69
	v_exp_f32_e32 v135, v135
	v_exp_f32_e32 v154, v154
	v_exp_f32_e32 v155, v155
	v_exp_f32_e32 v156, v156
	v_add_f32_e32 v135, 1.0, v135
	v_add_f32_e32 v154, 1.0, v154
	v_add_f32_e32 v155, 1.0, v155
	v_add_f32_e32 v156, 1.0, v156
	v_rcp_f32_e32 v132, v132
	v_rcp_f32_e32 v133, v133
	v_rcp_f32_e32 v134, v134
	v_rcp_f32_e32 v135, v135
	v_rcp_f32_e32 v154, v154
	v_rcp_f32_e32 v155, v155
	v_rcp_f32_e32 v156, v156
	v_cvt_pk_bf16_f32 v132, v132, v133
	v_cvt_pk_bf16_f32 v134, v153, v134
	v_cvt_pk_bf16_f32 v133, v135, v155
	v_cvt_pk_bf16_f32 v135, v154, v156
	global_store_dwordx4 v[136:137], v[132:135], off offset:256 sc1
	v_mul_f32_e32 v154, 0xbfb8aa3b, v60
	v_mul_f32_e32 v155, 0xbfb8aa3b, v65
	v_mul_f32_e32 v134, 0xbfb8aa3b, v62
	v_mul_f32_e32 v135, 0xbfb8aa3b, v58
	v_exp_f32_e32 v134, v134
	v_exp_f32_e32 v135, v135
	v_add_u32_e32 v132, 0x20000, v0
	v_mov_b32_e32 v133, v1
	v_lshl_add_u64 v[136:137], v[132:133], 1, v[130:131]
	v_add_f32_e32 v132, 1.0, v134
	v_add_f32_e32 v133, 1.0, v135
	v_mul_f32_e32 v134, 0xbfb8aa3b, v63
	v_mul_f32_e32 v135, 0xbfb8aa3b, v59
	v_exp_f32_e32 v134, v134
	v_exp_f32_e32 v135, v135
	v_rcp_f32_e32 v153, v133
	v_mul_f32_e32 v156, 0xbfb8aa3b, v61
	v_add_f32_e32 v133, 1.0, v134
	v_add_f32_e32 v134, 1.0, v135
	v_mul_f32_e32 v135, 0xbfb8aa3b, v64
	v_exp_f32_e32 v135, v135
	v_exp_f32_e32 v154, v154
	v_exp_f32_e32 v155, v155
	v_exp_f32_e32 v156, v156
	v_add_f32_e32 v135, 1.0, v135
	v_add_f32_e32 v154, 1.0, v154
	v_add_f32_e32 v155, 1.0, v155
	v_add_f32_e32 v156, 1.0, v156
	v_rcp_f32_e32 v132, v132
	v_rcp_f32_e32 v133, v133
	v_rcp_f32_e32 v134, v134
	v_rcp_f32_e32 v135, v135
	v_rcp_f32_e32 v154, v154
	v_rcp_f32_e32 v155, v155
	v_rcp_f32_e32 v156, v156
	v_cvt_pk_bf16_f32 v132, v132, v133
; __device__ __forceinline__ void st8(bf16_t* p, f32x4 a, f32x4 b) { u32x4 w; w.x = pk2(a[0], a[1]); w.y = pk2(a[2], a[3]); w.z = pk2(b[0], b[1]); w.w = pk2(b[2], b[3]); *(u32x4*)p = w; }
; __device__ __forceinline__ float sigm(float x) { return __builtin_amdgcn_rcpf(1.f + __builtin_amdgcn_exp2f(-1.4426950408889634f * x)); }
;     __device__ __forceinline__ void operator()(ACC_T, const pg8::Unit& u, int wr, int wc, int fr, int fq) const {
;     ...
;             bf16_t* O = pn < 30 ? SGA : SGB; const int c0 = ((pn - 26) & 3) * 256;
; #pragma unroll
;             for (int ai = 0; ai < 2; ++ai)
; #pragma unroll
;                 for (int m = 0; m < 4; ++m) { const int row = row0 + ai * 128 + m * 16;
; #pragma unroll
;                     for (int bj = 0; bj < 2; ++bj) { f32x4 v0 = acc[ai][bj][m][0], v1 = acc[ai][bj][m][1];
; #pragma unroll
;                         for (int e = 0; e < 4; ++e) { v0[e] = sigm(v0[e]); v1[e] = sigm(v1[e]); }
;                         st8(O + (unsigned)row * 1024u + c0 + cw + bj * 128, v0, v1); }
;                     asm volatile("" ::: "memory"); }
	v_cvt_pk_bf16_f32 v134, v153, v134
	v_cvt_pk_bf16_f32 v133, v135, v155
	v_cvt_pk_bf16_f32 v135, v154, v156
	v_mul_f32_e32 v154, 0xbfb8aa3b, v50
	v_mul_f32_e32 v153, 0xbfb8aa3b, v54
	v_exp_f32_e32 v154, v154
	global_store_dwordx4 v[136:137], v[132:135], off sc1
	v_exp_f32_e32 v153, v153
	v_mul_f32_e32 v155, 0xbfb8aa3b, v57
	v_mul_f32_e32 v134, 0xbfb8aa3b, v55
	v_mul_f32_e32 v135, 0xbfb8aa3b, v51
	v_exp_f32_e32 v134, v134
	v_exp_f32_e32 v135, v135
	v_add_f32_e32 v133, 1.0, v154
	v_add_f32_e32 v132, 1.0, v153
	v_rcp_f32_e32 v153, v133
	v_add_f32_e32 v133, 1.0, v134
	v_add_f32_e32 v134, 1.0, v135
	v_mul_f32_e32 v135, 0xbfb8aa3b, v56
	v_mul_f32_e32 v154, 0xbfb8aa3b, v52
	v_mul_f32_e32 v156, 0xbfb8aa3b, v53
	v_exp_f32_e32 v135, v135
	v_exp_f32_e32 v154, v154
	v_exp_f32_e32 v155, v155
	v_exp_f32_e32 v156, v156
	v_add_f32_e32 v135, 1.0, v135
	v_add_f32_e32 v154, 1.0, v154
	v_add_f32_e32 v155, 1.0, v155
	v_add_f32_e32 v156, 1.0, v156
	v_rcp_f32_e32 v132, v132
	v_rcp_f32_e32 v133, v133
	v_rcp_f32_e32 v134, v134
	v_rcp_f32_e32 v135, v135
	v_rcp_f32_e32 v154, v154
	v_rcp_f32_e32 v155, v155
	v_rcp_f32_e32 v156, v156
	v_cvt_pk_bf16_f32 v132, v132, v133
	v_cvt_pk_bf16_f32 v134, v153, v134
	v_cvt_pk_bf16_f32 v133, v135, v155
	v_cvt_pk_bf16_f32 v135, v154, v156
	global_store_dwordx4 v[136:137], v[132:135], off offset:256 sc1
	v_mul_f32_e32 v154, 0xbfb8aa3b, v44
	v_mul_f32_e32 v155, 0xbfb8aa3b, v49
	v_mul_f32_e32 v134, 0xbfb8aa3b, v46
	v_mul_f32_e32 v135, 0xbfb8aa3b, v42
	v_exp_f32_e32 v134, v134
	v_exp_f32_e32 v135, v135
	v_add_u32_e32 v132, 0x24000, v0
	v_mov_b32_e32 v133, v1
	v_lshl_add_u64 v[136:137], v[132:133], 1, v[130:131]
	v_add_f32_e32 v132, 1.0, v134
	v_add_f32_e32 v133, 1.0, v135
	v_mul_f32_e32 v134, 0xbfb8aa3b, v47
	v_mul_f32_e32 v135, 0xbfb8aa3b, v43
	v_exp_f32_e32 v134, v134
	v_exp_f32_e32 v135, v135
	v_rcp_f32_e32 v153, v133
	v_mul_f32_e32 v156, 0xbfb8aa3b, v45
	v_add_f32_e32 v133, 1.0, v134
	v_add_f32_e32 v134, 1.0, v135
	v_mul_f32_e32 v135, 0xbfb8aa3b, v48
	v_exp_f32_e32 v135, v135
	v_exp_f32_e32 v154, v154
	v_exp_f32_e32 v155, v155
	v_exp_f32_e32 v156, v156
	v_add_f32_e32 v135, 1.0, v135
	v_add_f32_e32 v154, 1.0, v154
	v_add_f32_e32 v155, 1.0, v155
	v_add_f32_e32 v156, 1.0, v156
	v_rcp_f32_e32 v132, v132
	v_rcp_f32_e32 v133, v133
	v_rcp_f32_e32 v134, v134
	v_rcp_f32_e32 v135, v135
	v_rcp_f32_e32 v154, v154
	v_rcp_f32_e32 v155, v155
	v_rcp_f32_e32 v156, v156
	v_cvt_pk_bf16_f32 v132, v132, v133
	v_cvt_pk_bf16_f32 v134, v153, v134
	v_cvt_pk_bf16_f32 v133, v135, v155
	v_cvt_pk_bf16_f32 v135, v154, v156
	v_mul_f32_e32 v154, 0xbfb8aa3b, v34
	v_mul_f32_e32 v153, 0xbfb8aa3b, v38
	v_exp_f32_e32 v154, v154
	global_store_dwordx4 v[136:137], v[132:135], off sc1
	v_exp_f32_e32 v153, v153
	v_mul_f32_e32 v155, 0xbfb8aa3b, v41
	v_mul_f32_e32 v134, 0xbfb8aa3b, v39
	v_mul_f32_e32 v135, 0xbfb8aa3b, v35
	v_exp_f32_e32 v134, v134
	v_exp_f32_e32 v135, v135
	v_add_f32_e32 v133, 1.0, v154
	v_add_f32_e32 v132, 1.0, v153
	v_rcp_f32_e32 v153, v133
	v_add_f32_e32 v133, 1.0, v134
	v_add_f32_e32 v134, 1.0, v135
	v_mul_f32_e32 v135, 0xbfb8aa3b, v40
	v_mul_f32_e32 v154, 0xbfb8aa3b, v36
	v_mul_f32_e32 v156, 0xbfb8aa3b, v37
	v_exp_f32_e32 v135, v135
	v_exp_f32_e32 v154, v154
	v_exp_f32_e32 v155, v155
	v_exp_f32_e32 v156, v156
	v_add_f32_e32 v135, 1.0, v135
	v_add_f32_e32 v154, 1.0, v154
	v_add_f32_e32 v155, 1.0, v155
	v_add_f32_e32 v156, 1.0, v156
	v_rcp_f32_e32 v132, v132
	v_rcp_f32_e32 v133, v133
	v_rcp_f32_e32 v134, v134
	v_rcp_f32_e32 v135, v135
	v_rcp_f32_e32 v154, v154
	v_rcp_f32_e32 v155, v155
	v_rcp_f32_e32 v156, v156
	v_cvt_pk_bf16_f32 v132, v132, v133
	v_cvt_pk_bf16_f32 v134, v153, v134
	v_cvt_pk_bf16_f32 v133, v135, v155
	v_cvt_pk_bf16_f32 v135, v154, v156
	global_store_dwordx4 v[136:137], v[132:135], off offset:256 sc1
	v_mul_f32_e32 v154, 0xbfb8aa3b, v28
	v_mul_f32_e32 v155, 0xbfb8aa3b, v33
	v_mul_f32_e32 v134, 0xbfb8aa3b, v30
	v_mul_f32_e32 v135, 0xbfb8aa3b, v26
	v_exp_f32_e32 v134, v134
	v_exp_f32_e32 v135, v135
	v_add_u32_e32 v132, 0x28000, v0
	v_mov_b32_e32 v133, v1
	v_lshl_add_u64 v[136:137], v[132:133], 1, v[130:131]
	v_add_f32_e32 v132, 1.0, v134
	v_add_f32_e32 v133, 1.0, v135
	v_mul_f32_e32 v134, 0xbfb8aa3b, v31
	v_mul_f32_e32 v135, 0xbfb8aa3b, v27
	v_exp_f32_e32 v134, v134
	v_exp_f32_e32 v135, v135
	v_rcp_f32_e32 v153, v133
; __device__ __forceinline__ void st8(bf16_t* p, f32x4 a, f32x4 b) { u32x4 w; w.x = pk2(a[0], a[1]); w.y = pk2(a[2], a[3]); w.z = pk2(b[0], b[1]); w.w = pk2(b[2], b[3]); *(u32x4*)p = w; }
; __device__ __forceinline__ float sigm(float x) { return __builtin_amdgcn_rcpf(1.f + __builtin_amdgcn_exp2f(-1.4426950408889634f * x)); }
;     __device__ __forceinline__ void operator()(ACC_T, const pg8::Unit& u, int wr, int wc, int fr, int fq) const {
;     ...
;             bf16_t* O = pn < 30 ? SGA : SGB; const int c0 = ((pn - 26) & 3) * 256;
; #pragma unroll
;             for (int ai = 0; ai < 2; ++ai)
; #pragma unroll
;                 for (int m = 0; m < 4; ++m) { const int row = row0 + ai * 128 + m * 16;
; #pragma unroll
;                     for (int bj = 0; bj < 2; ++bj) { f32x4 v0 = acc[ai][bj][m][0], v1 = acc[ai][bj][m][1];
; #pragma unroll
;                         for (int e = 0; e < 4; ++e) { v0[e] = sigm(v0[e]); v1[e] = sigm(v1[e]); }
;                         st8(O + (unsigned)row * 1024u + c0 + cw + bj * 128, v0, v1); }
;                     asm volatile("" ::: "memory"); }
	v_mul_f32_e32 v156, 0xbfb8aa3b, v29
	v_add_f32_e32 v133, 1.0, v134
	v_add_f32_e32 v134, 1.0, v135
	v_mul_f32_e32 v135, 0xbfb8aa3b, v32
	v_exp_f32_e32 v135, v135
	v_exp_f32_e32 v154, v154
	v_exp_f32_e32 v155, v155
	v_exp_f32_e32 v156, v156
	v_add_f32_e32 v135, 1.0, v135
	v_add_f32_e32 v154, 1.0, v154
	v_add_f32_e32 v155, 1.0, v155
	v_add_f32_e32 v156, 1.0, v156
	v_rcp_f32_e32 v132, v132
	v_rcp_f32_e32 v133, v133
	v_rcp_f32_e32 v134, v134
	v_rcp_f32_e32 v135, v135
	v_rcp_f32_e32 v154, v154
	v_rcp_f32_e32 v155, v155
	v_rcp_f32_e32 v156, v156
	v_cvt_pk_bf16_f32 v132, v132, v133
	v_cvt_pk_bf16_f32 v134, v153, v134
	v_cvt_pk_bf16_f32 v133, v135, v155
	v_cvt_pk_bf16_f32 v135, v154, v156
	v_mul_f32_e32 v154, 0xbfb8aa3b, v18
	v_mul_f32_e32 v153, 0xbfb8aa3b, v22
	v_exp_f32_e32 v154, v154
	global_store_dwordx4 v[136:137], v[132:135], off sc1
	v_exp_f32_e32 v153, v153
	v_mul_f32_e32 v155, 0xbfb8aa3b, v25
	v_mul_f32_e32 v134, 0xbfb8aa3b, v23
	v_mul_f32_e32 v135, 0xbfb8aa3b, v19
	v_exp_f32_e32 v134, v134
	v_exp_f32_e32 v135, v135
	v_add_f32_e32 v133, 1.0, v154
	v_add_f32_e32 v132, 1.0, v153
	v_rcp_f32_e32 v153, v133
	v_add_f32_e32 v133, 1.0, v134
	v_add_f32_e32 v134, 1.0, v135
	v_mul_f32_e32 v135, 0xbfb8aa3b, v24
	v_mul_f32_e32 v154, 0xbfb8aa3b, v20
	v_mul_f32_e32 v156, 0xbfb8aa3b, v21
	v_exp_f32_e32 v135, v135
	v_exp_f32_e32 v154, v154
	v_exp_f32_e32 v155, v155
	v_exp_f32_e32 v156, v156
	v_add_f32_e32 v135, 1.0, v135
	v_add_f32_e32 v154, 1.0, v154
	v_add_f32_e32 v155, 1.0, v155
	v_add_f32_e32 v156, 1.0, v156
	v_rcp_f32_e32 v132, v132
	v_rcp_f32_e32 v133, v133
	v_rcp_f32_e32 v134, v134
	v_rcp_f32_e32 v135, v135
	v_rcp_f32_e32 v154, v154
	v_rcp_f32_e32 v155, v155
	v_rcp_f32_e32 v156, v156
	v_cvt_pk_bf16_f32 v132, v132, v133
	v_cvt_pk_bf16_f32 v134, v153, v134
	v_cvt_pk_bf16_f32 v133, v135, v155
	v_cvt_pk_bf16_f32 v135, v154, v156
	global_store_dwordx4 v[136:137], v[132:135], off offset:256 sc1
	v_add_u32_e32 v0, 0x2c000, v0
	v_mul_f32_e32 v136, 0xbfb8aa3b, v12
	v_mul_f32_e32 v132, 0xbfb8aa3b, v14
	v_exp_f32_e32 v132, v132
	v_mul_f32_e32 v133, 0xbfb8aa3b, v10
	v_exp_f32_e32 v133, v133
	v_lshl_add_u64 v[134:135], v[0:1], 1, v[130:131]
	v_add_f32_e32 v0, 1.0, v132
	v_mul_f32_e32 v131, 0xbfb8aa3b, v15
	v_mul_f32_e32 v132, 0xbfb8aa3b, v11
	v_exp_f32_e32 v131, v131
	v_exp_f32_e32 v132, v132
	v_add_f32_e32 v130, 1.0, v133
	v_rcp_f32_e32 v133, v130
	v_add_f32_e32 v130, 1.0, v131
	v_add_f32_e32 v131, 1.0, v132
	v_mul_f32_e32 v132, 0xbfb8aa3b, v16
	v_exp_f32_e32 v132, v132
	v_exp_f32_e32 v136, v136
	v_rcp_f32_e32 v137, v131
	v_mul_f32_e32 v153, 0xbfb8aa3b, v13
	v_add_f32_e32 v131, 1.0, v132
	v_add_f32_e32 v132, 1.0, v136
	v_mul_f32_e32 v136, 0xbfb8aa3b, v17
	v_exp_f32_e32 v136, v136
	v_exp_f32_e32 v153, v153
	v_rcp_f32_e32 v154, v132
	v_rcp_f32_e32 v0, v0
	v_add_f32_e32 v132, 1.0, v136
	v_add_f32_e32 v136, 1.0, v153
	v_rcp_f32_e32 v130, v130
	v_rcp_f32_e32 v131, v131
	v_rcp_f32_e32 v132, v132
	v_rcp_f32_e32 v136, v136
	v_cvt_pk_bf16_f32 v130, v0, v130
	v_cvt_pk_bf16_f32 v131, v131, v132
	v_cvt_pk_bf16_f32 v132, v133, v137
	v_cvt_pk_bf16_f32 v133, v154, v136
	v_mul_f32_e32 v136, 0xbfb8aa3b, v2
	v_exp_f32_e32 v136, v136
	global_store_dwordx4 v[134:135], v[130:133], off sc1
	v_mul_f32_e32 v0, 0xbfb8aa3b, v6
	v_mul_f32_e32 v153, 0xbfb8aa3b, v5
	v_mul_f32_e32 v131, 0xbfb8aa3b, v7
	v_mul_f32_e32 v132, 0xbfb8aa3b, v3
	v_exp_f32_e32 v131, v131
	v_exp_f32_e32 v132, v132
	v_add_f32_e32 v130, 1.0, v136
	v_rcp_f32_e32 v133, v130
	v_add_f32_e32 v130, 1.0, v131
	v_add_f32_e32 v131, 1.0, v132
	v_mul_f32_e32 v132, 0xbfb8aa3b, v8
	v_mul_f32_e32 v136, 0xbfb8aa3b, v4
	v_exp_f32_e32 v132, v132
	v_exp_f32_e32 v136, v136
	v_rcp_f32_e32 v137, v131
	v_exp_f32_e32 v0, v0
	v_add_f32_e32 v131, 1.0, v132
	v_add_f32_e32 v132, 1.0, v136
	v_mul_f32_e32 v136, 0xbfb8aa3b, v9
	v_exp_f32_e32 v136, v136
	v_exp_f32_e32 v153, v153
	v_add_f32_e32 v0, 1.0, v0
	v_rcp_f32_e32 v154, v132
	v_add_f32_e32 v132, 1.0, v136
	v_add_f32_e32 v136, 1.0, v153
	v_rcp_f32_e32 v0, v0
	v_rcp_f32_e32 v130, v130
	v_rcp_f32_e32 v131, v131
	v_rcp_f32_e32 v132, v132
	v_rcp_f32_e32 v136, v136
	v_cvt_pk_bf16_f32 v130, v0, v130
	v_cvt_pk_bf16_f32 v131, v131, v132
	v_cvt_pk_bf16_f32 v132, v133, v137
	v_cvt_pk_bf16_f32 v133, v154, v136
	global_store_dwordx4 v[134:135], v[130:133], off offset:256 sc1

; __device__ __forceinline__ void st8(bf16_t* p, f32x4 a, f32x4 b) { u32x4 w; w.x = pk2(a[0], a[1]); w.y = pk2(a[2], a[3]); w.z = pk2(b[0], b[1]); w.w = pk2(b[2], b[3]); *(u32x4*)p = w; }
;     __device__ __forceinline__ void operator()(ACC_T, const pg8::Unit& u, int wr, int wc, int fr, int fq) const {
;     ...
;             bf16_t* O; int ld, c0; if (pn < 10) { O = Z; ld = 2048; c0 = (pn - 2) * 256; } else { O = XBC; ld = 4096; c0 = (pn - 10) * 256; }
; #pragma unroll
;             for (int ai = 0; ai < 2; ++ai)
; #pragma unroll
;                 for (int m = 0; m < 4; ++m) { const int row = row0 + ai * 128 + m * 16;
; #pragma unroll
;                     for (int bj = 0; bj < 2; ++bj) st8(O + (unsigned)row * (unsigned)ld + c0 + cw + bj * 128, acc[ai][bj][m][0], acc[ai][bj][m][1]); }
.LBB0_515:
	s_andn2_b64 vcc, exec, s[8:9]
	s_cbranch_vccnz .LBB0_517
	s_cmp_lt_u32 s96, 10
	s_cselect_b64 s[8:9], -1, 0
	s_lshl_b32 s2, s96, 8
	s_and_b64 s[10:11], s[8:9], exec
	s_movk_i32 s7, 0xfe00
	s_cselect_b32 s7, s7, 0xfffff600
	s_add_i32 s68, s7, s2
	s_and_b64 s[10:11], s[8:9], exec
	s_mov_b32 s2, 0x7600000
	s_cselect_b32 s2, s2, 0xb600000
	s_add_u32 s2, s42, s2
	s_addc_u32 s7, s43, 0
	s_and_b64 s[8:9], s[8:9], exec
	s_cselect_b32 s10, 11, 12
	s_lshl_b64 s[8:9], s[68:69], 1
	s_add_u32 s8, s2, s8
	s_addc_u32 s9, s7, s9
	v_ashrrev_i32_e32 v153, 31, v152
	v_lshl_add_u64 v[134:135], v[152:153], 1, s[8:9]
	v_lshlrev_b32_e32 v0, s10, v150
	v_lshl_add_u64 v[136:137], v[0:1], 1, v[134:135]
	v_cvt_pk_bf16_f32 v130, v126, v127
	v_cvt_pk_bf16_f32 v131, v128, v129
	v_cvt_pk_bf16_f32 v132, v122, v123
	v_cvt_pk_bf16_f32 v133, v124, v125
	global_store_dwordx4 v[136:137], v[130:133], off sc1
	v_add_lshl_u32 v0, v150, 16, s10
	s_nop 0
	v_cvt_pk_bf16_f32 v130, v118, v119
	v_cvt_pk_bf16_f32 v131, v120, v121
	v_cvt_pk_bf16_f32 v132, v114, v115
	v_cvt_pk_bf16_f32 v133, v116, v117
	global_store_dwordx4 v[136:137], v[130:133], off offset:256 sc1
	v_lshl_add_u64 v[136:137], v[0:1], 1, v[134:135]
	v_add_lshl_u32 v0, v150, 32, s10
	v_cvt_pk_bf16_f32 v130, v110, v111
	v_cvt_pk_bf16_f32 v131, v112, v113
	v_cvt_pk_bf16_f32 v132, v106, v107
	v_cvt_pk_bf16_f32 v133, v108, v109
	global_store_dwordx4 v[136:137], v[130:133], off sc1
	s_nop 1
	v_cvt_pk_bf16_f32 v130, v102, v103
	v_cvt_pk_bf16_f32 v131, v104, v105
	v_cvt_pk_bf16_f32 v132, v98, v99
	v_cvt_pk_bf16_f32 v133, v100, v101
	global_store_dwordx4 v[136:137], v[130:133], off offset:256 sc1
	v_lshl_add_u64 v[136:137], v[0:1], 1, v[134:135]
	v_add_lshl_u32 v0, v150, 48, s10
	v_cvt_pk_bf16_f32 v130, v94, v95
	v_cvt_pk_bf16_f32 v131, v96, v97
	v_cvt_pk_bf16_f32 v132, v90, v91
	v_cvt_pk_bf16_f32 v133, v92, v93
	global_store_dwordx4 v[136:137], v[130:133], off sc1
	s_nop 1
	v_cvt_pk_bf16_f32 v130, v86, v87
	v_cvt_pk_bf16_f32 v131, v88, v89
	v_cvt_pk_bf16_f32 v132, v82, v83
	v_cvt_pk_bf16_f32 v133, v84, v85
	global_store_dwordx4 v[136:137], v[130:133], off offset:256 sc1
	v_lshl_add_u64 v[136:137], v[0:1], 1, v[134:135]
	v_add_u32_e32 v0, 0x80, v150
	v_cvt_pk_bf16_f32 v130, v78, v79
	v_cvt_pk_bf16_f32 v131, v80, v81
	v_cvt_pk_bf16_f32 v132, v74, v75
	v_cvt_pk_bf16_f32 v133, v76, v77
	global_store_dwordx4 v[136:137], v[130:133], off sc1
	v_lshlrev_b32_e32 v0, s10, v0
	s_nop 0
	v_cvt_pk_bf16_f32 v130, v70, v71
	v_cvt_pk_bf16_f32 v131, v72, v73
	v_cvt_pk_bf16_f32 v132, v66, v67
	v_cvt_pk_bf16_f32 v133, v68, v69
	global_store_dwordx4 v[136:137], v[130:133], off offset:256 sc1
	v_lshl_add_u64 v[136:137], v[0:1], 1, v[134:135]
	v_add_u32_e32 v0, 0x90, v150
	v_cvt_pk_bf16_f32 v130, v62, v63
	v_cvt_pk_bf16_f32 v131, v64, v65
	v_cvt_pk_bf16_f32 v132, v58, v59
	v_cvt_pk_bf16_f32 v133, v60, v61
	global_store_dwordx4 v[136:137], v[130:133], off sc1
	v_lshlrev_b32_e32 v0, s10, v0
	s_nop 0
	v_cvt_pk_bf16_f32 v130, v54, v55
	v_cvt_pk_bf16_f32 v131, v56, v57
	v_cvt_pk_bf16_f32 v132, v50, v51
	v_cvt_pk_bf16_f32 v133, v52, v53
	global_store_dwordx4 v[136:137], v[130:133], off offset:256 sc1
	v_lshl_add_u64 v[136:137], v[0:1], 1, v[134:135]
	v_add_u32_e32 v0, 0xa0, v150
	v_cvt_pk_bf16_f32 v130, v46, v47
	v_cvt_pk_bf16_f32 v131, v48, v49
	v_cvt_pk_bf16_f32 v132, v42, v43
	v_cvt_pk_bf16_f32 v133, v44, v45
	global_store_dwordx4 v[136:137], v[130:133], off sc1
	v_lshlrev_b32_e32 v0, s10, v0
	s_nop 0
	v_cvt_pk_bf16_f32 v130, v38, v39
	v_cvt_pk_bf16_f32 v131, v40, v41
	v_cvt_pk_bf16_f32 v132, v34, v35
	v_cvt_pk_bf16_f32 v133, v36, v37
	global_store_dwordx4 v[136:137], v[130:133], off offset:256 sc1
	v_lshl_add_u64 v[136:137], v[0:1], 1, v[134:135]
	v_add_u32_e32 v0, 0xb0, v150
	v_cvt_pk_bf16_f32 v130, v30, v31
	v_cvt_pk_bf16_f32 v131, v32, v33
	v_cvt_pk_bf16_f32 v132, v26, v27
	v_cvt_pk_bf16_f32 v133, v28, v29
	global_store_dwordx4 v[136:137], v[130:133], off sc1
	v_lshlrev_b32_e32 v0, s10, v0
	v_lshl_add_u64 v[134:135], v[0:1], 1, v[134:135]
	v_cvt_pk_bf16_f32 v130, v22, v23
	v_cvt_pk_bf16_f32 v131, v24, v25
	v_cvt_pk_bf16_f32 v132, v18, v19
	v_cvt_pk_bf16_f32 v133, v20, v21
	global_store_dwordx4 v[136:137], v[130:133], off offset:256 sc1
	s_nop 1
	v_cvt_pk_bf16_f32 v130, v14, v15
	v_cvt_pk_bf16_f32 v131, v16, v17
	v_cvt_pk_bf16_f32 v132, v10, v11
	v_cvt_pk_bf16_f32 v133, v12, v13
	global_store_dwordx4 v[134:135], v[130:133], off sc1
	s_nop 1
	v_cvt_pk_bf16_f32 v130, v6, v7
	v_cvt_pk_bf16_f32 v131, v8, v9
	v_cvt_pk_bf16_f32 v132, v2, v3
	v_cvt_pk_bf16_f32 v133, v4, v5
	global_store_dwordx4 v[134:135], v[130:133], off offset:256 sc1

; __device__ __forceinline__ void st8(bf16_t* p, f32x4 a, f32x4 b) { u32x4 w; w.x = pk2(a[0], a[1]); w.y = pk2(a[2], a[3]); w.z = pk2(b[0], b[1]); w.w = pk2(b[2], b[3]); *(u32x4*)p = w; }
; __device__ __forceinline__ float dot4(f32x4 a) { return (a[0] * a[0] + a[1] * a[1]) + (a[2] * a[2] + a[3] * a[3]); }
;     __device__ __forceinline__ void operator()(ACC_T, const pg8::Unit& u, int wr, int wc, int fr, int fq) const {
;     ...
;             bf16_t* O = pn == 0 ? QL : KVL; float* sq = (pn == 0 ? ssq_q : ssq_kv) + wc * TT + tbase;
; #pragma unroll
;             for (int ai = 0; ai < 2; ++ai)
; #pragma unroll
;                 for (int m = 0; m < 4; ++m) { const int row = row0 + ai * 128 + m * 16; float s = 0.f;
; #pragma unroll
;                     for (int bj = 0; bj < 2; ++bj) { const f32x4 v0 = acc[ai][bj][m][0], v1 = acc[ai][bj][m][1]; st8(O + (unsigned)row * 256u + cw + bj * 128, v0, v1); s += dot4(v0) + dot4(v1); }
;                     s += __shfl_xor(s, 16); s += __shfl_xor(s, 32);
;                     if (fq == 0) sq[row] = s; }
.LBB0_518:
	s_andn2_b64 vcc, exec, s[8:9]
	s_cbranch_vccnz .LBB0_536
	v_mbcnt_hi_u32_b32 v0, -1, v234
	v_and_b32_e32 v133, 64, v0
	v_xor_b32_e32 v132, 16, v0
	v_add_u32_e32 v134, 64, v133
	v_cmp_lt_i32_e32 vcc, v132, v134
	s_cmp_eq_u32 s96, 0
	s_mov_b32 s2, 0x6200000
	v_cndmask_b32_e32 v132, v0, v132, vcc
	s_cselect_b32 s2, s2, 0x6a00000
	s_mov_b32 s7, 0x3a600000
	v_lshlrev_b32_e32 v133, 2, v132
	v_xor_b32_e32 v132, 32, v0
	s_cselect_b32 s7, s7, 0x3a700000
	s_add_u32 s8, s42, s2
	v_cmp_lt_i32_e32 vcc, v132, v134
	s_addc_u32 s9, s43, 0
	v_ashrrev_i32_e32 v153, 31, v152
	v_cndmask_b32_e32 v0, v0, v132, vcc
	v_lshl_add_u64 v[130:131], v[152:153], 1, s[8:9]
	v_lshlrev_b32_e32 v132, 2, v0
	v_lshlrev_b32_e32 v0, 8, v150
	v_lshl_add_u64 v[152:153], v[0:1], 1, v[130:131]
	v_cvt_pk_bf16_f32 v136, v122, v123
	v_mul_f32_e32 v0, v127, v127
	v_mul_f32_e32 v123, v123, v123
	v_cvt_pk_bf16_f32 v134, v126, v127
	v_fmac_f32_e32 v0, v126, v126
	v_mul_f32_e32 v126, v129, v129
	v_fmac_f32_e32 v123, v122, v122
	v_mul_f32_e32 v122, v125, v125
	v_fmac_f32_e32 v126, v128, v128
	v_fmac_f32_e32 v122, v124, v124
	v_add_f32_e32 v0, v0, v126
	v_add_f32_e32 v122, v123, v122
	v_add_f32_e32 v0, v0, v122
	v_mul_f32_e32 v122, v119, v119
	v_mul_f32_e32 v123, v121, v121
	v_fmac_f32_e32 v122, v118, v118
	v_fmac_f32_e32 v123, v120, v120
	v_add_f32_e32 v122, v122, v123
	v_mul_f32_e32 v123, v115, v115
	v_mul_f32_e32 v126, v117, v117
	v_fmac_f32_e32 v123, v114, v114
	v_fmac_f32_e32 v126, v116, v116
	v_add_f32_e32 v123, v123, v126
	v_add_f32_e32 v122, v122, v123
	v_add_f32_e32 v0, v0, v122
	ds_bpermute_b32 v126, v133, v0
	v_cvt_pk_bf16_f32 v122, v118, v119
	s_add_u32 s40, s79, s7
	s_addc_u32 s41, s37, 0
	v_cmp_eq_u32_e32 vcc, 0, v151
	s_waitcnt lgkmcnt(0)
	v_add_f32_e32 v0, v0, v126
	ds_bpermute_b32 v118, v132, v0
	v_cvt_pk_bf16_f32 v135, v128, v129
	v_cvt_pk_bf16_f32 v137, v124, v125
	v_cvt_pk_bf16_f32 v123, v120, v121
	v_cvt_pk_bf16_f32 v124, v114, v115
	v_cvt_pk_bf16_f32 v125, v116, v117
	v_ashrrev_i32_e32 v151, 31, v150
	global_store_dwordx4 v[152:153], v[134:137], off sc1
	global_store_dwordx4 v[152:153], v[122:125], off offset:256 sc1
	s_and_saveexec_b64 s[8:9], vcc
	s_cbranch_execz .LBB0_521
	s_waitcnt lgkmcnt(0)
	v_add_f32_e32 v0, v0, v118
	v_lshl_add_u64 v[114:115], v[150:151], 2, s[40:41]
	global_store_dword v[114:115], v0, off sc1
.LBB0_521:
	s_or_b64 exec, exec, s[8:9]
	v_mov_b32_e32 v0, 0x1000
	v_lshl_add_u32 v0, v150, 8, v0
	s_waitcnt lgkmcnt(0)
	v_lshl_add_u64 v[118:119], v[0:1], 1, v[130:131]
	v_mul_f32_e32 v0, v111, v111
	v_cvt_pk_bf16_f32 v114, v110, v111
	v_fmac_f32_e32 v0, v110, v110
	v_mul_f32_e32 v110, v113, v113
	v_fmac_f32_e32 v110, v112, v112
	v_add_f32_e32 v0, v0, v110
	v_mul_f32_e32 v110, v107, v107
	v_mul_f32_e32 v111, v109, v109
	v_fmac_f32_e32 v110, v106, v106
	v_fmac_f32_e32 v111, v108, v108
	v_add_f32_e32 v110, v110, v111
	v_add_f32_e32 v0, v0, v110
	v_mul_f32_e32 v110, v103, v103
	v_mul_f32_e32 v111, v105, v105
	v_fmac_f32_e32 v110, v102, v102
	v_fmac_f32_e32 v111, v104, v104
	v_cvt_pk_bf16_f32 v115, v112, v113
	v_add_f32_e32 v110, v110, v111
	v_mul_f32_e32 v111, v99, v99
	v_mul_f32_e32 v112, v101, v101
	v_fmac_f32_e32 v111, v98, v98
	v_fmac_f32_e32 v112, v100, v100
	v_add_f32_e32 v111, v111, v112
	v_add_f32_e32 v110, v110, v111
	v_add_f32_e32 v0, v0, v110
	ds_bpermute_b32 v110, v133, v0
	v_cvt_pk_bf16_f32 v116, v106, v107
	v_cvt_pk_bf16_f32 v106, v102, v103
	v_cvt_pk_bf16_f32 v117, v108, v109
	v_cvt_pk_bf16_f32 v107, v104, v105
	s_waitcnt lgkmcnt(0)
	v_add_f32_e32 v0, v0, v110
	ds_bpermute_b32 v102, v132, v0
	v_cvt_pk_bf16_f32 v108, v98, v99
	v_cvt_pk_bf16_f32 v109, v100, v101
	global_store_dwordx4 v[118:119], v[114:117], off sc1
	global_store_dwordx4 v[118:119], v[106:109], off offset:256 sc1
	s_and_saveexec_b64 s[8:9], vcc
	s_cbranch_execz .LBB0_523
	s_waitcnt lgkmcnt(0)
	v_add_f32_e32 v0, v0, v102
	v_lshl_add_u64 v[98:99], v[150:151], 2, s[40:41]
	global_store_dword v[98:99], v0, off offset:64 sc1
.LBB0_523:
	s_or_b64 exec, exec, s[8:9]
	v_mov_b32_e32 v0, 0x2000
	v_lshl_add_u32 v0, v150, 8, v0
	s_waitcnt lgkmcnt(0)
	v_lshl_add_u64 v[102:103], v[0:1], 1, v[130:131]
	v_mul_f32_e32 v0, v95, v95
	v_cvt_pk_bf16_f32 v98, v94, v95
	v_fmac_f32_e32 v0, v94, v94
	v_mul_f32_e32 v94, v97, v97
	v_fmac_f32_e32 v94, v96, v96
	v_add_f32_e32 v0, v0, v94
	v_mul_f32_e32 v94, v91, v91
	v_mul_f32_e32 v95, v93, v93
	v_fmac_f32_e32 v94, v90, v90
	v_fmac_f32_e32 v95, v92, v92
	v_add_f32_e32 v94, v94, v95
	v_add_f32_e32 v0, v0, v94
	v_mul_f32_e32 v94, v87, v87
	v_mul_f32_e32 v95, v89, v89
	v_fmac_f32_e32 v94, v86, v86
	v_fmac_f32_e32 v95, v88, v88
	v_cvt_pk_bf16_f32 v99, v96, v97
	v_add_f32_e32 v94, v94, v95
	v_mul_f32_e32 v95, v83, v83
	v_mul_f32_e32 v96, v85, v85
	v_fmac_f32_e32 v95, v82, v82
	v_fmac_f32_e32 v96, v84, v84
	v_add_f32_e32 v95, v95, v96
	v_add_f32_e32 v94, v94, v95
	v_add_f32_e32 v0, v0, v94
	ds_bpermute_b32 v94, v133, v0
	v_cvt_pk_bf16_f32 v100, v90, v91
	v_cvt_pk_bf16_f32 v90, v86, v87
	v_cvt_pk_bf16_f32 v101, v92, v93
	v_cvt_pk_bf16_f32 v91, v88, v89
	s_waitcnt lgkmcnt(0)
	v_add_f32_e32 v0, v0, v94
	ds_bpermute_b32 v86, v132, v0
	v_cvt_pk_bf16_f32 v92, v82, v83
	v_cvt_pk_bf16_f32 v93, v84, v85
	global_store_dwordx4 v[102:103], v[98:101], off sc1
	global_store_dwordx4 v[102:103], v[90:93], off offset:256 sc1
	s_and_saveexec_b64 s[8:9], vcc
	s_cbranch_execz .LBB0_525
	s_waitcnt lgkmcnt(0)
	v_add_f32_e32 v0, v0, v86
	v_lshl_add_u64 v[82:83], v[150:151], 2, s[40:41]
	global_store_dword v[82:83], v0, off offset:128 sc1
; __device__ __forceinline__ void st8(bf16_t* p, f32x4 a, f32x4 b) { u32x4 w; w.x = pk2(a[0], a[1]); w.y = pk2(a[2], a[3]); w.z = pk2(b[0], b[1]); w.w = pk2(b[2], b[3]); *(u32x4*)p = w; }
; __device__ __forceinline__ float dot4(f32x4 a) { return (a[0] * a[0] + a[1] * a[1]) + (a[2] * a[2] + a[3] * a[3]); }
;     __device__ __forceinline__ void operator()(ACC_T, const pg8::Unit& u, int wr, int wc, int fr, int fq) const {
;     ...
;             bf16_t* O = pn == 0 ? QL : KVL; float* sq = (pn == 0 ? ssq_q : ssq_kv) + wc * TT + tbase;
; #pragma unroll
;             for (int ai = 0; ai < 2; ++ai)
; #pragma unroll
;                 for (int m = 0; m < 4; ++m) { const int row = row0 + ai * 128 + m * 16; float s = 0.f;
; #pragma unroll
;                     for (int bj = 0; bj < 2; ++bj) { const f32x4 v0 = acc[ai][bj][m][0], v1 = acc[ai][bj][m][1]; st8(O + (unsigned)row * 256u + cw + bj * 128, v0, v1); s += dot4(v0) + dot4(v1); }
;                     s += __shfl_xor(s, 16); s += __shfl_xor(s, 32);
;                     if (fq == 0) sq[row] = s; }
.LBB0_525:
	s_or_b64 exec, exec, s[8:9]
	v_mov_b32_e32 v0, 0x3000
	v_lshl_add_u32 v0, v150, 8, v0
	s_waitcnt lgkmcnt(0)
	v_lshl_add_u64 v[86:87], v[0:1], 1, v[130:131]
	v_mul_f32_e32 v0, v79, v79
	v_cvt_pk_bf16_f32 v82, v78, v79
	v_fmac_f32_e32 v0, v78, v78
	v_mul_f32_e32 v78, v81, v81
	v_fmac_f32_e32 v78, v80, v80
	v_add_f32_e32 v0, v0, v78
	v_mul_f32_e32 v78, v75, v75
	v_mul_f32_e32 v79, v77, v77
	v_fmac_f32_e32 v78, v74, v74
	v_fmac_f32_e32 v79, v76, v76
	v_add_f32_e32 v78, v78, v79
	v_add_f32_e32 v0, v0, v78
	v_mul_f32_e32 v78, v71, v71
	v_mul_f32_e32 v79, v73, v73
	v_fmac_f32_e32 v78, v70, v70
	v_fmac_f32_e32 v79, v72, v72
	v_cvt_pk_bf16_f32 v83, v80, v81
	v_add_f32_e32 v78, v78, v79
	v_mul_f32_e32 v79, v67, v67
	v_mul_f32_e32 v80, v69, v69
	v_fmac_f32_e32 v79, v66, v66
	v_fmac_f32_e32 v80, v68, v68
	v_add_f32_e32 v79, v79, v80
	v_add_f32_e32 v78, v78, v79
	v_add_f32_e32 v0, v0, v78
	ds_bpermute_b32 v78, v133, v0
	v_cvt_pk_bf16_f32 v84, v74, v75
	v_cvt_pk_bf16_f32 v74, v70, v71
	v_cvt_pk_bf16_f32 v85, v76, v77
	v_cvt_pk_bf16_f32 v75, v72, v73
	s_waitcnt lgkmcnt(0)
	v_add_f32_e32 v0, v0, v78
	ds_bpermute_b32 v70, v132, v0
	v_cvt_pk_bf16_f32 v76, v66, v67
	v_cvt_pk_bf16_f32 v77, v68, v69
	global_store_dwordx4 v[86:87], v[82:85], off sc1
	global_store_dwordx4 v[86:87], v[74:77], off offset:256 sc1
	s_and_saveexec_b64 s[8:9], vcc
	s_cbranch_execz .LBB0_527
	s_waitcnt lgkmcnt(0)
	v_add_f32_e32 v0, v0, v70
	v_lshl_add_u64 v[66:67], v[150:151], 2, s[40:41]
	global_store_dword v[66:67], v0, off offset:192 sc1
.LBB0_527:
	s_or_b64 exec, exec, s[8:9]
	v_mov_b32_e32 v0, 0x8000
	v_lshl_add_u32 v0, v150, 8, v0
	s_waitcnt lgkmcnt(0)
	v_lshl_add_u64 v[70:71], v[0:1], 1, v[130:131]
	v_mul_f32_e32 v0, v63, v63
	v_cvt_pk_bf16_f32 v66, v62, v63
	v_fmac_f32_e32 v0, v62, v62
	v_mul_f32_e32 v62, v65, v65
	v_fmac_f32_e32 v62, v64, v64
	v_add_f32_e32 v0, v0, v62
	v_mul_f32_e32 v62, v59, v59
	v_mul_f32_e32 v63, v61, v61
	v_fmac_f32_e32 v62, v58, v58
	v_fmac_f32_e32 v63, v60, v60
	v_add_f32_e32 v62, v62, v63
	v_add_f32_e32 v0, v0, v62
	v_mul_f32_e32 v62, v55, v55
	v_mul_f32_e32 v63, v57, v57
	v_fmac_f32_e32 v62, v54, v54
	v_fmac_f32_e32 v63, v56, v56
	v_cvt_pk_bf16_f32 v67, v64, v65
	v_add_f32_e32 v62, v62, v63
	v_mul_f32_e32 v63, v51, v51
	v_mul_f32_e32 v64, v53, v53
	v_fmac_f32_e32 v63, v50, v50
	v_fmac_f32_e32 v64, v52, v52
	v_add_f32_e32 v63, v63, v64
	v_add_f32_e32 v62, v62, v63
	v_add_f32_e32 v0, v0, v62
	ds_bpermute_b32 v62, v133, v0
	v_cvt_pk_bf16_f32 v68, v58, v59
	v_cvt_pk_bf16_f32 v58, v54, v55
	v_cvt_pk_bf16_f32 v69, v60, v61
	v_cvt_pk_bf16_f32 v59, v56, v57
	s_waitcnt lgkmcnt(0)
	v_add_f32_e32 v0, v0, v62
	ds_bpermute_b32 v54, v132, v0
	v_cvt_pk_bf16_f32 v60, v50, v51
	v_cvt_pk_bf16_f32 v61, v52, v53
	global_store_dwordx4 v[70:71], v[66:69], off sc1
	global_store_dwordx4 v[70:71], v[58:61], off offset:256 sc1
	s_and_saveexec_b64 s[8:9], vcc
	s_cbranch_execz .LBB0_529
	s_waitcnt lgkmcnt(0)
	v_add_f32_e32 v0, v0, v54
	v_lshl_add_u64 v[50:51], v[150:151], 2, s[40:41]
	global_store_dword v[50:51], v0, off offset:512 sc1
; __device__ __forceinline__ void st8(bf16_t* p, f32x4 a, f32x4 b) { u32x4 w; w.x = pk2(a[0], a[1]); w.y = pk2(a[2], a[3]); w.z = pk2(b[0], b[1]); w.w = pk2(b[2], b[3]); *(u32x4*)p = w; }
; __device__ __forceinline__ float dot4(f32x4 a) { return (a[0] * a[0] + a[1] * a[1]) + (a[2] * a[2] + a[3] * a[3]); }
;     __device__ __forceinline__ void operator()(ACC_T, const pg8::Unit& u, int wr, int wc, int fr, int fq) const {
;     ...
;             bf16_t* O = pn == 0 ? QL : KVL; float* sq = (pn == 0 ? ssq_q : ssq_kv) + wc * TT + tbase;
; #pragma unroll
;             for (int ai = 0; ai < 2; ++ai)
; #pragma unroll
;                 for (int m = 0; m < 4; ++m) { const int row = row0 + ai * 128 + m * 16; float s = 0.f;
; #pragma unroll
;                     for (int bj = 0; bj < 2; ++bj) { const f32x4 v0 = acc[ai][bj][m][0], v1 = acc[ai][bj][m][1]; st8(O + (unsigned)row * 256u + cw + bj * 128, v0, v1); s += dot4(v0) + dot4(v1); }
;                     s += __shfl_xor(s, 16); s += __shfl_xor(s, 32);
;                     if (fq == 0) sq[row] = s; }
.LBB0_529:
	s_or_b64 exec, exec, s[8:9]
	v_mov_b32_e32 v0, 0x9000
	v_lshl_add_u32 v0, v150, 8, v0
	s_waitcnt lgkmcnt(0)
	v_lshl_add_u64 v[54:55], v[0:1], 1, v[130:131]
	v_mul_f32_e32 v0, v47, v47
	v_cvt_pk_bf16_f32 v50, v46, v47
	v_fmac_f32_e32 v0, v46, v46
	v_mul_f32_e32 v46, v49, v49
	v_fmac_f32_e32 v46, v48, v48
	v_add_f32_e32 v0, v0, v46
	v_mul_f32_e32 v46, v43, v43
	v_mul_f32_e32 v47, v45, v45
	v_fmac_f32_e32 v46, v42, v42
	v_fmac_f32_e32 v47, v44, v44
	v_add_f32_e32 v46, v46, v47
	v_add_f32_e32 v0, v0, v46
	v_mul_f32_e32 v46, v39, v39
	v_mul_f32_e32 v47, v41, v41
	v_fmac_f32_e32 v46, v38, v38
	v_fmac_f32_e32 v47, v40, v40
	v_cvt_pk_bf16_f32 v51, v48, v49
	v_add_f32_e32 v46, v46, v47
	v_mul_f32_e32 v47, v35, v35
	v_mul_f32_e32 v48, v37, v37
	v_fmac_f32_e32 v47, v34, v34
	v_fmac_f32_e32 v48, v36, v36
	v_add_f32_e32 v47, v47, v48
	v_add_f32_e32 v46, v46, v47
	v_add_f32_e32 v0, v0, v46
	ds_bpermute_b32 v46, v133, v0
	v_cvt_pk_bf16_f32 v52, v42, v43
	v_cvt_pk_bf16_f32 v42, v38, v39
	v_cvt_pk_bf16_f32 v53, v44, v45
	v_cvt_pk_bf16_f32 v43, v40, v41
	s_waitcnt lgkmcnt(0)
	v_add_f32_e32 v0, v0, v46
	ds_bpermute_b32 v38, v132, v0
	v_cvt_pk_bf16_f32 v44, v34, v35
	v_cvt_pk_bf16_f32 v45, v36, v37
	global_store_dwordx4 v[54:55], v[50:53], off sc1
	global_store_dwordx4 v[54:55], v[42:45], off offset:256 sc1
	s_and_saveexec_b64 s[8:9], vcc
	s_cbranch_execz .LBB0_531
	s_waitcnt lgkmcnt(0)
	v_add_f32_e32 v0, v0, v38
	v_lshl_add_u64 v[34:35], v[150:151], 2, s[40:41]
	global_store_dword v[34:35], v0, off offset:576 sc1
.LBB0_531:
	s_or_b64 exec, exec, s[8:9]
	v_mov_b32_e32 v0, 0xa000
	v_lshl_add_u32 v0, v150, 8, v0
	s_waitcnt lgkmcnt(0)
	v_lshl_add_u64 v[38:39], v[0:1], 1, v[130:131]
	v_mul_f32_e32 v0, v31, v31
	v_cvt_pk_bf16_f32 v34, v30, v31
	v_fmac_f32_e32 v0, v30, v30
	v_mul_f32_e32 v30, v33, v33
	v_fmac_f32_e32 v30, v32, v32
	v_add_f32_e32 v0, v0, v30
	v_mul_f32_e32 v30, v27, v27
	v_mul_f32_e32 v31, v29, v29
	v_fmac_f32_e32 v30, v26, v26
	v_fmac_f32_e32 v31, v28, v28
	v_add_f32_e32 v30, v30, v31
	v_add_f32_e32 v0, v0, v30
	v_mul_f32_e32 v30, v23, v23
	v_mul_f32_e32 v31, v25, v25
	v_fmac_f32_e32 v30, v22, v22
	v_fmac_f32_e32 v31, v24, v24
	v_cvt_pk_bf16_f32 v35, v32, v33
	v_add_f32_e32 v30, v30, v31
	v_mul_f32_e32 v31, v19, v19
	v_mul_f32_e32 v32, v21, v21
	v_fmac_f32_e32 v31, v18, v18
	v_fmac_f32_e32 v32, v20, v20
	v_add_f32_e32 v31, v31, v32
	v_add_f32_e32 v30, v30, v31
	v_add_f32_e32 v0, v0, v30
	ds_bpermute_b32 v30, v133, v0
	v_cvt_pk_bf16_f32 v36, v26, v27
	v_cvt_pk_bf16_f32 v26, v22, v23
	v_cvt_pk_bf16_f32 v37, v28, v29
	v_cvt_pk_bf16_f32 v27, v24, v25
	s_waitcnt lgkmcnt(0)
	v_add_f32_e32 v0, v0, v30
	ds_bpermute_b32 v22, v132, v0
	v_cvt_pk_bf16_f32 v28, v18, v19
	v_cvt_pk_bf16_f32 v29, v20, v21
	global_store_dwordx4 v[38:39], v[34:37], off sc1
	global_store_dwordx4 v[38:39], v[26:29], off offset:256 sc1
	s_and_saveexec_b64 s[8:9], vcc
	s_cbranch_execz .LBB0_533
	s_waitcnt lgkmcnt(0)
	v_add_f32_e32 v0, v0, v22
	v_lshl_add_u64 v[18:19], v[150:151], 2, s[40:41]
	global_store_dword v[18:19], v0, off offset:640 sc1
.LBB0_533:
	s_or_b64 exec, exec, s[8:9]
	v_mov_b32_e32 v0, 0xb000
	v_lshl_add_u32 v0, v150, 8, v0
	s_waitcnt lgkmcnt(0)
	v_lshl_add_u64 v[22:23], v[0:1], 1, v[130:131]
	v_mul_f32_e32 v0, v15, v15
	v_cvt_pk_bf16_f32 v18, v14, v15
	v_fmac_f32_e32 v0, v14, v14
	v_mul_f32_e32 v14, v17, v17
	v_fmac_f32_e32 v14, v16, v16
	v_add_f32_e32 v0, v0, v14
	v_mul_f32_e32 v14, v11, v11
	v_mul_f32_e32 v15, v13, v13
	v_fmac_f32_e32 v14, v10, v10
	v_fmac_f32_e32 v15, v12, v12
	v_add_f32_e32 v14, v14, v15
	v_add_f32_e32 v0, v0, v14
	v_mul_f32_e32 v14, v7, v7
	v_mul_f32_e32 v15, v9, v9
	v_fmac_f32_e32 v14, v6, v6
	v_fmac_f32_e32 v15, v8, v8
	v_cvt_pk_bf16_f32 v19, v16, v17
	v_add_f32_e32 v14, v14, v15
	v_mul_f32_e32 v15, v3, v3
	v_mul_f32_e32 v16, v5, v5
	v_fmac_f32_e32 v15, v2, v2
	v_fmac_f32_e32 v16, v4, v4
	v_add_f32_e32 v15, v15, v16
	v_add_f32_e32 v14, v14, v15
	v_add_f32_e32 v0, v0, v14
	ds_bpermute_b32 v14, v133, v0
	v_cvt_pk_bf16_f32 v20, v10, v11
	v_cvt_pk_bf16_f32 v10, v6, v7
	v_cvt_pk_bf16_f32 v21, v12, v13
	v_cvt_pk_bf16_f32 v11, v8, v9
	s_waitcnt lgkmcnt(0)
	v_add_f32_e32 v0, v0, v14
	ds_bpermute_b32 v6, v132, v0
	v_cvt_pk_bf16_f32 v12, v2, v3
	v_cvt_pk_bf16_f32 v13, v4, v5
	global_store_dwordx4 v[22:23], v[18:21], off sc1
	global_store_dwordx4 v[22:23], v[10:13], off offset:256 sc1
	s_and_saveexec_b64 s[8:9], vcc
	s_cbranch_execz .LBB0_535
	s_waitcnt lgkmcnt(0)
	v_add_f32_e32 v0, v0, v6
	v_lshl_add_u64 v[2:3], v[150:151], 2, s[40:41]
	global_store_dword v[2:3], v0, off offset:704 sc1

; __device__ __forceinline__ void st8(bf16_t* p, f32x4 a, f32x4 b) { u32x4 w; w.x = pk2(a[0], a[1]); w.y = pk2(a[2], a[3]); w.z = pk2(b[0], b[1]); w.w = pk2(b[2], b[3]); *(u32x4*)p = w; }
;     __device__ __forceinline__ void operator()(ACC_T, const pg8::Unit& u, int wr, int wc, int fr, int fq) const {
;     ...
;             for (int m = 0; m < 4; ++m) { const int row = row0 + ai * 128 + m * 16; const float* sp = ssq + tbase + row; const float rs = rsqrtf(((sp[0] + sp[TT]) + (sp[2 * TT] + sp[3 * TT])) * (1.f / 256.f) + EPS) * c2;
; #pragma unroll
;                 for (int bj = 0; bj < 2; ++bj) { const f32x4 v0 = acc[ai][bj][m][0] * rs, v1 = acc[ai][bj][m][1] * rs;
;                     if (pn < 4) st8(QN + (unsigned)row * 1024u + pn * 256 + cw + bj * 128, v0, v1);
;                     else { const int colr = (pn - 4) * 256 + cw + bj * 128, g8 = (colr & 63) >> 3;
;                         const f32x4* rp = (const f32x4*)(rope + (unsigned)((tbase + row) * 64 + 8 * g8)); const f32x4 c01 = rp[0], c23 = rp[1];
;                         f32x4 o1, o2;
;                         o1[0] = v0[0] * c01[0] - v1[0] * c01[1]; o2[0] = v0[0] * c01[1] + v1[0] * c01[0];
;                         o1[1] = v0[1] * c01[2] - v1[1] * c01[3]; o2[1] = v0[1] * c01[3] + v1[1] * c01[2];
;                         o1[2] = v0[2] * c23[0] - v1[2] * c23[1]; o2[2] = v0[2] * c23[1] + v1[2] * c23[0];
;                         o1[3] = v0[3] * c23[2] - v1[3] * c23[3]; o2[3] = v0[3] * c23[3] + v1[3] * c23[2];
;                         st8(QR + (unsigned)row * 512u + colr, o1, o2); } }
.LBB0_606:
	s_lshl_b32 s2, s90, 8
	v_mov_b32_e32 v0, v154
	v_mov_b32_e32 v138, v155
	s_add_i32 s2, s2, s68
	s_mov_b32 s97, 0x40000
	v_add_u32_e32 v144, s2, v0
	v_ashrrev_i32_e32 v145, 31, v144
	v_lshl_add_u64 v[142:143], v[144:145], 2, s[80:81]
	s_cmp_gt_i32 s40, 3
	v_add_co_u32_e32 v148, vcc, s97, v142
	s_cselect_b64 s[92:93], -1, 0
	s_lshl_b32 s90, s40, 8
	v_addc_co_u32_e32 v149, vcc, 0, v143, vcc
	s_mov_b32 s96, 0x80000
	v_lshl_add_u32 v138, v138, 3, s71
	s_add_i32 s2, s90, 0xfffffc00
	v_add_co_u32_e32 v150, vcc, s96, v142
	v_add_u32_e32 v140, s2, v138
	s_nop 0
	v_addc_co_u32_e32 v151, vcc, 0, v143, vcc
	s_mov_b32 s2, 0xc0000
	global_load_dword v146, v[142:143], off
	global_load_dword v147, v[150:151], off
	v_add_co_u32_e32 v150, vcc, s2, v142
	global_load_dword v148, v[148:149], off
	s_nop 0
	v_addc_co_u32_e32 v151, vcc, 0, v143, vcc
	global_load_dword v149, v[150:151], off
	v_and_b32_e32 v158, 56, v138
	v_ashrrev_i32_e32 v141, 31, v140
	s_waitcnt vmcnt(0)
	v_pk_add_f32 v[146:147], v[146:147], v[148:149]
	s_nop 0
	v_add_f32_e32 v0, v146, v147
	v_fmamk_f32 v0, v0, 0x3b800000, v220
	v_cmp_gt_f32_e32 vcc, s51, v0
	v_mul_f32_e32 v139, 0x4b800000, v0
	s_nop 0
	v_cndmask_b32_e32 v0, v0, v139, vcc
	v_rsq_f32_e32 v0, v0
	s_nop 0
	v_mul_f32_e32 v139, 0x45800000, v0
	v_cndmask_b32_e32 v0, v0, v139, vcc
	v_mul_f32_e32 v146, 0x3dd53b94, v0
	v_lshlrev_b32_e32 v0, 9, v144
	v_add_u32_e32 v139, s78, v144
	v_pk_mul_f32 v[128:129], v[128:129], v[146:147] op_sel_hi:[1,0]
	v_pk_mul_f32 v[126:127], v[126:127], v[146:147] op_sel_hi:[1,0]
	v_pk_mul_f32 v[124:125], v[124:125], v[146:147] op_sel_hi:[1,0]
	v_pk_mul_f32 v[122:123], v[122:123], v[146:147] op_sel_hi:[1,0]
	s_and_b64 vcc, exec, s[92:93]
	v_lshl_or_b32 v150, v139, 6, v158
	v_lshl_add_u64 v[148:149], v[0:1], 1, s[42:43]
	s_cbranch_vccz .LBB0_608
	v_mov_b32_e32 v151, v1
	v_lshl_add_u64 v[152:153], v[150:151], 2, s[64:65]
	global_load_dwordx4 v[160:163], v[152:153], off offset:16
	global_load_dwordx4 v[164:167], v[152:153], off
	v_lshl_add_u64 v[170:171], v[140:141], 1, v[148:149]
	s_mov_b64 s[8:9], 0
	s_waitcnt vmcnt(0)
	v_mov_b32_e32 v153, v166
	v_mov_b32_e32 v166, v165
	v_mov_b32_e32 v152, v164
	v_pk_mul_f32 v[164:165], v[122:123], v[166:167]
	s_nop 0
	v_pk_fma_f32 v[164:165], v[126:127], v[152:153], v[164:165] neg_lo:[0,0,1] neg_hi:[0,0,1]
	v_pk_mul_f32 v[152:153], v[122:123], v[152:153]
	s_nop 0
	v_pk_fma_f32 v[152:153], v[126:127], v[166:167], v[152:153]
	v_mov_b32_e32 v167, v162
	v_mov_b32_e32 v162, v161
	v_mov_b32_e32 v166, v160
	v_pk_mul_f32 v[160:161], v[124:125], v[162:163]
	s_nop 0
	v_pk_fma_f32 v[168:169], v[128:129], v[166:167], v[160:161] neg_lo:[0,0,1] neg_hi:[0,0,1]
	v_pk_mul_f32 v[160:161], v[124:125], v[166:167]
	s_nop 0
	v_pk_fma_f32 v[166:167], v[128:129], v[162:163], v[160:161]
	v_cvt_pk_bf16_f32 v160, v164, v165
	v_cvt_pk_bf16_f32 v161, v168, v169
	v_cvt_pk_bf16_f32 v162, v152, v153
	v_cvt_pk_bf16_f32 v163, v166, v167
	global_store_dwordx4 v[170:171], v[160:163], off sc1
.LBB0_608:
	v_lshlrev_b32_e32 v0, 10, v144
	s_ashr_i32 s91, s90, 31
	v_ashrrev_i32_e32 v139, 31, v138
	s_andn2_b64 vcc, exec, s[8:9]
	v_lshl_add_u64 v[152:153], v[0:1], 1, s[6:7]
	s_cbranch_vccnz .LBB0_610
	v_lshl_add_u64 v[160:161], s[90:91], 1, v[152:153]
	v_lshl_add_u64 v[160:161], v[138:139], 1, v[160:161]
	v_cvt_pk_bf16_f32 v126, v126, v127
	v_cvt_pk_bf16_f32 v127, v128, v129
	v_cvt_pk_bf16_f32 v128, v122, v123
	v_cvt_pk_bf16_f32 v129, v124, v125
	global_store_dwordx4 v[160:161], v[126:129], off sc1
.LBB0_610:
	v_mov_b32_e32 v147, v146
	v_mov_b32_e32 v122, v146
	v_mov_b32_e32 v123, v146
	v_cndmask_b32_e64 v0, 0, 1, s[92:93]
	v_pk_mul_f32 v[120:121], v[120:121], v[122:123]
	v_pk_mul_f32 v[118:119], v[118:119], v[146:147]
	v_pk_mul_f32 v[116:117], v[116:117], v[122:123]
	v_pk_mul_f32 v[114:115], v[114:115], v[146:147]
	v_cmp_ne_u32_e64 s[40:41], 1, v0
	s_andn2_b64 vcc, exec, s[92:93]
	s_mov_b64 s[8:9], -1
	s_cbranch_vccnz .LBB0_612
	v_mov_b32_e32 v151, v1
	v_lshl_add_u64 v[126:127], v[150:151], 2, s[64:65]
	global_load_dwordx4 v[122:125], v[126:127], off offset:16
	s_nop 0
	global_load_dwordx4 v[126:129], v[126:127], off
	v_lshl_add_u64 v[148:149], v[140:141], 1, v[148:149]
	s_mov_b64 s[8:9], 0
	s_waitcnt vmcnt(0)
	v_mov_b32_e32 v147, v128
	v_mov_b32_e32 v128, v127
	v_mov_b32_e32 v146, v126
	v_pk_mul_f32 v[126:127], v[114:115], v[128:129]
	s_nop 0
	v_pk_fma_f32 v[126:127], v[118:119], v[146:147], v[126:127] neg_lo:[0,0,1] neg_hi:[0,0,1]
	v_pk_mul_f32 v[146:147], v[114:115], v[146:147]
	s_nop 0
	v_pk_fma_f32 v[128:129], v[118:119], v[128:129], v[146:147]
	v_mov_b32_e32 v147, v124
	v_mov_b32_e32 v124, v123
	v_mov_b32_e32 v146, v122
	v_pk_mul_f32 v[122:123], v[116:117], v[124:125]
	s_nop 0
	v_pk_fma_f32 v[150:151], v[120:121], v[146:147], v[122:123] neg_lo:[0,0,1] neg_hi:[0,0,1]
	v_pk_mul_f32 v[122:123], v[116:117], v[146:147]
	s_nop 0
	v_pk_fma_f32 v[146:147], v[120:121], v[124:125], v[122:123]
	v_cvt_pk_bf16_f32 v122, v126, v127
	v_cvt_pk_bf16_f32 v123, v150, v151
	v_cvt_pk_bf16_f32 v124, v128, v129
	v_cvt_pk_bf16_f32 v125, v146, v147
	global_store_dwordx4 v[148:149], v[122:125], off offset:256 sc1
.LBB0_612:
	s_andn2_b64 vcc, exec, s[8:9]
	s_cbranch_vccnz .LBB0_614
	v_lshl_add_u64 v[122:123], s[90:91], 1, v[152:153]
	v_lshl_add_u64 v[122:123], v[138:139], 1, v[122:123]
	v_cvt_pk_bf16_f32 v118, v118, v119
	v_cvt_pk_bf16_f32 v119, v120, v121
	v_cvt_pk_bf16_f32 v120, v114, v115
	v_cvt_pk_bf16_f32 v121, v116, v117
	global_store_dwordx4 v[122:123], v[118:121], off offset:256 sc1
; __device__ __forceinline__ void st8(bf16_t* p, f32x4 a, f32x4 b) { u32x4 w; w.x = pk2(a[0], a[1]); w.y = pk2(a[2], a[3]); w.z = pk2(b[0], b[1]); w.w = pk2(b[2], b[3]); *(u32x4*)p = w; }
;     __device__ __forceinline__ void operator()(ACC_T, const pg8::Unit& u, int wr, int wc, int fr, int fq) const {
;     ...
;             for (int m = 0; m < 4; ++m) { const int row = row0 + ai * 128 + m * 16; const float* sp = ssq + tbase + row; const float rs = rsqrtf(((sp[0] + sp[TT]) + (sp[2 * TT] + sp[3 * TT])) * (1.f / 256.f) + EPS) * c2;
; #pragma unroll
;                 for (int bj = 0; bj < 2; ++bj) { const f32x4 v0 = acc[ai][bj][m][0] * rs, v1 = acc[ai][bj][m][1] * rs;
;                     if (pn < 4) st8(QN + (unsigned)row * 1024u + pn * 256 + cw + bj * 128, v0, v1);
;                     else { const int colr = (pn - 4) * 256 + cw + bj * 128, g8 = (colr & 63) >> 3;
;                         const f32x4* rp = (const f32x4*)(rope + (unsigned)((tbase + row) * 64 + 8 * g8)); const f32x4 c01 = rp[0], c23 = rp[1];
;                         f32x4 o1, o2;
;                         o1[0] = v0[0] * c01[0] - v1[0] * c01[1]; o2[0] = v0[0] * c01[1] + v1[0] * c01[0];
;                         o1[1] = v0[1] * c01[2] - v1[1] * c01[3]; o2[1] = v0[1] * c01[3] + v1[1] * c01[2];
;                         o1[2] = v0[2] * c23[0] - v1[2] * c23[1]; o2[2] = v0[2] * c23[1] + v1[2] * c23[0];
;                         o1[3] = v0[3] * c23[2] - v1[3] * c23[3]; o2[3] = v0[3] * c23[3] + v1[3] * c23[2];
;                         st8(QR + (unsigned)row * 512u + colr, o1, o2); } }
.LBB0_614:
	s_nop 1
	v_add_co_u32_e32 v118, vcc, 0x40000, v142
	global_load_dword v116, v[142:143], off offset:64
	s_nop 0
	v_addc_co_u32_e32 v119, vcc, 0, v143, vcc
	v_add_co_u32_e32 v120, vcc, 0x80000, v142
	global_load_dword v118, v[118:119], off offset:64
	s_nop 0
	v_addc_co_u32_e32 v121, vcc, 0, v143, vcc
	global_load_dword v117, v[120:121], off offset:64
	v_add_co_u32_e32 v120, vcc, 0xc0000, v142
	v_add_u32_e32 v115, 16, v144
	s_nop 0
	v_addc_co_u32_e32 v121, vcc, 0, v143, vcc
	global_load_dword v119, v[120:121], off offset:64
	s_mov_b64 s[8:9], -1
	s_waitcnt vmcnt(0)
	v_pk_add_f32 v[116:117], v[116:117], v[118:119]
	s_nop 0
	v_add_f32_e32 v0, v116, v117
	v_fmamk_f32 v0, v0, 0x3b800000, v220
	v_cmp_gt_f32_e32 vcc, s51, v0
	v_mul_f32_e32 v114, 0x4b800000, v0
	v_add_u32_e32 v116, s78, v115
	v_cndmask_b32_e32 v0, v0, v114, vcc
	v_rsq_f32_e32 v0, v0
	v_lshl_or_b32 v118, v116, 6, v158
	v_mul_f32_e32 v114, 0x45800000, v0
	v_cndmask_b32_e32 v0, v0, v114, vcc
	v_mul_f32_e32 v114, 0x3dd53b94, v0
	v_lshlrev_b32_e32 v0, 9, v115
	v_pk_mul_f32 v[112:113], v[112:113], v[114:115] op_sel_hi:[1,0]
	v_pk_mul_f32 v[110:111], v[110:111], v[114:115] op_sel_hi:[1,0]
	v_pk_mul_f32 v[108:109], v[108:109], v[114:115] op_sel_hi:[1,0]
	v_pk_mul_f32 v[106:107], v[106:107], v[114:115] op_sel_hi:[1,0]
	s_and_b64 vcc, exec, s[40:41]
	v_lshl_add_u64 v[116:117], v[0:1], 1, s[42:43]
	s_cbranch_vccnz .LBB0_616
	v_mov_b32_e32 v119, v1
	v_lshl_add_u64 v[124:125], v[118:119], 2, s[64:65]
	global_load_dwordx4 v[120:123], v[124:125], off offset:16
	s_nop 0
	global_load_dwordx4 v[124:127], v[124:125], off
	v_lshl_add_u64 v[148:149], v[140:141], 1, v[116:117]
	s_mov_b64 s[8:9], 0
	s_waitcnt vmcnt(0)
	v_mov_b32_e32 v129, v126
	v_mov_b32_e32 v126, v125
	v_mov_b32_e32 v128, v124
	v_pk_mul_f32 v[124:125], v[106:107], v[126:127]
	s_nop 0
	v_pk_fma_f32 v[124:125], v[110:111], v[128:129], v[124:125] neg_lo:[0,0,1] neg_hi:[0,0,1]
	v_pk_mul_f32 v[128:129], v[106:107], v[128:129]
	s_nop 0
	v_pk_fma_f32 v[126:127], v[110:111], v[126:127], v[128:129]
	v_mov_b32_e32 v129, v122
	v_mov_b32_e32 v122, v121
	v_mov_b32_e32 v128, v120
	v_pk_mul_f32 v[120:121], v[108:109], v[122:123]
	s_nop 0
	v_pk_fma_f32 v[146:147], v[112:113], v[128:129], v[120:121] neg_lo:[0,0,1] neg_hi:[0,0,1]
	v_pk_mul_f32 v[120:121], v[108:109], v[128:129]
	s_nop 0
	v_pk_fma_f32 v[128:129], v[112:113], v[122:123], v[120:121]
	v_cvt_pk_bf16_f32 v120, v124, v125
	v_cvt_pk_bf16_f32 v121, v146, v147
	v_cvt_pk_bf16_f32 v122, v126, v127
	v_cvt_pk_bf16_f32 v123, v128, v129
	global_store_dwordx4 v[148:149], v[120:123], off sc1
.LBB0_616:
	v_lshlrev_b32_e32 v0, 10, v115
	s_andn2_b64 vcc, exec, s[8:9]
	v_lshl_add_u64 v[120:121], v[0:1], 1, s[6:7]
	s_cbranch_vccnz .LBB0_618
	v_lshl_add_u64 v[122:123], s[90:91], 1, v[120:121]
	v_lshl_add_u64 v[122:123], v[138:139], 1, v[122:123]
	v_cvt_pk_bf16_f32 v110, v110, v111
	v_cvt_pk_bf16_f32 v111, v112, v113
	v_cvt_pk_bf16_f32 v112, v106, v107
	v_cvt_pk_bf16_f32 v113, v108, v109
	global_store_dwordx4 v[122:123], v[110:113], off sc1
.LBB0_618:
	v_mov_b32_e32 v115, v114
	v_mov_b32_e32 v106, v114
	v_mov_b32_e32 v107, v114
	v_pk_mul_f32 v[104:105], v[104:105], v[106:107]
	v_pk_mul_f32 v[102:103], v[102:103], v[114:115]
	v_pk_mul_f32 v[100:101], v[100:101], v[106:107]
	v_pk_mul_f32 v[98:99], v[98:99], v[114:115]
	s_and_b64 vcc, exec, s[40:41]
	s_mov_b64 s[8:9], -1
	s_cbranch_vccnz .LBB0_620
	v_mov_b32_e32 v119, v1
	v_lshl_add_u64 v[110:111], v[118:119], 2, s[64:65]
	global_load_dwordx4 v[106:109], v[110:111], off offset:16
	s_nop 0
	global_load_dwordx4 v[110:113], v[110:111], off
	v_lshl_add_u64 v[116:117], v[140:141], 1, v[116:117]
	s_mov_b64 s[8:9], 0
	s_waitcnt vmcnt(0)
	v_mov_b32_e32 v115, v112
	v_mov_b32_e32 v112, v111
	v_mov_b32_e32 v114, v110
	v_pk_mul_f32 v[110:111], v[98:99], v[112:113]
	s_nop 0
	v_pk_fma_f32 v[110:111], v[102:103], v[114:115], v[110:111] neg_lo:[0,0,1] neg_hi:[0,0,1]
	v_pk_mul_f32 v[114:115], v[98:99], v[114:115]
	s_nop 0
	v_pk_fma_f32 v[112:113], v[102:103], v[112:113], v[114:115]
	v_mov_b32_e32 v115, v108
	v_mov_b32_e32 v108, v107
	v_mov_b32_e32 v114, v106
	v_pk_mul_f32 v[106:107], v[100:101], v[108:109]
	s_nop 0
	v_pk_fma_f32 v[118:119], v[104:105], v[114:115], v[106:107] neg_lo:[0,0,1] neg_hi:[0,0,1]
	v_pk_mul_f32 v[106:107], v[100:101], v[114:115]
	s_nop 0
	v_pk_fma_f32 v[114:115], v[104:105], v[108:109], v[106:107]
	v_cvt_pk_bf16_f32 v106, v110, v111
	v_cvt_pk_bf16_f32 v107, v118, v119
	v_cvt_pk_bf16_f32 v108, v112, v113
	v_cvt_pk_bf16_f32 v109, v114, v115
	global_store_dwordx4 v[116:117], v[106:109], off offset:256 sc1
.LBB0_620:
	s_andn2_b64 vcc, exec, s[8:9]
	s_cbranch_vccnz .LBB0_622
	v_lshl_add_u64 v[106:107], s[90:91], 1, v[120:121]
	v_lshl_add_u64 v[106:107], v[138:139], 1, v[106:107]
	v_cvt_pk_bf16_f32 v102, v102, v103
	v_cvt_pk_bf16_f32 v103, v104, v105
	v_cvt_pk_bf16_f32 v104, v98, v99
	v_cvt_pk_bf16_f32 v105, v100, v101
	global_store_dwordx4 v[106:107], v[102:105], off offset:256 sc1
; __device__ __forceinline__ void st8(bf16_t* p, f32x4 a, f32x4 b) { u32x4 w; w.x = pk2(a[0], a[1]); w.y = pk2(a[2], a[3]); w.z = pk2(b[0], b[1]); w.w = pk2(b[2], b[3]); *(u32x4*)p = w; }
;     __device__ __forceinline__ void operator()(ACC_T, const pg8::Unit& u, int wr, int wc, int fr, int fq) const {
;     ...
;             for (int m = 0; m < 4; ++m) { const int row = row0 + ai * 128 + m * 16; const float* sp = ssq + tbase + row; const float rs = rsqrtf(((sp[0] + sp[TT]) + (sp[2 * TT] + sp[3 * TT])) * (1.f / 256.f) + EPS) * c2;
; #pragma unroll
;                 for (int bj = 0; bj < 2; ++bj) { const f32x4 v0 = acc[ai][bj][m][0] * rs, v1 = acc[ai][bj][m][1] * rs;
;                     if (pn < 4) st8(QN + (unsigned)row * 1024u + pn * 256 + cw + bj * 128, v0, v1);
;                     else { const int colr = (pn - 4) * 256 + cw + bj * 128, g8 = (colr & 63) >> 3;
;                         const f32x4* rp = (const f32x4*)(rope + (unsigned)((tbase + row) * 64 + 8 * g8)); const f32x4 c01 = rp[0], c23 = rp[1];
;                         f32x4 o1, o2;
;                         o1[0] = v0[0] * c01[0] - v1[0] * c01[1]; o2[0] = v0[0] * c01[1] + v1[0] * c01[0];
;                         o1[1] = v0[1] * c01[2] - v1[1] * c01[3]; o2[1] = v0[1] * c01[3] + v1[1] * c01[2];
;                         o1[2] = v0[2] * c23[0] - v1[2] * c23[1]; o2[2] = v0[2] * c23[1] + v1[2] * c23[0];
;                         o1[3] = v0[3] * c23[2] - v1[3] * c23[3]; o2[3] = v0[3] * c23[3] + v1[3] * c23[2];
;                         st8(QR + (unsigned)row * 512u + colr, o1, o2); } }
.LBB0_622:
	s_nop 1
	v_add_co_u32_e32 v102, vcc, 0x40000, v142
	global_load_dword v100, v[142:143], off offset:128
	s_nop 0
	v_addc_co_u32_e32 v103, vcc, 0, v143, vcc
	v_add_co_u32_e32 v104, vcc, 0x80000, v142
	global_load_dword v102, v[102:103], off offset:128
	s_nop 0
	v_addc_co_u32_e32 v105, vcc, 0, v143, vcc
	global_load_dword v101, v[104:105], off offset:128
	v_add_co_u32_e32 v104, vcc, 0xc0000, v142
	v_add_u32_e32 v99, 32, v144
	s_nop 0
	v_addc_co_u32_e32 v105, vcc, 0, v143, vcc
	global_load_dword v103, v[104:105], off offset:128
	s_mov_b64 s[8:9], -1
	s_waitcnt vmcnt(0)
	v_pk_add_f32 v[100:101], v[100:101], v[102:103]
	s_nop 0
	v_add_f32_e32 v0, v100, v101
	v_fmamk_f32 v0, v0, 0x3b800000, v220
	v_cmp_gt_f32_e32 vcc, s51, v0
	v_mul_f32_e32 v98, 0x4b800000, v0
	v_add_u32_e32 v100, s78, v99
	v_cndmask_b32_e32 v0, v0, v98, vcc
	v_rsq_f32_e32 v0, v0
	v_lshl_or_b32 v102, v100, 6, v158
	v_mul_f32_e32 v98, 0x45800000, v0
	v_cndmask_b32_e32 v0, v0, v98, vcc
	v_mul_f32_e32 v98, 0x3dd53b94, v0
	v_lshlrev_b32_e32 v0, 9, v99
	v_pk_mul_f32 v[96:97], v[96:97], v[98:99] op_sel_hi:[1,0]
	v_pk_mul_f32 v[94:95], v[94:95], v[98:99] op_sel_hi:[1,0]
	v_pk_mul_f32 v[92:93], v[92:93], v[98:99] op_sel_hi:[1,0]
	v_pk_mul_f32 v[90:91], v[90:91], v[98:99] op_sel_hi:[1,0]
	s_and_b64 vcc, exec, s[40:41]
	v_lshl_add_u64 v[100:101], v[0:1], 1, s[42:43]
	s_cbranch_vccnz .LBB0_624
	v_mov_b32_e32 v103, v1
	v_lshl_add_u64 v[108:109], v[102:103], 2, s[64:65]
	global_load_dwordx4 v[104:107], v[108:109], off offset:16
	s_nop 0
	global_load_dwordx4 v[108:111], v[108:109], off
	v_lshl_add_u64 v[116:117], v[140:141], 1, v[100:101]
	s_mov_b64 s[8:9], 0
	s_waitcnt vmcnt(0)
	v_mov_b32_e32 v113, v110
	v_mov_b32_e32 v110, v109
	v_mov_b32_e32 v112, v108
	v_pk_mul_f32 v[108:109], v[90:91], v[110:111]
	s_nop 0
	v_pk_fma_f32 v[108:109], v[94:95], v[112:113], v[108:109] neg_lo:[0,0,1] neg_hi:[0,0,1]
	v_pk_mul_f32 v[112:113], v[90:91], v[112:113]
	s_nop 0
	v_pk_fma_f32 v[110:111], v[94:95], v[110:111], v[112:113]
	v_mov_b32_e32 v113, v106
	v_mov_b32_e32 v106, v105
	v_mov_b32_e32 v112, v104
	v_pk_mul_f32 v[104:105], v[92:93], v[106:107]
	s_nop 0
	v_pk_fma_f32 v[114:115], v[96:97], v[112:113], v[104:105] neg_lo:[0,0,1] neg_hi:[0,0,1]
	v_pk_mul_f32 v[104:105], v[92:93], v[112:113]
	s_nop 0
	v_pk_fma_f32 v[112:113], v[96:97], v[106:107], v[104:105]
	v_cvt_pk_bf16_f32 v104, v108, v109
	v_cvt_pk_bf16_f32 v105, v114, v115
	v_cvt_pk_bf16_f32 v106, v110, v111
	v_cvt_pk_bf16_f32 v107, v112, v113
	global_store_dwordx4 v[116:117], v[104:107], off sc1
.LBB0_624:
	v_lshlrev_b32_e32 v0, 10, v99
	s_andn2_b64 vcc, exec, s[8:9]
	v_lshl_add_u64 v[104:105], v[0:1], 1, s[6:7]
	s_cbranch_vccnz .LBB0_626
	v_lshl_add_u64 v[106:107], s[90:91], 1, v[104:105]
	v_lshl_add_u64 v[106:107], v[138:139], 1, v[106:107]
	v_cvt_pk_bf16_f32 v94, v94, v95
	v_cvt_pk_bf16_f32 v95, v96, v97
	v_cvt_pk_bf16_f32 v96, v90, v91
	v_cvt_pk_bf16_f32 v97, v92, v93
	global_store_dwordx4 v[106:107], v[94:97], off sc1
.LBB0_626:
	v_mov_b32_e32 v99, v98
	v_mov_b32_e32 v90, v98
	v_mov_b32_e32 v91, v98
	v_pk_mul_f32 v[88:89], v[88:89], v[90:91]
	v_pk_mul_f32 v[86:87], v[86:87], v[98:99]
	v_pk_mul_f32 v[84:85], v[84:85], v[90:91]
	v_pk_mul_f32 v[82:83], v[82:83], v[98:99]
	s_and_b64 vcc, exec, s[40:41]
	s_mov_b64 s[8:9], -1
	s_cbranch_vccnz .LBB0_628
	v_mov_b32_e32 v103, v1
	v_lshl_add_u64 v[94:95], v[102:103], 2, s[64:65]
	global_load_dwordx4 v[90:93], v[94:95], off offset:16
	s_nop 0
	global_load_dwordx4 v[94:97], v[94:95], off
	v_lshl_add_u64 v[100:101], v[140:141], 1, v[100:101]
	s_mov_b64 s[8:9], 0
	s_waitcnt vmcnt(0)
	v_mov_b32_e32 v99, v96
	v_mov_b32_e32 v96, v95
	v_mov_b32_e32 v98, v94
	v_pk_mul_f32 v[94:95], v[82:83], v[96:97]
	s_nop 0
	v_pk_fma_f32 v[94:95], v[86:87], v[98:99], v[94:95] neg_lo:[0,0,1] neg_hi:[0,0,1]
	v_pk_mul_f32 v[98:99], v[82:83], v[98:99]
	s_nop 0
	v_pk_fma_f32 v[96:97], v[86:87], v[96:97], v[98:99]
	v_mov_b32_e32 v99, v92
	v_mov_b32_e32 v92, v91
	v_mov_b32_e32 v98, v90
	v_pk_mul_f32 v[90:91], v[84:85], v[92:93]
	s_nop 0
	v_pk_fma_f32 v[102:103], v[88:89], v[98:99], v[90:91] neg_lo:[0,0,1] neg_hi:[0,0,1]
	v_pk_mul_f32 v[90:91], v[84:85], v[98:99]
	s_nop 0
	v_pk_fma_f32 v[98:99], v[88:89], v[92:93], v[90:91]
	v_cvt_pk_bf16_f32 v90, v94, v95
	v_cvt_pk_bf16_f32 v91, v102, v103
	v_cvt_pk_bf16_f32 v92, v96, v97
	v_cvt_pk_bf16_f32 v93, v98, v99
	global_store_dwordx4 v[100:101], v[90:93], off offset:256 sc1
.LBB0_628:
	s_andn2_b64 vcc, exec, s[8:9]
	s_cbranch_vccnz .LBB0_630
	v_lshl_add_u64 v[90:91], s[90:91], 1, v[104:105]
	v_lshl_add_u64 v[90:91], v[138:139], 1, v[90:91]
	v_cvt_pk_bf16_f32 v86, v86, v87
	v_cvt_pk_bf16_f32 v87, v88, v89
	v_cvt_pk_bf16_f32 v88, v82, v83
	v_cvt_pk_bf16_f32 v89, v84, v85
	global_store_dwordx4 v[90:91], v[86:89], off offset:256 sc1
; __device__ __forceinline__ void st8(bf16_t* p, f32x4 a, f32x4 b) { u32x4 w; w.x = pk2(a[0], a[1]); w.y = pk2(a[2], a[3]); w.z = pk2(b[0], b[1]); w.w = pk2(b[2], b[3]); *(u32x4*)p = w; }
;     __device__ __forceinline__ void operator()(ACC_T, const pg8::Unit& u, int wr, int wc, int fr, int fq) const {
;     ...
;             for (int m = 0; m < 4; ++m) { const int row = row0 + ai * 128 + m * 16; const float* sp = ssq + tbase + row; const float rs = rsqrtf(((sp[0] + sp[TT]) + (sp[2 * TT] + sp[3 * TT])) * (1.f / 256.f) + EPS) * c2;
; #pragma unroll
;                 for (int bj = 0; bj < 2; ++bj) { const f32x4 v0 = acc[ai][bj][m][0] * rs, v1 = acc[ai][bj][m][1] * rs;
;                     if (pn < 4) st8(QN + (unsigned)row * 1024u + pn * 256 + cw + bj * 128, v0, v1);
;                     else { const int colr = (pn - 4) * 256 + cw + bj * 128, g8 = (colr & 63) >> 3;
;                         const f32x4* rp = (const f32x4*)(rope + (unsigned)((tbase + row) * 64 + 8 * g8)); const f32x4 c01 = rp[0], c23 = rp[1];
;                         f32x4 o1, o2;
;                         o1[0] = v0[0] * c01[0] - v1[0] * c01[1]; o2[0] = v0[0] * c01[1] + v1[0] * c01[0];
;                         o1[1] = v0[1] * c01[2] - v1[1] * c01[3]; o2[1] = v0[1] * c01[3] + v1[1] * c01[2];
;                         o1[2] = v0[2] * c23[0] - v1[2] * c23[1]; o2[2] = v0[2] * c23[1] + v1[2] * c23[0];
;                         o1[3] = v0[3] * c23[2] - v1[3] * c23[3]; o2[3] = v0[3] * c23[3] + v1[3] * c23[2];
;                         st8(QR + (unsigned)row * 512u + colr, o1, o2); } }
.LBB0_630:
	s_nop 1
	v_add_co_u32_e32 v86, vcc, 0x40000, v142
	global_load_dword v84, v[142:143], off offset:192
	s_nop 0
	v_addc_co_u32_e32 v87, vcc, 0, v143, vcc
	v_add_co_u32_e32 v88, vcc, 0x80000, v142
	global_load_dword v86, v[86:87], off offset:192
	s_nop 0
	v_addc_co_u32_e32 v89, vcc, 0, v143, vcc
	global_load_dword v85, v[88:89], off offset:192
	v_add_co_u32_e32 v88, vcc, 0xc0000, v142
	v_add_u32_e32 v83, 48, v144
	s_nop 0
	v_addc_co_u32_e32 v89, vcc, 0, v143, vcc
	global_load_dword v87, v[88:89], off offset:192
	s_mov_b64 s[8:9], -1
	s_waitcnt vmcnt(0)
	v_pk_add_f32 v[84:85], v[84:85], v[86:87]
	s_nop 0
	v_add_f32_e32 v0, v84, v85
	v_fmamk_f32 v0, v0, 0x3b800000, v220
	v_cmp_gt_f32_e32 vcc, s51, v0
	v_mul_f32_e32 v82, 0x4b800000, v0
	v_add_u32_e32 v84, s78, v83
	v_cndmask_b32_e32 v0, v0, v82, vcc
	v_rsq_f32_e32 v0, v0
	v_lshl_or_b32 v86, v84, 6, v158
	v_mul_f32_e32 v82, 0x45800000, v0
	v_cndmask_b32_e32 v0, v0, v82, vcc
	v_mul_f32_e32 v82, 0x3dd53b94, v0
	v_lshlrev_b32_e32 v0, 9, v83
	v_pk_mul_f32 v[80:81], v[80:81], v[82:83] op_sel_hi:[1,0]
	v_pk_mul_f32 v[78:79], v[78:79], v[82:83] op_sel_hi:[1,0]
	v_pk_mul_f32 v[76:77], v[76:77], v[82:83] op_sel_hi:[1,0]
	v_pk_mul_f32 v[74:75], v[74:75], v[82:83] op_sel_hi:[1,0]
	s_and_b64 vcc, exec, s[40:41]
	v_lshl_add_u64 v[84:85], v[0:1], 1, s[42:43]
	s_cbranch_vccnz .LBB0_632
	v_mov_b32_e32 v87, v1
	v_lshl_add_u64 v[92:93], v[86:87], 2, s[64:65]
	global_load_dwordx4 v[88:91], v[92:93], off offset:16
	s_nop 0
	global_load_dwordx4 v[92:95], v[92:93], off
	v_lshl_add_u64 v[100:101], v[140:141], 1, v[84:85]
	s_mov_b64 s[8:9], 0
	s_waitcnt vmcnt(0)
	v_mov_b32_e32 v97, v94
	v_mov_b32_e32 v94, v93
	v_mov_b32_e32 v96, v92
	v_pk_mul_f32 v[92:93], v[74:75], v[94:95]
	s_nop 0
	v_pk_fma_f32 v[92:93], v[78:79], v[96:97], v[92:93] neg_lo:[0,0,1] neg_hi:[0,0,1]
	v_pk_mul_f32 v[96:97], v[74:75], v[96:97]
	s_nop 0
	v_pk_fma_f32 v[94:95], v[78:79], v[94:95], v[96:97]
	v_mov_b32_e32 v97, v90
	v_mov_b32_e32 v90, v89
	v_mov_b32_e32 v96, v88
	v_pk_mul_f32 v[88:89], v[76:77], v[90:91]
	s_nop 0
	v_pk_fma_f32 v[98:99], v[80:81], v[96:97], v[88:89] neg_lo:[0,0,1] neg_hi:[0,0,1]
	v_pk_mul_f32 v[88:89], v[76:77], v[96:97]
	s_nop 0
	v_pk_fma_f32 v[96:97], v[80:81], v[90:91], v[88:89]
	v_cvt_pk_bf16_f32 v88, v92, v93
	v_cvt_pk_bf16_f32 v89, v98, v99
	v_cvt_pk_bf16_f32 v90, v94, v95
	v_cvt_pk_bf16_f32 v91, v96, v97
	global_store_dwordx4 v[100:101], v[88:91], off sc1
.LBB0_632:
	v_lshlrev_b32_e32 v0, 10, v83
	s_andn2_b64 vcc, exec, s[8:9]
	v_lshl_add_u64 v[88:89], v[0:1], 1, s[6:7]
	s_cbranch_vccnz .LBB0_634
	v_lshl_add_u64 v[90:91], s[90:91], 1, v[88:89]
	v_lshl_add_u64 v[90:91], v[138:139], 1, v[90:91]
	v_cvt_pk_bf16_f32 v78, v78, v79
	v_cvt_pk_bf16_f32 v79, v80, v81
	v_cvt_pk_bf16_f32 v80, v74, v75
	v_cvt_pk_bf16_f32 v81, v76, v77
	global_store_dwordx4 v[90:91], v[78:81], off sc1
.LBB0_634:
	v_mov_b32_e32 v83, v82
	v_mov_b32_e32 v74, v82
	v_mov_b32_e32 v75, v82
	v_pk_mul_f32 v[72:73], v[72:73], v[74:75]
	v_pk_mul_f32 v[70:71], v[70:71], v[82:83]
	v_pk_mul_f32 v[68:69], v[68:69], v[74:75]
	v_pk_mul_f32 v[66:67], v[66:67], v[82:83]
	s_and_b64 vcc, exec, s[40:41]
	s_mov_b64 s[8:9], -1
	s_cbranch_vccnz .LBB0_636
	v_mov_b32_e32 v87, v1
	v_lshl_add_u64 v[78:79], v[86:87], 2, s[64:65]
	global_load_dwordx4 v[74:77], v[78:79], off offset:16
	s_nop 0
	global_load_dwordx4 v[78:81], v[78:79], off
	v_lshl_add_u64 v[84:85], v[140:141], 1, v[84:85]
	s_mov_b64 s[8:9], 0
	s_waitcnt vmcnt(0)
	v_mov_b32_e32 v83, v80
	v_mov_b32_e32 v80, v79
	v_mov_b32_e32 v82, v78
	v_pk_mul_f32 v[78:79], v[66:67], v[80:81]
	s_nop 0
	v_pk_fma_f32 v[78:79], v[70:71], v[82:83], v[78:79] neg_lo:[0,0,1] neg_hi:[0,0,1]
	v_pk_mul_f32 v[82:83], v[66:67], v[82:83]
	s_nop 0
	v_pk_fma_f32 v[80:81], v[70:71], v[80:81], v[82:83]
	v_mov_b32_e32 v83, v76
	v_mov_b32_e32 v76, v75
	v_mov_b32_e32 v82, v74
	v_pk_mul_f32 v[74:75], v[68:69], v[76:77]
	s_nop 0
	v_pk_fma_f32 v[86:87], v[72:73], v[82:83], v[74:75] neg_lo:[0,0,1] neg_hi:[0,0,1]
	v_pk_mul_f32 v[74:75], v[68:69], v[82:83]
	s_nop 0
	v_pk_fma_f32 v[82:83], v[72:73], v[76:77], v[74:75]
	v_cvt_pk_bf16_f32 v74, v78, v79
	v_cvt_pk_bf16_f32 v75, v86, v87
	v_cvt_pk_bf16_f32 v76, v80, v81
	v_cvt_pk_bf16_f32 v77, v82, v83
	global_store_dwordx4 v[84:85], v[74:77], off offset:256 sc1
.LBB0_636:
	s_andn2_b64 vcc, exec, s[8:9]
	s_cbranch_vccnz .LBB0_638
	v_lshl_add_u64 v[74:75], s[90:91], 1, v[88:89]
	v_lshl_add_u64 v[74:75], v[138:139], 1, v[74:75]
	v_cvt_pk_bf16_f32 v70, v70, v71
	v_cvt_pk_bf16_f32 v71, v72, v73
	v_cvt_pk_bf16_f32 v72, v66, v67
	v_cvt_pk_bf16_f32 v73, v68, v69
	global_store_dwordx4 v[74:75], v[70:73], off offset:256 sc1
; __device__ __forceinline__ void st8(bf16_t* p, f32x4 a, f32x4 b) { u32x4 w; w.x = pk2(a[0], a[1]); w.y = pk2(a[2], a[3]); w.z = pk2(b[0], b[1]); w.w = pk2(b[2], b[3]); *(u32x4*)p = w; }
;     __device__ __forceinline__ void operator()(ACC_T, const pg8::Unit& u, int wr, int wc, int fr, int fq) const {
;     ...
;             for (int m = 0; m < 4; ++m) { const int row = row0 + ai * 128 + m * 16; const float* sp = ssq + tbase + row; const float rs = rsqrtf(((sp[0] + sp[TT]) + (sp[2 * TT] + sp[3 * TT])) * (1.f / 256.f) + EPS) * c2;
; #pragma unroll
;                 for (int bj = 0; bj < 2; ++bj) { const f32x4 v0 = acc[ai][bj][m][0] * rs, v1 = acc[ai][bj][m][1] * rs;
;                     if (pn < 4) st8(QN + (unsigned)row * 1024u + pn * 256 + cw + bj * 128, v0, v1);
;                     else { const int colr = (pn - 4) * 256 + cw + bj * 128, g8 = (colr & 63) >> 3;
;                         const f32x4* rp = (const f32x4*)(rope + (unsigned)((tbase + row) * 64 + 8 * g8)); const f32x4 c01 = rp[0], c23 = rp[1];
;                         f32x4 o1, o2;
;                         o1[0] = v0[0] * c01[0] - v1[0] * c01[1]; o2[0] = v0[0] * c01[1] + v1[0] * c01[0];
;                         o1[1] = v0[1] * c01[2] - v1[1] * c01[3]; o2[1] = v0[1] * c01[3] + v1[1] * c01[2];
;                         o1[2] = v0[2] * c23[0] - v1[2] * c23[1]; o2[2] = v0[2] * c23[1] + v1[2] * c23[0];
;                         o1[3] = v0[3] * c23[2] - v1[3] * c23[3]; o2[3] = v0[3] * c23[3] + v1[3] * c23[2];
;                         st8(QR + (unsigned)row * 512u + colr, o1, o2); } }
.LBB0_638:
	s_nop 1
	v_add_co_u32_e32 v70, vcc, 0x40000, v142
	global_load_dword v68, v[142:143], off offset:512
	s_nop 0
	v_addc_co_u32_e32 v71, vcc, 0, v143, vcc
	v_add_co_u32_e32 v72, vcc, 0x80000, v142
	global_load_dword v70, v[70:71], off offset:512
	s_nop 0
	v_addc_co_u32_e32 v73, vcc, 0, v143, vcc
	global_load_dword v69, v[72:73], off offset:512
	v_add_co_u32_e32 v72, vcc, 0xc0000, v142
	v_add_u32_e32 v67, 0x80, v144
	s_nop 0
	v_addc_co_u32_e32 v73, vcc, 0, v143, vcc
	global_load_dword v71, v[72:73], off offset:512
	s_mov_b64 s[8:9], -1
	s_waitcnt vmcnt(0)
	v_pk_add_f32 v[68:69], v[68:69], v[70:71]
	s_nop 0
	v_add_f32_e32 v0, v68, v69
	v_fmamk_f32 v0, v0, 0x3b800000, v220
	v_cmp_gt_f32_e32 vcc, s51, v0
	v_mul_f32_e32 v66, 0x4b800000, v0
	v_add_u32_e32 v68, s78, v67
	v_cndmask_b32_e32 v0, v0, v66, vcc
	v_rsq_f32_e32 v0, v0
	v_lshl_or_b32 v70, v68, 6, v158
	v_mul_f32_e32 v66, 0x45800000, v0
	v_cndmask_b32_e32 v0, v0, v66, vcc
	v_mul_f32_e32 v66, 0x3dd53b94, v0
	v_lshlrev_b32_e32 v0, 9, v67
	v_pk_mul_f32 v[64:65], v[64:65], v[66:67] op_sel_hi:[1,0]
	v_pk_mul_f32 v[62:63], v[62:63], v[66:67] op_sel_hi:[1,0]
	v_pk_mul_f32 v[60:61], v[60:61], v[66:67] op_sel_hi:[1,0]
	v_pk_mul_f32 v[58:59], v[58:59], v[66:67] op_sel_hi:[1,0]
	s_and_b64 vcc, exec, s[40:41]
	v_lshl_add_u64 v[68:69], v[0:1], 1, s[42:43]
	s_cbranch_vccnz .LBB0_640
	v_mov_b32_e32 v71, v1
	v_lshl_add_u64 v[76:77], v[70:71], 2, s[64:65]
	global_load_dwordx4 v[72:75], v[76:77], off offset:16
	s_nop 0
	global_load_dwordx4 v[76:79], v[76:77], off
	v_lshl_add_u64 v[84:85], v[140:141], 1, v[68:69]
	s_mov_b64 s[8:9], 0
	s_waitcnt vmcnt(0)
	v_mov_b32_e32 v81, v78
	v_mov_b32_e32 v78, v77
	v_mov_b32_e32 v80, v76
	v_pk_mul_f32 v[76:77], v[58:59], v[78:79]
	s_nop 0
	v_pk_fma_f32 v[76:77], v[62:63], v[80:81], v[76:77] neg_lo:[0,0,1] neg_hi:[0,0,1]
	v_pk_mul_f32 v[80:81], v[58:59], v[80:81]
	s_nop 0
	v_pk_fma_f32 v[78:79], v[62:63], v[78:79], v[80:81]
	v_mov_b32_e32 v81, v74
	v_mov_b32_e32 v74, v73
	v_mov_b32_e32 v80, v72
	v_pk_mul_f32 v[72:73], v[60:61], v[74:75]
	s_nop 0
	v_pk_fma_f32 v[82:83], v[64:65], v[80:81], v[72:73] neg_lo:[0,0,1] neg_hi:[0,0,1]
	v_pk_mul_f32 v[72:73], v[60:61], v[80:81]
	s_nop 0
	v_pk_fma_f32 v[80:81], v[64:65], v[74:75], v[72:73]
	v_cvt_pk_bf16_f32 v72, v76, v77
	v_cvt_pk_bf16_f32 v73, v82, v83
	v_cvt_pk_bf16_f32 v74, v78, v79
	v_cvt_pk_bf16_f32 v75, v80, v81
	global_store_dwordx4 v[84:85], v[72:75], off sc1
.LBB0_640:
	v_lshlrev_b32_e32 v0, 10, v67
	s_andn2_b64 vcc, exec, s[8:9]
	v_lshl_add_u64 v[72:73], v[0:1], 1, s[6:7]
	s_cbranch_vccnz .LBB0_642
	v_lshl_add_u64 v[74:75], s[90:91], 1, v[72:73]
	v_lshl_add_u64 v[74:75], v[138:139], 1, v[74:75]
	v_cvt_pk_bf16_f32 v62, v62, v63
	v_cvt_pk_bf16_f32 v63, v64, v65
	v_cvt_pk_bf16_f32 v64, v58, v59
	v_cvt_pk_bf16_f32 v65, v60, v61
	global_store_dwordx4 v[74:75], v[62:65], off sc1
.LBB0_642:
	v_mov_b32_e32 v67, v66
	v_mov_b32_e32 v58, v66
	v_mov_b32_e32 v59, v66
	v_pk_mul_f32 v[56:57], v[56:57], v[58:59]
	v_pk_mul_f32 v[54:55], v[54:55], v[66:67]
	v_pk_mul_f32 v[52:53], v[52:53], v[58:59]
	v_pk_mul_f32 v[50:51], v[50:51], v[66:67]
	s_and_b64 vcc, exec, s[40:41]
	s_mov_b64 s[8:9], -1
	s_cbranch_vccnz .LBB0_644
	v_mov_b32_e32 v71, v1
	v_lshl_add_u64 v[62:63], v[70:71], 2, s[64:65]
	global_load_dwordx4 v[58:61], v[62:63], off offset:16
	s_nop 0
	global_load_dwordx4 v[62:65], v[62:63], off
	v_lshl_add_u64 v[68:69], v[140:141], 1, v[68:69]
	s_mov_b64 s[8:9], 0
	s_waitcnt vmcnt(0)
	v_mov_b32_e32 v67, v64
	v_mov_b32_e32 v64, v63
	v_mov_b32_e32 v66, v62
	v_pk_mul_f32 v[62:63], v[50:51], v[64:65]
	s_nop 0
	v_pk_fma_f32 v[62:63], v[54:55], v[66:67], v[62:63] neg_lo:[0,0,1] neg_hi:[0,0,1]
	v_pk_mul_f32 v[66:67], v[50:51], v[66:67]
	s_nop 0
	v_pk_fma_f32 v[64:65], v[54:55], v[64:65], v[66:67]
	v_mov_b32_e32 v67, v60
	v_mov_b32_e32 v60, v59
	v_mov_b32_e32 v66, v58
	v_pk_mul_f32 v[58:59], v[52:53], v[60:61]
	s_nop 0
	v_pk_fma_f32 v[70:71], v[56:57], v[66:67], v[58:59] neg_lo:[0,0,1] neg_hi:[0,0,1]
	v_pk_mul_f32 v[58:59], v[52:53], v[66:67]
	s_nop 0
	v_pk_fma_f32 v[66:67], v[56:57], v[60:61], v[58:59]
	v_cvt_pk_bf16_f32 v58, v62, v63
	v_cvt_pk_bf16_f32 v59, v70, v71
	v_cvt_pk_bf16_f32 v60, v64, v65
	v_cvt_pk_bf16_f32 v61, v66, v67
	global_store_dwordx4 v[68:69], v[58:61], off offset:256 sc1
.LBB0_644:
	s_andn2_b64 vcc, exec, s[8:9]
	s_cbranch_vccnz .LBB0_646
	v_lshl_add_u64 v[58:59], s[90:91], 1, v[72:73]
	v_lshl_add_u64 v[58:59], v[138:139], 1, v[58:59]
	v_cvt_pk_bf16_f32 v54, v54, v55
	v_cvt_pk_bf16_f32 v55, v56, v57
	v_cvt_pk_bf16_f32 v56, v50, v51
	v_cvt_pk_bf16_f32 v57, v52, v53
	global_store_dwordx4 v[58:59], v[54:57], off offset:256 sc1
; __device__ __forceinline__ void st8(bf16_t* p, f32x4 a, f32x4 b) { u32x4 w; w.x = pk2(a[0], a[1]); w.y = pk2(a[2], a[3]); w.z = pk2(b[0], b[1]); w.w = pk2(b[2], b[3]); *(u32x4*)p = w; }
;     __device__ __forceinline__ void operator()(ACC_T, const pg8::Unit& u, int wr, int wc, int fr, int fq) const {
;     ...
;             for (int m = 0; m < 4; ++m) { const int row = row0 + ai * 128 + m * 16; const float* sp = ssq + tbase + row; const float rs = rsqrtf(((sp[0] + sp[TT]) + (sp[2 * TT] + sp[3 * TT])) * (1.f / 256.f) + EPS) * c2;
; #pragma unroll
;                 for (int bj = 0; bj < 2; ++bj) { const f32x4 v0 = acc[ai][bj][m][0] * rs, v1 = acc[ai][bj][m][1] * rs;
;                     if (pn < 4) st8(QN + (unsigned)row * 1024u + pn * 256 + cw + bj * 128, v0, v1);
;                     else { const int colr = (pn - 4) * 256 + cw + bj * 128, g8 = (colr & 63) >> 3;
;                         const f32x4* rp = (const f32x4*)(rope + (unsigned)((tbase + row) * 64 + 8 * g8)); const f32x4 c01 = rp[0], c23 = rp[1];
;                         f32x4 o1, o2;
;                         o1[0] = v0[0] * c01[0] - v1[0] * c01[1]; o2[0] = v0[0] * c01[1] + v1[0] * c01[0];
;                         o1[1] = v0[1] * c01[2] - v1[1] * c01[3]; o2[1] = v0[1] * c01[3] + v1[1] * c01[2];
;                         o1[2] = v0[2] * c23[0] - v1[2] * c23[1]; o2[2] = v0[2] * c23[1] + v1[2] * c23[0];
;                         o1[3] = v0[3] * c23[2] - v1[3] * c23[3]; o2[3] = v0[3] * c23[3] + v1[3] * c23[2];
;                         st8(QR + (unsigned)row * 512u + colr, o1, o2); } }
.LBB0_646:
	s_nop 1
	v_add_co_u32_e32 v54, vcc, 0x40000, v142
	global_load_dword v52, v[142:143], off offset:576
	s_nop 0
	v_addc_co_u32_e32 v55, vcc, 0, v143, vcc
	v_add_co_u32_e32 v56, vcc, 0x80000, v142
	global_load_dword v54, v[54:55], off offset:576
	s_nop 0
	v_addc_co_u32_e32 v57, vcc, 0, v143, vcc
	global_load_dword v53, v[56:57], off offset:576
	v_add_co_u32_e32 v56, vcc, 0xc0000, v142
	v_add_u32_e32 v51, 0x90, v144
	s_nop 0
	v_addc_co_u32_e32 v57, vcc, 0, v143, vcc
	global_load_dword v55, v[56:57], off offset:576
	s_mov_b64 s[8:9], -1
	s_waitcnt vmcnt(0)
	v_pk_add_f32 v[52:53], v[52:53], v[54:55]
	s_nop 0
	v_add_f32_e32 v0, v52, v53
	v_fmamk_f32 v0, v0, 0x3b800000, v220
	v_cmp_gt_f32_e32 vcc, s51, v0
	v_mul_f32_e32 v50, 0x4b800000, v0
	v_add_u32_e32 v52, s78, v51
	v_cndmask_b32_e32 v0, v0, v50, vcc
	v_rsq_f32_e32 v0, v0
	v_lshl_or_b32 v54, v52, 6, v158
	v_mul_f32_e32 v50, 0x45800000, v0
	v_cndmask_b32_e32 v0, v0, v50, vcc
	v_mul_f32_e32 v50, 0x3dd53b94, v0
	v_lshlrev_b32_e32 v0, 9, v51
	v_pk_mul_f32 v[48:49], v[48:49], v[50:51] op_sel_hi:[1,0]
	v_pk_mul_f32 v[46:47], v[46:47], v[50:51] op_sel_hi:[1,0]
	v_pk_mul_f32 v[44:45], v[44:45], v[50:51] op_sel_hi:[1,0]
	v_pk_mul_f32 v[42:43], v[42:43], v[50:51] op_sel_hi:[1,0]
	s_and_b64 vcc, exec, s[40:41]
	v_lshl_add_u64 v[52:53], v[0:1], 1, s[42:43]
	s_cbranch_vccnz .LBB0_648
	v_mov_b32_e32 v55, v1
	v_lshl_add_u64 v[60:61], v[54:55], 2, s[64:65]
	global_load_dwordx4 v[56:59], v[60:61], off offset:16
	s_nop 0
	global_load_dwordx4 v[60:63], v[60:61], off
	v_lshl_add_u64 v[68:69], v[140:141], 1, v[52:53]
	s_mov_b64 s[8:9], 0
	s_waitcnt vmcnt(0)
	v_mov_b32_e32 v65, v62
	v_mov_b32_e32 v62, v61
	v_mov_b32_e32 v64, v60
	v_pk_mul_f32 v[60:61], v[42:43], v[62:63]
	s_nop 0
	v_pk_fma_f32 v[60:61], v[46:47], v[64:65], v[60:61] neg_lo:[0,0,1] neg_hi:[0,0,1]
	v_pk_mul_f32 v[64:65], v[42:43], v[64:65]
	s_nop 0
	v_pk_fma_f32 v[62:63], v[46:47], v[62:63], v[64:65]
	v_mov_b32_e32 v65, v58
	v_mov_b32_e32 v58, v57
	v_mov_b32_e32 v64, v56
	v_pk_mul_f32 v[56:57], v[44:45], v[58:59]
	s_nop 0
	v_pk_fma_f32 v[66:67], v[48:49], v[64:65], v[56:57] neg_lo:[0,0,1] neg_hi:[0,0,1]
	v_pk_mul_f32 v[56:57], v[44:45], v[64:65]
	s_nop 0
	v_pk_fma_f32 v[64:65], v[48:49], v[58:59], v[56:57]
	v_cvt_pk_bf16_f32 v56, v60, v61
	v_cvt_pk_bf16_f32 v57, v66, v67
	v_cvt_pk_bf16_f32 v58, v62, v63
	v_cvt_pk_bf16_f32 v59, v64, v65
	global_store_dwordx4 v[68:69], v[56:59], off sc1
.LBB0_648:
	v_lshlrev_b32_e32 v0, 10, v51
	s_andn2_b64 vcc, exec, s[8:9]
	v_lshl_add_u64 v[56:57], v[0:1], 1, s[6:7]
	s_cbranch_vccnz .LBB0_650
	v_lshl_add_u64 v[58:59], s[90:91], 1, v[56:57]
	v_lshl_add_u64 v[58:59], v[138:139], 1, v[58:59]
	v_cvt_pk_bf16_f32 v46, v46, v47
	v_cvt_pk_bf16_f32 v47, v48, v49
	v_cvt_pk_bf16_f32 v48, v42, v43
	v_cvt_pk_bf16_f32 v49, v44, v45
	global_store_dwordx4 v[58:59], v[46:49], off sc1
.LBB0_650:
	v_mov_b32_e32 v51, v50
	v_mov_b32_e32 v42, v50
	v_mov_b32_e32 v43, v50
	v_pk_mul_f32 v[40:41], v[40:41], v[42:43]
	v_pk_mul_f32 v[38:39], v[38:39], v[50:51]
	v_pk_mul_f32 v[36:37], v[36:37], v[42:43]
	v_pk_mul_f32 v[34:35], v[34:35], v[50:51]
	s_and_b64 vcc, exec, s[40:41]
	s_mov_b64 s[8:9], -1
	s_cbranch_vccnz .LBB0_652
	v_mov_b32_e32 v55, v1
	v_lshl_add_u64 v[46:47], v[54:55], 2, s[64:65]
	global_load_dwordx4 v[42:45], v[46:47], off offset:16
	s_nop 0
	global_load_dwordx4 v[46:49], v[46:47], off
	v_lshl_add_u64 v[52:53], v[140:141], 1, v[52:53]
	s_mov_b64 s[8:9], 0
	s_waitcnt vmcnt(0)
	v_mov_b32_e32 v51, v48
	v_mov_b32_e32 v48, v47
	v_mov_b32_e32 v50, v46
	v_pk_mul_f32 v[46:47], v[34:35], v[48:49]
	s_nop 0
	v_pk_fma_f32 v[46:47], v[38:39], v[50:51], v[46:47] neg_lo:[0,0,1] neg_hi:[0,0,1]
	v_pk_mul_f32 v[50:51], v[34:35], v[50:51]
	s_nop 0
	v_pk_fma_f32 v[48:49], v[38:39], v[48:49], v[50:51]
	v_mov_b32_e32 v51, v44
	v_mov_b32_e32 v44, v43
	v_mov_b32_e32 v50, v42
	v_pk_mul_f32 v[42:43], v[36:37], v[44:45]
	s_nop 0
	v_pk_fma_f32 v[54:55], v[40:41], v[50:51], v[42:43] neg_lo:[0,0,1] neg_hi:[0,0,1]
	v_pk_mul_f32 v[42:43], v[36:37], v[50:51]
	s_nop 0
	v_pk_fma_f32 v[50:51], v[40:41], v[44:45], v[42:43]
	v_cvt_pk_bf16_f32 v42, v46, v47
	v_cvt_pk_bf16_f32 v43, v54, v55
	v_cvt_pk_bf16_f32 v44, v48, v49
	v_cvt_pk_bf16_f32 v45, v50, v51
	global_store_dwordx4 v[52:53], v[42:45], off offset:256 sc1
.LBB0_652:
	s_andn2_b64 vcc, exec, s[8:9]
	s_cbranch_vccnz .LBB0_654
	v_lshl_add_u64 v[42:43], s[90:91], 1, v[56:57]
	v_lshl_add_u64 v[42:43], v[138:139], 1, v[42:43]
	v_cvt_pk_bf16_f32 v38, v38, v39
	v_cvt_pk_bf16_f32 v39, v40, v41
	v_cvt_pk_bf16_f32 v40, v34, v35
	v_cvt_pk_bf16_f32 v41, v36, v37
	global_store_dwordx4 v[42:43], v[38:41], off offset:256 sc1
; __device__ __forceinline__ void st8(bf16_t* p, f32x4 a, f32x4 b) { u32x4 w; w.x = pk2(a[0], a[1]); w.y = pk2(a[2], a[3]); w.z = pk2(b[0], b[1]); w.w = pk2(b[2], b[3]); *(u32x4*)p = w; }
;     __device__ __forceinline__ void operator()(ACC_T, const pg8::Unit& u, int wr, int wc, int fr, int fq) const {
;     ...
;             for (int m = 0; m < 4; ++m) { const int row = row0 + ai * 128 + m * 16; const float* sp = ssq + tbase + row; const float rs = rsqrtf(((sp[0] + sp[TT]) + (sp[2 * TT] + sp[3 * TT])) * (1.f / 256.f) + EPS) * c2;
; #pragma unroll
;                 for (int bj = 0; bj < 2; ++bj) { const f32x4 v0 = acc[ai][bj][m][0] * rs, v1 = acc[ai][bj][m][1] * rs;
;                     if (pn < 4) st8(QN + (unsigned)row * 1024u + pn * 256 + cw + bj * 128, v0, v1);
;                     else { const int colr = (pn - 4) * 256 + cw + bj * 128, g8 = (colr & 63) >> 3;
;                         const f32x4* rp = (const f32x4*)(rope + (unsigned)((tbase + row) * 64 + 8 * g8)); const f32x4 c01 = rp[0], c23 = rp[1];
;                         f32x4 o1, o2;
;                         o1[0] = v0[0] * c01[0] - v1[0] * c01[1]; o2[0] = v0[0] * c01[1] + v1[0] * c01[0];
;                         o1[1] = v0[1] * c01[2] - v1[1] * c01[3]; o2[1] = v0[1] * c01[3] + v1[1] * c01[2];
;                         o1[2] = v0[2] * c23[0] - v1[2] * c23[1]; o2[2] = v0[2] * c23[1] + v1[2] * c23[0];
;                         o1[3] = v0[3] * c23[2] - v1[3] * c23[3]; o2[3] = v0[3] * c23[3] + v1[3] * c23[2];
;                         st8(QR + (unsigned)row * 512u + colr, o1, o2); } }
.LBB0_654:
	s_nop 1
	v_add_co_u32_e32 v38, vcc, 0x40000, v142
	global_load_dword v36, v[142:143], off offset:640
	s_nop 0
	v_addc_co_u32_e32 v39, vcc, 0, v143, vcc
	v_add_co_u32_e32 v40, vcc, 0x80000, v142
	global_load_dword v38, v[38:39], off offset:640
	s_nop 0
	v_addc_co_u32_e32 v41, vcc, 0, v143, vcc
	global_load_dword v37, v[40:41], off offset:640
	v_add_co_u32_e32 v40, vcc, 0xc0000, v142
	v_add_u32_e32 v35, 0xa0, v144
	s_nop 0
	v_addc_co_u32_e32 v41, vcc, 0, v143, vcc
	global_load_dword v39, v[40:41], off offset:640
	s_mov_b64 s[8:9], -1
	s_waitcnt vmcnt(0)
	v_pk_add_f32 v[36:37], v[36:37], v[38:39]
	s_nop 0
	v_add_f32_e32 v0, v36, v37
	v_fmamk_f32 v0, v0, 0x3b800000, v220
	v_cmp_gt_f32_e32 vcc, s51, v0
	v_mul_f32_e32 v34, 0x4b800000, v0
	v_add_u32_e32 v36, s78, v35
	v_cndmask_b32_e32 v0, v0, v34, vcc
	v_rsq_f32_e32 v0, v0
	v_lshl_or_b32 v38, v36, 6, v158
	v_mul_f32_e32 v34, 0x45800000, v0
	v_cndmask_b32_e32 v0, v0, v34, vcc
	v_mul_f32_e32 v34, 0x3dd53b94, v0
	v_lshlrev_b32_e32 v0, 9, v35
	v_pk_mul_f32 v[32:33], v[32:33], v[34:35] op_sel_hi:[1,0]
	v_pk_mul_f32 v[30:31], v[30:31], v[34:35] op_sel_hi:[1,0]
	v_pk_mul_f32 v[28:29], v[28:29], v[34:35] op_sel_hi:[1,0]
	v_pk_mul_f32 v[26:27], v[26:27], v[34:35] op_sel_hi:[1,0]
	s_and_b64 vcc, exec, s[40:41]
	v_lshl_add_u64 v[36:37], v[0:1], 1, s[42:43]
	s_cbranch_vccnz .LBB0_656
	v_mov_b32_e32 v39, v1
	v_lshl_add_u64 v[44:45], v[38:39], 2, s[64:65]
	global_load_dwordx4 v[40:43], v[44:45], off offset:16
	s_nop 0
	global_load_dwordx4 v[44:47], v[44:45], off
	v_lshl_add_u64 v[52:53], v[140:141], 1, v[36:37]
	s_mov_b64 s[8:9], 0
	s_waitcnt vmcnt(0)
	v_mov_b32_e32 v49, v46
	v_mov_b32_e32 v46, v45
	v_mov_b32_e32 v48, v44
	v_pk_mul_f32 v[44:45], v[26:27], v[46:47]
	s_nop 0
	v_pk_fma_f32 v[44:45], v[30:31], v[48:49], v[44:45] neg_lo:[0,0,1] neg_hi:[0,0,1]
	v_pk_mul_f32 v[48:49], v[26:27], v[48:49]
	s_nop 0
	v_pk_fma_f32 v[46:47], v[30:31], v[46:47], v[48:49]
	v_mov_b32_e32 v49, v42
	v_mov_b32_e32 v42, v41
	v_mov_b32_e32 v48, v40
	v_pk_mul_f32 v[40:41], v[28:29], v[42:43]
	s_nop 0
	v_pk_fma_f32 v[50:51], v[32:33], v[48:49], v[40:41] neg_lo:[0,0,1] neg_hi:[0,0,1]
	v_pk_mul_f32 v[40:41], v[28:29], v[48:49]
	s_nop 0
	v_pk_fma_f32 v[48:49], v[32:33], v[42:43], v[40:41]
	v_cvt_pk_bf16_f32 v40, v44, v45
	v_cvt_pk_bf16_f32 v41, v50, v51
	v_cvt_pk_bf16_f32 v42, v46, v47
	v_cvt_pk_bf16_f32 v43, v48, v49
	global_store_dwordx4 v[52:53], v[40:43], off sc1
.LBB0_656:
	v_lshlrev_b32_e32 v0, 10, v35
	s_andn2_b64 vcc, exec, s[8:9]
	v_lshl_add_u64 v[40:41], v[0:1], 1, s[6:7]
	s_cbranch_vccnz .LBB0_658
	v_lshl_add_u64 v[42:43], s[90:91], 1, v[40:41]
	v_lshl_add_u64 v[42:43], v[138:139], 1, v[42:43]
	v_cvt_pk_bf16_f32 v30, v30, v31
	v_cvt_pk_bf16_f32 v31, v32, v33
	v_cvt_pk_bf16_f32 v32, v26, v27
	v_cvt_pk_bf16_f32 v33, v28, v29
	global_store_dwordx4 v[42:43], v[30:33], off sc1
.LBB0_658:
	v_mov_b32_e32 v35, v34
	v_mov_b32_e32 v26, v34
	v_mov_b32_e32 v27, v34
	v_pk_mul_f32 v[24:25], v[24:25], v[26:27]
	v_pk_mul_f32 v[22:23], v[22:23], v[34:35]
	v_pk_mul_f32 v[20:21], v[20:21], v[26:27]
	v_pk_mul_f32 v[18:19], v[18:19], v[34:35]
	s_and_b64 vcc, exec, s[40:41]
	s_mov_b64 s[8:9], -1
	s_cbranch_vccnz .LBB0_660
	v_mov_b32_e32 v39, v1
	v_lshl_add_u64 v[30:31], v[38:39], 2, s[64:65]
	global_load_dwordx4 v[26:29], v[30:31], off offset:16
	s_nop 0
	global_load_dwordx4 v[30:33], v[30:31], off
	v_lshl_add_u64 v[36:37], v[140:141], 1, v[36:37]
	s_mov_b64 s[8:9], 0
	s_waitcnt vmcnt(0)
	v_mov_b32_e32 v35, v32
	v_mov_b32_e32 v32, v31
	v_mov_b32_e32 v34, v30
	v_pk_mul_f32 v[30:31], v[18:19], v[32:33]
	s_nop 0
	v_pk_fma_f32 v[30:31], v[22:23], v[34:35], v[30:31] neg_lo:[0,0,1] neg_hi:[0,0,1]
	v_pk_mul_f32 v[34:35], v[18:19], v[34:35]
	s_nop 0
	v_pk_fma_f32 v[32:33], v[22:23], v[32:33], v[34:35]
	v_mov_b32_e32 v35, v28
	v_mov_b32_e32 v28, v27
	v_mov_b32_e32 v34, v26
	v_pk_mul_f32 v[26:27], v[20:21], v[28:29]
	s_nop 0
	v_pk_fma_f32 v[38:39], v[24:25], v[34:35], v[26:27] neg_lo:[0,0,1] neg_hi:[0,0,1]
	v_pk_mul_f32 v[26:27], v[20:21], v[34:35]
	s_nop 0
	v_pk_fma_f32 v[34:35], v[24:25], v[28:29], v[26:27]
	v_cvt_pk_bf16_f32 v26, v30, v31
	v_cvt_pk_bf16_f32 v27, v38, v39
	v_cvt_pk_bf16_f32 v28, v32, v33
	v_cvt_pk_bf16_f32 v29, v34, v35
	global_store_dwordx4 v[36:37], v[26:29], off offset:256 sc1
.LBB0_660:
	s_andn2_b64 vcc, exec, s[8:9]
	s_cbranch_vccnz .LBB0_662
	v_lshl_add_u64 v[26:27], s[90:91], 1, v[40:41]
	v_lshl_add_u64 v[26:27], v[138:139], 1, v[26:27]
	v_cvt_pk_bf16_f32 v22, v22, v23
	v_cvt_pk_bf16_f32 v23, v24, v25
	v_cvt_pk_bf16_f32 v24, v18, v19
	v_cvt_pk_bf16_f32 v25, v20, v21
	global_store_dwordx4 v[26:27], v[22:25], off offset:256 sc1
; __device__ __forceinline__ void st8(bf16_t* p, f32x4 a, f32x4 b) { u32x4 w; w.x = pk2(a[0], a[1]); w.y = pk2(a[2], a[3]); w.z = pk2(b[0], b[1]); w.w = pk2(b[2], b[3]); *(u32x4*)p = w; }
;     __device__ __forceinline__ void operator()(ACC_T, const pg8::Unit& u, int wr, int wc, int fr, int fq) const {
;     ...
;             for (int m = 0; m < 4; ++m) { const int row = row0 + ai * 128 + m * 16; const float* sp = ssq + tbase + row; const float rs = rsqrtf(((sp[0] + sp[TT]) + (sp[2 * TT] + sp[3 * TT])) * (1.f / 256.f) + EPS) * c2;
; #pragma unroll
;                 for (int bj = 0; bj < 2; ++bj) { const f32x4 v0 = acc[ai][bj][m][0] * rs, v1 = acc[ai][bj][m][1] * rs;
;                     if (pn < 4) st8(QN + (unsigned)row * 1024u + pn * 256 + cw + bj * 128, v0, v1);
;                     else { const int colr = (pn - 4) * 256 + cw + bj * 128, g8 = (colr & 63) >> 3;
;                         const f32x4* rp = (const f32x4*)(rope + (unsigned)((tbase + row) * 64 + 8 * g8)); const f32x4 c01 = rp[0], c23 = rp[1];
;                         f32x4 o1, o2;
;                         o1[0] = v0[0] * c01[0] - v1[0] * c01[1]; o2[0] = v0[0] * c01[1] + v1[0] * c01[0];
;                         o1[1] = v0[1] * c01[2] - v1[1] * c01[3]; o2[1] = v0[1] * c01[3] + v1[1] * c01[2];
;                         o1[2] = v0[2] * c23[0] - v1[2] * c23[1]; o2[2] = v0[2] * c23[1] + v1[2] * c23[0];
;                         o1[3] = v0[3] * c23[2] - v1[3] * c23[3]; o2[3] = v0[3] * c23[3] + v1[3] * c23[2];
;                         st8(QR + (unsigned)row * 512u + colr, o1, o2); } }
.LBB0_662:
	s_nop 1
	v_add_co_u32_e32 v22, vcc, 0x40000, v142
	global_load_dword v20, v[142:143], off offset:704
	s_nop 0
	v_addc_co_u32_e32 v23, vcc, 0, v143, vcc
	v_add_co_u32_e32 v24, vcc, 0x80000, v142
	global_load_dword v22, v[22:23], off offset:704
	s_nop 0
	v_addc_co_u32_e32 v25, vcc, 0, v143, vcc
	global_load_dword v21, v[24:25], off offset:704
	v_add_co_u32_e32 v24, vcc, 0xc0000, v142
	v_add_u32_e32 v19, 0xb0, v144
	s_nop 0
	v_addc_co_u32_e32 v25, vcc, 0, v143, vcc
	global_load_dword v23, v[24:25], off offset:704
	s_mov_b64 s[8:9], -1
	s_waitcnt vmcnt(0)
	v_pk_add_f32 v[20:21], v[20:21], v[22:23]
	s_nop 0
	v_add_f32_e32 v0, v20, v21
	v_fmamk_f32 v0, v0, 0x3b800000, v220
	v_cmp_gt_f32_e32 vcc, s51, v0
	v_mul_f32_e32 v18, 0x4b800000, v0
	v_add_u32_e32 v20, s78, v19
	v_cndmask_b32_e32 v0, v0, v18, vcc
	v_rsq_f32_e32 v0, v0
	v_lshl_or_b32 v22, v20, 6, v158
	v_mul_f32_e32 v18, 0x45800000, v0
	v_cndmask_b32_e32 v0, v0, v18, vcc
	v_mul_f32_e32 v18, 0x3dd53b94, v0
	v_lshlrev_b32_e32 v0, 9, v19
	v_pk_mul_f32 v[16:17], v[16:17], v[18:19] op_sel_hi:[1,0]
	v_pk_mul_f32 v[14:15], v[14:15], v[18:19] op_sel_hi:[1,0]
	v_pk_mul_f32 v[12:13], v[12:13], v[18:19] op_sel_hi:[1,0]
	v_pk_mul_f32 v[10:11], v[10:11], v[18:19] op_sel_hi:[1,0]
	s_and_b64 vcc, exec, s[40:41]
	v_lshl_add_u64 v[20:21], v[0:1], 1, s[42:43]
	s_cbranch_vccnz .LBB0_664
	v_mov_b32_e32 v23, v1
	v_lshl_add_u64 v[28:29], v[22:23], 2, s[64:65]
	global_load_dwordx4 v[24:27], v[28:29], off offset:16
	s_nop 0
	global_load_dwordx4 v[28:31], v[28:29], off
	v_lshl_add_u64 v[36:37], v[140:141], 1, v[20:21]
	s_mov_b64 s[8:9], 0
	s_waitcnt vmcnt(0)
	v_mov_b32_e32 v33, v30
	v_mov_b32_e32 v30, v29
	v_mov_b32_e32 v32, v28
	v_pk_mul_f32 v[28:29], v[10:11], v[30:31]
	s_nop 0
	v_pk_fma_f32 v[28:29], v[14:15], v[32:33], v[28:29] neg_lo:[0,0,1] neg_hi:[0,0,1]
	v_pk_mul_f32 v[32:33], v[10:11], v[32:33]
	s_nop 0
	v_pk_fma_f32 v[30:31], v[14:15], v[30:31], v[32:33]
	v_mov_b32_e32 v33, v26
	v_mov_b32_e32 v26, v25
	v_mov_b32_e32 v32, v24
	v_pk_mul_f32 v[24:25], v[12:13], v[26:27]
	s_nop 0
	v_pk_fma_f32 v[34:35], v[16:17], v[32:33], v[24:25] neg_lo:[0,0,1] neg_hi:[0,0,1]
	v_pk_mul_f32 v[24:25], v[12:13], v[32:33]
	s_nop 0
	v_pk_fma_f32 v[32:33], v[16:17], v[26:27], v[24:25]
	v_cvt_pk_bf16_f32 v24, v28, v29
	v_cvt_pk_bf16_f32 v25, v34, v35
	v_cvt_pk_bf16_f32 v26, v30, v31
	v_cvt_pk_bf16_f32 v27, v32, v33
	global_store_dwordx4 v[36:37], v[24:27], off sc1
.LBB0_664:
	v_lshlrev_b32_e32 v0, 10, v19
	s_andn2_b64 vcc, exec, s[8:9]
	v_lshl_add_u64 v[24:25], v[0:1], 1, s[6:7]
	s_cbranch_vccnz .LBB0_666
	v_lshl_add_u64 v[26:27], s[90:91], 1, v[24:25]
	v_lshl_add_u64 v[26:27], v[138:139], 1, v[26:27]
	v_cvt_pk_bf16_f32 v14, v14, v15
	v_cvt_pk_bf16_f32 v15, v16, v17
	v_cvt_pk_bf16_f32 v16, v10, v11
	v_cvt_pk_bf16_f32 v17, v12, v13
	global_store_dwordx4 v[26:27], v[14:17], off sc1
.LBB0_666:
	v_mov_b32_e32 v19, v18
	v_mov_b32_e32 v10, v18
	v_mov_b32_e32 v11, v18
	v_pk_mul_f32 v[8:9], v[8:9], v[10:11]
	v_pk_mul_f32 v[6:7], v[6:7], v[18:19]
	v_pk_mul_f32 v[4:5], v[4:5], v[10:11]
	v_pk_mul_f32 v[2:3], v[2:3], v[18:19]
	s_and_b64 vcc, exec, s[40:41]
	s_mov_b64 s[8:9], -1
	s_cbranch_vccnz .LBB0_668
	v_mov_b32_e32 v23, v1
	v_lshl_add_u64 v[14:15], v[22:23], 2, s[64:65]
	global_load_dwordx4 v[10:13], v[14:15], off offset:16
	s_nop 0
	global_load_dwordx4 v[14:17], v[14:15], off
	v_lshl_add_u64 v[20:21], v[140:141], 1, v[20:21]
	s_mov_b64 s[8:9], 0
	s_waitcnt vmcnt(0)
	v_mov_b32_e32 v19, v16
	v_mov_b32_e32 v16, v15
	v_mov_b32_e32 v18, v14
	v_pk_mul_f32 v[14:15], v[2:3], v[16:17]
	s_nop 0
	v_pk_fma_f32 v[14:15], v[6:7], v[18:19], v[14:15] neg_lo:[0,0,1] neg_hi:[0,0,1]
	v_pk_mul_f32 v[18:19], v[2:3], v[18:19]
	s_nop 0
	v_pk_fma_f32 v[16:17], v[6:7], v[16:17], v[18:19]
	v_mov_b32_e32 v19, v12
	v_mov_b32_e32 v12, v11
	v_mov_b32_e32 v18, v10
	v_pk_mul_f32 v[10:11], v[4:5], v[12:13]
	s_nop 0
	v_pk_fma_f32 v[22:23], v[8:9], v[18:19], v[10:11] neg_lo:[0,0,1] neg_hi:[0,0,1]
	v_pk_mul_f32 v[10:11], v[4:5], v[18:19]
	s_nop 0
	v_pk_fma_f32 v[18:19], v[8:9], v[12:13], v[10:11]
	v_cvt_pk_bf16_f32 v10, v14, v15
	v_cvt_pk_bf16_f32 v11, v22, v23
	v_cvt_pk_bf16_f32 v12, v16, v17
	v_cvt_pk_bf16_f32 v13, v18, v19
	global_store_dwordx4 v[20:21], v[10:13], off offset:256 sc1
.LBB0_668:
	s_andn2_b64 vcc, exec, s[8:9]
	s_cbranch_vccnz .LBB0_670
	v_lshl_add_u64 v[10:11], s[90:91], 1, v[24:25]
	v_lshl_add_u64 v[10:11], v[138:139], 1, v[10:11]
	v_cvt_pk_bf16_f32 v6, v6, v7
	v_cvt_pk_bf16_f32 v7, v8, v9
	v_cvt_pk_bf16_f32 v8, v2, v3
	v_cvt_pk_bf16_f32 v9, v4, v5
	global_store_dwordx4 v[10:11], v[6:9], off offset:256 sc1

; __device__ __forceinline__ void st8(bf16_t* p, f32x4 a, f32x4 b) { u32x4 w; w.x = pk2(a[0], a[1]); w.y = pk2(a[2], a[3]); w.z = pk2(b[0], b[1]); w.w = pk2(b[2], b[3]); *(u32x4*)p = w; }
;     __device__ __forceinline__ void operator()(ACC_T, const pg8::Unit& u, int wr, int wc, int fr, int fq) const {
;     ...
;             for (int m = 0; m < 4; ++m) { const int row = row0 + ai * 128 + m * 16; const float* sp = ssq + tbase + row; const float rs = rsqrtf(((sp[0] + sp[TT]) + (sp[2 * TT] + sp[3 * TT])) * (1.f / 256.f) + EPS);
; #pragma unroll
;                 for (int bj = 0; bj < 2; ++bj) st8(O + (unsigned)row * (unsigned)ldc + col0 + bj * 128, acc[ai][bj][m][0] * rs, acc[ai][bj][m][1] * rs);
;                 asm volatile("" ::: "memory"); }
.LBB0_694:
	s_lshl_b32 s2, s84, 8
	v_mov_b32_e32 v0, v148
	v_mov_b32_e32 v138, v149
	s_add_i32 s2, s2, s66
	s_nop 0
	v_add_u32_e32 v146, s2, v0
	s_lshl_b32 s2, s85, 8
	s_or_b32 s2, s2, s67
	v_ashrrev_i32_e32 v147, 31, v146
	v_lshl_add_u32 v152, v138, 3, s2
	v_lshl_add_u64 v[138:139], v[146:147], 2, s[42:43]
	v_add_co_u32_e32 v140, vcc, s97, v138
	s_mov_b32 s2, 0xc0000
	s_nop 0
	v_addc_co_u32_e32 v141, vcc, 0, v139, vcc
	v_add_co_u32_e32 v142, vcc, s96, v138
	global_load_dword v154, v[138:139], off
	global_load_dword v156, v[140:141], off
	v_addc_co_u32_e32 v143, vcc, 0, v139, vcc
	v_add_co_u32_e32 v144, vcc, s2, v138
	global_load_dword v155, v[142:143], off
	s_nop 0
	v_addc_co_u32_e32 v145, vcc, 0, v139, vcc
	global_load_dword v157, v[144:145], off
	v_ashrrev_i32_e32 v153, 31, v152
	s_waitcnt vmcnt(0)
	v_pk_add_f32 v[154:155], v[154:155], v[156:157]
	s_nop 0
	v_add_f32_e32 v0, v154, v155
	v_fmamk_f32 v0, v0, 0x3b800000, v220
	v_cmp_gt_f32_e32 vcc, s51, v0
	v_mul_f32_e32 v147, 0x4b800000, v0
	s_nop 0
	v_cndmask_b32_e32 v0, v0, v147, vcc
	v_rsq_f32_e32 v0, v0
	s_nop 0
	v_mul_f32_e32 v147, 0x45800000, v0
	v_cndmask_b32_e32 v154, v0, v147, vcc
	v_lshlrev_b32_e32 v0, 10, v146
	v_lshl_add_u64 v[156:157], v[0:1], 1, s[6:7]
	v_lshlrev_b64 v[146:147], 1, v[152:153]
	v_lshl_add_u64 v[152:153], v[156:157], 0, v[146:147]
	v_pk_mul_f32 v[128:129], v[128:129], v[154:155] op_sel_hi:[1,0]
	v_pk_mul_f32 v[126:127], v[126:127], v[154:155] op_sel_hi:[1,0]
	v_pk_mul_f32 v[156:157], v[124:125], v[154:155] op_sel_hi:[1,0]
	v_pk_mul_f32 v[124:125], v[122:123], v[154:155] op_sel_hi:[1,0]
	v_cvt_pk_bf16_f32 v122, v126, v127
	v_cvt_pk_bf16_f32 v123, v128, v129
	v_cvt_pk_bf16_f32 v124, v124, v125
	v_cvt_pk_bf16_f32 v125, v156, v157
	global_store_dwordx4 v[152:153], v[122:125], off sc1
	v_pk_mul_f32 v[120:121], v[120:121], v[154:155] op_sel_hi:[1,0]
	v_pk_mul_f32 v[118:119], v[118:119], v[154:155] op_sel_hi:[1,0]
	v_pk_mul_f32 v[122:123], v[116:117], v[154:155] op_sel_hi:[1,0]
	v_pk_mul_f32 v[116:117], v[114:115], v[154:155] op_sel_hi:[1,0]
	v_cvt_pk_bf16_f32 v114, v118, v119
	v_cvt_pk_bf16_f32 v115, v120, v121
	v_cvt_pk_bf16_f32 v116, v116, v117
	v_cvt_pk_bf16_f32 v117, v122, v123
	global_store_dwordx4 v[152:153], v[114:117], off offset:256 sc1
	global_load_dword v114, v[138:139], off offset:64
	global_load_dword v116, v[140:141], off offset:64
	global_load_dword v115, v[142:143], off offset:64
	global_load_dword v117, v[144:145], off offset:64
	s_waitcnt vmcnt(0)
	v_pk_add_f32 v[114:115], v[114:115], v[116:117]
	s_nop 0
	v_add_f32_e32 v114, v114, v115
	v_fmamk_f32 v114, v114, 0x3b800000, v220
	v_cmp_gt_f32_e32 vcc, s51, v114
	v_mul_f32_e32 v115, 0x4b800000, v114
	v_add_u32_e32 v116, 0x4000, v0
	v_cndmask_b32_e32 v114, v114, v115, vcc
	v_rsq_f32_e32 v114, v114
	v_mov_b32_e32 v117, v1
	v_lshl_add_u64 v[116:117], v[116:117], 1, s[6:7]
	v_lshl_add_u64 v[116:117], v[116:117], 0, v[146:147]
	v_mul_f32_e32 v115, 0x45800000, v114
	v_cndmask_b32_e32 v114, v114, v115, vcc
	v_pk_mul_f32 v[112:113], v[112:113], v[114:115] op_sel_hi:[1,0]
	v_pk_mul_f32 v[110:111], v[110:111], v[114:115] op_sel_hi:[1,0]
	v_pk_mul_f32 v[118:119], v[108:109], v[114:115] op_sel_hi:[1,0]
	v_pk_mul_f32 v[108:109], v[106:107], v[114:115] op_sel_hi:[1,0]
	v_cvt_pk_bf16_f32 v106, v110, v111
	v_cvt_pk_bf16_f32 v107, v112, v113
	v_cvt_pk_bf16_f32 v108, v108, v109
	v_cvt_pk_bf16_f32 v109, v118, v119
	global_store_dwordx4 v[116:117], v[106:109], off sc1
	v_pk_mul_f32 v[104:105], v[104:105], v[114:115] op_sel_hi:[1,0]
	v_pk_mul_f32 v[102:103], v[102:103], v[114:115] op_sel_hi:[1,0]
	v_pk_mul_f32 v[106:107], v[100:101], v[114:115] op_sel_hi:[1,0]
	v_pk_mul_f32 v[100:101], v[98:99], v[114:115] op_sel_hi:[1,0]
	v_cvt_pk_bf16_f32 v98, v102, v103
	v_cvt_pk_bf16_f32 v99, v104, v105
	v_cvt_pk_bf16_f32 v100, v100, v101
	v_cvt_pk_bf16_f32 v101, v106, v107
	global_store_dwordx4 v[116:117], v[98:101], off offset:256 sc1
	global_load_dword v98, v[138:139], off offset:128
	global_load_dword v100, v[140:141], off offset:128
	global_load_dword v99, v[142:143], off offset:128
	global_load_dword v101, v[144:145], off offset:128
	s_waitcnt vmcnt(0)
	v_pk_add_f32 v[98:99], v[98:99], v[100:101]
	s_nop 0
	v_add_f32_e32 v98, v98, v99
	v_fmamk_f32 v98, v98, 0x3b800000, v220
	v_cmp_gt_f32_e32 vcc, s51, v98
	v_mul_f32_e32 v99, 0x4b800000, v98
	v_add_u32_e32 v100, 0x8000, v0
	v_cndmask_b32_e32 v98, v98, v99, vcc
	v_rsq_f32_e32 v98, v98
	v_mov_b32_e32 v101, v1
	v_lshl_add_u64 v[100:101], v[100:101], 1, s[6:7]
	v_lshl_add_u64 v[100:101], v[100:101], 0, v[146:147]
	v_mul_f32_e32 v99, 0x45800000, v98
	v_cndmask_b32_e32 v98, v98, v99, vcc
	v_pk_mul_f32 v[96:97], v[96:97], v[98:99] op_sel_hi:[1,0]
	v_pk_mul_f32 v[94:95], v[94:95], v[98:99] op_sel_hi:[1,0]
	v_pk_mul_f32 v[102:103], v[92:93], v[98:99] op_sel_hi:[1,0]
	v_pk_mul_f32 v[92:93], v[90:91], v[98:99] op_sel_hi:[1,0]
	v_cvt_pk_bf16_f32 v90, v94, v95
	v_cvt_pk_bf16_f32 v91, v96, v97
	v_cvt_pk_bf16_f32 v92, v92, v93
	v_cvt_pk_bf16_f32 v93, v102, v103
	global_store_dwordx4 v[100:101], v[90:93], off sc1
	v_pk_mul_f32 v[88:89], v[88:89], v[98:99] op_sel_hi:[1,0]
	v_pk_mul_f32 v[86:87], v[86:87], v[98:99] op_sel_hi:[1,0]
	v_pk_mul_f32 v[90:91], v[84:85], v[98:99] op_sel_hi:[1,0]
	v_pk_mul_f32 v[84:85], v[82:83], v[98:99] op_sel_hi:[1,0]
	v_cvt_pk_bf16_f32 v82, v86, v87
	v_cvt_pk_bf16_f32 v83, v88, v89
	v_cvt_pk_bf16_f32 v84, v84, v85
	v_cvt_pk_bf16_f32 v85, v90, v91
	global_store_dwordx4 v[100:101], v[82:85], off offset:256 sc1
	global_load_dword v82, v[138:139], off offset:192
	global_load_dword v84, v[140:141], off offset:192
	global_load_dword v83, v[142:143], off offset:192
	global_load_dword v85, v[144:145], off offset:192
	s_waitcnt vmcnt(0)
; __device__ __forceinline__ void st8(bf16_t* p, f32x4 a, f32x4 b) { u32x4 w; w.x = pk2(a[0], a[1]); w.y = pk2(a[2], a[3]); w.z = pk2(b[0], b[1]); w.w = pk2(b[2], b[3]); *(u32x4*)p = w; }
;     __device__ __forceinline__ void operator()(ACC_T, const pg8::Unit& u, int wr, int wc, int fr, int fq) const {
;     ...
;             for (int m = 0; m < 4; ++m) { const int row = row0 + ai * 128 + m * 16; const float* sp = ssq + tbase + row; const float rs = rsqrtf(((sp[0] + sp[TT]) + (sp[2 * TT] + sp[3 * TT])) * (1.f / 256.f) + EPS);
; #pragma unroll
;                 for (int bj = 0; bj < 2; ++bj) st8(O + (unsigned)row * (unsigned)ldc + col0 + bj * 128, acc[ai][bj][m][0] * rs, acc[ai][bj][m][1] * rs);
;                 asm volatile("" ::: "memory"); }
	v_pk_add_f32 v[82:83], v[82:83], v[84:85]
	s_nop 0
	v_add_f32_e32 v82, v82, v83
	v_fmamk_f32 v82, v82, 0x3b800000, v220
	v_cmp_gt_f32_e32 vcc, s51, v82
	v_mul_f32_e32 v83, 0x4b800000, v82
	v_add_u32_e32 v84, 0xc000, v0
	v_cndmask_b32_e32 v82, v82, v83, vcc
	v_rsq_f32_e32 v82, v82
	v_mov_b32_e32 v85, v1
	v_lshl_add_u64 v[84:85], v[84:85], 1, s[6:7]
	v_lshl_add_u64 v[84:85], v[84:85], 0, v[146:147]
	v_mul_f32_e32 v83, 0x45800000, v82
	v_cndmask_b32_e32 v82, v82, v83, vcc
	v_pk_mul_f32 v[80:81], v[80:81], v[82:83] op_sel_hi:[1,0]
	v_pk_mul_f32 v[78:79], v[78:79], v[82:83] op_sel_hi:[1,0]
	v_pk_mul_f32 v[86:87], v[76:77], v[82:83] op_sel_hi:[1,0]
	v_pk_mul_f32 v[76:77], v[74:75], v[82:83] op_sel_hi:[1,0]
	v_cvt_pk_bf16_f32 v74, v78, v79
	v_cvt_pk_bf16_f32 v75, v80, v81
	v_cvt_pk_bf16_f32 v76, v76, v77
	v_cvt_pk_bf16_f32 v77, v86, v87
	global_store_dwordx4 v[84:85], v[74:77], off sc1
	v_pk_mul_f32 v[72:73], v[72:73], v[82:83] op_sel_hi:[1,0]
	v_pk_mul_f32 v[70:71], v[70:71], v[82:83] op_sel_hi:[1,0]
	v_pk_mul_f32 v[74:75], v[68:69], v[82:83] op_sel_hi:[1,0]
	v_pk_mul_f32 v[68:69], v[66:67], v[82:83] op_sel_hi:[1,0]
	v_cvt_pk_bf16_f32 v66, v70, v71
	v_cvt_pk_bf16_f32 v67, v72, v73
	v_cvt_pk_bf16_f32 v68, v68, v69
	v_cvt_pk_bf16_f32 v69, v74, v75
	global_store_dwordx4 v[84:85], v[66:69], off offset:256 sc1
	global_load_dword v66, v[138:139], off offset:512
	global_load_dword v68, v[140:141], off offset:512
	global_load_dword v67, v[142:143], off offset:512
	global_load_dword v69, v[144:145], off offset:512
	s_waitcnt vmcnt(0)
	v_pk_add_f32 v[66:67], v[66:67], v[68:69]
	s_nop 0
	v_add_f32_e32 v66, v66, v67
	v_fmamk_f32 v66, v66, 0x3b800000, v220
	v_cmp_gt_f32_e32 vcc, s51, v66
	v_mul_f32_e32 v67, 0x4b800000, v66
	v_add_u32_e32 v68, 0x20000, v0
	v_cndmask_b32_e32 v66, v66, v67, vcc
	v_rsq_f32_e32 v66, v66
	v_mov_b32_e32 v69, v1
	v_lshl_add_u64 v[68:69], v[68:69], 1, s[6:7]
	v_lshl_add_u64 v[68:69], v[68:69], 0, v[146:147]
	v_mul_f32_e32 v67, 0x45800000, v66
	v_cndmask_b32_e32 v66, v66, v67, vcc
	v_pk_mul_f32 v[64:65], v[64:65], v[66:67] op_sel_hi:[1,0]
	v_pk_mul_f32 v[62:63], v[62:63], v[66:67] op_sel_hi:[1,0]
	v_pk_mul_f32 v[70:71], v[60:61], v[66:67] op_sel_hi:[1,0]
	v_pk_mul_f32 v[60:61], v[58:59], v[66:67] op_sel_hi:[1,0]
	v_cvt_pk_bf16_f32 v58, v62, v63
	v_cvt_pk_bf16_f32 v59, v64, v65
	v_cvt_pk_bf16_f32 v60, v60, v61
	v_cvt_pk_bf16_f32 v61, v70, v71
	global_store_dwordx4 v[68:69], v[58:61], off sc1
	v_pk_mul_f32 v[56:57], v[56:57], v[66:67] op_sel_hi:[1,0]
	v_pk_mul_f32 v[54:55], v[54:55], v[66:67] op_sel_hi:[1,0]
	v_pk_mul_f32 v[58:59], v[52:53], v[66:67] op_sel_hi:[1,0]
	v_pk_mul_f32 v[52:53], v[50:51], v[66:67] op_sel_hi:[1,0]
	v_cvt_pk_bf16_f32 v50, v54, v55
	v_cvt_pk_bf16_f32 v51, v56, v57
	v_cvt_pk_bf16_f32 v52, v52, v53
	v_cvt_pk_bf16_f32 v53, v58, v59
	global_store_dwordx4 v[68:69], v[50:53], off offset:256 sc1
	global_load_dword v50, v[138:139], off offset:576
	global_load_dword v52, v[140:141], off offset:576
	global_load_dword v51, v[142:143], off offset:576
	global_load_dword v53, v[144:145], off offset:576
	s_waitcnt vmcnt(0)
; #define PG8_BAR __builtin_amdgcn_s_barrier()
; __device__ __forceinline__ void st8(bf16_t* p, f32x4 a, f32x4 b) { u32x4 w; w.x = pk2(a[0], a[1]); w.y = pk2(a[2], a[3]); w.z = pk2(b[0], b[1]); w.w = pk2(b[2], b[3]); *(u32x4*)p = w; }
; template <class Epi, class Sched, bool ALIGN_EPI = false, bool SP2 = false>
; __device__ __forceinline__ void gemm_phase(PG8_LAS unsigned char* lds, const Gemm g, const Sched& S, const Epi& E) {
;     ...
;         if (!has_next) break;
; #pragma unroll
;         for (int a = 0; a < 2; ++a)
; #pragma unroll
;             for (int b = 0; b < 2; ++b)
; #pragma unroll
;                 for (int m = 0; m < 4; ++m)
; #pragma unroll
;                     for (int n = 0; n < 2; ++n) acc[a][b][m][n] = (f32x4){0.f, 0.f, 0.f, 0.f};
;         cur = nxt; cA = nA; cB = nB; ++ui;
;         if constexpr (ALIGN_EPI) { if (wr == 1) PG8_BAR; }
;     __device__ __forceinline__ void operator()(ACC_T, const pg8::Unit& u, int wr, int wc, int fr, int fq) const {
;     ...
;             for (int m = 0; m < 4; ++m) { const int row = row0 + ai * 128 + m * 16; const float* sp = ssq + tbase + row; const float rs = rsqrtf(((sp[0] + sp[TT]) + (sp[2 * TT] + sp[3 * TT])) * (1.f / 256.f) + EPS);
; #pragma unroll
;                 for (int bj = 0; bj < 2; ++bj) st8(O + (unsigned)row * (unsigned)ldc + col0 + bj * 128, acc[ai][bj][m][0] * rs, acc[ai][bj][m][1] * rs);
;                 asm volatile("" ::: "memory"); }
	v_pk_add_f32 v[50:51], v[50:51], v[52:53]
	s_nop 0
	v_add_f32_e32 v50, v50, v51
	v_fmamk_f32 v50, v50, 0x3b800000, v220
	v_cmp_gt_f32_e32 vcc, s51, v50
	v_mul_f32_e32 v51, 0x4b800000, v50
	v_add_u32_e32 v52, 0x24000, v0
	v_cndmask_b32_e32 v50, v50, v51, vcc
	v_rsq_f32_e32 v50, v50
	v_mov_b32_e32 v53, v1
	v_lshl_add_u64 v[52:53], v[52:53], 1, s[6:7]
	v_lshl_add_u64 v[52:53], v[52:53], 0, v[146:147]
	v_mul_f32_e32 v51, 0x45800000, v50
	v_cndmask_b32_e32 v50, v50, v51, vcc
	v_pk_mul_f32 v[48:49], v[48:49], v[50:51] op_sel_hi:[1,0]
	v_pk_mul_f32 v[46:47], v[46:47], v[50:51] op_sel_hi:[1,0]
	v_pk_mul_f32 v[54:55], v[44:45], v[50:51] op_sel_hi:[1,0]
	v_pk_mul_f32 v[44:45], v[42:43], v[50:51] op_sel_hi:[1,0]
	v_cvt_pk_bf16_f32 v42, v46, v47
	v_cvt_pk_bf16_f32 v43, v48, v49
	v_cvt_pk_bf16_f32 v44, v44, v45
	v_cvt_pk_bf16_f32 v45, v54, v55
	global_store_dwordx4 v[52:53], v[42:45], off sc1
	v_pk_mul_f32 v[40:41], v[40:41], v[50:51] op_sel_hi:[1,0]
	v_pk_mul_f32 v[38:39], v[38:39], v[50:51] op_sel_hi:[1,0]
	v_pk_mul_f32 v[42:43], v[36:37], v[50:51] op_sel_hi:[1,0]
	v_pk_mul_f32 v[36:37], v[34:35], v[50:51] op_sel_hi:[1,0]
	v_cvt_pk_bf16_f32 v34, v38, v39
	v_cvt_pk_bf16_f32 v35, v40, v41
	v_cvt_pk_bf16_f32 v36, v36, v37
	v_cvt_pk_bf16_f32 v37, v42, v43
	global_store_dwordx4 v[52:53], v[34:37], off offset:256 sc1
	global_load_dword v34, v[138:139], off offset:640
	global_load_dword v36, v[140:141], off offset:640
	global_load_dword v35, v[142:143], off offset:640
	global_load_dword v37, v[144:145], off offset:640
	s_waitcnt vmcnt(0)
	v_pk_add_f32 v[34:35], v[34:35], v[36:37]
	s_nop 0
	v_add_f32_e32 v34, v34, v35
	v_fmamk_f32 v34, v34, 0x3b800000, v220
	v_cmp_gt_f32_e32 vcc, s51, v34
	v_mul_f32_e32 v35, 0x4b800000, v34
	v_add_u32_e32 v36, 0x28000, v0
	v_cndmask_b32_e32 v34, v34, v35, vcc
	v_rsq_f32_e32 v34, v34
	v_mov_b32_e32 v37, v1
	v_lshl_add_u64 v[36:37], v[36:37], 1, s[6:7]
	v_lshl_add_u64 v[36:37], v[36:37], 0, v[146:147]
	v_mul_f32_e32 v35, 0x45800000, v34
	v_cndmask_b32_e32 v34, v34, v35, vcc
	v_pk_mul_f32 v[32:33], v[32:33], v[34:35] op_sel_hi:[1,0]
	v_pk_mul_f32 v[30:31], v[30:31], v[34:35] op_sel_hi:[1,0]
	v_pk_mul_f32 v[38:39], v[28:29], v[34:35] op_sel_hi:[1,0]
	v_pk_mul_f32 v[28:29], v[26:27], v[34:35] op_sel_hi:[1,0]
	v_cvt_pk_bf16_f32 v26, v30, v31
	v_cvt_pk_bf16_f32 v27, v32, v33
	v_cvt_pk_bf16_f32 v28, v28, v29
	v_cvt_pk_bf16_f32 v29, v38, v39
	global_store_dwordx4 v[36:37], v[26:29], off sc1
	v_pk_mul_f32 v[24:25], v[24:25], v[34:35] op_sel_hi:[1,0]
	v_pk_mul_f32 v[22:23], v[22:23], v[34:35] op_sel_hi:[1,0]
	v_pk_mul_f32 v[26:27], v[20:21], v[34:35] op_sel_hi:[1,0]
	v_pk_mul_f32 v[20:21], v[18:19], v[34:35] op_sel_hi:[1,0]
	v_cvt_pk_bf16_f32 v18, v22, v23
	v_cvt_pk_bf16_f32 v19, v24, v25
	v_cvt_pk_bf16_f32 v20, v20, v21
	v_cvt_pk_bf16_f32 v21, v26, v27
	global_store_dwordx4 v[36:37], v[18:21], off offset:256 sc1
	global_load_dword v18, v[138:139], off offset:704
	global_load_dword v20, v[140:141], off offset:704
	global_load_dword v19, v[142:143], off offset:704
	global_load_dword v21, v[144:145], off offset:704
	v_add_u32_e32 v0, 0x2c000, v0
	s_waitcnt vmcnt(0)
	v_pk_add_f32 v[18:19], v[18:19], v[20:21]
	s_nop 0
	v_add_f32_e32 v18, v18, v19
	v_fmamk_f32 v18, v18, 0x3b800000, v220
	v_cmp_gt_f32_e32 vcc, s51, v18
	v_mul_f32_e32 v19, 0x4b800000, v18
	v_lshl_add_u64 v[20:21], v[0:1], 1, s[6:7]
	v_cndmask_b32_e32 v18, v18, v19, vcc
	v_rsq_f32_e32 v18, v18
	v_lshl_add_u64 v[20:21], v[20:21], 0, v[146:147]
	v_mul_f32_e32 v19, 0x45800000, v18
	v_cndmask_b32_e32 v18, v18, v19, vcc
	v_pk_mul_f32 v[16:17], v[16:17], v[18:19] op_sel_hi:[1,0]
	v_pk_mul_f32 v[14:15], v[14:15], v[18:19] op_sel_hi:[1,0]
	v_pk_mul_f32 v[22:23], v[12:13], v[18:19] op_sel_hi:[1,0]
	v_pk_mul_f32 v[12:13], v[10:11], v[18:19] op_sel_hi:[1,0]
	v_cvt_pk_bf16_f32 v10, v14, v15
	v_cvt_pk_bf16_f32 v11, v16, v17
	v_cvt_pk_bf16_f32 v12, v12, v13
	v_cvt_pk_bf16_f32 v13, v22, v23
	global_store_dwordx4 v[20:21], v[10:13], off sc1
	v_pk_mul_f32 v[8:9], v[8:9], v[18:19] op_sel_hi:[1,0]
	v_pk_mul_f32 v[6:7], v[6:7], v[18:19] op_sel_hi:[1,0]
	v_pk_mul_f32 v[10:11], v[4:5], v[18:19] op_sel_hi:[1,0]
	v_pk_mul_f32 v[4:5], v[2:3], v[18:19] op_sel_hi:[1,0]
	v_cvt_pk_bf16_f32 v2, v6, v7
	v_cvt_pk_bf16_f32 v3, v8, v9
	v_cvt_pk_bf16_f32 v4, v4, v5
	v_cvt_pk_bf16_f32 v5, v10, v11
	global_store_dwordx4 v[20:21], v[2:5], off offset:256 sc1
	s_andn2_b64 vcc, exec, s[38:39]
	s_cbranch_vccnz .LBB0_683
	s_andn2_b64 vcc, exec, s[4:5]
	s_cbranch_vccnz .LBB0_682
	s_barrier
	s_branch .LBB0_682

; __device__ __forceinline__ void st8(bf16_t* p, f32x4 a, f32x4 b) { u32x4 w; w.x = pk2(a[0], a[1]); w.y = pk2(a[2], a[3]); w.z = pk2(b[0], b[1]); w.w = pk2(b[2], b[3]); *(u32x4*)p = w; }
;     __device__ __forceinline__ void operator()(ACC_T, const pg8::Unit& u, int wr, int wc, int fr, int fq) const {
;         const int row0 = u.pm * 256 + wr * 64 + fr, col0 = u.pn * 256 + wc * 32 + 8 * fq;
; #pragma unroll
;         for (int bj = 0; bj < 2; ++bj) {
;             const float* sp = ssq + tbase + col0 + bj * 128;
;             f32x4 r0 = (*(const f32x4*)sp + *(const f32x4*)(sp + TT)) + (*(const f32x4*)(sp + 2 * TT) + *(const f32x4*)(sp + 3 * TT));
;             f32x4 r1 = (*(const f32x4*)(sp + 4) + *(const f32x4*)(sp + TT + 4)) + (*(const f32x4*)(sp + 2 * TT + 4) + *(const f32x4*)(sp + 3 * TT + 4));
; #pragma unroll
;             for (int e = 0; e < 4; ++e) { r0[e] = rsqrtf(r0[e] * (1.f / 256.f) + EPS); r1[e] = rsqrtf(r1[e] * (1.f / 256.f) + EPS); }
; #pragma unroll
;             for (int ai = 0; ai < 2; ++ai)
; #pragma unroll
;                 for (int m = 0; m < 4; ++m) { const int row = row0 + ai * 128 + m * 16; st8(O + (unsigned)row * (unsigned)ldc + col0 + bj * 128, acc[ai][bj][m][0] * r0, acc[ai][bj][m][1] * r1); }
.LBB0_718:
	s_lshl_b32 s2, s41, 8
	v_mov_b32_e32 v0, v160
	v_mov_b32_e32 v138, v161
	s_or_b32 s2, s2, s67
	s_mov_b64 s[10:11], 0x40000
	v_lshl_add_u32 v150, v138, 3, s2
	v_ashrrev_i32_e32 v151, 31, v150
	v_lshl_add_u64 v[140:141], v[150:151], 2, s[64:65]
	v_add_co_u32_e32 v146, vcc, s97, v140
	global_load_dwordx4 v[152:155], v[140:141], off offset:16
	global_load_dwordx4 v[142:145], v[140:141], off
	v_addc_co_u32_e32 v147, vcc, 0, v141, vcc
	v_lshl_add_u64 v[138:139], v[140:141], 0, s[10:11]
	global_load_dwordx4 v[156:159], v[146:147], off
	global_load_dwordx4 v[164:167], v[138:139], off offset:16
	s_mov_b64 s[10:11], 0x80000
	s_mov_b32 s2, 0xc0000
	s_lshl_b32 s8, s40, 8
	s_add_i32 s8, s8, s66
	v_add_lshl_u32 v0, s8, v0, 14
	s_mov_b64 s[8:9], 0x40200
	s_waitcnt vmcnt(0)
	v_pk_add_f32 v[148:149], v[142:143], v[156:157]
	v_add_co_u32_e32 v142, vcc, s96, v140
	v_pk_add_f32 v[138:139], v[144:145], v[158:159]
	v_lshl_add_u64 v[144:145], v[140:141], 0, s[10:11]
	v_addc_co_u32_e32 v143, vcc, 0, v141, vcc
	global_load_dwordx4 v[156:159], v[142:143], off
	global_load_dwordx4 v[168:171], v[144:145], off offset:16
	s_mov_b64 s[10:11], 0xc0000
	v_add_co_u32_e32 v144, vcc, s2, v140
	v_lshl_add_u64 v[176:177], v[140:141], 0, s[10:11]
	s_nop 0
	v_addc_co_u32_e32 v145, vcc, 0, v141, vcc
	global_load_dwordx4 v[172:175], v[144:145], off
	s_nop 0
	global_load_dwordx4 v[176:179], v[176:177], off offset:16
	s_mov_b32 s2, 0x358637bd
	v_pk_add_f32 v[152:153], v[152:153], v[164:165]
	s_waitcnt vmcnt(1)
	v_pk_add_f32 v[158:159], v[158:159], v[174:175]
	v_pk_add_f32 v[156:157], v[156:157], v[172:173]
	v_pk_add_f32 v[158:159], v[138:139], v[158:159]
	v_pk_add_f32 v[138:139], v[154:155], v[166:167]
	s_waitcnt vmcnt(0)
	v_pk_add_f32 v[154:155], v[170:171], v[178:179]
	v_pk_add_f32 v[148:149], v[148:149], v[156:157]
	v_pk_add_f32 v[164:165], v[138:139], v[154:155]
	v_mov_b64_e32 v[138:139], s[2:3]
	v_pk_fma_f32 v[148:149], v[148:149], s[76:77], v[138:139] op_sel_hi:[1,0,0]
	v_pk_add_f32 v[156:157], v[168:169], v[176:177]
	v_mul_f32_e32 v154, 0x4b800000, v148
	v_cmp_gt_f32_e64 s[40:41], s51, v148
	v_cmp_gt_f32_e32 vcc, s51, v149
	v_pk_add_f32 v[152:153], v[152:153], v[156:157]
	v_cndmask_b32_e64 v148, v148, v154, s[40:41]
	v_mul_f32_e32 v154, 0x4b800000, v149
	v_cndmask_b32_e32 v149, v149, v154, vcc
	v_rsq_f32_e32 v148, v148
	v_rsq_f32_e32 v149, v149
	s_mov_b32 s2, 0x45800000
	v_pk_fma_f32 v[152:153], v[152:153], s[76:77], v[138:139] op_sel_hi:[1,0,0]
	v_pk_mul_f32 v[154:155], v[148:149], s[2:3] op_sel_hi:[1,0]
	s_nop 0
	v_cndmask_b32_e64 v148, v148, v154, s[40:41]
	v_mul_f32_e32 v154, 0x4b800000, v152
	v_cmp_gt_f32_e64 s[40:41], s51, v152
	v_cndmask_b32_e32 v149, v149, v155, vcc
	v_cmp_gt_f32_e32 vcc, s51, v153
	v_cndmask_b32_e64 v152, v152, v154, s[40:41]
	v_mul_f32_e32 v154, 0x4b800000, v153
	v_cndmask_b32_e32 v153, v153, v154, vcc
	v_rsq_f32_e32 v152, v152
	v_rsq_f32_e32 v153, v153
	v_pk_mul_f32 v[126:127], v[126:127], v[148:149]
	v_pk_mul_f32 v[118:119], v[118:119], v[148:149]
	v_pk_mul_f32 v[110:111], v[110:111], v[148:149]
	v_pk_mul_f32 v[154:155], v[152:153], s[2:3] op_sel_hi:[1,0]
	v_pk_mul_f32 v[102:103], v[102:103], v[148:149]
	v_cndmask_b32_e32 v153, v153, v155, vcc
	v_cndmask_b32_e64 v152, v152, v154, s[40:41]
	v_pk_fma_f32 v[154:155], v[158:159], s[76:77], v[138:139] op_sel_hi:[1,0,0]
	v_pk_mul_f32 v[94:95], v[94:95], v[148:149]
	v_mul_f32_e32 v156, 0x4b800000, v154
	v_cmp_gt_f32_e64 s[40:41], s51, v154
	v_cmp_gt_f32_e32 vcc, s51, v155
	v_pk_mul_f32 v[86:87], v[86:87], v[148:149]
	v_cndmask_b32_e64 v154, v154, v156, s[40:41]
	v_mul_f32_e32 v156, 0x4b800000, v155
	v_cndmask_b32_e32 v155, v155, v156, vcc
	v_rsq_f32_e32 v154, v154
	v_rsq_f32_e32 v155, v155
	v_pk_mul_f32 v[78:79], v[78:79], v[148:149]
	v_pk_mul_f32 v[70:71], v[70:71], v[148:149]
	v_pk_mul_f32 v[156:157], v[154:155], s[2:3] op_sel_hi:[1,0]
	s_nop 0
	v_cndmask_b32_e32 v155, v155, v157, vcc
	v_cndmask_b32_e64 v154, v154, v156, s[40:41]
	v_pk_fma_f32 v[156:157], v[164:165], s[76:77], v[138:139] op_sel_hi:[1,0,0]
	v_lshl_add_u64 v[164:165], v[0:1], 1, s[6:7]
	v_mul_f32_e32 v158, 0x4b800000, v156
	v_cmp_gt_f32_e64 s[40:41], s51, v156
	v_cmp_gt_f32_e32 vcc, s51, v157
	v_pk_mul_f32 v[128:129], v[128:129], v[154:155]
	v_cndmask_b32_e64 v156, v156, v158, s[40:41]
	v_mul_f32_e32 v158, 0x4b800000, v157
	v_cndmask_b32_e32 v157, v157, v158, vcc
	v_rsq_f32_e32 v156, v156
	v_rsq_f32_e32 v157, v157
	v_pk_mul_f32 v[120:121], v[120:121], v[154:155]
	v_pk_mul_f32 v[112:113], v[112:113], v[154:155]
	v_pk_mul_f32 v[104:105], v[104:105], v[154:155]
	v_pk_mul_f32 v[158:159], v[156:157], s[2:3] op_sel_hi:[1,0]
	v_pk_mul_f32 v[96:97], v[96:97], v[154:155]
	v_cndmask_b32_e32 v157, v157, v159, vcc
	v_cndmask_b32_e64 v156, v156, v158, s[40:41]
	v_lshlrev_b64 v[158:159], 1, v[150:151]
	v_lshl_add_u64 v[150:151], v[164:165], 0, v[158:159]
	v_pk_mul_f32 v[164:165], v[124:125], v[156:157]
	v_pk_mul_f32 v[124:125], v[122:123], v[152:153]
	v_cvt_pk_bf16_f32 v122, v126, v127
	v_cvt_pk_bf16_f32 v123, v128, v129
	v_cvt_pk_bf16_f32 v124, v124, v125
	v_cvt_pk_bf16_f32 v125, v164, v165
	global_store_dwordx4 v[150:151], v[122:125], off sc1
	v_pk_mul_f32 v[88:89], v[88:89], v[154:155]
	v_pk_mul_f32 v[80:81], v[80:81], v[154:155]
	v_add_u32_e32 v122, 0x40000, v0
	v_mov_b32_e32 v123, v1
	v_lshl_add_u64 v[122:123], v[122:123], 1, s[6:7]
	v_pk_mul_f32 v[124:125], v[116:117], v[156:157]
	v_pk_mul_f32 v[116:117], v[114:115], v[152:153]
	v_lshl_add_u64 v[122:123], v[122:123], 0, v[158:159]
	v_cvt_pk_bf16_f32 v114, v118, v119
	v_cvt_pk_bf16_f32 v115, v120, v121
	v_cvt_pk_bf16_f32 v116, v116, v117
	v_cvt_pk_bf16_f32 v117, v124, v125
; __device__ __forceinline__ void st8(bf16_t* p, f32x4 a, f32x4 b) { u32x4 w; w.x = pk2(a[0], a[1]); w.y = pk2(a[2], a[3]); w.z = pk2(b[0], b[1]); w.w = pk2(b[2], b[3]); *(u32x4*)p = w; }
;     __device__ __forceinline__ void operator()(ACC_T, const pg8::Unit& u, int wr, int wc, int fr, int fq) const {
;     ...
;         for (int bj = 0; bj < 2; ++bj) {
;             const float* sp = ssq + tbase + col0 + bj * 128;
;             f32x4 r0 = (*(const f32x4*)sp + *(const f32x4*)(sp + TT)) + (*(const f32x4*)(sp + 2 * TT) + *(const f32x4*)(sp + 3 * TT));
;             f32x4 r1 = (*(const f32x4*)(sp + 4) + *(const f32x4*)(sp + TT + 4)) + (*(const f32x4*)(sp + 2 * TT + 4) + *(const f32x4*)(sp + 3 * TT + 4));
; #pragma unroll
;             for (int e = 0; e < 4; ++e) { r0[e] = rsqrtf(r0[e] * (1.f / 256.f) + EPS); r1[e] = rsqrtf(r1[e] * (1.f / 256.f) + EPS); }
; #pragma unroll
;             for (int ai = 0; ai < 2; ++ai)
; #pragma unroll
;                 for (int m = 0; m < 4; ++m) { const int row = row0 + ai * 128 + m * 16; st8(O + (unsigned)row * (unsigned)ldc + col0 + bj * 128, acc[ai][bj][m][0] * r0, acc[ai][bj][m][1] * r1); }
;             asm volatile("" ::: "memory");
	global_store_dwordx4 v[122:123], v[114:117], off sc1
	v_pk_mul_f32 v[72:73], v[72:73], v[154:155]
	s_nop 0
	v_add_u32_e32 v114, 0x80000, v0
	v_mov_b32_e32 v115, v1
	v_lshl_add_u64 v[114:115], v[114:115], 1, s[6:7]
	v_pk_mul_f32 v[116:117], v[108:109], v[156:157]
	v_pk_mul_f32 v[108:109], v[106:107], v[152:153]
	v_lshl_add_u64 v[114:115], v[114:115], 0, v[158:159]
	v_cvt_pk_bf16_f32 v106, v110, v111
	v_cvt_pk_bf16_f32 v107, v112, v113
	v_cvt_pk_bf16_f32 v108, v108, v109
	v_cvt_pk_bf16_f32 v109, v116, v117
	global_store_dwordx4 v[114:115], v[106:109], off sc1
	s_nop 1
	v_add_u32_e32 v106, 0xc0000, v0
	v_mov_b32_e32 v107, v1
	v_lshl_add_u64 v[106:107], v[106:107], 1, s[6:7]
	v_pk_mul_f32 v[108:109], v[100:101], v[156:157]
	v_pk_mul_f32 v[100:101], v[98:99], v[152:153]
	v_lshl_add_u64 v[106:107], v[106:107], 0, v[158:159]
	v_cvt_pk_bf16_f32 v98, v102, v103
	v_cvt_pk_bf16_f32 v99, v104, v105
	v_cvt_pk_bf16_f32 v100, v100, v101
	v_cvt_pk_bf16_f32 v101, v108, v109
	global_store_dwordx4 v[106:107], v[98:101], off sc1
	s_nop 1
	v_add_u32_e32 v98, 0x200000, v0
	v_mov_b32_e32 v99, v1
	v_lshl_add_u64 v[98:99], v[98:99], 1, s[6:7]
	v_pk_mul_f32 v[100:101], v[92:93], v[156:157]
	v_pk_mul_f32 v[92:93], v[90:91], v[152:153]
	v_lshl_add_u64 v[98:99], v[98:99], 0, v[158:159]
	v_cvt_pk_bf16_f32 v90, v94, v95
	v_cvt_pk_bf16_f32 v91, v96, v97
	v_cvt_pk_bf16_f32 v92, v92, v93
	v_cvt_pk_bf16_f32 v93, v100, v101
	global_store_dwordx4 v[98:99], v[90:93], off sc1
	s_nop 1
	v_add_u32_e32 v90, 0x240000, v0
	v_mov_b32_e32 v91, v1
	v_lshl_add_u64 v[90:91], v[90:91], 1, s[6:7]
	v_pk_mul_f32 v[92:93], v[84:85], v[156:157]
	v_pk_mul_f32 v[84:85], v[82:83], v[152:153]
	v_lshl_add_u64 v[90:91], v[90:91], 0, v[158:159]
	v_cvt_pk_bf16_f32 v82, v86, v87
	v_cvt_pk_bf16_f32 v83, v88, v89
	v_cvt_pk_bf16_f32 v84, v84, v85
	v_cvt_pk_bf16_f32 v85, v92, v93
	global_store_dwordx4 v[90:91], v[82:85], off sc1
	s_nop 1
	v_add_u32_e32 v82, 0x280000, v0
	v_mov_b32_e32 v83, v1
	v_lshl_add_u64 v[82:83], v[82:83], 1, s[6:7]
	v_pk_mul_f32 v[84:85], v[76:77], v[156:157]
	v_pk_mul_f32 v[76:77], v[74:75], v[152:153]
	v_lshl_add_u64 v[82:83], v[82:83], 0, v[158:159]
	v_cvt_pk_bf16_f32 v74, v78, v79
	v_cvt_pk_bf16_f32 v75, v80, v81
	v_cvt_pk_bf16_f32 v76, v76, v77
	v_cvt_pk_bf16_f32 v77, v84, v85
	v_add_u32_e32 v0, 0x2c0000, v0
	global_store_dwordx4 v[82:83], v[74:77], off sc1
	v_lshl_add_u64 v[80:81], v[140:141], 0, s[8:9]
	s_mov_b64 s[8:9], 0x80200
	v_lshl_add_u64 v[74:75], v[0:1], 1, s[6:7]
	v_pk_mul_f32 v[76:77], v[68:69], v[156:157]
	v_pk_mul_f32 v[68:69], v[66:67], v[152:153]
	v_lshl_add_u64 v[74:75], v[74:75], 0, v[158:159]
	v_cvt_pk_bf16_f32 v66, v70, v71
	v_cvt_pk_bf16_f32 v67, v72, v73
	v_cvt_pk_bf16_f32 v68, v68, v69
	v_cvt_pk_bf16_f32 v69, v76, v77
	global_store_dwordx4 v[74:75], v[66:69], off sc1
	global_load_dwordx4 v[66:69], v[140:141], off offset:528
	global_load_dwordx4 v[70:73], v[140:141], off offset:512
	global_load_dwordx4 v[76:79], v[146:147], off offset:512
	global_load_dwordx4 v[84:87], v[80:81], off offset:16
	s_waitcnt vmcnt(1)
	v_pk_add_f32 v[88:89], v[70:71], v[76:77]
	v_lshl_add_u64 v[76:77], v[140:141], 0, s[8:9]
	s_mov_b64 s[8:9], 0xc0200
	v_pk_add_f32 v[80:81], v[72:73], v[78:79]
	global_load_dwordx4 v[70:73], v[142:143], off offset:512
	s_nop 0
	global_load_dwordx4 v[76:79], v[76:77], off offset:16
	v_lshl_add_u64 v[96:97], v[140:141], 0, s[8:9]
	global_load_dwordx4 v[92:95], v[144:145], off offset:512
	global_load_dwordx4 v[100:103], v[96:97], off offset:16
	s_waitcnt vmcnt(4)
	v_pk_add_f32 v[66:67], v[66:67], v[84:85]
	v_pk_add_f32 v[68:69], v[68:69], v[86:87]
	s_waitcnt vmcnt(1)
	v_pk_add_f32 v[70:71], v[70:71], v[92:93]
	s_nop 0
	v_pk_add_f32 v[70:71], v[88:89], v[70:71]
	s_waitcnt vmcnt(0)
; __device__ __forceinline__ void st8(bf16_t* p, f32x4 a, f32x4 b) { u32x4 w; w.x = pk2(a[0], a[1]); w.y = pk2(a[2], a[3]); w.z = pk2(b[0], b[1]); w.w = pk2(b[2], b[3]); *(u32x4*)p = w; }
;     __device__ __forceinline__ void operator()(ACC_T, const pg8::Unit& u, int wr, int wc, int fr, int fq) const {
;     ...
;         for (int bj = 0; bj < 2; ++bj) {
;             const float* sp = ssq + tbase + col0 + bj * 128;
;             f32x4 r0 = (*(const f32x4*)sp + *(const f32x4*)(sp + TT)) + (*(const f32x4*)(sp + 2 * TT) + *(const f32x4*)(sp + 3 * TT));
;             f32x4 r1 = (*(const f32x4*)(sp + 4) + *(const f32x4*)(sp + TT + 4)) + (*(const f32x4*)(sp + 2 * TT + 4) + *(const f32x4*)(sp + 3 * TT + 4));
; #pragma unroll
;             for (int e = 0; e < 4; ++e) { r0[e] = rsqrtf(r0[e] * (1.f / 256.f) + EPS); r1[e] = rsqrtf(r1[e] * (1.f / 256.f) + EPS); }
; #pragma unroll
;             for (int ai = 0; ai < 2; ++ai)
; #pragma unroll
;                 for (int m = 0; m < 4; ++m) { const int row = row0 + ai * 128 + m * 16; st8(O + (unsigned)row * (unsigned)ldc + col0 + bj * 128, acc[ai][bj][m][0] * r0, acc[ai][bj][m][1] * r1); }
;             asm volatile("" ::: "memory");
;         }
	v_pk_add_f32 v[76:77], v[76:77], v[100:101]
	v_pk_fma_f32 v[70:71], v[70:71], s[76:77], v[138:139] op_sel_hi:[1,0,0]
	v_pk_add_f32 v[66:67], v[66:67], v[76:77]
	v_mul_f32_e32 v0, 0x4b800000, v70
	v_cmp_gt_f32_e64 s[40:41], s51, v70
	v_cmp_gt_f32_e32 vcc, s51, v71
	v_pk_fma_f32 v[66:67], v[66:67], s[76:77], v[138:139] op_sel_hi:[1,0,0]
	v_cndmask_b32_e64 v0, v70, v0, s[40:41]
	v_rsq_f32_e32 v70, v0
	v_mul_f32_e32 v0, 0x4b800000, v71
	v_cndmask_b32_e32 v0, v71, v0, vcc
	v_rsq_f32_e32 v71, v0
	v_mul_f32_e32 v0, 0x4b800000, v66
	v_pk_add_f32 v[72:73], v[72:73], v[94:95]
	v_pk_add_f32 v[78:79], v[78:79], v[102:103]
	v_pk_mul_f32 v[76:77], v[70:71], s[2:3] op_sel_hi:[1,0]
	v_pk_add_f32 v[72:73], v[80:81], v[72:73]
	v_cndmask_b32_e64 v70, v70, v76, s[40:41]
	v_cmp_gt_f32_e64 s[40:41], s51, v66
	v_cndmask_b32_e32 v71, v71, v77, vcc
	v_cmp_gt_f32_e32 vcc, s51, v67
	v_cndmask_b32_e64 v0, v66, v0, s[40:41]
	v_rsq_f32_e32 v66, v0
	v_mul_f32_e32 v0, 0x4b800000, v67
	v_cndmask_b32_e32 v0, v67, v0, vcc
	v_rsq_f32_e32 v67, v0
	v_pk_fma_f32 v[72:73], v[72:73], s[76:77], v[138:139] op_sel_hi:[1,0,0]
	v_pk_add_f32 v[68:69], v[68:69], v[78:79]
	v_mul_f32_e32 v0, 0x4b800000, v72
	v_pk_mul_f32 v[76:77], v[66:67], s[2:3] op_sel_hi:[1,0]
	v_pk_fma_f32 v[68:69], v[68:69], s[76:77], v[138:139] op_sel_hi:[1,0,0]
	v_cndmask_b32_e64 v66, v66, v76, s[40:41]
	v_cmp_gt_f32_e64 s[40:41], s51, v72
	v_cndmask_b32_e32 v67, v67, v77, vcc
	v_cmp_gt_f32_e32 vcc, s51, v73
	v_cndmask_b32_e64 v0, v72, v0, s[40:41]
	v_rsq_f32_e32 v72, v0
	v_mul_f32_e32 v0, 0x4b800000, v73
	v_cndmask_b32_e32 v0, v73, v0, vcc
	v_rsq_f32_e32 v73, v0
	v_mul_f32_e32 v0, 0x4b800000, v68
	v_pk_mul_f32 v[62:63], v[62:63], v[70:71]
	v_pk_mul_f32 v[54:55], v[54:55], v[70:71]
	v_pk_mul_f32 v[76:77], v[72:73], s[2:3] op_sel_hi:[1,0]
	v_pk_mul_f32 v[46:47], v[46:47], v[70:71]
	v_cndmask_b32_e64 v72, v72, v76, s[40:41]
	v_cmp_gt_f32_e64 s[40:41], s51, v68
	v_cndmask_b32_e32 v73, v73, v77, vcc
	v_cmp_gt_f32_e32 vcc, s51, v69
	v_cndmask_b32_e64 v0, v68, v0, s[40:41]
	v_rsq_f32_e32 v68, v0
	v_mul_f32_e32 v0, 0x4b800000, v69
	v_cndmask_b32_e32 v0, v69, v0, vcc
	v_rsq_f32_e32 v69, v0
	v_pk_mul_f32 v[64:65], v[64:65], v[72:73]
	v_pk_mul_f32 v[56:57], v[56:57], v[72:73]
	v_pk_mul_f32 v[48:49], v[48:49], v[72:73]
	v_pk_mul_f32 v[76:77], v[68:69], s[2:3] op_sel_hi:[1,0]
	v_pk_mul_f32 v[40:41], v[40:41], v[72:73]
	v_cndmask_b32_e32 v69, v69, v77, vcc
	v_cndmask_b32_e64 v68, v68, v76, s[40:41]
	v_pk_mul_f32 v[76:77], v[60:61], v[68:69]
	v_pk_mul_f32 v[60:61], v[58:59], v[66:67]
	v_cvt_pk_bf16_f32 v58, v62, v63
	v_cvt_pk_bf16_f32 v59, v64, v65
	v_cvt_pk_bf16_f32 v60, v60, v61
	v_cvt_pk_bf16_f32 v61, v76, v77
	global_store_dwordx4 v[150:151], v[58:61], off offset:256 sc1
	v_pk_mul_f32 v[38:39], v[38:39], v[70:71]
	v_pk_mul_f32 v[32:33], v[32:33], v[72:73]
	v_pk_mul_f32 v[58:59], v[52:53], v[68:69]
	v_pk_mul_f32 v[52:53], v[50:51], v[66:67]
	v_cvt_pk_bf16_f32 v50, v54, v55
	v_cvt_pk_bf16_f32 v51, v56, v57
	v_cvt_pk_bf16_f32 v52, v52, v53
	v_cvt_pk_bf16_f32 v53, v58, v59
	global_store_dwordx4 v[122:123], v[50:53], off offset:256 sc1
	v_pk_mul_f32 v[30:31], v[30:31], v[70:71]
	v_pk_mul_f32 v[24:25], v[24:25], v[72:73]
	v_pk_mul_f32 v[50:51], v[44:45], v[68:69]
	v_pk_mul_f32 v[44:45], v[42:43], v[66:67]
	v_cvt_pk_bf16_f32 v42, v46, v47
	v_cvt_pk_bf16_f32 v43, v48, v49
	v_cvt_pk_bf16_f32 v44, v44, v45
	v_cvt_pk_bf16_f32 v45, v50, v51
	global_store_dwordx4 v[114:115], v[42:45], off offset:256 sc1
	v_pk_mul_f32 v[22:23], v[22:23], v[70:71]
	v_pk_mul_f32 v[16:17], v[16:17], v[72:73]
	v_pk_mul_f32 v[42:43], v[36:37], v[68:69]
	v_pk_mul_f32 v[36:37], v[34:35], v[66:67]
	v_cvt_pk_bf16_f32 v34, v38, v39
	v_cvt_pk_bf16_f32 v35, v40, v41
	v_cvt_pk_bf16_f32 v36, v36, v37
	v_cvt_pk_bf16_f32 v37, v42, v43
	global_store_dwordx4 v[106:107], v[34:37], off offset:256 sc1
	v_pk_mul_f32 v[14:15], v[14:15], v[70:71]
	v_pk_mul_f32 v[8:9], v[8:9], v[72:73]
	v_pk_mul_f32 v[34:35], v[28:29], v[68:69]
	v_pk_mul_f32 v[28:29], v[26:27], v[66:67]
	v_cvt_pk_bf16_f32 v26, v30, v31
	v_cvt_pk_bf16_f32 v27, v32, v33
	v_cvt_pk_bf16_f32 v28, v28, v29
	v_cvt_pk_bf16_f32 v29, v34, v35
	global_store_dwordx4 v[98:99], v[26:29], off offset:256 sc1
	v_pk_mul_f32 v[6:7], v[6:7], v[70:71]
	s_nop 0
	v_pk_mul_f32 v[26:27], v[20:21], v[68:69]
	v_pk_mul_f32 v[20:21], v[18:19], v[66:67]
	v_cvt_pk_bf16_f32 v18, v22, v23
	v_cvt_pk_bf16_f32 v19, v24, v25
	v_cvt_pk_bf16_f32 v20, v20, v21
	v_cvt_pk_bf16_f32 v21, v26, v27
	global_store_dwordx4 v[90:91], v[18:21], off offset:256 sc1
	s_nop 1
	v_pk_mul_f32 v[18:19], v[12:13], v[68:69]
	v_pk_mul_f32 v[12:13], v[10:11], v[66:67]
	v_cvt_pk_bf16_f32 v10, v14, v15
	v_cvt_pk_bf16_f32 v11, v16, v17
	v_cvt_pk_bf16_f32 v12, v12, v13
	v_cvt_pk_bf16_f32 v13, v18, v19
	global_store_dwordx4 v[82:83], v[10:13], off offset:256 sc1
	s_nop 1
	v_pk_mul_f32 v[10:11], v[4:5], v[68:69]
	v_pk_mul_f32 v[4:5], v[2:3], v[66:67]
	v_cvt_pk_bf16_f32 v2, v6, v7
	v_cvt_pk_bf16_f32 v3, v8, v9
	v_cvt_pk_bf16_f32 v4, v4, v5
	v_cvt_pk_bf16_f32 v5, v10, v11
	global_store_dwordx4 v[74:75], v[2:5], off offset:256 sc1
	s_andn2_b64 vcc, exec, s[38:39]
	s_mov_b64 s[8:9], -1
	s_cbranch_vccnz .LBB0_707
	s_andn2_b64 vcc, exec, s[4:5]
	s_cbranch_vccnz .LBB0_706
	s_barrier
	s_branch .LBB0_706

; __device__ __forceinline__ int ltid() { int t = threadIdx.x; asm volatile("" : "+v"(t)); return t; }
; __device__ __forceinline__ void attn_unit(LAS unsigned char* lds, const bf16_t* QN, const bf16_t* QR, const bf16_t* KN, const bf16_t* KR, const bf16_t* VT, bf16_t* ATT, int b, int h, int qb) {
;     const int tid = ltid(), wid = __builtin_amdgcn_readfirstlane(tid >> 6), lane = tid & 63, r32 = lane & 31, hf = lane >> 5;
;     const int tb = b * SEQ, q0w = qb * 256 + wid * 32;
;     bf16x8 qf[12];
;     { const unsigned t = (unsigned)(tb + q0w + r32);
; #pragma unroll
;       for (int ks = 0; ks < 8; ++ks) qf[ks] = *(const bf16x8*)(QN + t * 1024u + h * 128 + ks * 16 + hf * 8);
; #pragma unroll
;       for (int ks = 0; ks < 4; ++ks) qf[8 + ks] = *(const bf16x8*)(QR + t * 512u + h * 64 + ks * 16 + hf * 8); }
;     f32x16 o[4];
; #pragma unroll
;     for (int i = 0; i < 4; ++i)
; #pragma unroll
;         for (int r = 0; r < 16; ++r) o[i][r] = 0.f;
;     float m_i = -INFINITY, l_i = 0.f;
;     const int nkt = 4 * (qb + 1);
;     unsigned ksrc[3]; unsigned vsrc[2];
; #pragma unroll
;     for (int i = 0; i < 3; ++i) { const int pid = (wid + 8 * i) * 64 + lane, row = pid / 24, cp = pid % 24, c = (cp & ~7) | ((cp ^ row) & 7);
;         ksrc[i] = c < 16 ? (unsigned)((tb + row) * 1024 + h * 128 + c * 8) : (0x80000000u | (unsigned)((tb + row) * 64 + (c - 16) * 8)); }
; #pragma unroll
;     for (int i = 0; i < 2; ++i) { const int pid = (wid + 8 * i) * 64 + lane, dv = pid >> 3, cp = pid & 7, c = cp ^ (dv & 7);
;         vsrc[i] = (unsigned)((h * 128 + dv) * TG + tb + c * 8); }
;     ...
;     __syncthreads();
;     ATT_DMA(0, 0);
;     const int tx = hf ^ (r32 & 7);
.LBB0_922:
	s_and_b64 s[10:11], s[8:9], exec
	v_mov_b32_e32 v8, v221
	s_cselect_b32 s2, s30, s24
	v_readfirstlane_b32 s10, v8
	s_ashr_i32 s20, s10, 6
	s_cmp_lt_u32 s20, 4
	s_cbranch_scc1 .Lattn_prio_skip
	s_setprio 1
.Lattn_prio_skip:
	s_lshl_b32 s2, s2, 8
	s_lshl_b32 s60, s20, 5
	s_add_i32 s60, s60, s2
	v_and_b32_e32 v10, 31, v8
	s_add_i32 s11, s60, s33
	v_or_b32_e32 v4, s11, v10
	v_bfe_u32 v9, v8, 5, 1
	v_lshlrev_b32_e32 v232, 10, v4
	v_mov_b32_e32 v233, v1
	v_lshl_add_u64 v[2:3], v[232:233], 1, s[80:81]
	v_lshlrev_b32_e32 v0, 4, v9
	v_lshl_add_u64 v[2:3], v[2:3], 0, v[0:1]
	global_load_dwordx4 v[160:163], v[2:3], off
	global_load_dwordx4 v[216:219], v[2:3], off offset:32
	global_load_dwordx4 v[212:215], v[2:3], off offset:64
	global_load_dwordx4 v[208:211], v[2:3], off offset:96
	global_load_dwordx4 v[204:207], v[2:3], off offset:128
	global_load_dwordx4 v[200:203], v[2:3], off offset:160
	global_load_dwordx4 v[196:199], v[2:3], off offset:192
	global_load_dwordx4 v[188:191], v[2:3], off offset:224
	v_lshlrev_b32_e32 v2, 9, v4
	v_mov_b32_e32 v3, v1
	v_lshl_add_u64 v[2:3], v[2:3], 1, s[82:83]
	v_lshl_add_u64 v[2:3], v[2:3], 0, v[0:1]
	global_load_dwordx4 v[192:195], v[2:3], off
	global_load_dwordx4 v[184:187], v[2:3], off offset:32
	global_load_dwordx4 v[180:183], v[2:3], off offset:64
	global_load_dwordx4 v[176:179], v[2:3], off offset:96
	v_mov_b32_e32 v0, s10
	s_movk_i32 s10, 0xffc0
	v_bfi_b32 v0, s10, v0, v8
	v_mul_hi_i32 v2, v0, s25
	v_lshrrev_b32_e32 v3, 31, v2
	v_ashrrev_i32_e32 v2, 2, v2
	v_add_u32_e32 v2, v2, v3
	v_mul_lo_u32 v3, v2, 24
	v_sub_u32_e32 v3, v0, v3
	v_lshrrev_b32_e32 v4, 1, v2
	v_bitop3_b32 v3, v4, v3, 7 bitop3:0x6c
	v_cmp_lt_i32_e32 vcc, 15, v3
	v_add_u32_e32 v4, s33, v2
	s_and_saveexec_b64 s[10:11], vcc
	s_xor_b64 s[10:11], exec, s[10:11]
	v_lshlrev_b32_e32 v2, 6, v4
	v_lshlrev_b32_e32 v3, 3, v3
	v_add3_u32 v2, v2, v3, s31
	v_or_b32_e32 v2, 0x80000000, v2
	s_andn2_saveexec_b64 s[10:11], s[10:11]
	v_lshl_or_b32 v2, v4, 10, s37
	v_lshl_add_u32 v2, v3, 3, v2
	s_or_b64 exec, exec, s[10:11]
	v_add_u32_e32 v3, 0x200, v0
	v_mul_hi_i32 v4, v3, s25
	v_lshrrev_b32_e32 v5, 31, v4
	v_ashrrev_i32_e32 v4, 2, v4
	v_add_u32_e32 v4, v4, v5
	v_mul_lo_u32 v5, v4, 24
	v_sub_u32_e32 v5, v3, v5
	v_lshrrev_b32_e32 v6, 1, v4
	v_bitop3_b32 v5, v6, v5, 7 bitop3:0x6c
	v_cmp_lt_i32_e32 vcc, 15, v5
	v_add_u32_e32 v6, s33, v4
	s_and_saveexec_b64 s[10:11], vcc
	s_xor_b64 s[10:11], exec, s[10:11]
	v_lshlrev_b32_e32 v4, 6, v6
	v_lshlrev_b32_e32 v5, 3, v5
	v_add3_u32 v4, v4, v5, s31
	v_or_b32_e32 v4, 0x80000000, v4
	s_andn2_saveexec_b64 s[10:11], s[10:11]
	v_lshl_or_b32 v4, v6, 10, s37
	v_lshl_add_u32 v4, v5, 3, v4
	s_or_b64 exec, exec, s[10:11]
	v_add_u32_e32 v5, 0x400, v0
	v_mul_hi_i32 v6, v5, s25
	v_lshrrev_b32_e32 v7, 31, v6
	v_ashrrev_i32_e32 v6, 2, v6
	v_add_u32_e32 v6, v6, v7
	v_mul_lo_u32 v7, v6, 24
	v_sub_u32_e32 v5, v5, v7
	v_lshrrev_b32_e32 v7, 1, v6
	v_bitop3_b32 v5, v7, v5, 7 bitop3:0x6c
	v_cmp_lt_i32_e32 vcc, 15, v5
	v_add_u32_e32 v7, s33, v6
	s_and_saveexec_b64 s[10:11], vcc
	s_xor_b64 s[10:11], exec, s[10:11]
	v_lshlrev_b32_e32 v6, 6, v7
	v_lshlrev_b32_e32 v5, 3, v5
	v_add3_u32 v5, v6, v5, s31
	v_or_b32_e32 v6, 0x80000000, v5
	s_andn2_saveexec_b64 s[10:11], s[10:11]
	v_lshl_or_b32 v6, v7, 10, s37
	v_lshl_add_u32 v6, v5, 3, v6
	s_or_b64 exec, exec, s[10:11]
	v_ashrrev_i32_e32 v0, 3, v0
	v_lshrrev_b32_e32 v5, 1, v0
	v_xor_b32_e32 v5, v5, v8
	v_lshlrev_b32_e32 v11, 14, v0
	v_lshlrev_b32_e32 v5, 3, v5
	v_add_u32_e32 v0, s44, v11
	v_and_b32_e32 v20, 56, v5
	v_or_b32_e32 v12, v20, v0
	v_ashrrev_i32_e32 v0, 3, v3
	v_lshrrev_b32_e32 v3, 1, v0
	v_xor_b32_e32 v3, v3, v8
	v_lshlrev_b32_e32 v21, 14, v0
	v_lshlrev_b32_e32 v3, 3, v3
	v_add_u32_e32 v0, s44, v21
	v_and_b32_e32 v22, 56, v3
	v_or_b32_e32 v14, v22, v0
	s_lshl_b32 s61, s20, 10
	v_lshlrev_b32_e32 v0, 1, v2
	v_mov_b32_e32 v3, v1
	s_add_i32 s66, s61, 0
	v_lshl_add_u64 v[16:17], s[6:7], 0, v[0:1]
	v_lshl_add_u64 v[18:19], v[2:3], 1, s[4:5]
	v_cmp_gt_i32_e32 vcc, 0, v2
	s_mov_b32 m0, s66
	v_lshlrev_b32_e32 v0, 1, v4
	v_cndmask_b32_e32 v17, v19, v17, vcc
	v_cndmask_b32_e32 v16, v18, v16, vcc
	v_mov_b32_e32 v5, v1
	s_barrier
	global_load_lds_dwordx4 v[16:17], off
	v_lshl_add_u64 v[16:17], s[6:7], 0, v[0:1]
	v_lshl_add_u64 v[18:19], v[4:5], 1, s[4:5]
	v_cmp_gt_i32_e32 vcc, 0, v4
	s_add_i32 m0, s66, 0x2000
	v_lshlrev_b32_e32 v0, 1, v6
	v_cndmask_b32_e32 v17, v19, v17, vcc
	v_cndmask_b32_e32 v16, v18, v16, vcc
	v_mov_b32_e32 v7, v1
	global_load_lds_dwordx4 v[16:17], off
	v_lshl_add_u64 v[16:17], s[6:7], 0, v[0:1]
	v_lshl_add_u64 v[18:19], v[6:7], 1, s[4:5]
	v_cmp_gt_i32_e32 vcc, 0, v6
	s_add_i32 m0, s66, 0x4000
	v_mov_b32_e32 v13, v1
	v_cndmask_b32_e32 v17, v19, v17, vcc
	v_cndmask_b32_e32 v16, v18, v16, vcc
	global_load_lds_dwordx4 v[16:17], off
	s_add_i32 m0, s66, 0x6000
	v_lshl_add_u64 v[12:13], v[12:13], 1, s[64:65]
	v_mov_b32_e32 v15, v1
	global_load_lds_dwordx4 v[12:13], off
	v_lshl_add_u64 v[12:13], v[14:15], 1, s[64:65]
	s_add_i32 m0, s66, 0x8000
	v_or_b32_e32 v247, s60, v10
	global_load_lds_dwordx4 v[12:13], off
	v_lshlrev_b32_e32 v242, 7, v10
	v_mul_u32_u24_e32 v144, 0x180, v10
	v_lshrrev_b32_e32 v8, 1, v8
	v_bitop3_b32 v10, v9, v8, 7 bitop3:0x78
	v_lshlrev_b32_e32 v145, 4, v10
	v_bitop3_b32 v10, v8, 2, 7 bitop3:0x6c
	v_xor_b32_e32 v12, v10, v9
	v_and_b32_e32 v7, 7, v8
	v_lshlrev_b32_e32 v166, 4, v12
	v_bitop3_b32 v12, v8, 4, 7 bitop3:0x6c
	v_bitop3_b32 v8, v8, 6, 7 bitop3:0x6c
	v_lshlrev_b32_e32 v241, 3, v9
	v_lshlrev_b32_e32 v250, 2, v9
	v_xor_b32_e32 v13, v12, v9
	v_xor_b32_e32 v9, v8, v9
	v_and_b32_e32 v0, 0x7fffffff, v2
	v_and_b32_e32 v3, 0x7fffffff, v4
	v_and_b32_e32 v5, 0x7fffffff, v6
; __device__ __forceinline__ void attn_unit(LAS unsigned char* lds, const bf16_t* QN, const bf16_t* QR, const bf16_t* KN, const bf16_t* KR, const bf16_t* VT, bf16_t* ATT, int b, int h, int qb) {
;     ...
;     f32x16 o[4];
; #pragma unroll
;     for (int i = 0; i < 4; ++i)
; #pragma unroll
;         for (int r = 0; r < 16; ++r) o[i][r] = 0.f;
;     float m_i = -INFINITY, l_i = 0.f;
;     const int nkt = 4 * (qb + 1);
;     unsigned ksrc[3]; unsigned vsrc[2];
; #pragma unroll
;     for (int i = 0; i < 3; ++i) { const int pid = (wid + 8 * i) * 64 + lane, row = pid / 24, cp = pid % 24, c = (cp & ~7) | ((cp ^ row) & 7);
;         ksrc[i] = c < 16 ? (unsigned)((tb + row) * 1024 + h * 128 + c * 8) : (0x80000000u | (unsigned)((tb + row) * 64 + (c - 16) * 8)); }
; #pragma unroll
;     for (int i = 0; i < 2; ++i) { const int pid = (wid + 8 * i) * 64 + lane, dv = pid >> 3, cp = pid & 7, c = cp ^ (dv & 7);
;         vsrc[i] = (unsigned)((h * 128 + dv) * TG + tb + c * 8); }
;     ...
;     __syncthreads();
;     ATT_DMA(0, 0);
;     const int tx = hf ^ (r32 & 7);
;     for (int kt = 0; kt < nkt; ++kt) {
;         asm volatile("s_waitcnt vmcnt(0)" ::: "memory");
;         __syncthreads();
;         if (kt + 1 < nkt) ATT_DMA(kt + 1, (kt + 1) & 1);
	v_lshlrev_b32_e32 v164, 4, v9
	v_lshlrev_b32_e32 v237, 4, v7
	v_lshlrev_b32_e32 v240, 4, v10
	v_lshlrev_b32_e32 v253, 4, v8
	v_mov_b32_e32 v7, s7
	v_mov_b32_e32 v8, s5
	v_cmp_lt_i32_e64 s[38:39], -1, v2
	v_mov_b32_e32 v9, s6
	v_mov_b32_e32 v10, s4
	v_cmp_lt_i32_e64 s[40:41], -1, v4
	v_cmp_lt_i32_e64 s[42:43], -1, v6
	v_mov_b32_e32 v14, v1
	v_lshlrev_b32_e32 v165, 4, v13
	v_lshlrev_b32_e32 v254, 4, v12
	v_cndmask_b32_e64 v113, v7, v8, s[38:39]
	v_cndmask_b32_e64 v112, v9, v10, s[38:39]
	v_cndmask_b32_e64 v115, v7, v8, s[40:41]
	v_cndmask_b32_e64 v114, v9, v10, s[40:41]
	v_cndmask_b32_e64 v117, v7, v8, s[42:43]
	v_cndmask_b32_e64 v116, v9, v10, s[42:43]
	v_add3_u32 v118, s45, v21, v22
	v_add3_u32 v119, s45, v11, v20
	v_add_u32_e32 v120, 0x10000, v6
	v_add_u32_e32 v121, 0x10000, v4
	v_add_u32_e32 v122, 0x10000, v2
	v_add_u32_e32 v123, 0x1000, v5
	v_add_u32_e32 v124, 0x1000, v3
	v_add_u32_e32 v125, 0x1000, v0
	v_mov_b32_e32 v0, v1
	v_mov_b32_e32 v2, v1
	v_mov_b32_e32 v3, v1
	v_mov_b32_e32 v4, v1
	v_mov_b32_e32 v5, v1
	v_mov_b32_e32 v6, v1
	v_mov_b32_e32 v7, v1
	v_mov_b32_e32 v8, v1
	v_mov_b32_e32 v9, v1
	v_mov_b32_e32 v10, v1
	v_mov_b32_e32 v11, v1
	v_mov_b32_e32 v12, v1
	v_mov_b32_e32 v13, v1
	v_mov_b64_e32 v[30:31], v[14:15]
	v_mov_b64_e32 v[46:47], v[14:15]
	v_mov_b64_e32 v[62:63], v[14:15]
	v_mov_b64_e32 v[78:79], v[14:15]
	s_xor_b64 s[86:87], s[8:9], -1
	s_mov_b32 s9, 0
	s_or_b32 s8, s60, 31
	v_xor_b32_e32 v235, 16, v237
	v_xor_b32_e32 v239, 48, v237
	v_xor_b32_e32 v249, 0x50, v237
	v_xor_b32_e32 v252, 0x70, v237
	s_add_i32 s11, s2, 0xc0
	v_mov_b32_e32 v222, 0xff800000
	v_mov_b32_e32 v251, 0
	v_mov_b64_e32 v[28:29], v[12:13]
	v_mov_b64_e32 v[26:27], v[10:11]
	v_mov_b64_e32 v[24:25], v[8:9]
	v_mov_b64_e32 v[22:23], v[6:7]
	v_mov_b64_e32 v[20:21], v[4:5]
	v_mov_b64_e32 v[18:19], v[2:3]
	v_mov_b64_e32 v[16:17], v[0:1]
	v_mov_b64_e32 v[44:45], v[12:13]
	v_mov_b64_e32 v[42:43], v[10:11]
	v_mov_b64_e32 v[40:41], v[8:9]
	v_mov_b64_e32 v[38:39], v[6:7]
	v_mov_b64_e32 v[36:37], v[4:5]
	v_mov_b64_e32 v[34:35], v[2:3]
	v_mov_b64_e32 v[32:33], v[0:1]
	v_mov_b64_e32 v[60:61], v[12:13]
	v_mov_b64_e32 v[58:59], v[10:11]
	v_mov_b64_e32 v[56:57], v[8:9]
	v_mov_b64_e32 v[54:55], v[6:7]
	v_mov_b64_e32 v[52:53], v[4:5]
	v_mov_b64_e32 v[50:51], v[2:3]
	v_mov_b64_e32 v[48:49], v[0:1]
	v_mov_b64_e32 v[76:77], v[12:13]
	v_mov_b64_e32 v[74:75], v[10:11]
	v_mov_b64_e32 v[72:73], v[8:9]
	v_mov_b64_e32 v[70:71], v[6:7]
	v_mov_b64_e32 v[68:69], v[4:5]
	v_mov_b64_e32 v[66:67], v[2:3]
	v_mov_b64_e32 v[64:65], v[0:1]
	s_add_i32 s20, s66, 0xa000
	v_cndmask_b32_e64 v0, v125, v122, s[38:39]
	v_lshl_add_u64 v[2:3], v[0:1], 1, v[112:113]
	s_mov_b32 m0, s20
	v_cndmask_b32_e64 v0, v124, v121, s[40:41]
	global_load_lds_dwordx4 v[2:3], off
	v_lshl_add_u64 v[2:3], v[0:1], 1, v[114:115]
	s_add_i32 m0, s20, 0x2000
	v_cndmask_b32_e64 v0, v123, v120, s[42:43]
	global_load_lds_dwordx4 v[2:3], off
	v_lshl_add_u64 v[2:3], v[0:1], 1, v[116:117]
	s_add_i32 m0, s20, 0x4000
	v_add_u32_e32 v0, s9, v119
	global_load_lds_dwordx4 v[2:3], off
	s_add_i32 m0, s20, 0x6000
	v_lshl_add_u64 v[2:3], v[0:1], 1, s[64:65]
	v_add_u32_e32 v0, s9, v118
	global_load_lds_dwordx4 v[2:3], off
	v_lshl_add_u64 v[2:3], v[0:1], 1, s[64:65]
	s_add_i32 m0, s20, 0x8000
	s_nop 0
	global_load_lds_dwordx4 v[2:3], off
	v_add_u32_e32 v120, 0x10000, v120
	v_add_u32_e32 v121, 0x10000, v121
	v_add_u32_e32 v122, 0x10000, v122
	v_add_u32_e32 v123, 0x1000, v123
	v_add_u32_e32 v124, 0x1000, v124
	v_add_u32_e32 v125, 0x1000, v125
	v_add_u32_e32 v118, 64, v118
	v_add_u32_e32 v119, 64, v119
	s_mov_b32 s91, 0x14000
	s_mov_b32 s92, 0
	s_mov_b32 s93, 0xa000
	s_mov_b32 s2, 0
	s_waitcnt vmcnt(5)
.LBB0_935:
	s_add_i32 s67, s2, 1
	s_add_i32 s20, s66, s91
	v_cndmask_b32_e64 v0, v125, v122, s[38:39]
	v_lshl_add_u64 v[2:3], v[0:1], 1, v[112:113]
	s_mov_b32 m0, s20
	v_cndmask_b32_e64 v0, v124, v121, s[40:41]
	s_waitcnt vmcnt(5)
	s_waitcnt lgkmcnt(0)
	s_barrier
	s_add_i32 s10, s9, 0x80
	s_cmp_gt_i32 s10, s11
	s_cbranch_scc1 .Lattn_nodma
	global_load_lds_dwordx4 v[2:3], off
	v_lshl_add_u64 v[2:3], v[0:1], 1, v[114:115]
	s_add_i32 m0, s20, 0x2000
	v_cndmask_b32_e64 v0, v123, v120, s[42:43]
	global_load_lds_dwordx4 v[2:3], off
	v_lshl_add_u64 v[2:3], v[0:1], 1, v[116:117]
	s_add_i32 m0, s20, 0x4000
	v_add_u32_e32 v0, s9, v119
	global_load_lds_dwordx4 v[2:3], off
	s_add_i32 m0, s20, 0x6000
	v_lshl_add_u64 v[2:3], v[0:1], 1, s[64:65]
	v_add_u32_e32 v0, s9, v118
	global_load_lds_dwordx4 v[2:3], off
	v_lshl_add_u64 v[2:3], v[0:1], 1, s[64:65]
	s_add_i32 m0, s20, 0x8000
	s_nop 0
	global_load_lds_dwordx4 v[2:3], off
; #define LAS __attribute__((address_space(3)))
; __device__ __forceinline__ void attn_unit(LAS unsigned char* lds, const bf16_t* QN, const bf16_t* QR, const bf16_t* KN, const bf16_t* KR, const bf16_t* VT, bf16_t* ATT, int b, int h, int qb) {
;     ...
;         const LAS unsigned char* kbuf = lds + (kt & 1) * ATT_BUF; const LAS unsigned char* vbuf = kbuf + ATT_KB;
;         const int key0 = kt * 64;
;         if (key0 <= q0w + 31) {
;             f32x16 s[2];
; #pragma unroll
;             for (int kb = 0; kb < 2; ++kb) {
; #pragma unroll
;                 for (int r = 0; r < 16; ++r) s[kb][r] = 0.f;
;                 const LAS unsigned char* krow = kbuf + (kb * 32 + r32) * 384;
; #pragma unroll
;                 for (int ks = 0; ks < 12; ++ks) { const bf16x8 a = *(const LAS bf16x8*)(krow + (((2 * ks) & ~7) + (((2 * ks) & 7) ^ tx)) * 16);
;                     s[kb] = __builtin_amdgcn_mfma_f32_32x32x16_bf16(a, qf[ks], s[kb], 0, 0, 0);
;                     if ((ks & 3) == 3) __builtin_amdgcn_sched_barrier(0); }
;             }
;     ...
;             const int vx = r32 & 7;
; #pragma unroll
;             for (int dvb = 0; dvb < 4; ++dvb) {
;                 const LAS unsigned char* vrow = vbuf + (dvb * 32 + r32) * 128 + hf * 8;
; #pragma unroll
;                 for (int kb = 0; kb < 2; ++kb)
; #pragma unroll
;                     for (int s2 = 0; s2 < 2; ++s2) { const int c = kb * 4 + s2 * 2;
;                         const u32x2 lo = *(const LAS u32x2*)(vrow + ((c ^ vx) * 16)), hi = *(const LAS u32x2*)(vrow + (((c + 1) ^ vx) * 16)); u32x4 w; w.x = lo.x; w.y = lo.y; w.z = hi.x; w.w = hi.y;
.Lattn_nodma:
	s_cmp_gt_i32 s9, s8
	s_cbranch_scc1 .LBB0_942
	s_add_i32 s68, s92, 0
	v_add_u32_e32 v0, s68, v144
	v_add_u32_e32 v6, v0, v145
	v_add_u32_e32 v7, v0, v166
	v_add_u32_e32 v8, v0, v165
	v_add_u32_e32 v0, v0, v164
	ds_read_b128 v[2:5], v6
	ds_read_b128 v[154:157], v7
	ds_read_b128 v[168:171], v8
	ds_read_b128 v[172:175], v0
	v_add3_u32 v153, s68, v242, v241
	v_add_u32_e32 v146, v153, v237
	v_add_u32_e32 v147, v153, v235
	v_add_u32_e32 v148, v153, v240
	v_add_u32_e32 v149, v153, v239
	v_add_u32_e32 v150, v153, v254
	v_add_u32_e32 v151, v153, v249
	v_add_u32_e32 v152, v153, v253
	v_add_u32_e32 v153, v153, v252
	s_waitcnt lgkmcnt(3)
	v_mfma_f32_32x32x16_bf16 v[80:95], v[2:5], v[160:163], 0
	ds_read_b128 v[2:5], v6 offset:128
	s_waitcnt lgkmcnt(3)
	v_mfma_f32_32x32x16_bf16 v[80:95], v[154:157], v[216:219], v[80:95]
	ds_read_b128 v[154:157], v7 offset:128
	s_waitcnt lgkmcnt(3)
	v_mfma_f32_32x32x16_bf16 v[80:95], v[168:171], v[212:215], v[80:95]
	ds_read_b128 v[168:171], v8 offset:128
	s_waitcnt lgkmcnt(3)
	v_mfma_f32_32x32x16_bf16 v[80:95], v[172:175], v[208:211], v[80:95]
	ds_read_b128 v[172:175], v0 offset:128
	s_waitcnt lgkmcnt(3)
	v_mfma_f32_32x32x16_bf16 v[80:95], v[2:5], v[204:207], v[80:95]
	ds_read_b128 v[2:5], v6 offset:256
	s_waitcnt lgkmcnt(3)
	v_mfma_f32_32x32x16_bf16 v[80:95], v[154:157], v[200:203], v[80:95]
	ds_read_b128 v[154:157], v7 offset:256
	s_waitcnt lgkmcnt(3)
	v_mfma_f32_32x32x16_bf16 v[80:95], v[168:171], v[196:199], v[80:95]
	ds_read_b128 v[168:171], v8 offset:256
	s_waitcnt lgkmcnt(3)
	v_mfma_f32_32x32x16_bf16 v[80:95], v[172:175], v[188:191], v[80:95]
	ds_read_b128 v[172:175], v0 offset:256
	s_waitcnt lgkmcnt(3)
	v_mfma_f32_32x32x16_bf16 v[80:95], v[2:5], v[192:195], v[80:95]
	ds_read_b128 v[2:5], v6 offset:12288
	s_waitcnt lgkmcnt(3)
	v_mfma_f32_32x32x16_bf16 v[80:95], v[154:157], v[184:187], v[80:95]
	ds_read_b128 v[154:157], v7 offset:12288
	s_waitcnt lgkmcnt(3)
	v_mfma_f32_32x32x16_bf16 v[80:95], v[168:171], v[180:183], v[80:95]
	ds_read_b128 v[168:171], v8 offset:12288
	s_waitcnt lgkmcnt(3)
	v_mfma_f32_32x32x16_bf16 v[80:95], v[172:175], v[176:179], v[80:95]
	ds_read_b128 v[172:175], v0 offset:12288
	s_waitcnt lgkmcnt(3)
	v_mfma_f32_32x32x16_bf16 v[96:111], v[2:5], v[160:163], 0
	ds_read_b128 v[2:5], v6 offset:12416
	s_waitcnt lgkmcnt(3)
	v_mfma_f32_32x32x16_bf16 v[96:111], v[154:157], v[216:219], v[96:111]
	ds_read_b128 v[154:157], v7 offset:12416
	s_waitcnt lgkmcnt(3)
	v_mfma_f32_32x32x16_bf16 v[96:111], v[168:171], v[212:215], v[96:111]
	ds_read_b128 v[168:171], v8 offset:12416
	s_waitcnt lgkmcnt(3)
	v_mfma_f32_32x32x16_bf16 v[96:111], v[172:175], v[208:211], v[96:111]
	ds_read_b128 v[172:175], v0 offset:12416
	s_waitcnt lgkmcnt(3)
	v_mfma_f32_32x32x16_bf16 v[96:111], v[2:5], v[204:207], v[96:111]
	ds_read_b128 v[2:5], v6 offset:12544
	s_waitcnt lgkmcnt(3)
	v_mfma_f32_32x32x16_bf16 v[96:111], v[154:157], v[200:203], v[96:111]
	ds_read_b128 v[154:157], v7 offset:12544
	s_waitcnt lgkmcnt(3)
	v_mfma_f32_32x32x16_bf16 v[96:111], v[168:171], v[196:199], v[96:111]
	ds_read_b128 v[168:171], v8 offset:12544
	s_waitcnt lgkmcnt(3)
	v_mfma_f32_32x32x16_bf16 v[96:111], v[172:175], v[188:191], v[96:111]
	ds_read_b128 v[172:175], v0 offset:12544
	s_waitcnt lgkmcnt(3)
	v_mfma_f32_32x32x16_bf16 v[96:111], v[2:5], v[192:195], v[96:111]
	s_waitcnt lgkmcnt(2)
	v_mfma_f32_32x32x16_bf16 v[96:111], v[154:157], v[184:187], v[96:111]
	s_waitcnt lgkmcnt(1)
	v_mfma_f32_32x32x16_bf16 v[96:111], v[168:171], v[180:183], v[96:111]
	s_waitcnt lgkmcnt(0)
	v_mfma_f32_32x32x16_bf16 v[96:111], v[172:175], v[176:179], v[96:111]
	ds_read_b64 v[154:155], v146 offset:24576
	ds_read_b64 v[156:157], v147 offset:24576
	ds_read_b64 v[168:169], v148 offset:24576
	ds_read_b64 v[170:171], v149 offset:24576
	ds_read_b64 v[172:173], v150 offset:24576
	ds_read_b64 v[174:175], v151 offset:24576
	s_add_i32 s2, s9, 63
	s_cmp_le_i32 s2, s60
	s_cbranch_scc1 .LBB0_938
; __device__ __forceinline__ void attn_unit(LAS unsigned char* lds, const bf16_t* QN, const bf16_t* QR, const bf16_t* KN, const bf16_t* KR, const bf16_t* VT, bf16_t* ATT, int b, int h, int qb) {
;     ...
;             if (key0 + 63 > q0w) {
;                 const int qi = q0w + r32;
; #pragma unroll
;                 for (int kb = 0; kb < 2; ++kb)
; #pragma unroll
;                     for (int r = 0; r < 16; ++r) { const int key = key0 + kb * 32 + (r & 3) + 8 * (r >> 2) + 4 * hf; if (key > qi) s[kb][r] = -INFINITY; }
;             }
	v_add_u32_e32 v0, s9, v250
	v_cmp_gt_i32_e32 vcc, v0, v247
	s_nop 1
	v_cndmask_b32_e32 v2, v80, v248, vcc
	v_cmp_lt_i32_e32 vcc, v0, v247
	s_nop 1
	v_cndmask_b32_e32 v80, v2, v80, vcc
	v_add_u32_e32 v2, 2, v0
	v_cndmask_b32_e32 v81, v248, v81, vcc
	v_cmp_le_i32_e32 vcc, v2, v247
	v_add_u32_e32 v2, 3, v0
	s_nop 0
	v_cndmask_b32_e32 v82, v248, v82, vcc
	v_cmp_le_i32_e32 vcc, v2, v247
	v_add_u32_e32 v2, 8, v0
	s_nop 0
	v_cndmask_b32_e32 v83, v248, v83, vcc
	v_cmp_le_i32_e32 vcc, v2, v247
	v_add_u32_e32 v2, 9, v0
	s_nop 0
	v_cndmask_b32_e32 v84, v248, v84, vcc
	v_cmp_le_i32_e32 vcc, v2, v247
	v_add_u32_e32 v2, 10, v0
	s_nop 0
	v_cndmask_b32_e32 v85, v248, v85, vcc
	v_cmp_le_i32_e32 vcc, v2, v247
	v_add_u32_e32 v2, 11, v0
	s_nop 0
	v_cndmask_b32_e32 v86, v248, v86, vcc
	v_cmp_le_i32_e32 vcc, v2, v247
	v_add_u32_e32 v2, 16, v0
	s_nop 0
	v_cndmask_b32_e32 v87, v248, v87, vcc
	v_cmp_le_i32_e32 vcc, v2, v247
	v_add_u32_e32 v2, 17, v0
	s_nop 0
	v_cndmask_b32_e32 v88, v248, v88, vcc
	v_cmp_le_i32_e32 vcc, v2, v247
	v_add_u32_e32 v2, 18, v0
	s_nop 0
	v_cndmask_b32_e32 v89, v248, v89, vcc
	v_cmp_le_i32_e32 vcc, v2, v247
	v_add_u32_e32 v2, 19, v0
	s_nop 0
	v_cndmask_b32_e32 v90, v248, v90, vcc
	v_cmp_le_i32_e32 vcc, v2, v247
	v_add_u32_e32 v2, 24, v0
	s_nop 0
	v_cndmask_b32_e32 v91, v248, v91, vcc
	v_cmp_le_i32_e32 vcc, v2, v247
	v_add_u32_e32 v2, 25, v0
	s_nop 0
	v_cndmask_b32_e32 v92, v248, v92, vcc
	v_cmp_le_i32_e32 vcc, v2, v247
	v_add_u32_e32 v2, 26, v0
	s_nop 0
	v_cndmask_b32_e32 v93, v248, v93, vcc
	v_cmp_le_i32_e32 vcc, v2, v247
	v_add_u32_e32 v2, 27, v0
	s_nop 0
	v_cndmask_b32_e32 v94, v248, v94, vcc
	v_cmp_le_i32_e32 vcc, v2, v247
	v_add_u32_e32 v2, 32, v0
	s_nop 0
	v_cndmask_b32_e32 v95, v248, v95, vcc
	v_cmp_le_i32_e32 vcc, v2, v247
	v_add_u32_e32 v2, 33, v0
	s_nop 0
	v_cndmask_b32_e32 v96, v248, v96, vcc
	v_cmp_le_i32_e32 vcc, v2, v247
	v_add_u32_e32 v2, 34, v0
	s_nop 0
	v_cndmask_b32_e32 v97, v248, v97, vcc
	v_cmp_le_i32_e32 vcc, v2, v247
	v_add_u32_e32 v2, 35, v0
	s_nop 0
	v_cndmask_b32_e32 v98, v248, v98, vcc
	v_cmp_le_i32_e32 vcc, v2, v247
	v_add_u32_e32 v2, 40, v0
	s_nop 0
	v_cndmask_b32_e32 v99, v248, v99, vcc
	v_cmp_le_i32_e32 vcc, v2, v247
	v_add_u32_e32 v2, 41, v0
	s_nop 0
	v_cndmask_b32_e32 v100, v248, v100, vcc
	v_cmp_le_i32_e32 vcc, v2, v247
	v_add_u32_e32 v2, 42, v0
	s_nop 0
	v_cndmask_b32_e32 v101, v248, v101, vcc
	v_cmp_le_i32_e32 vcc, v2, v247
	v_add_u32_e32 v2, 43, v0
	s_nop 0
	v_cndmask_b32_e32 v102, v248, v102, vcc
	v_cmp_le_i32_e32 vcc, v2, v247
	v_add_u32_e32 v2, 48, v0
	s_nop 0
	v_cndmask_b32_e32 v103, v248, v103, vcc
	v_cmp_le_i32_e32 vcc, v2, v247
	v_add_u32_e32 v2, 49, v0
	s_nop 0
	v_cndmask_b32_e32 v104, v248, v104, vcc
	v_cmp_le_i32_e32 vcc, v2, v247
	v_add_u32_e32 v2, 50, v0
	s_nop 0
	v_cndmask_b32_e32 v105, v248, v105, vcc
	v_cmp_le_i32_e32 vcc, v2, v247
	v_add_u32_e32 v2, 51, v0
	s_nop 0
	v_cndmask_b32_e32 v106, v248, v106, vcc
	v_cmp_le_i32_e32 vcc, v2, v247
	v_add_u32_e32 v2, 56, v0
	s_nop 0
	v_cndmask_b32_e32 v107, v248, v107, vcc
	v_cmp_le_i32_e32 vcc, v2, v247
	v_add_u32_e32 v2, 57, v0
	s_nop 0
	v_cndmask_b32_e32 v108, v248, v108, vcc
	v_cmp_le_i32_e32 vcc, v2, v247
	v_add_u32_e32 v2, 58, v0
	v_add_u32_e32 v0, 59, v0
	v_cndmask_b32_e32 v109, v248, v109, vcc
	v_cmp_le_i32_e32 vcc, v2, v247
	s_nop 1
	v_cndmask_b32_e32 v110, v248, v110, vcc
	v_cmp_le_i32_e32 vcc, v0, v247
	s_nop 1
	v_cndmask_b32_e32 v111, v248, v111, vcc

; __device__ __forceinline__ void attn_unit(LAS unsigned char* lds, const bf16_t* QN, const bf16_t* QR, const bf16_t* KN, const bf16_t* KR, const bf16_t* VT, bf16_t* ATT, int b, int h, int qb) {
;     ...
;     for (int kt = 0; kt < nkt; ++kt) {
;         asm volatile("s_waitcnt vmcnt(0)" ::: "memory");
;         __syncthreads();
;         if (kt + 1 < nkt) ATT_DMA(kt + 1, (kt + 1) & 1);
.LBB0_942:
	s_add_i32 s9, s9, 64
	v_add_u32_e32 v120, 0x10000, v120
	v_add_u32_e32 v121, 0x10000, v121
	v_add_u32_e32 v122, 0x10000, v122
	v_add_u32_e32 v123, 0x1000, v123
	v_add_u32_e32 v124, 0x1000, v124
	s_mov_b32 s10, s92
	s_mov_b32 s92, s93
	s_mov_b32 s93, s91
	s_mov_b32 s91, s10
	s_cmp_eq_u32 s11, s9
	v_add_u32_e32 v125, 0x1000, v125
	s_cbranch_scc1 .LBB0_944
	s_mov_b32 s2, s67
	s_branch .LBB0_935
; #define LAS __attribute__((address_space(3)))
; __device__ __forceinline__ void attn_unit(LAS unsigned char* lds, const bf16_t* QN, const bf16_t* QR, const bf16_t* KN, const bf16_t* KR, const bf16_t* VT, bf16_t* ATT, int b, int h, int qb) {
;     ...
;         if (key0 <= q0w + 31) {
;             f32x16 s[2];
; #pragma unroll
;             for (int kb = 0; kb < 2; ++kb) {
; #pragma unroll
;                 for (int r = 0; r < 16; ++r) s[kb][r] = 0.f;
;                 const LAS unsigned char* krow = kbuf + (kb * 32 + r32) * 384;
; #pragma unroll
;                 for (int ks = 0; ks < 12; ++ks) { const bf16x8 a = *(const LAS bf16x8*)(krow + (((2 * ks) & ~7) + (((2 * ks) & 7) ^ tx)) * 16);
;                     s[kb] = __builtin_amdgcn_mfma_f32_32x32x16_bf16(a, qf[ks], s[kb], 0, 0, 0);
;                     if ((ks & 3) == 3) __builtin_amdgcn_sched_barrier(0); }
;             }
;             if (key0 + 63 > q0w) {
;                 const int qi = q0w + r32;
; #pragma unroll
;                 for (int kb = 0; kb < 2; ++kb)
; #pragma unroll
;                     for (int r = 0; r < 16; ++r) { const int key = key0 + kb * 32 + (r & 3) + 8 * (r >> 2) + 4 * hf; if (key > qi) s[kb][r] = -INFINITY; }
.LBB0_944:
	s_mov_b32 s10, s92
	s_waitcnt vmcnt(0)
	s_cmp_le_i32 s11, s8
	s_mov_b64 s[8:9], -1
	s_waitcnt vmcnt(0) lgkmcnt(0)
	s_barrier
	s_cbranch_scc0 .LBB0_951
	v_add_u32_e32 v0, s10, v144
	v_add_u32_e32 v6, v0, v145
	ds_read_b128 v[2:5], v6
	v_add_u32_e32 v7, v0, v166
	v_add_u32_e32 v8, v0, v165
	v_add_u32_e32 v0, v0, v164
	s_waitcnt lgkmcnt(0)
	v_mfma_f32_32x32x16_bf16 v[144:159], v[2:5], v[160:163], 0
	ds_read_b128 v[2:5], v7
	s_waitcnt lgkmcnt(0)
	v_mfma_f32_32x32x16_bf16 v[144:159], v[2:5], v[216:219], v[144:159]
	ds_read_b128 v[2:5], v8
	s_waitcnt lgkmcnt(0)
	v_mfma_f32_32x32x16_bf16 v[144:159], v[2:5], v[212:215], v[144:159]
	ds_read_b128 v[2:5], v0
	s_waitcnt lgkmcnt(0)
	v_mfma_f32_32x32x16_bf16 v[144:159], v[2:5], v[208:211], v[144:159]
	ds_read_b128 v[2:5], v6 offset:128
	s_waitcnt lgkmcnt(0)
	v_mfma_f32_32x32x16_bf16 v[144:159], v[2:5], v[204:207], v[144:159]
	ds_read_b128 v[2:5], v7 offset:128
	s_waitcnt lgkmcnt(0)
	v_mfma_f32_32x32x16_bf16 v[144:159], v[2:5], v[200:203], v[144:159]
	ds_read_b128 v[2:5], v8 offset:128
	s_waitcnt lgkmcnt(0)
	v_mfma_f32_32x32x16_bf16 v[144:159], v[2:5], v[196:199], v[144:159]
	ds_read_b128 v[2:5], v0 offset:128
	s_waitcnt lgkmcnt(0)
	v_mfma_f32_32x32x16_bf16 v[144:159], v[2:5], v[188:191], v[144:159]
	ds_read_b128 v[2:5], v6 offset:256
	s_waitcnt lgkmcnt(0)
	v_mfma_f32_32x32x16_bf16 v[144:159], v[2:5], v[192:195], v[144:159]
	ds_read_b128 v[2:5], v7 offset:256
	s_waitcnt lgkmcnt(0)
	v_mfma_f32_32x32x16_bf16 v[144:159], v[2:5], v[184:187], v[144:159]
	ds_read_b128 v[2:5], v8 offset:256
	s_waitcnt lgkmcnt(0)
	v_mfma_f32_32x32x16_bf16 v[144:159], v[2:5], v[180:183], v[144:159]
	ds_read_b128 v[2:5], v0 offset:256
	s_waitcnt lgkmcnt(0)
	v_mfma_f32_32x32x16_bf16 v[144:159], v[2:5], v[176:179], v[144:159]
	ds_read_b128 v[2:5], v6 offset:12288
	s_waitcnt lgkmcnt(0)
	v_mfma_f32_32x32x16_bf16 v[160:175], v[2:5], v[160:163], 0
	ds_read_b128 v[2:5], v7 offset:12288
	s_waitcnt lgkmcnt(0)
	v_mfma_f32_32x32x16_bf16 v[160:175], v[2:5], v[216:219], v[160:175]
	ds_read_b128 v[2:5], v8 offset:12288
	s_waitcnt lgkmcnt(0)
	v_mfma_f32_32x32x16_bf16 v[160:175], v[2:5], v[212:215], v[160:175]
	ds_read_b128 v[2:5], v0 offset:12288
	s_waitcnt lgkmcnt(0)
	v_mfma_f32_32x32x16_bf16 v[160:175], v[2:5], v[208:211], v[160:175]
	ds_read_b128 v[2:5], v6 offset:12416
	s_waitcnt lgkmcnt(0)
	v_mfma_f32_32x32x16_bf16 v[160:175], v[2:5], v[204:207], v[160:175]
	ds_read_b128 v[2:5], v7 offset:12416
	s_waitcnt lgkmcnt(0)
	v_mfma_f32_32x32x16_bf16 v[160:175], v[2:5], v[200:203], v[160:175]
	ds_read_b128 v[2:5], v8 offset:12416
	s_waitcnt lgkmcnt(0)
	v_mfma_f32_32x32x16_bf16 v[160:175], v[2:5], v[196:199], v[160:175]
	ds_read_b128 v[2:5], v0 offset:12416
	s_waitcnt lgkmcnt(0)
	v_mfma_f32_32x32x16_bf16 v[160:175], v[2:5], v[188:191], v[160:175]
	ds_read_b128 v[2:5], v6 offset:12544
	s_waitcnt lgkmcnt(0)
	v_mfma_f32_32x32x16_bf16 v[160:175], v[2:5], v[192:195], v[160:175]
	ds_read_b128 v[2:5], v7 offset:12544
	s_waitcnt lgkmcnt(0)
	v_mfma_f32_32x32x16_bf16 v[160:175], v[2:5], v[184:187], v[160:175]
	ds_read_b128 v[2:5], v8 offset:12544
	s_waitcnt lgkmcnt(0)
	v_mfma_f32_32x32x16_bf16 v[160:175], v[2:5], v[180:183], v[160:175]
	ds_read_b128 v[2:5], v0 offset:12544
	s_waitcnt lgkmcnt(0)
	v_mfma_f32_32x32x16_bf16 v[160:175], v[2:5], v[176:179], v[160:175]
	s_or_b32 s2, s11, 63
	s_cmp_le_i32 s2, s60
	s_cbranch_scc1 .LBB0_947
	v_or_b32_e32 v0, s11, v250
	v_cmp_gt_i32_e32 vcc, v0, v247
	s_nop 1
	v_cndmask_b32_e32 v2, v144, v248, vcc
	v_cmp_lt_i32_e32 vcc, v0, v247
	s_nop 1
	v_cndmask_b32_e32 v144, v2, v144, vcc
	v_or_b32_e32 v2, 2, v0
	v_cndmask_b32_e32 v145, v248, v145, vcc
	v_cmp_le_i32_e32 vcc, v2, v247
	v_or_b32_e32 v2, 3, v0
	s_nop 0
	v_cndmask_b32_e32 v146, v248, v146, vcc
	v_cmp_le_i32_e32 vcc, v2, v247
	v_or_b32_e32 v2, 8, v0
	s_nop 0
	v_cndmask_b32_e32 v147, v248, v147, vcc
	v_cmp_le_i32_e32 vcc, v2, v247
	v_or_b32_e32 v2, 9, v0
	s_nop 0
	v_cndmask_b32_e32 v148, v248, v148, vcc
	v_cmp_le_i32_e32 vcc, v2, v247
	v_or_b32_e32 v2, 10, v0
	s_nop 0
	v_cndmask_b32_e32 v149, v248, v149, vcc
	v_cmp_le_i32_e32 vcc, v2, v247
	v_or_b32_e32 v2, 11, v0
	s_nop 0
	v_cndmask_b32_e32 v150, v248, v150, vcc
	v_cmp_le_i32_e32 vcc, v2, v247
	v_or_b32_e32 v2, 16, v0
	s_nop 0
	v_cndmask_b32_e32 v151, v248, v151, vcc
	v_cmp_le_i32_e32 vcc, v2, v247
	v_or_b32_e32 v2, 17, v0
	s_nop 0
	v_cndmask_b32_e32 v152, v248, v152, vcc
	v_cmp_le_i32_e32 vcc, v2, v247
	v_or_b32_e32 v2, 18, v0
	s_nop 0
	v_cndmask_b32_e32 v153, v248, v153, vcc
	v_cmp_le_i32_e32 vcc, v2, v247
	v_or_b32_e32 v2, 19, v0
	s_nop 0
	v_cndmask_b32_e32 v154, v248, v154, vcc
	v_cmp_le_i32_e32 vcc, v2, v247
	v_or_b32_e32 v2, 24, v0
	s_nop 0
	v_cndmask_b32_e32 v155, v248, v155, vcc
	v_cmp_le_i32_e32 vcc, v2, v247
	v_or_b32_e32 v2, 25, v0
	s_nop 0
	v_cndmask_b32_e32 v156, v248, v156, vcc
	v_cmp_le_i32_e32 vcc, v2, v247
	v_or_b32_e32 v2, 26, v0
	s_nop 0
	v_cndmask_b32_e32 v157, v248, v157, vcc
	v_cmp_le_i32_e32 vcc, v2, v247
	v_or_b32_e32 v2, 27, v0
	s_nop 0
	v_cndmask_b32_e32 v158, v248, v158, vcc
	v_cmp_le_i32_e32 vcc, v2, v247
	v_or_b32_e32 v2, 32, v0
	s_nop 0
	v_cndmask_b32_e32 v159, v248, v159, vcc
	v_cmp_le_i32_e32 vcc, v2, v247
	v_or_b32_e32 v2, 33, v0
	s_nop 0
	v_cndmask_b32_e32 v160, v248, v160, vcc
	v_cmp_le_i32_e32 vcc, v2, v247
	v_or_b32_e32 v2, 34, v0
	s_nop 0
	v_cndmask_b32_e32 v161, v248, v161, vcc
	v_cmp_le_i32_e32 vcc, v2, v247
	v_or_b32_e32 v2, 35, v0
	s_nop 0
	v_cndmask_b32_e32 v162, v248, v162, vcc
	v_cmp_le_i32_e32 vcc, v2, v247
	v_or_b32_e32 v2, 40, v0
	s_nop 0
	v_cndmask_b32_e32 v163, v248, v163, vcc
	v_cmp_le_i32_e32 vcc, v2, v247
	v_or_b32_e32 v2, 41, v0
	s_nop 0
	v_cndmask_b32_e32 v164, v248, v164, vcc
	v_cmp_le_i32_e32 vcc, v2, v247
	v_or_b32_e32 v2, 42, v0
	s_nop 0
	v_cndmask_b32_e32 v165, v248, v165, vcc
	v_cmp_le_i32_e32 vcc, v2, v247
	v_or_b32_e32 v2, 43, v0
	s_nop 0
	v_cndmask_b32_e32 v166, v248, v166, vcc
	v_cmp_le_i32_e32 vcc, v2, v247
	v_or_b32_e32 v2, 48, v0
	s_nop 0
	v_cndmask_b32_e32 v167, v248, v167, vcc
	v_cmp_le_i32_e32 vcc, v2, v247
	v_or_b32_e32 v2, 49, v0
	s_nop 0
	v_cndmask_b32_e32 v168, v248, v168, vcc
	v_cmp_le_i32_e32 vcc, v2, v247
	v_or_b32_e32 v2, 50, v0
	s_nop 0
	v_cndmask_b32_e32 v169, v248, v169, vcc
	v_cmp_le_i32_e32 vcc, v2, v247
	v_or_b32_e32 v2, 51, v0
	s_nop 0
	v_cndmask_b32_e32 v170, v248, v170, vcc
	v_cmp_le_i32_e32 vcc, v2, v247
	v_or_b32_e32 v2, 56, v0
	s_nop 0
	v_cndmask_b32_e32 v171, v248, v171, vcc
	v_cmp_le_i32_e32 vcc, v2, v247
	v_or_b32_e32 v2, 57, v0
	s_nop 0
	v_cndmask_b32_e32 v172, v248, v172, vcc
	v_cmp_le_i32_e32 vcc, v2, v247
	v_or_b32_e32 v2, 58, v0
	v_or_b32_e32 v0, 59, v0
	v_cndmask_b32_e32 v173, v248, v173, vcc
	v_cmp_le_i32_e32 vcc, v2, v247
	s_nop 1
	v_cndmask_b32_e32 v174, v248, v174, vcc
	v_cmp_le_i32_e32 vcc, v0, v247
	s_nop 1
	v_cndmask_b32_e32 v175, v248, v175, vcc

; __device__ __forceinline__ void ph_attn(LAS unsigned char* lds) {
;     ...
;     for (int pi0 = bx; pi0 < NB * 64; pi0 += G) {
;         const int pi = (G % 8 == 0 && NB * 64 % 8 == 0 && pi0 - bx + G <= NB * 64) ? ((pi0 - bx) + (bx & 7) * (G >> 3) + (bx >> 3)) : pi0;
;         const int b = pi >> 6, h = (pi >> 3) & 7, j = pi & 7;
; #pragma unroll 1
;         for (int k = 0; k < 2; ++k) attn_unit(lds, QN, QR, KN, KR, VT, ATT, b, h, k ? j : 15 - j); }
;     __syncthreads();
.LBB0_953:
	s_setprio 0
	v_readlane_b32 s36, v255, 0
	v_readlane_b32 s46, v255, 45
	v_readlane_b32 s44, v255, 47
	v_readlane_b32 s60, v255, 49
	v_readlane_b32 s28, v255, 2
	v_readlane_b32 s37, v255, 1
	v_readlane_b32 s47, v255, 46
	v_readlane_b32 s45, v255, 48
	v_readlane_b32 s61, v255, 50

; __device__ __forceinline__ void st8(bf16_t* p, f32x4 a, f32x4 b) { u32x4 w; w.x = pk2(a[0], a[1]); w.y = pk2(a[2], a[3]); w.z = pk2(b[0], b[1]); w.w = pk2(b[2], b[3]); *(u32x4*)p = w; }
; __device__ __forceinline__ void ld8(const bf16_t* p, f32x4& a, f32x4& b) { const u32x4 w = *(const u32x4*)p; a[0] = bflo(w.x); a[1] = bfhi(w.x); a[2] = bflo(w.y); a[3] = bfhi(w.y); b[0] = bflo(w.z); b[1] = bfhi(w.z); b[2] = bflo(w.w); b[3] = bfhi(w.w); }
;     __device__ __forceinline__ void operator()(ACC_T, const pg8::Unit& u, int wr, int wc, int fr, int fq) const {
;         const int row0 = u.pm * 256 + wr * 64 + fr, col0 = u.pn * 256 + wc * 32 + 8 * fq;
; #pragma unroll
;         for (int ai = 0; ai < 2; ++ai)
; #pragma unroll
;             for (int m = 0; m < 4; ++m) { const int row = row0 + ai * 128 + m * 16;
; #pragma unroll
;                 for (int bj = 0; bj < 2; ++bj) { const unsigned off = (unsigned)row * 1024u + col0 + bj * 128; f32x4 g0, g1; ld8(G + off, g0, g1);
;                     f32x4 v0 = acc[ai][bj][m][0] * g0, v1 = acc[ai][bj][m][1] * g1;
;                     if (MODE == 1) { f32x4 p0, p1; ld8(P + off, p0, p1); v0 += p0; v1 += p1; }
;                     st8(O + off, v0, v1); }
;                 asm volatile("" ::: "memory"); }
;     }
.LBB0_1041:
	v_mov_b32_e32 v0, v142
	v_mov_b32_e32 v146, v143
	s_lshl_b32 s2, s84, 8
	s_add_i32 s2, s2, s45
	s_lshl_b32 s8, s68, 8
	v_lshlrev_b32_e32 v146, 3, v146
	v_add_lshl_u32 v0, s2, v0, 10
	s_or_b32 s2, s8, s60
	v_add3_u32 v0, s2, v146, v0
	v_lshlrev_b64 v[150:151], 1, v[0:1]
	v_lshl_add_u64 v[146:147], s[40:41], 0, v[150:151]
	global_load_dwordx4 v[146:149], v[146:147], off
	s_waitcnt vmcnt(0)
	v_lshlrev_b32_e32 v152, 16, v146
	v_and_b32_e32 v153, 0xffff0000, v146
	v_lshlrev_b32_e32 v146, 16, v147
	v_and_b32_e32 v147, 0xffff0000, v147
	v_lshlrev_b32_e32 v154, 16, v148
	v_and_b32_e32 v155, 0xffff0000, v148
	v_lshlrev_b32_e32 v148, 16, v149
	v_and_b32_e32 v149, 0xffff0000, v149
	v_pk_mul_f32 v[128:129], v[128:129], v[146:147]
	v_pk_mul_f32 v[126:127], v[126:127], v[152:153]
	v_pk_mul_f32 v[146:147], v[124:125], v[148:149]
	v_pk_mul_f32 v[124:125], v[122:123], v[154:155]
	v_lshl_add_u64 v[148:149], s[6:7], 0, v[150:151]
	v_cvt_pk_bf16_f32 v122, v126, v127
	v_cvt_pk_bf16_f32 v123, v128, v129
	v_cvt_pk_bf16_f32 v124, v124, v125
	v_cvt_pk_bf16_f32 v125, v146, v147
	global_store_dwordx4 v[148:149], v[122:125], off sc1
	s_nop 1
	v_add_u32_e32 v122, 0x80, v0
	v_mov_b32_e32 v123, v1
	v_lshlrev_b64 v[126:127], 1, v[122:123]
	v_lshl_add_u64 v[122:123], s[40:41], 0, v[126:127]
	global_load_dwordx4 v[122:125], v[122:123], off
	s_waitcnt vmcnt(0)
	v_lshlrev_b32_e32 v128, 16, v122
	v_and_b32_e32 v129, 0xffff0000, v122
	v_lshlrev_b32_e32 v122, 16, v123
	v_and_b32_e32 v123, 0xffff0000, v123
	v_lshlrev_b32_e32 v146, 16, v124
	v_and_b32_e32 v147, 0xffff0000, v124
	v_lshlrev_b32_e32 v124, 16, v125
	v_and_b32_e32 v125, 0xffff0000, v125
	v_pk_mul_f32 v[120:121], v[120:121], v[122:123]
	v_pk_mul_f32 v[118:119], v[118:119], v[128:129]
	v_pk_mul_f32 v[122:123], v[116:117], v[124:125]
	v_pk_mul_f32 v[116:117], v[114:115], v[146:147]
	v_lshl_add_u64 v[124:125], s[6:7], 0, v[126:127]
	v_cvt_pk_bf16_f32 v114, v118, v119
	v_cvt_pk_bf16_f32 v115, v120, v121
	v_cvt_pk_bf16_f32 v116, v116, v117
	v_cvt_pk_bf16_f32 v117, v122, v123
	global_store_dwordx4 v[124:125], v[114:117], off sc1
	s_nop 1
	v_add_u32_e32 v114, 0x4000, v0
	v_mov_b32_e32 v115, v1
	v_lshlrev_b64 v[118:119], 1, v[114:115]
	v_lshl_add_u64 v[114:115], s[40:41], 0, v[118:119]
	global_load_dwordx4 v[114:117], v[114:115], off
	s_waitcnt vmcnt(0)
	v_lshlrev_b32_e32 v120, 16, v114
	v_and_b32_e32 v121, 0xffff0000, v114
	v_lshlrev_b32_e32 v114, 16, v115
	v_and_b32_e32 v115, 0xffff0000, v115
	v_lshlrev_b32_e32 v122, 16, v116
	v_and_b32_e32 v123, 0xffff0000, v116
	v_lshlrev_b32_e32 v116, 16, v117
	v_and_b32_e32 v117, 0xffff0000, v117
	v_pk_mul_f32 v[112:113], v[112:113], v[114:115]
	v_pk_mul_f32 v[110:111], v[110:111], v[120:121]
	v_pk_mul_f32 v[114:115], v[108:109], v[116:117]
	v_pk_mul_f32 v[108:109], v[106:107], v[122:123]
	v_lshl_add_u64 v[116:117], s[6:7], 0, v[118:119]
	v_cvt_pk_bf16_f32 v106, v110, v111
	v_cvt_pk_bf16_f32 v107, v112, v113
	v_cvt_pk_bf16_f32 v108, v108, v109
	v_cvt_pk_bf16_f32 v109, v114, v115
	global_store_dwordx4 v[116:117], v[106:109], off sc1
	s_nop 1
	v_add_u32_e32 v106, 0x4080, v0
	v_mov_b32_e32 v107, v1
	v_lshlrev_b64 v[110:111], 1, v[106:107]
	v_lshl_add_u64 v[106:107], s[40:41], 0, v[110:111]
	global_load_dwordx4 v[106:109], v[106:107], off
	s_waitcnt vmcnt(0)
	v_lshlrev_b32_e32 v112, 16, v106
	v_and_b32_e32 v113, 0xffff0000, v106
	v_lshlrev_b32_e32 v106, 16, v107
	v_and_b32_e32 v107, 0xffff0000, v107
	v_lshlrev_b32_e32 v114, 16, v108
	v_and_b32_e32 v115, 0xffff0000, v108
	v_lshlrev_b32_e32 v108, 16, v109
	v_and_b32_e32 v109, 0xffff0000, v109
	v_pk_mul_f32 v[104:105], v[104:105], v[106:107]
	v_pk_mul_f32 v[102:103], v[102:103], v[112:113]
	v_pk_mul_f32 v[106:107], v[100:101], v[108:109]
	v_pk_mul_f32 v[100:101], v[98:99], v[114:115]
	v_lshl_add_u64 v[108:109], s[6:7], 0, v[110:111]
	v_cvt_pk_bf16_f32 v98, v102, v103
	v_cvt_pk_bf16_f32 v99, v104, v105
	v_cvt_pk_bf16_f32 v100, v100, v101
	v_cvt_pk_bf16_f32 v101, v106, v107
	global_store_dwordx4 v[108:109], v[98:101], off sc1
	s_nop 1
	v_add_u32_e32 v98, 0x8000, v0
	v_mov_b32_e32 v99, v1
	v_lshlrev_b64 v[102:103], 1, v[98:99]
	v_lshl_add_u64 v[98:99], s[40:41], 0, v[102:103]
	global_load_dwordx4 v[98:101], v[98:99], off
	s_waitcnt vmcnt(0)
	v_lshlrev_b32_e32 v104, 16, v98
	v_and_b32_e32 v105, 0xffff0000, v98
	v_lshlrev_b32_e32 v98, 16, v99
	v_and_b32_e32 v99, 0xffff0000, v99
	v_lshlrev_b32_e32 v106, 16, v100
	v_and_b32_e32 v107, 0xffff0000, v100
	v_lshlrev_b32_e32 v100, 16, v101
	v_and_b32_e32 v101, 0xffff0000, v101
	v_pk_mul_f32 v[96:97], v[96:97], v[98:99]
	v_pk_mul_f32 v[94:95], v[94:95], v[104:105]
	v_pk_mul_f32 v[98:99], v[92:93], v[100:101]
	v_pk_mul_f32 v[92:93], v[90:91], v[106:107]
	v_lshl_add_u64 v[100:101], s[6:7], 0, v[102:103]
	v_cvt_pk_bf16_f32 v90, v94, v95
	v_cvt_pk_bf16_f32 v91, v96, v97
	v_cvt_pk_bf16_f32 v92, v92, v93
	v_cvt_pk_bf16_f32 v93, v98, v99
	global_store_dwordx4 v[100:101], v[90:93], off sc1
	s_nop 1
	v_add_u32_e32 v90, 0x8080, v0
	v_mov_b32_e32 v91, v1
	v_lshlrev_b64 v[94:95], 1, v[90:91]
	v_lshl_add_u64 v[90:91], s[40:41], 0, v[94:95]
	global_load_dwordx4 v[90:93], v[90:91], off
	s_waitcnt vmcnt(0)
	v_lshlrev_b32_e32 v96, 16, v90
	v_and_b32_e32 v97, 0xffff0000, v90
	v_lshlrev_b32_e32 v90, 16, v91
	v_and_b32_e32 v91, 0xffff0000, v91
	v_lshlrev_b32_e32 v98, 16, v92
	v_and_b32_e32 v99, 0xffff0000, v92
	v_lshlrev_b32_e32 v92, 16, v93
	v_and_b32_e32 v93, 0xffff0000, v93
	v_pk_mul_f32 v[88:89], v[88:89], v[90:91]
	v_pk_mul_f32 v[86:87], v[86:87], v[96:97]
	v_pk_mul_f32 v[90:91], v[84:85], v[92:93]
	v_pk_mul_f32 v[84:85], v[82:83], v[98:99]
	v_lshl_add_u64 v[92:93], s[6:7], 0, v[94:95]
	v_cvt_pk_bf16_f32 v82, v86, v87
	v_cvt_pk_bf16_f32 v83, v88, v89
	v_cvt_pk_bf16_f32 v84, v84, v85
	v_cvt_pk_bf16_f32 v85, v90, v91
	global_store_dwordx4 v[92:93], v[82:85], off sc1
	s_nop 1
	v_add_u32_e32 v82, 0xc000, v0
	v_mov_b32_e32 v83, v1
	v_lshlrev_b64 v[86:87], 1, v[82:83]
	v_lshl_add_u64 v[82:83], s[40:41], 0, v[86:87]
	global_load_dwordx4 v[82:85], v[82:83], off
	s_waitcnt vmcnt(0)
; __device__ __forceinline__ void st8(bf16_t* p, f32x4 a, f32x4 b) { u32x4 w; w.x = pk2(a[0], a[1]); w.y = pk2(a[2], a[3]); w.z = pk2(b[0], b[1]); w.w = pk2(b[2], b[3]); *(u32x4*)p = w; }
; __device__ __forceinline__ void ld8(const bf16_t* p, f32x4& a, f32x4& b) { const u32x4 w = *(const u32x4*)p; a[0] = bflo(w.x); a[1] = bfhi(w.x); a[2] = bflo(w.y); a[3] = bfhi(w.y); b[0] = bflo(w.z); b[1] = bfhi(w.z); b[2] = bflo(w.w); b[3] = bfhi(w.w); }
;     __device__ __forceinline__ void operator()(ACC_T, const pg8::Unit& u, int wr, int wc, int fr, int fq) const {
;         const int row0 = u.pm * 256 + wr * 64 + fr, col0 = u.pn * 256 + wc * 32 + 8 * fq;
; #pragma unroll
;         for (int ai = 0; ai < 2; ++ai)
; #pragma unroll
;             for (int m = 0; m < 4; ++m) { const int row = row0 + ai * 128 + m * 16;
; #pragma unroll
;                 for (int bj = 0; bj < 2; ++bj) { const unsigned off = (unsigned)row * 1024u + col0 + bj * 128; f32x4 g0, g1; ld8(G + off, g0, g1);
;                     f32x4 v0 = acc[ai][bj][m][0] * g0, v1 = acc[ai][bj][m][1] * g1;
;                     if (MODE == 1) { f32x4 p0, p1; ld8(P + off, p0, p1); v0 += p0; v1 += p1; }
;                     st8(O + off, v0, v1); }
;                 asm volatile("" ::: "memory"); }
;     }
	v_lshlrev_b32_e32 v88, 16, v82
	v_and_b32_e32 v89, 0xffff0000, v82
	v_lshlrev_b32_e32 v82, 16, v83
	v_and_b32_e32 v83, 0xffff0000, v83
	v_lshlrev_b32_e32 v90, 16, v84
	v_and_b32_e32 v91, 0xffff0000, v84
	v_lshlrev_b32_e32 v84, 16, v85
	v_and_b32_e32 v85, 0xffff0000, v85
	v_pk_mul_f32 v[80:81], v[80:81], v[82:83]
	v_pk_mul_f32 v[78:79], v[78:79], v[88:89]
	v_pk_mul_f32 v[82:83], v[76:77], v[84:85]
	v_pk_mul_f32 v[76:77], v[74:75], v[90:91]
	v_lshl_add_u64 v[84:85], s[6:7], 0, v[86:87]
	v_cvt_pk_bf16_f32 v74, v78, v79
	v_cvt_pk_bf16_f32 v75, v80, v81
	v_cvt_pk_bf16_f32 v76, v76, v77
	v_cvt_pk_bf16_f32 v77, v82, v83
	global_store_dwordx4 v[84:85], v[74:77], off sc1
	s_nop 1
	v_add_u32_e32 v74, 0xc080, v0
	v_mov_b32_e32 v75, v1
	v_lshlrev_b64 v[78:79], 1, v[74:75]
	v_lshl_add_u64 v[74:75], s[40:41], 0, v[78:79]
	global_load_dwordx4 v[74:77], v[74:75], off
	s_waitcnt vmcnt(0)
	v_lshlrev_b32_e32 v80, 16, v74
	v_and_b32_e32 v81, 0xffff0000, v74
	v_lshlrev_b32_e32 v74, 16, v75
	v_and_b32_e32 v75, 0xffff0000, v75
	v_lshlrev_b32_e32 v82, 16, v76
	v_and_b32_e32 v83, 0xffff0000, v76
	v_lshlrev_b32_e32 v76, 16, v77
	v_and_b32_e32 v77, 0xffff0000, v77
	v_pk_mul_f32 v[72:73], v[72:73], v[74:75]
	v_pk_mul_f32 v[70:71], v[70:71], v[80:81]
	v_pk_mul_f32 v[74:75], v[68:69], v[76:77]
	v_pk_mul_f32 v[68:69], v[66:67], v[82:83]
	v_lshl_add_u64 v[76:77], s[6:7], 0, v[78:79]
	v_cvt_pk_bf16_f32 v66, v70, v71
	v_cvt_pk_bf16_f32 v67, v72, v73
	v_cvt_pk_bf16_f32 v68, v68, v69
	v_cvt_pk_bf16_f32 v69, v74, v75
	global_store_dwordx4 v[76:77], v[66:69], off sc1
	s_nop 1
	v_add_u32_e32 v66, 0x20000, v0
	v_mov_b32_e32 v67, v1
	v_lshlrev_b64 v[70:71], 1, v[66:67]
	v_lshl_add_u64 v[66:67], s[40:41], 0, v[70:71]
	global_load_dwordx4 v[66:69], v[66:67], off
	s_waitcnt vmcnt(0)
	v_lshlrev_b32_e32 v72, 16, v66
	v_and_b32_e32 v73, 0xffff0000, v66
	v_lshlrev_b32_e32 v66, 16, v67
	v_and_b32_e32 v67, 0xffff0000, v67
	v_lshlrev_b32_e32 v74, 16, v68
	v_and_b32_e32 v75, 0xffff0000, v68
	v_lshlrev_b32_e32 v68, 16, v69
	v_and_b32_e32 v69, 0xffff0000, v69
	v_pk_mul_f32 v[64:65], v[64:65], v[66:67]
	v_pk_mul_f32 v[62:63], v[62:63], v[72:73]
	v_pk_mul_f32 v[66:67], v[60:61], v[68:69]
	v_pk_mul_f32 v[60:61], v[58:59], v[74:75]
	v_lshl_add_u64 v[68:69], s[6:7], 0, v[70:71]
	v_cvt_pk_bf16_f32 v58, v62, v63
	v_cvt_pk_bf16_f32 v59, v64, v65
	v_cvt_pk_bf16_f32 v60, v60, v61
	v_cvt_pk_bf16_f32 v61, v66, v67
	global_store_dwordx4 v[68:69], v[58:61], off sc1
	s_nop 1
	v_add_u32_e32 v58, 0x20080, v0
	v_mov_b32_e32 v59, v1
	v_lshlrev_b64 v[62:63], 1, v[58:59]
	v_lshl_add_u64 v[58:59], s[40:41], 0, v[62:63]
	global_load_dwordx4 v[58:61], v[58:59], off
	s_waitcnt vmcnt(0)
	v_lshlrev_b32_e32 v64, 16, v58
	v_and_b32_e32 v65, 0xffff0000, v58
	v_lshlrev_b32_e32 v58, 16, v59
	v_and_b32_e32 v59, 0xffff0000, v59
	v_lshlrev_b32_e32 v66, 16, v60
	v_and_b32_e32 v67, 0xffff0000, v60
	v_lshlrev_b32_e32 v60, 16, v61
	v_and_b32_e32 v61, 0xffff0000, v61
	v_pk_mul_f32 v[56:57], v[56:57], v[58:59]
	v_pk_mul_f32 v[54:55], v[54:55], v[64:65]
	v_pk_mul_f32 v[58:59], v[52:53], v[60:61]
	v_pk_mul_f32 v[52:53], v[50:51], v[66:67]
	v_lshl_add_u64 v[60:61], s[6:7], 0, v[62:63]
	v_cvt_pk_bf16_f32 v50, v54, v55
	v_cvt_pk_bf16_f32 v51, v56, v57
	v_cvt_pk_bf16_f32 v52, v52, v53
	v_cvt_pk_bf16_f32 v53, v58, v59
	global_store_dwordx4 v[60:61], v[50:53], off sc1
	s_nop 1
	v_add_u32_e32 v50, 0x24000, v0
	v_mov_b32_e32 v51, v1
	v_lshlrev_b64 v[54:55], 1, v[50:51]
	v_lshl_add_u64 v[50:51], s[40:41], 0, v[54:55]
	global_load_dwordx4 v[50:53], v[50:51], off
	s_waitcnt vmcnt(0)
	v_lshlrev_b32_e32 v56, 16, v50
	v_and_b32_e32 v57, 0xffff0000, v50
	v_lshlrev_b32_e32 v50, 16, v51
	v_and_b32_e32 v51, 0xffff0000, v51
	v_lshlrev_b32_e32 v58, 16, v52
	v_and_b32_e32 v59, 0xffff0000, v52
	v_lshlrev_b32_e32 v52, 16, v53
	v_and_b32_e32 v53, 0xffff0000, v53
	v_pk_mul_f32 v[48:49], v[48:49], v[50:51]
	v_pk_mul_f32 v[46:47], v[46:47], v[56:57]
	v_pk_mul_f32 v[50:51], v[44:45], v[52:53]
	v_pk_mul_f32 v[44:45], v[42:43], v[58:59]
	v_lshl_add_u64 v[52:53], s[6:7], 0, v[54:55]
	v_cvt_pk_bf16_f32 v42, v46, v47
	v_cvt_pk_bf16_f32 v43, v48, v49
	v_cvt_pk_bf16_f32 v44, v44, v45
	v_cvt_pk_bf16_f32 v45, v50, v51
	global_store_dwordx4 v[52:53], v[42:45], off sc1
	s_nop 1
	v_add_u32_e32 v42, 0x24080, v0
	v_mov_b32_e32 v43, v1
	v_lshlrev_b64 v[46:47], 1, v[42:43]
	v_lshl_add_u64 v[42:43], s[40:41], 0, v[46:47]
	global_load_dwordx4 v[42:45], v[42:43], off
	s_waitcnt vmcnt(0)
; __device__ __forceinline__ void st8(bf16_t* p, f32x4 a, f32x4 b) { u32x4 w; w.x = pk2(a[0], a[1]); w.y = pk2(a[2], a[3]); w.z = pk2(b[0], b[1]); w.w = pk2(b[2], b[3]); *(u32x4*)p = w; }
; __device__ __forceinline__ void ld8(const bf16_t* p, f32x4& a, f32x4& b) { const u32x4 w = *(const u32x4*)p; a[0] = bflo(w.x); a[1] = bfhi(w.x); a[2] = bflo(w.y); a[3] = bfhi(w.y); b[0] = bflo(w.z); b[1] = bfhi(w.z); b[2] = bflo(w.w); b[3] = bfhi(w.w); }
;     __device__ __forceinline__ void operator()(ACC_T, const pg8::Unit& u, int wr, int wc, int fr, int fq) const {
;         const int row0 = u.pm * 256 + wr * 64 + fr, col0 = u.pn * 256 + wc * 32 + 8 * fq;
; #pragma unroll
;         for (int ai = 0; ai < 2; ++ai)
; #pragma unroll
;             for (int m = 0; m < 4; ++m) { const int row = row0 + ai * 128 + m * 16;
; #pragma unroll
;                 for (int bj = 0; bj < 2; ++bj) { const unsigned off = (unsigned)row * 1024u + col0 + bj * 128; f32x4 g0, g1; ld8(G + off, g0, g1);
;                     f32x4 v0 = acc[ai][bj][m][0] * g0, v1 = acc[ai][bj][m][1] * g1;
;                     if (MODE == 1) { f32x4 p0, p1; ld8(P + off, p0, p1); v0 += p0; v1 += p1; }
;                     st8(O + off, v0, v1); }
;                 asm volatile("" ::: "memory"); }
;     }
	v_lshlrev_b32_e32 v48, 16, v42
	v_and_b32_e32 v49, 0xffff0000, v42
	v_lshlrev_b32_e32 v42, 16, v43
	v_and_b32_e32 v43, 0xffff0000, v43
	v_lshlrev_b32_e32 v50, 16, v44
	v_and_b32_e32 v51, 0xffff0000, v44
	v_lshlrev_b32_e32 v44, 16, v45
	v_and_b32_e32 v45, 0xffff0000, v45
	v_pk_mul_f32 v[40:41], v[40:41], v[42:43]
	v_pk_mul_f32 v[38:39], v[38:39], v[48:49]
	v_pk_mul_f32 v[42:43], v[36:37], v[44:45]
	v_pk_mul_f32 v[36:37], v[34:35], v[50:51]
	v_lshl_add_u64 v[44:45], s[6:7], 0, v[46:47]
	v_cvt_pk_bf16_f32 v34, v38, v39
	v_cvt_pk_bf16_f32 v35, v40, v41
	v_cvt_pk_bf16_f32 v36, v36, v37
	v_cvt_pk_bf16_f32 v37, v42, v43
	global_store_dwordx4 v[44:45], v[34:37], off sc1
	s_nop 1
	v_add_u32_e32 v34, 0x28000, v0
	v_mov_b32_e32 v35, v1
	v_lshlrev_b64 v[38:39], 1, v[34:35]
	v_lshl_add_u64 v[34:35], s[40:41], 0, v[38:39]
	global_load_dwordx4 v[34:37], v[34:35], off
	s_waitcnt vmcnt(0)
	v_lshlrev_b32_e32 v40, 16, v34
	v_and_b32_e32 v41, 0xffff0000, v34
	v_lshlrev_b32_e32 v34, 16, v35
	v_and_b32_e32 v35, 0xffff0000, v35
	v_lshlrev_b32_e32 v42, 16, v36
	v_and_b32_e32 v43, 0xffff0000, v36
	v_lshlrev_b32_e32 v36, 16, v37
	v_and_b32_e32 v37, 0xffff0000, v37
	v_pk_mul_f32 v[32:33], v[32:33], v[34:35]
	v_pk_mul_f32 v[30:31], v[30:31], v[40:41]
	v_pk_mul_f32 v[34:35], v[28:29], v[36:37]
	v_pk_mul_f32 v[28:29], v[26:27], v[42:43]
	v_lshl_add_u64 v[36:37], s[6:7], 0, v[38:39]
	v_cvt_pk_bf16_f32 v26, v30, v31
	v_cvt_pk_bf16_f32 v27, v32, v33
	v_cvt_pk_bf16_f32 v28, v28, v29
	v_cvt_pk_bf16_f32 v29, v34, v35
	global_store_dwordx4 v[36:37], v[26:29], off sc1
	s_nop 1
	v_add_u32_e32 v26, 0x28080, v0
	v_mov_b32_e32 v27, v1
	v_lshlrev_b64 v[30:31], 1, v[26:27]
	v_lshl_add_u64 v[26:27], s[40:41], 0, v[30:31]
	global_load_dwordx4 v[26:29], v[26:27], off
	s_waitcnt vmcnt(0)
	v_lshlrev_b32_e32 v32, 16, v26
	v_and_b32_e32 v33, 0xffff0000, v26
	v_lshlrev_b32_e32 v26, 16, v27
	v_and_b32_e32 v27, 0xffff0000, v27
	v_lshlrev_b32_e32 v34, 16, v28
	v_and_b32_e32 v35, 0xffff0000, v28
	v_lshlrev_b32_e32 v28, 16, v29
	v_and_b32_e32 v29, 0xffff0000, v29
	v_pk_mul_f32 v[24:25], v[24:25], v[26:27]
	v_pk_mul_f32 v[22:23], v[22:23], v[32:33]
	v_pk_mul_f32 v[26:27], v[20:21], v[28:29]
	v_pk_mul_f32 v[20:21], v[18:19], v[34:35]
	v_lshl_add_u64 v[28:29], s[6:7], 0, v[30:31]
	v_cvt_pk_bf16_f32 v18, v22, v23
	v_cvt_pk_bf16_f32 v19, v24, v25
	v_cvt_pk_bf16_f32 v20, v20, v21
	v_cvt_pk_bf16_f32 v21, v26, v27
	global_store_dwordx4 v[28:29], v[18:21], off sc1
	s_nop 1
	v_add_u32_e32 v18, 0x2c000, v0
	v_mov_b32_e32 v19, v1
	v_lshlrev_b64 v[22:23], 1, v[18:19]
	v_lshl_add_u64 v[18:19], s[40:41], 0, v[22:23]
	global_load_dwordx4 v[18:21], v[18:19], off
	v_add_u32_e32 v0, 0x2c080, v0
	s_waitcnt vmcnt(0)
	v_lshlrev_b32_e32 v24, 16, v18
	v_and_b32_e32 v25, 0xffff0000, v18
	v_lshlrev_b32_e32 v18, 16, v19
	v_and_b32_e32 v19, 0xffff0000, v19
	v_lshlrev_b32_e32 v26, 16, v20
	v_and_b32_e32 v27, 0xffff0000, v20
	v_lshlrev_b32_e32 v20, 16, v21
	v_and_b32_e32 v21, 0xffff0000, v21
	v_pk_mul_f32 v[16:17], v[16:17], v[18:19]
	v_pk_mul_f32 v[14:15], v[14:15], v[24:25]
	v_pk_mul_f32 v[18:19], v[12:13], v[20:21]
	v_pk_mul_f32 v[12:13], v[10:11], v[26:27]
	v_lshl_add_u64 v[20:21], s[6:7], 0, v[22:23]
	v_cvt_pk_bf16_f32 v10, v14, v15
	v_cvt_pk_bf16_f32 v11, v16, v17
	v_cvt_pk_bf16_f32 v12, v12, v13
	v_cvt_pk_bf16_f32 v13, v18, v19
	v_lshlrev_b64 v[14:15], 1, v[0:1]
	global_store_dwordx4 v[20:21], v[10:13], off sc1
	s_nop 1
	v_lshl_add_u64 v[10:11], s[40:41], 0, v[14:15]
	global_load_dwordx4 v[10:13], v[10:11], off
	s_waitcnt vmcnt(0)
	v_lshlrev_b32_e32 v16, 16, v10
	v_and_b32_e32 v17, 0xffff0000, v10
	v_lshlrev_b32_e32 v10, 16, v11
	v_and_b32_e32 v11, 0xffff0000, v11
	v_lshlrev_b32_e32 v18, 16, v12
	v_and_b32_e32 v19, 0xffff0000, v12
	v_lshlrev_b32_e32 v12, 16, v13
	v_and_b32_e32 v13, 0xffff0000, v13
	v_pk_mul_f32 v[8:9], v[8:9], v[10:11]
	v_pk_mul_f32 v[6:7], v[6:7], v[16:17]
	v_pk_mul_f32 v[10:11], v[4:5], v[12:13]
	v_pk_mul_f32 v[4:5], v[2:3], v[18:19]
	v_lshl_add_u64 v[12:13], s[6:7], 0, v[14:15]
	v_cvt_pk_bf16_f32 v2, v6, v7
	v_cvt_pk_bf16_f32 v3, v8, v9
	v_cvt_pk_bf16_f32 v4, v4, v5
	v_cvt_pk_bf16_f32 v5, v10, v11
	global_store_dwordx4 v[12:13], v[2:5], off sc1
	s_andn2_b64 vcc, exec, s[38:39]
	s_mov_b64 s[8:9], -1
	s_cbranch_vccnz .LBB0_1030
	s_andn2_b64 vcc, exec, s[4:5]
	s_cbranch_vccnz .LBB0_1029
	s_barrier
	s_branch .LBB0_1029

; __device__ __forceinline__ void st8(bf16_t* p, f32x4 a, f32x4 b) { u32x4 w; w.x = pk2(a[0], a[1]); w.y = pk2(a[2], a[3]); w.z = pk2(b[0], b[1]); w.w = pk2(b[2], b[3]); *(u32x4*)p = w; }
; __device__ __forceinline__ void ld8(const bf16_t* p, f32x4& a, f32x4& b) { const u32x4 w = *(const u32x4*)p; a[0] = bflo(w.x); a[1] = bfhi(w.x); a[2] = bflo(w.y); a[3] = bfhi(w.y); b[0] = bflo(w.z); b[1] = bfhi(w.z); b[2] = bflo(w.w); b[3] = bfhi(w.w); }
;     __device__ __forceinline__ void operator()(ACC_T, const pg8::Unit& u, int wr, int wc, int fr, int fq) const {
;         const int row0 = u.pm * 256 + wr * 64 + fr, col0 = u.pn * 256 + wc * 32 + 8 * fq;
; #pragma unroll
;         for (int ai = 0; ai < 2; ++ai)
; #pragma unroll
;             for (int m = 0; m < 4; ++m) { const int row = row0 + ai * 128 + m * 16;
; #pragma unroll
;                 for (int bj = 0; bj < 2; ++bj) { const unsigned off = (unsigned)row * 1024u + col0 + bj * 128; f32x4 g0, g1; ld8(G + off, g0, g1);
;                     f32x4 v0 = acc[ai][bj][m][0] * g0, v1 = acc[ai][bj][m][1] * g1;
;                     if (MODE == 1) { f32x4 p0, p1; ld8(P + off, p0, p1); v0 += p0; v1 += p1; }
;                     st8(O + off, v0, v1); }
;                 asm volatile("" ::: "memory"); }
;     }
.LBB0_1065:
	v_mov_b32_e32 v0, v143
	v_mov_b32_e32 v146, v142
	s_lshl_b32 s2, s86, 8
	s_add_i32 s2, s2, s45
	s_lshl_b32 s8, s68, 8
	v_lshlrev_b32_e32 v0, 3, v0
	v_add_lshl_u32 v146, s2, v146, 10
	s_or_b32 s2, s8, s60
	v_add3_u32 v0, s2, v0, v146
	v_lshlrev_b64 v[150:151], 1, v[0:1]
	v_lshl_add_u64 v[146:147], s[40:41], 0, v[150:151]
	global_load_dwordx4 v[146:149], v[146:147], off
	s_waitcnt vmcnt(0)
	v_lshlrev_b32_e32 v152, 16, v146
	v_and_b32_e32 v153, 0xffff0000, v146
	v_lshlrev_b32_e32 v154, 16, v147
	v_and_b32_e32 v155, 0xffff0000, v147
	v_lshl_add_u64 v[146:147], s[42:43], 0, v[150:151]
	v_lshlrev_b32_e32 v156, 16, v148
	v_and_b32_e32 v157, 0xffff0000, v148
	v_lshlrev_b32_e32 v158, 16, v149
	v_and_b32_e32 v159, 0xffff0000, v149
	global_load_dwordx4 v[146:149], v[146:147], off
	s_waitcnt vmcnt(0)
	v_lshlrev_b32_e32 v160, 16, v146
	v_and_b32_e32 v161, 0xffff0000, v146
	v_lshlrev_b32_e32 v146, 16, v147
	v_and_b32_e32 v147, 0xffff0000, v147
	v_lshlrev_b32_e32 v162, 16, v148
	v_and_b32_e32 v163, 0xffff0000, v148
	v_lshlrev_b32_e32 v148, 16, v149
	v_and_b32_e32 v149, 0xffff0000, v149
	v_pk_fma_f32 v[128:129], v[128:129], v[154:155], v[146:147]
	v_pk_fma_f32 v[126:127], v[126:127], v[152:153], v[160:161]
	v_pk_fma_f32 v[146:147], v[124:125], v[158:159], v[148:149]
	v_pk_fma_f32 v[124:125], v[122:123], v[156:157], v[162:163]
	v_lshl_add_u64 v[148:149], s[6:7], 0, v[150:151]
	v_cvt_pk_bf16_f32 v122, v126, v127
	v_cvt_pk_bf16_f32 v123, v128, v129
	v_cvt_pk_bf16_f32 v124, v124, v125
	v_cvt_pk_bf16_f32 v125, v146, v147
	global_store_dwordx4 v[148:149], v[122:125], off sc1
	s_nop 1
	v_add_u32_e32 v122, 0x80, v0
	v_mov_b32_e32 v123, v1
	v_lshlrev_b64 v[126:127], 1, v[122:123]
	v_lshl_add_u64 v[122:123], s[40:41], 0, v[126:127]
	global_load_dwordx4 v[122:125], v[122:123], off
	s_waitcnt vmcnt(0)
	v_lshlrev_b32_e32 v128, 16, v122
	v_and_b32_e32 v129, 0xffff0000, v122
	v_lshlrev_b32_e32 v146, 16, v123
	v_and_b32_e32 v147, 0xffff0000, v123
	v_lshl_add_u64 v[122:123], s[42:43], 0, v[126:127]
	v_lshlrev_b32_e32 v148, 16, v124
	v_and_b32_e32 v149, 0xffff0000, v124
	v_lshlrev_b32_e32 v150, 16, v125
	v_and_b32_e32 v151, 0xffff0000, v125
	global_load_dwordx4 v[122:125], v[122:123], off
	s_waitcnt vmcnt(0)
	v_lshlrev_b32_e32 v152, 16, v122
	v_and_b32_e32 v153, 0xffff0000, v122
	v_lshlrev_b32_e32 v122, 16, v123
	v_and_b32_e32 v123, 0xffff0000, v123
	v_lshlrev_b32_e32 v154, 16, v124
	v_and_b32_e32 v155, 0xffff0000, v124
	v_lshlrev_b32_e32 v124, 16, v125
	v_and_b32_e32 v125, 0xffff0000, v125
	v_pk_fma_f32 v[120:121], v[120:121], v[146:147], v[122:123]
	v_pk_fma_f32 v[118:119], v[118:119], v[128:129], v[152:153]
	v_pk_fma_f32 v[122:123], v[116:117], v[150:151], v[124:125]
	v_pk_fma_f32 v[116:117], v[114:115], v[148:149], v[154:155]
	v_lshl_add_u64 v[124:125], s[6:7], 0, v[126:127]
	v_cvt_pk_bf16_f32 v114, v118, v119
	v_cvt_pk_bf16_f32 v115, v120, v121
	v_cvt_pk_bf16_f32 v116, v116, v117
	v_cvt_pk_bf16_f32 v117, v122, v123
	global_store_dwordx4 v[124:125], v[114:117], off sc1
	s_nop 1
	v_add_u32_e32 v114, 0x4000, v0
	v_mov_b32_e32 v115, v1
	v_lshlrev_b64 v[118:119], 1, v[114:115]
	v_lshl_add_u64 v[114:115], s[40:41], 0, v[118:119]
	global_load_dwordx4 v[114:117], v[114:115], off
	s_waitcnt vmcnt(0)
	v_lshlrev_b32_e32 v120, 16, v114
	v_and_b32_e32 v121, 0xffff0000, v114
	v_lshlrev_b32_e32 v122, 16, v115
	v_and_b32_e32 v123, 0xffff0000, v115
	v_lshl_add_u64 v[114:115], s[42:43], 0, v[118:119]
	v_lshlrev_b32_e32 v124, 16, v116
	v_and_b32_e32 v125, 0xffff0000, v116
	v_lshlrev_b32_e32 v126, 16, v117
	v_and_b32_e32 v127, 0xffff0000, v117
	global_load_dwordx4 v[114:117], v[114:115], off
	s_waitcnt vmcnt(0)
	v_lshlrev_b32_e32 v128, 16, v114
	v_and_b32_e32 v129, 0xffff0000, v114
	v_lshlrev_b32_e32 v114, 16, v115
	v_and_b32_e32 v115, 0xffff0000, v115
	v_lshlrev_b32_e32 v146, 16, v116
	v_and_b32_e32 v147, 0xffff0000, v116
	v_lshlrev_b32_e32 v116, 16, v117
	v_and_b32_e32 v117, 0xffff0000, v117
	v_pk_fma_f32 v[112:113], v[112:113], v[122:123], v[114:115]
	v_pk_fma_f32 v[110:111], v[110:111], v[120:121], v[128:129]
	v_pk_fma_f32 v[114:115], v[108:109], v[126:127], v[116:117]
	v_pk_fma_f32 v[108:109], v[106:107], v[124:125], v[146:147]
	v_lshl_add_u64 v[116:117], s[6:7], 0, v[118:119]
	v_cvt_pk_bf16_f32 v106, v110, v111
	v_cvt_pk_bf16_f32 v107, v112, v113
	v_cvt_pk_bf16_f32 v108, v108, v109
	v_cvt_pk_bf16_f32 v109, v114, v115
	global_store_dwordx4 v[116:117], v[106:109], off sc1
	s_nop 1
	v_add_u32_e32 v106, 0x4080, v0
	v_mov_b32_e32 v107, v1
	v_lshlrev_b64 v[110:111], 1, v[106:107]
	v_lshl_add_u64 v[106:107], s[40:41], 0, v[110:111]
	global_load_dwordx4 v[106:109], v[106:107], off
	s_waitcnt vmcnt(0)
	v_lshlrev_b32_e32 v112, 16, v106
	v_and_b32_e32 v113, 0xffff0000, v106
	v_lshlrev_b32_e32 v114, 16, v107
	v_and_b32_e32 v115, 0xffff0000, v107
	v_lshl_add_u64 v[106:107], s[42:43], 0, v[110:111]
	v_lshlrev_b32_e32 v116, 16, v108
	v_and_b32_e32 v117, 0xffff0000, v108
	v_lshlrev_b32_e32 v118, 16, v109
	v_and_b32_e32 v119, 0xffff0000, v109
	global_load_dwordx4 v[106:109], v[106:107], off
	s_waitcnt vmcnt(0)
	v_lshlrev_b32_e32 v120, 16, v106
	v_and_b32_e32 v121, 0xffff0000, v106
	v_lshlrev_b32_e32 v106, 16, v107
	v_and_b32_e32 v107, 0xffff0000, v107
	v_lshlrev_b32_e32 v122, 16, v108
	v_and_b32_e32 v123, 0xffff0000, v108
	v_lshlrev_b32_e32 v108, 16, v109
	v_and_b32_e32 v109, 0xffff0000, v109
	v_pk_fma_f32 v[104:105], v[104:105], v[114:115], v[106:107]
	v_pk_fma_f32 v[102:103], v[102:103], v[112:113], v[120:121]
	v_pk_fma_f32 v[106:107], v[100:101], v[118:119], v[108:109]
	v_pk_fma_f32 v[100:101], v[98:99], v[116:117], v[122:123]
	v_lshl_add_u64 v[108:109], s[6:7], 0, v[110:111]
	v_cvt_pk_bf16_f32 v98, v102, v103
	v_cvt_pk_bf16_f32 v99, v104, v105
	v_cvt_pk_bf16_f32 v100, v100, v101
	v_cvt_pk_bf16_f32 v101, v106, v107
	global_store_dwordx4 v[108:109], v[98:101], off sc1
	s_nop 1
	v_add_u32_e32 v98, 0x8000, v0
	v_mov_b32_e32 v99, v1
	v_lshlrev_b64 v[102:103], 1, v[98:99]
	v_lshl_add_u64 v[98:99], s[40:41], 0, v[102:103]
	global_load_dwordx4 v[98:101], v[98:99], off
	s_waitcnt vmcnt(0)
; __device__ __forceinline__ void st8(bf16_t* p, f32x4 a, f32x4 b) { u32x4 w; w.x = pk2(a[0], a[1]); w.y = pk2(a[2], a[3]); w.z = pk2(b[0], b[1]); w.w = pk2(b[2], b[3]); *(u32x4*)p = w; }
; __device__ __forceinline__ void ld8(const bf16_t* p, f32x4& a, f32x4& b) { const u32x4 w = *(const u32x4*)p; a[0] = bflo(w.x); a[1] = bfhi(w.x); a[2] = bflo(w.y); a[3] = bfhi(w.y); b[0] = bflo(w.z); b[1] = bfhi(w.z); b[2] = bflo(w.w); b[3] = bfhi(w.w); }
;     __device__ __forceinline__ void operator()(ACC_T, const pg8::Unit& u, int wr, int wc, int fr, int fq) const {
;         const int row0 = u.pm * 256 + wr * 64 + fr, col0 = u.pn * 256 + wc * 32 + 8 * fq;
; #pragma unroll
;         for (int ai = 0; ai < 2; ++ai)
; #pragma unroll
;             for (int m = 0; m < 4; ++m) { const int row = row0 + ai * 128 + m * 16;
; #pragma unroll
;                 for (int bj = 0; bj < 2; ++bj) { const unsigned off = (unsigned)row * 1024u + col0 + bj * 128; f32x4 g0, g1; ld8(G + off, g0, g1);
;                     f32x4 v0 = acc[ai][bj][m][0] * g0, v1 = acc[ai][bj][m][1] * g1;
;                     if (MODE == 1) { f32x4 p0, p1; ld8(P + off, p0, p1); v0 += p0; v1 += p1; }
;                     st8(O + off, v0, v1); }
;                 asm volatile("" ::: "memory"); }
;     }
	v_lshlrev_b32_e32 v104, 16, v98
	v_and_b32_e32 v105, 0xffff0000, v98
	v_lshlrev_b32_e32 v106, 16, v99
	v_and_b32_e32 v107, 0xffff0000, v99
	v_lshl_add_u64 v[98:99], s[42:43], 0, v[102:103]
	v_lshlrev_b32_e32 v108, 16, v100
	v_and_b32_e32 v109, 0xffff0000, v100
	v_lshlrev_b32_e32 v110, 16, v101
	v_and_b32_e32 v111, 0xffff0000, v101
	global_load_dwordx4 v[98:101], v[98:99], off
	s_waitcnt vmcnt(0)
	v_lshlrev_b32_e32 v112, 16, v98
	v_and_b32_e32 v113, 0xffff0000, v98
	v_lshlrev_b32_e32 v98, 16, v99
	v_and_b32_e32 v99, 0xffff0000, v99
	v_lshlrev_b32_e32 v114, 16, v100
	v_and_b32_e32 v115, 0xffff0000, v100
	v_lshlrev_b32_e32 v100, 16, v101
	v_and_b32_e32 v101, 0xffff0000, v101
	v_pk_fma_f32 v[96:97], v[96:97], v[106:107], v[98:99]
	v_pk_fma_f32 v[94:95], v[94:95], v[104:105], v[112:113]
	v_pk_fma_f32 v[98:99], v[92:93], v[110:111], v[100:101]
	v_pk_fma_f32 v[92:93], v[90:91], v[108:109], v[114:115]
	v_lshl_add_u64 v[100:101], s[6:7], 0, v[102:103]
	v_cvt_pk_bf16_f32 v90, v94, v95
	v_cvt_pk_bf16_f32 v91, v96, v97
	v_cvt_pk_bf16_f32 v92, v92, v93
	v_cvt_pk_bf16_f32 v93, v98, v99
	global_store_dwordx4 v[100:101], v[90:93], off sc1
	s_nop 1
	v_add_u32_e32 v90, 0x8080, v0
	v_mov_b32_e32 v91, v1
	v_lshlrev_b64 v[94:95], 1, v[90:91]
	v_lshl_add_u64 v[90:91], s[40:41], 0, v[94:95]
	global_load_dwordx4 v[90:93], v[90:91], off
	s_waitcnt vmcnt(0)
	v_lshlrev_b32_e32 v96, 16, v90
	v_and_b32_e32 v97, 0xffff0000, v90
	v_lshlrev_b32_e32 v98, 16, v91
	v_and_b32_e32 v99, 0xffff0000, v91
	v_lshl_add_u64 v[90:91], s[42:43], 0, v[94:95]
	v_lshlrev_b32_e32 v100, 16, v92
	v_and_b32_e32 v101, 0xffff0000, v92
	v_lshlrev_b32_e32 v102, 16, v93
	v_and_b32_e32 v103, 0xffff0000, v93
	global_load_dwordx4 v[90:93], v[90:91], off
	s_waitcnt vmcnt(0)
	v_lshlrev_b32_e32 v104, 16, v90
	v_and_b32_e32 v105, 0xffff0000, v90
	v_lshlrev_b32_e32 v90, 16, v91
	v_and_b32_e32 v91, 0xffff0000, v91
	v_lshlrev_b32_e32 v106, 16, v92
	v_and_b32_e32 v107, 0xffff0000, v92
	v_lshlrev_b32_e32 v92, 16, v93
	v_and_b32_e32 v93, 0xffff0000, v93
	v_pk_fma_f32 v[88:89], v[88:89], v[98:99], v[90:91]
	v_pk_fma_f32 v[86:87], v[86:87], v[96:97], v[104:105]
	v_pk_fma_f32 v[90:91], v[84:85], v[102:103], v[92:93]
	v_pk_fma_f32 v[84:85], v[82:83], v[100:101], v[106:107]
	v_lshl_add_u64 v[92:93], s[6:7], 0, v[94:95]
	v_cvt_pk_bf16_f32 v82, v86, v87
	v_cvt_pk_bf16_f32 v83, v88, v89
	v_cvt_pk_bf16_f32 v84, v84, v85
	v_cvt_pk_bf16_f32 v85, v90, v91
	global_store_dwordx4 v[92:93], v[82:85], off sc1
	s_nop 1
	v_add_u32_e32 v82, 0xc000, v0
	v_mov_b32_e32 v83, v1
	v_lshlrev_b64 v[86:87], 1, v[82:83]
	v_lshl_add_u64 v[82:83], s[40:41], 0, v[86:87]
	global_load_dwordx4 v[82:85], v[82:83], off
	s_waitcnt vmcnt(0)
	v_lshlrev_b32_e32 v88, 16, v82
	v_and_b32_e32 v89, 0xffff0000, v82
	v_lshlrev_b32_e32 v90, 16, v83
	v_and_b32_e32 v91, 0xffff0000, v83
	v_lshl_add_u64 v[82:83], s[42:43], 0, v[86:87]
	v_lshlrev_b32_e32 v92, 16, v84
	v_and_b32_e32 v93, 0xffff0000, v84
	v_lshlrev_b32_e32 v94, 16, v85
	v_and_b32_e32 v95, 0xffff0000, v85
	global_load_dwordx4 v[82:85], v[82:83], off
	s_waitcnt vmcnt(0)
	v_lshlrev_b32_e32 v96, 16, v82
	v_and_b32_e32 v97, 0xffff0000, v82
	v_lshlrev_b32_e32 v82, 16, v83
	v_and_b32_e32 v83, 0xffff0000, v83
	v_lshlrev_b32_e32 v98, 16, v84
	v_and_b32_e32 v99, 0xffff0000, v84
	v_lshlrev_b32_e32 v84, 16, v85
	v_and_b32_e32 v85, 0xffff0000, v85
	v_pk_fma_f32 v[80:81], v[80:81], v[90:91], v[82:83]
	v_pk_fma_f32 v[78:79], v[78:79], v[88:89], v[96:97]
	v_pk_fma_f32 v[82:83], v[76:77], v[94:95], v[84:85]
	v_pk_fma_f32 v[76:77], v[74:75], v[92:93], v[98:99]
	v_lshl_add_u64 v[84:85], s[6:7], 0, v[86:87]
	v_cvt_pk_bf16_f32 v74, v78, v79
	v_cvt_pk_bf16_f32 v75, v80, v81
	v_cvt_pk_bf16_f32 v76, v76, v77
	v_cvt_pk_bf16_f32 v77, v82, v83
	global_store_dwordx4 v[84:85], v[74:77], off sc1
	s_nop 1
	v_add_u32_e32 v74, 0xc080, v0
	v_mov_b32_e32 v75, v1
	v_lshlrev_b64 v[78:79], 1, v[74:75]
	v_lshl_add_u64 v[74:75], s[40:41], 0, v[78:79]
	global_load_dwordx4 v[74:77], v[74:75], off
	s_waitcnt vmcnt(0)
	v_lshlrev_b32_e32 v80, 16, v74
	v_and_b32_e32 v81, 0xffff0000, v74
	v_lshlrev_b32_e32 v82, 16, v75
	v_and_b32_e32 v83, 0xffff0000, v75
	v_lshl_add_u64 v[74:75], s[42:43], 0, v[78:79]
	v_lshlrev_b32_e32 v84, 16, v76
	v_and_b32_e32 v85, 0xffff0000, v76
	v_lshlrev_b32_e32 v86, 16, v77
	v_and_b32_e32 v87, 0xffff0000, v77
	global_load_dwordx4 v[74:77], v[74:75], off
	s_waitcnt vmcnt(0)
	v_lshlrev_b32_e32 v88, 16, v74
	v_and_b32_e32 v89, 0xffff0000, v74
	v_lshlrev_b32_e32 v74, 16, v75
	v_and_b32_e32 v75, 0xffff0000, v75
	v_lshlrev_b32_e32 v90, 16, v76
	v_and_b32_e32 v91, 0xffff0000, v76
	v_lshlrev_b32_e32 v76, 16, v77
	v_and_b32_e32 v77, 0xffff0000, v77
	v_pk_fma_f32 v[72:73], v[72:73], v[82:83], v[74:75]
	v_pk_fma_f32 v[70:71], v[70:71], v[80:81], v[88:89]
	v_pk_fma_f32 v[74:75], v[68:69], v[86:87], v[76:77]
	v_pk_fma_f32 v[68:69], v[66:67], v[84:85], v[90:91]
	v_lshl_add_u64 v[76:77], s[6:7], 0, v[78:79]
	v_cvt_pk_bf16_f32 v66, v70, v71
	v_cvt_pk_bf16_f32 v67, v72, v73
	v_cvt_pk_bf16_f32 v68, v68, v69
	v_cvt_pk_bf16_f32 v69, v74, v75
	global_store_dwordx4 v[76:77], v[66:69], off sc1
	s_nop 1
	v_add_u32_e32 v66, 0x20000, v0
	v_mov_b32_e32 v67, v1
	v_lshlrev_b64 v[70:71], 1, v[66:67]
	v_lshl_add_u64 v[66:67], s[40:41], 0, v[70:71]
	global_load_dwordx4 v[66:69], v[66:67], off
	s_waitcnt vmcnt(0)
	v_lshlrev_b32_e32 v72, 16, v66
	v_and_b32_e32 v73, 0xffff0000, v66
	v_lshlrev_b32_e32 v74, 16, v67
	v_and_b32_e32 v75, 0xffff0000, v67
	v_lshl_add_u64 v[66:67], s[42:43], 0, v[70:71]
	v_lshlrev_b32_e32 v76, 16, v68
	v_and_b32_e32 v77, 0xffff0000, v68
	v_lshlrev_b32_e32 v78, 16, v69
	v_and_b32_e32 v79, 0xffff0000, v69
	global_load_dwordx4 v[66:69], v[66:67], off
	s_waitcnt vmcnt(0)
; __device__ __forceinline__ void st8(bf16_t* p, f32x4 a, f32x4 b) { u32x4 w; w.x = pk2(a[0], a[1]); w.y = pk2(a[2], a[3]); w.z = pk2(b[0], b[1]); w.w = pk2(b[2], b[3]); *(u32x4*)p = w; }
; __device__ __forceinline__ void ld8(const bf16_t* p, f32x4& a, f32x4& b) { const u32x4 w = *(const u32x4*)p; a[0] = bflo(w.x); a[1] = bfhi(w.x); a[2] = bflo(w.y); a[3] = bfhi(w.y); b[0] = bflo(w.z); b[1] = bfhi(w.z); b[2] = bflo(w.w); b[3] = bfhi(w.w); }
;     __device__ __forceinline__ void operator()(ACC_T, const pg8::Unit& u, int wr, int wc, int fr, int fq) const {
;         const int row0 = u.pm * 256 + wr * 64 + fr, col0 = u.pn * 256 + wc * 32 + 8 * fq;
; #pragma unroll
;         for (int ai = 0; ai < 2; ++ai)
; #pragma unroll
;             for (int m = 0; m < 4; ++m) { const int row = row0 + ai * 128 + m * 16;
; #pragma unroll
;                 for (int bj = 0; bj < 2; ++bj) { const unsigned off = (unsigned)row * 1024u + col0 + bj * 128; f32x4 g0, g1; ld8(G + off, g0, g1);
;                     f32x4 v0 = acc[ai][bj][m][0] * g0, v1 = acc[ai][bj][m][1] * g1;
;                     if (MODE == 1) { f32x4 p0, p1; ld8(P + off, p0, p1); v0 += p0; v1 += p1; }
;                     st8(O + off, v0, v1); }
;                 asm volatile("" ::: "memory"); }
;     }
	v_lshlrev_b32_e32 v80, 16, v66
	v_and_b32_e32 v81, 0xffff0000, v66
	v_lshlrev_b32_e32 v66, 16, v67
	v_and_b32_e32 v67, 0xffff0000, v67
	v_lshlrev_b32_e32 v82, 16, v68
	v_and_b32_e32 v83, 0xffff0000, v68
	v_lshlrev_b32_e32 v68, 16, v69
	v_and_b32_e32 v69, 0xffff0000, v69
	v_pk_fma_f32 v[64:65], v[64:65], v[74:75], v[66:67]
	v_pk_fma_f32 v[62:63], v[62:63], v[72:73], v[80:81]
	v_pk_fma_f32 v[66:67], v[60:61], v[78:79], v[68:69]
	v_pk_fma_f32 v[60:61], v[58:59], v[76:77], v[82:83]
	v_lshl_add_u64 v[68:69], s[6:7], 0, v[70:71]
	v_cvt_pk_bf16_f32 v58, v62, v63
	v_cvt_pk_bf16_f32 v59, v64, v65
	v_cvt_pk_bf16_f32 v60, v60, v61
	v_cvt_pk_bf16_f32 v61, v66, v67
	global_store_dwordx4 v[68:69], v[58:61], off sc1
	s_nop 1
	v_add_u32_e32 v58, 0x20080, v0
	v_mov_b32_e32 v59, v1
	v_lshlrev_b64 v[62:63], 1, v[58:59]
	v_lshl_add_u64 v[58:59], s[40:41], 0, v[62:63]
	global_load_dwordx4 v[58:61], v[58:59], off
	s_waitcnt vmcnt(0)
	v_lshlrev_b32_e32 v64, 16, v58
	v_and_b32_e32 v65, 0xffff0000, v58
	v_lshlrev_b32_e32 v66, 16, v59
	v_and_b32_e32 v67, 0xffff0000, v59
	v_lshl_add_u64 v[58:59], s[42:43], 0, v[62:63]
	v_lshlrev_b32_e32 v68, 16, v60
	v_and_b32_e32 v69, 0xffff0000, v60
	v_lshlrev_b32_e32 v70, 16, v61
	v_and_b32_e32 v71, 0xffff0000, v61
	global_load_dwordx4 v[58:61], v[58:59], off
	s_waitcnt vmcnt(0)
	v_lshlrev_b32_e32 v72, 16, v58
	v_and_b32_e32 v73, 0xffff0000, v58
	v_lshlrev_b32_e32 v58, 16, v59
	v_and_b32_e32 v59, 0xffff0000, v59
	v_lshlrev_b32_e32 v74, 16, v60
	v_and_b32_e32 v75, 0xffff0000, v60
	v_lshlrev_b32_e32 v60, 16, v61
	v_and_b32_e32 v61, 0xffff0000, v61
	v_pk_fma_f32 v[56:57], v[56:57], v[66:67], v[58:59]
	v_pk_fma_f32 v[54:55], v[54:55], v[64:65], v[72:73]
	v_pk_fma_f32 v[58:59], v[52:53], v[70:71], v[60:61]
	v_pk_fma_f32 v[52:53], v[50:51], v[68:69], v[74:75]
	v_lshl_add_u64 v[60:61], s[6:7], 0, v[62:63]
	v_cvt_pk_bf16_f32 v50, v54, v55
	v_cvt_pk_bf16_f32 v51, v56, v57
	v_cvt_pk_bf16_f32 v52, v52, v53
	v_cvt_pk_bf16_f32 v53, v58, v59
	global_store_dwordx4 v[60:61], v[50:53], off sc1
	s_nop 1
	v_add_u32_e32 v50, 0x24000, v0
	v_mov_b32_e32 v51, v1
	v_lshlrev_b64 v[54:55], 1, v[50:51]
	v_lshl_add_u64 v[50:51], s[40:41], 0, v[54:55]
	global_load_dwordx4 v[50:53], v[50:51], off
	s_waitcnt vmcnt(0)
	v_lshlrev_b32_e32 v56, 16, v50
	v_and_b32_e32 v57, 0xffff0000, v50
	v_lshlrev_b32_e32 v58, 16, v51
	v_and_b32_e32 v59, 0xffff0000, v51
	v_lshl_add_u64 v[50:51], s[42:43], 0, v[54:55]
	v_lshlrev_b32_e32 v60, 16, v52
	v_and_b32_e32 v61, 0xffff0000, v52
	v_lshlrev_b32_e32 v62, 16, v53
	v_and_b32_e32 v63, 0xffff0000, v53
	global_load_dwordx4 v[50:53], v[50:51], off
	s_waitcnt vmcnt(0)
	v_lshlrev_b32_e32 v64, 16, v50
	v_and_b32_e32 v65, 0xffff0000, v50
	v_lshlrev_b32_e32 v50, 16, v51
	v_and_b32_e32 v51, 0xffff0000, v51
	v_lshlrev_b32_e32 v66, 16, v52
	v_and_b32_e32 v67, 0xffff0000, v52
	v_lshlrev_b32_e32 v52, 16, v53
	v_and_b32_e32 v53, 0xffff0000, v53
	v_pk_fma_f32 v[48:49], v[48:49], v[58:59], v[50:51]
	v_pk_fma_f32 v[46:47], v[46:47], v[56:57], v[64:65]
	v_pk_fma_f32 v[50:51], v[44:45], v[62:63], v[52:53]
	v_pk_fma_f32 v[44:45], v[42:43], v[60:61], v[66:67]
	v_lshl_add_u64 v[52:53], s[6:7], 0, v[54:55]
	v_cvt_pk_bf16_f32 v42, v46, v47
	v_cvt_pk_bf16_f32 v43, v48, v49
	v_cvt_pk_bf16_f32 v44, v44, v45
	v_cvt_pk_bf16_f32 v45, v50, v51
	global_store_dwordx4 v[52:53], v[42:45], off sc1
	s_nop 1
	v_add_u32_e32 v42, 0x24080, v0
	v_mov_b32_e32 v43, v1
	v_lshlrev_b64 v[46:47], 1, v[42:43]
	v_lshl_add_u64 v[42:43], s[40:41], 0, v[46:47]
	global_load_dwordx4 v[42:45], v[42:43], off
	s_waitcnt vmcnt(0)
	v_lshlrev_b32_e32 v48, 16, v42
	v_and_b32_e32 v49, 0xffff0000, v42
	v_lshlrev_b32_e32 v50, 16, v43
	v_and_b32_e32 v51, 0xffff0000, v43
	v_lshl_add_u64 v[42:43], s[42:43], 0, v[46:47]
	v_lshlrev_b32_e32 v52, 16, v44
	v_and_b32_e32 v53, 0xffff0000, v44
	v_lshlrev_b32_e32 v54, 16, v45
	v_and_b32_e32 v55, 0xffff0000, v45
	global_load_dwordx4 v[42:45], v[42:43], off
	s_waitcnt vmcnt(0)
	v_lshlrev_b32_e32 v56, 16, v42
	v_and_b32_e32 v57, 0xffff0000, v42
	v_lshlrev_b32_e32 v42, 16, v43
	v_and_b32_e32 v43, 0xffff0000, v43
	v_lshlrev_b32_e32 v58, 16, v44
	v_and_b32_e32 v59, 0xffff0000, v44
	v_lshlrev_b32_e32 v44, 16, v45
	v_and_b32_e32 v45, 0xffff0000, v45
	v_pk_fma_f32 v[40:41], v[40:41], v[50:51], v[42:43]
	v_pk_fma_f32 v[38:39], v[38:39], v[48:49], v[56:57]
	v_pk_fma_f32 v[42:43], v[36:37], v[54:55], v[44:45]
	v_pk_fma_f32 v[36:37], v[34:35], v[52:53], v[58:59]
	v_lshl_add_u64 v[44:45], s[6:7], 0, v[46:47]
	v_cvt_pk_bf16_f32 v34, v38, v39
	v_cvt_pk_bf16_f32 v35, v40, v41
	v_cvt_pk_bf16_f32 v36, v36, v37
	v_cvt_pk_bf16_f32 v37, v42, v43
	global_store_dwordx4 v[44:45], v[34:37], off sc1
	s_nop 1
	v_add_u32_e32 v34, 0x28000, v0
	v_mov_b32_e32 v35, v1
	v_lshlrev_b64 v[38:39], 1, v[34:35]
	v_lshl_add_u64 v[34:35], s[40:41], 0, v[38:39]
	global_load_dwordx4 v[34:37], v[34:35], off
	s_waitcnt vmcnt(0)
; __device__ __forceinline__ void st8(bf16_t* p, f32x4 a, f32x4 b) { u32x4 w; w.x = pk2(a[0], a[1]); w.y = pk2(a[2], a[3]); w.z = pk2(b[0], b[1]); w.w = pk2(b[2], b[3]); *(u32x4*)p = w; }
; __device__ __forceinline__ void ld8(const bf16_t* p, f32x4& a, f32x4& b) { const u32x4 w = *(const u32x4*)p; a[0] = bflo(w.x); a[1] = bfhi(w.x); a[2] = bflo(w.y); a[3] = bfhi(w.y); b[0] = bflo(w.z); b[1] = bfhi(w.z); b[2] = bflo(w.w); b[3] = bfhi(w.w); }
;     __device__ __forceinline__ void operator()(ACC_T, const pg8::Unit& u, int wr, int wc, int fr, int fq) const {
;         const int row0 = u.pm * 256 + wr * 64 + fr, col0 = u.pn * 256 + wc * 32 + 8 * fq;
; #pragma unroll
;         for (int ai = 0; ai < 2; ++ai)
; #pragma unroll
;             for (int m = 0; m < 4; ++m) { const int row = row0 + ai * 128 + m * 16;
; #pragma unroll
;                 for (int bj = 0; bj < 2; ++bj) { const unsigned off = (unsigned)row * 1024u + col0 + bj * 128; f32x4 g0, g1; ld8(G + off, g0, g1);
;                     f32x4 v0 = acc[ai][bj][m][0] * g0, v1 = acc[ai][bj][m][1] * g1;
;                     if (MODE == 1) { f32x4 p0, p1; ld8(P + off, p0, p1); v0 += p0; v1 += p1; }
;                     st8(O + off, v0, v1); }
;                 asm volatile("" ::: "memory"); }
;     }
	v_lshlrev_b32_e32 v40, 16, v34
	v_and_b32_e32 v41, 0xffff0000, v34
	v_lshlrev_b32_e32 v42, 16, v35
	v_and_b32_e32 v43, 0xffff0000, v35
	v_lshl_add_u64 v[34:35], s[42:43], 0, v[38:39]
	v_lshlrev_b32_e32 v44, 16, v36
	v_and_b32_e32 v45, 0xffff0000, v36
	v_lshlrev_b32_e32 v46, 16, v37
	v_and_b32_e32 v47, 0xffff0000, v37
	global_load_dwordx4 v[34:37], v[34:35], off
	s_waitcnt vmcnt(0)
	v_lshlrev_b32_e32 v48, 16, v34
	v_and_b32_e32 v49, 0xffff0000, v34
	v_lshlrev_b32_e32 v34, 16, v35
	v_and_b32_e32 v35, 0xffff0000, v35
	v_lshlrev_b32_e32 v50, 16, v36
	v_and_b32_e32 v51, 0xffff0000, v36
	v_lshlrev_b32_e32 v36, 16, v37
	v_and_b32_e32 v37, 0xffff0000, v37
	v_pk_fma_f32 v[32:33], v[32:33], v[42:43], v[34:35]
	v_pk_fma_f32 v[30:31], v[30:31], v[40:41], v[48:49]
	v_pk_fma_f32 v[34:35], v[28:29], v[46:47], v[36:37]
	v_pk_fma_f32 v[28:29], v[26:27], v[44:45], v[50:51]
	v_lshl_add_u64 v[36:37], s[6:7], 0, v[38:39]
	v_cvt_pk_bf16_f32 v26, v30, v31
	v_cvt_pk_bf16_f32 v27, v32, v33
	v_cvt_pk_bf16_f32 v28, v28, v29
	v_cvt_pk_bf16_f32 v29, v34, v35
	global_store_dwordx4 v[36:37], v[26:29], off sc1
	s_nop 1
	v_add_u32_e32 v26, 0x28080, v0
	v_mov_b32_e32 v27, v1
	v_lshlrev_b64 v[30:31], 1, v[26:27]
	v_lshl_add_u64 v[26:27], s[40:41], 0, v[30:31]
	global_load_dwordx4 v[26:29], v[26:27], off
	s_waitcnt vmcnt(0)
	v_lshlrev_b32_e32 v32, 16, v26
	v_and_b32_e32 v33, 0xffff0000, v26
	v_lshlrev_b32_e32 v34, 16, v27
	v_and_b32_e32 v35, 0xffff0000, v27
	v_lshl_add_u64 v[26:27], s[42:43], 0, v[30:31]
	v_lshlrev_b32_e32 v36, 16, v28
	v_and_b32_e32 v37, 0xffff0000, v28
	v_lshlrev_b32_e32 v38, 16, v29
	v_and_b32_e32 v39, 0xffff0000, v29
	global_load_dwordx4 v[26:29], v[26:27], off
	s_waitcnt vmcnt(0)
	v_lshlrev_b32_e32 v40, 16, v26
	v_and_b32_e32 v41, 0xffff0000, v26
	v_lshlrev_b32_e32 v26, 16, v27
	v_and_b32_e32 v27, 0xffff0000, v27
	v_lshlrev_b32_e32 v42, 16, v28
	v_and_b32_e32 v43, 0xffff0000, v28
	v_lshlrev_b32_e32 v28, 16, v29
	v_and_b32_e32 v29, 0xffff0000, v29
	v_pk_fma_f32 v[24:25], v[24:25], v[34:35], v[26:27]
	v_pk_fma_f32 v[22:23], v[22:23], v[32:33], v[40:41]
	v_pk_fma_f32 v[26:27], v[20:21], v[38:39], v[28:29]
	v_pk_fma_f32 v[20:21], v[18:19], v[36:37], v[42:43]
	v_lshl_add_u64 v[28:29], s[6:7], 0, v[30:31]
	v_cvt_pk_bf16_f32 v18, v22, v23
	v_cvt_pk_bf16_f32 v19, v24, v25
	v_cvt_pk_bf16_f32 v20, v20, v21
	v_cvt_pk_bf16_f32 v21, v26, v27
	global_store_dwordx4 v[28:29], v[18:21], off sc1
	s_nop 1
	v_add_u32_e32 v18, 0x2c000, v0
	v_mov_b32_e32 v19, v1
	v_lshlrev_b64 v[22:23], 1, v[18:19]
	v_lshl_add_u64 v[18:19], s[40:41], 0, v[22:23]
	global_load_dwordx4 v[18:21], v[18:19], off
	v_add_u32_e32 v0, 0x2c080, v0
	s_waitcnt vmcnt(0)
	v_lshlrev_b32_e32 v24, 16, v18
	v_and_b32_e32 v25, 0xffff0000, v18
	v_lshlrev_b32_e32 v26, 16, v19
	v_and_b32_e32 v27, 0xffff0000, v19
	v_lshl_add_u64 v[18:19], s[42:43], 0, v[22:23]
	v_lshlrev_b32_e32 v28, 16, v20
	v_and_b32_e32 v29, 0xffff0000, v20
	v_lshlrev_b32_e32 v30, 16, v21
	v_and_b32_e32 v31, 0xffff0000, v21
	global_load_dwordx4 v[18:21], v[18:19], off
	s_waitcnt vmcnt(0)
	v_lshlrev_b32_e32 v32, 16, v18
	v_and_b32_e32 v33, 0xffff0000, v18
	v_lshlrev_b32_e32 v18, 16, v19
	v_and_b32_e32 v19, 0xffff0000, v19
	v_lshlrev_b32_e32 v34, 16, v20
	v_and_b32_e32 v35, 0xffff0000, v20
	v_lshlrev_b32_e32 v20, 16, v21
	v_and_b32_e32 v21, 0xffff0000, v21
	v_pk_fma_f32 v[16:17], v[16:17], v[26:27], v[18:19]
	v_pk_fma_f32 v[14:15], v[14:15], v[24:25], v[32:33]
	v_pk_fma_f32 v[18:19], v[12:13], v[30:31], v[20:21]
	v_pk_fma_f32 v[12:13], v[10:11], v[28:29], v[34:35]
	v_lshl_add_u64 v[20:21], s[6:7], 0, v[22:23]
	v_cvt_pk_bf16_f32 v10, v14, v15
	v_cvt_pk_bf16_f32 v11, v16, v17
	v_cvt_pk_bf16_f32 v12, v12, v13
	v_cvt_pk_bf16_f32 v13, v18, v19
	v_lshlrev_b64 v[14:15], 1, v[0:1]
	global_store_dwordx4 v[20:21], v[10:13], off sc1
	s_nop 1
	v_lshl_add_u64 v[10:11], s[40:41], 0, v[14:15]
	global_load_dwordx4 v[10:13], v[10:11], off
	s_waitcnt vmcnt(0)
	v_lshlrev_b32_e32 v16, 16, v10
	v_and_b32_e32 v17, 0xffff0000, v10
	v_lshlrev_b32_e32 v18, 16, v11
	v_and_b32_e32 v19, 0xffff0000, v11
	v_lshl_add_u64 v[10:11], s[42:43], 0, v[14:15]
	v_lshlrev_b32_e32 v20, 16, v12
	v_and_b32_e32 v21, 0xffff0000, v12
	v_lshlrev_b32_e32 v22, 16, v13
	v_and_b32_e32 v23, 0xffff0000, v13
	global_load_dwordx4 v[10:13], v[10:11], off
	s_waitcnt vmcnt(0)
	v_lshlrev_b32_e32 v24, 16, v10
	v_and_b32_e32 v25, 0xffff0000, v10
	v_lshlrev_b32_e32 v10, 16, v11
	v_and_b32_e32 v11, 0xffff0000, v11
	v_lshlrev_b32_e32 v26, 16, v12
	v_and_b32_e32 v27, 0xffff0000, v12
	v_lshlrev_b32_e32 v12, 16, v13
	v_and_b32_e32 v13, 0xffff0000, v13
	v_pk_fma_f32 v[8:9], v[8:9], v[18:19], v[10:11]
	v_pk_fma_f32 v[6:7], v[6:7], v[16:17], v[24:25]
	v_pk_fma_f32 v[10:11], v[4:5], v[22:23], v[12:13]
	v_pk_fma_f32 v[4:5], v[2:3], v[20:21], v[26:27]
	v_lshl_add_u64 v[12:13], s[6:7], 0, v[14:15]
	v_cvt_pk_bf16_f32 v2, v6, v7
	v_cvt_pk_bf16_f32 v3, v8, v9
	v_cvt_pk_bf16_f32 v4, v4, v5
	v_cvt_pk_bf16_f32 v5, v10, v11
	global_store_dwordx4 v[12:13], v[2:5], off sc1
	s_andn2_b64 vcc, exec, s[38:39]
	s_mov_b64 s[8:9], -1
	s_cbranch_vccnz .LBB0_1054
	s_andn2_b64 vcc, exec, s[4:5]
	s_cbranch_vccnz .LBB0_1053
	s_barrier
	s_branch .LBB0_1053

; __device__ __forceinline__ void st8(bf16_t* p, f32x4 a, f32x4 b) { u32x4 w; w.x = pk2(a[0], a[1]); w.y = pk2(a[2], a[3]); w.z = pk2(b[0], b[1]); w.w = pk2(b[2], b[3]); *(u32x4*)p = w; }
; __device__ __forceinline__ float dot4(f32x4 a) { return (a[0] * a[0] + a[1] * a[1]) + (a[2] * a[2] + a[3] * a[3]); }
;     __device__ __forceinline__ void operator()(ACC_T, const pg8::Unit& u, int wr, int wc, int fr, int fq) const {
;         const int row0 = u.pm * 256 + wr * 64 + fr, col0 = u.pn * 256 + wc * 32 + 8 * fq;
; #pragma unroll
;         for (int ai = 0; ai < 2; ++ai)
; #pragma unroll
;             for (int m = 0; m < 4; ++m) { const int row = row0 + ai * 128 + m * 16; float s = 0.f;
; #pragma unroll
;                 for (int bj = 0; bj < 2; ++bj) { const f32x4 v0 = acc[ai][bj][m][0], v1 = acc[ai][bj][m][1]; st8(O + (unsigned)row * (unsigned)ldc + col0 + bj * 128, v0, v1); s += dot4(v0) + dot4(v1); }
;                 s += __shfl_xor(s, 16); s += __shfl_xor(s, 32);
;                 if (fq == 0) ssq[(u.pn * 4 + wc) * TT + tbase + row] = s; }
;     }
.LBB0_1143:
	v_mov_b32_e32 v0, v145
	v_mov_b32_e32 v151, v144
	s_lshl_b32 s2, s86, 8
	s_add_i32 s2, s2, s37
	v_cmp_lt_i32_e32 vcc, v245, v238
	v_add_u32_e32 v150, s2, v0
	s_lshl_b32 s2, s84, 8
	v_cndmask_b32_e32 v0, v236, v245, vcc
	v_cmp_lt_i32_e32 vcc, v246, v238
	s_or_b32 s2, s2, s44
	v_lshlrev_b32_e32 v149, 2, v0
	v_cndmask_b32_e32 v0, v236, v246, vcc
	v_lshl_add_u32 v142, v151, 3, s2
	v_lshlrev_b32_e32 v148, 2, v0
	v_lshlrev_b32_e32 v0, 10, v150
	v_ashrrev_i32_e32 v143, 31, v142
	v_lshl_add_u64 v[152:153], v[0:1], 1, s[6:7]
	v_mul_f32_e32 v0, v127, v127
	v_lshl_add_u64 v[156:157], v[142:143], 1, v[152:153]
	v_cvt_pk_bf16_f32 v152, v126, v127
	v_fmac_f32_e32 v0, v126, v126
	v_mul_f32_e32 v126, v129, v129
	v_fmac_f32_e32 v126, v128, v128
	v_add_f32_e32 v0, v0, v126
	v_mul_f32_e32 v126, v123, v123
	v_mul_f32_e32 v127, v125, v125
	v_fmac_f32_e32 v126, v122, v122
	v_fmac_f32_e32 v127, v124, v124
	v_add_f32_e32 v126, v126, v127
	v_add_f32_e32 v0, v0, v126
	v_mul_f32_e32 v126, v119, v119
	v_mul_f32_e32 v127, v121, v121
	v_fmac_f32_e32 v126, v118, v118
	v_fmac_f32_e32 v127, v120, v120
	v_cvt_pk_bf16_f32 v153, v128, v129
	v_add_f32_e32 v126, v126, v127
	v_mul_f32_e32 v127, v115, v115
	v_mul_f32_e32 v128, v117, v117
	v_fmac_f32_e32 v127, v114, v114
	v_fmac_f32_e32 v128, v116, v116
	v_add_f32_e32 v127, v127, v128
	v_add_f32_e32 v126, v126, v127
	v_add_f32_e32 v0, v0, v126
	ds_bpermute_b32 v126, v149, v0
	v_cvt_pk_bf16_f32 v154, v122, v123
	v_cvt_pk_bf16_f32 v122, v118, v119
	s_lshl_b32 s2, s84, 18
	v_cmp_eq_u32_e32 vcc, 0, v151
	s_waitcnt lgkmcnt(0)
	v_add_f32_e32 v0, v0, v126
	ds_bpermute_b32 v118, v148, v0
	s_or_b32 s10, s2, s61
	v_cvt_pk_bf16_f32 v155, v124, v125
	v_cvt_pk_bf16_f32 v123, v120, v121
	v_cvt_pk_bf16_f32 v124, v114, v115
	v_cvt_pk_bf16_f32 v125, v116, v117
	global_store_dwordx4 v[156:157], v[152:155], off sc1
	global_store_dwordx4 v[156:157], v[122:125], off offset:256 sc1
	s_and_saveexec_b64 s[8:9], vcc
	s_cbranch_execz .LBB0_1145
	s_add_i32 s2, s10, s78
	v_add_u32_e32 v114, s2, v150
	v_ashrrev_i32_e32 v115, 31, v114
	s_waitcnt lgkmcnt(0)
	v_add_f32_e32 v0, v0, v118
	v_lshl_add_u64 v[114:115], v[114:115], 2, s[40:41]
	global_store_dword v[114:115], v0, off sc1
.LBB0_1145:
	s_or_b64 exec, exec, s[8:9]
	v_add_u32_e32 v114, 16, v150
	v_lshlrev_b32_e32 v0, 10, v114
	v_lshl_add_u64 v[116:117], v[0:1], 1, s[6:7]
	v_mul_f32_e32 v0, v111, v111
	v_lshl_add_u64 v[120:121], v[142:143], 1, v[116:117]
	v_cvt_pk_bf16_f32 v116, v110, v111
	v_fmac_f32_e32 v0, v110, v110
	v_mul_f32_e32 v110, v113, v113
	v_fmac_f32_e32 v110, v112, v112
	v_add_f32_e32 v0, v0, v110
	v_mul_f32_e32 v110, v107, v107
	v_mul_f32_e32 v111, v109, v109
	v_fmac_f32_e32 v110, v106, v106
	v_fmac_f32_e32 v111, v108, v108
	v_add_f32_e32 v110, v110, v111
	v_add_f32_e32 v0, v0, v110
	v_mul_f32_e32 v110, v103, v103
	v_mul_f32_e32 v111, v105, v105
	v_fmac_f32_e32 v110, v102, v102
	v_fmac_f32_e32 v111, v104, v104
	v_cvt_pk_bf16_f32 v117, v112, v113
	v_add_f32_e32 v110, v110, v111
	v_mul_f32_e32 v111, v99, v99
	v_mul_f32_e32 v112, v101, v101
	v_fmac_f32_e32 v111, v98, v98
	v_fmac_f32_e32 v112, v100, v100
	v_add_f32_e32 v111, v111, v112
	v_add_f32_e32 v110, v110, v111
	v_add_f32_e32 v0, v0, v110
	ds_bpermute_b32 v110, v149, v0
	s_waitcnt lgkmcnt(0)
	v_cvt_pk_bf16_f32 v118, v106, v107
	v_cvt_pk_bf16_f32 v106, v102, v103
	v_cvt_pk_bf16_f32 v119, v108, v109
	v_cvt_pk_bf16_f32 v107, v104, v105
	v_add_f32_e32 v0, v0, v110
	ds_bpermute_b32 v102, v148, v0
	v_cvt_pk_bf16_f32 v108, v98, v99
	v_cvt_pk_bf16_f32 v109, v100, v101
	global_store_dwordx4 v[120:121], v[116:119], off sc1
	global_store_dwordx4 v[120:121], v[106:109], off offset:256 sc1
	s_and_saveexec_b64 s[8:9], vcc
	s_cbranch_execz .LBB0_1147
	s_add_i32 s2, s10, s78
	v_add_u32_e32 v98, s2, v114
	v_ashrrev_i32_e32 v99, 31, v98
	s_waitcnt lgkmcnt(0)
	v_add_f32_e32 v0, v0, v102
	v_lshl_add_u64 v[98:99], v[98:99], 2, s[40:41]
	global_store_dword v[98:99], v0, off sc1
.LBB0_1147:
	s_or_b64 exec, exec, s[8:9]
	v_add_u32_e32 v98, 32, v150
	v_lshlrev_b32_e32 v0, 10, v98
	v_lshl_add_u64 v[100:101], v[0:1], 1, s[6:7]
	v_mul_f32_e32 v0, v95, v95
	v_lshl_add_u64 v[104:105], v[142:143], 1, v[100:101]
	v_cvt_pk_bf16_f32 v100, v94, v95
	v_fmac_f32_e32 v0, v94, v94
	v_mul_f32_e32 v94, v97, v97
	v_fmac_f32_e32 v94, v96, v96
	v_add_f32_e32 v0, v0, v94
	v_mul_f32_e32 v94, v91, v91
	v_mul_f32_e32 v95, v93, v93
	v_fmac_f32_e32 v94, v90, v90
	v_fmac_f32_e32 v95, v92, v92
	v_add_f32_e32 v94, v94, v95
	v_add_f32_e32 v0, v0, v94
	v_mul_f32_e32 v94, v87, v87
	v_mul_f32_e32 v95, v89, v89
	v_fmac_f32_e32 v94, v86, v86
	v_fmac_f32_e32 v95, v88, v88
	v_cvt_pk_bf16_f32 v101, v96, v97
	v_add_f32_e32 v94, v94, v95
	v_mul_f32_e32 v95, v83, v83
	v_mul_f32_e32 v96, v85, v85
	v_fmac_f32_e32 v95, v82, v82
	v_fmac_f32_e32 v96, v84, v84
	v_add_f32_e32 v95, v95, v96
	v_add_f32_e32 v94, v94, v95
	v_add_f32_e32 v0, v0, v94
	ds_bpermute_b32 v94, v149, v0
	s_waitcnt lgkmcnt(0)
	v_cvt_pk_bf16_f32 v102, v90, v91
	v_cvt_pk_bf16_f32 v90, v86, v87
	v_cvt_pk_bf16_f32 v103, v92, v93
	v_cvt_pk_bf16_f32 v91, v88, v89
	v_add_f32_e32 v0, v0, v94
	ds_bpermute_b32 v86, v148, v0
	v_cvt_pk_bf16_f32 v92, v82, v83
	v_cvt_pk_bf16_f32 v93, v84, v85
	global_store_dwordx4 v[104:105], v[100:103], off sc1
	global_store_dwordx4 v[104:105], v[90:93], off offset:256 sc1
	s_and_saveexec_b64 s[8:9], vcc
	s_cbranch_execz .LBB0_1149
	s_add_i32 s2, s10, s78
	v_add_u32_e32 v82, s2, v98
	v_ashrrev_i32_e32 v83, 31, v82
	s_waitcnt lgkmcnt(0)
	v_add_f32_e32 v0, v0, v86
	v_lshl_add_u64 v[82:83], v[82:83], 2, s[40:41]
	global_store_dword v[82:83], v0, off sc1
; __device__ __forceinline__ void st8(bf16_t* p, f32x4 a, f32x4 b) { u32x4 w; w.x = pk2(a[0], a[1]); w.y = pk2(a[2], a[3]); w.z = pk2(b[0], b[1]); w.w = pk2(b[2], b[3]); *(u32x4*)p = w; }
; __device__ __forceinline__ float dot4(f32x4 a) { return (a[0] * a[0] + a[1] * a[1]) + (a[2] * a[2] + a[3] * a[3]); }
;     __device__ __forceinline__ void operator()(ACC_T, const pg8::Unit& u, int wr, int wc, int fr, int fq) const {
;     ...
;             for (int m = 0; m < 4; ++m) { const int row = row0 + ai * 128 + m * 16; float s = 0.f;
; #pragma unroll
;                 for (int bj = 0; bj < 2; ++bj) { const f32x4 v0 = acc[ai][bj][m][0], v1 = acc[ai][bj][m][1]; st8(O + (unsigned)row * (unsigned)ldc + col0 + bj * 128, v0, v1); s += dot4(v0) + dot4(v1); }
;                 s += __shfl_xor(s, 16); s += __shfl_xor(s, 32);
;                 if (fq == 0) ssq[(u.pn * 4 + wc) * TT + tbase + row] = s; }
.LBB0_1149:
	s_or_b64 exec, exec, s[8:9]
	v_add_u32_e32 v82, 48, v150
	v_lshlrev_b32_e32 v0, 10, v82
	v_lshl_add_u64 v[84:85], v[0:1], 1, s[6:7]
	v_mul_f32_e32 v0, v79, v79
	v_lshl_add_u64 v[88:89], v[142:143], 1, v[84:85]
	v_cvt_pk_bf16_f32 v84, v78, v79
	v_fmac_f32_e32 v0, v78, v78
	v_mul_f32_e32 v78, v81, v81
	v_fmac_f32_e32 v78, v80, v80
	v_add_f32_e32 v0, v0, v78
	v_mul_f32_e32 v78, v75, v75
	v_mul_f32_e32 v79, v77, v77
	v_fmac_f32_e32 v78, v74, v74
	v_fmac_f32_e32 v79, v76, v76
	v_add_f32_e32 v78, v78, v79
	v_add_f32_e32 v0, v0, v78
	v_mul_f32_e32 v78, v71, v71
	v_mul_f32_e32 v79, v73, v73
	v_fmac_f32_e32 v78, v70, v70
	v_fmac_f32_e32 v79, v72, v72
	v_cvt_pk_bf16_f32 v85, v80, v81
	v_add_f32_e32 v78, v78, v79
	v_mul_f32_e32 v79, v67, v67
	v_mul_f32_e32 v80, v69, v69
	v_fmac_f32_e32 v79, v66, v66
	v_fmac_f32_e32 v80, v68, v68
	v_add_f32_e32 v79, v79, v80
	v_add_f32_e32 v78, v78, v79
	v_add_f32_e32 v0, v0, v78
	ds_bpermute_b32 v78, v149, v0
	s_waitcnt lgkmcnt(0)
	v_cvt_pk_bf16_f32 v86, v74, v75
	v_cvt_pk_bf16_f32 v74, v70, v71
	v_cvt_pk_bf16_f32 v87, v76, v77
	v_cvt_pk_bf16_f32 v75, v72, v73
	v_add_f32_e32 v0, v0, v78
	ds_bpermute_b32 v70, v148, v0
	v_cvt_pk_bf16_f32 v76, v66, v67
	v_cvt_pk_bf16_f32 v77, v68, v69
	global_store_dwordx4 v[88:89], v[84:87], off sc1
	global_store_dwordx4 v[88:89], v[74:77], off offset:256 sc1
	s_and_saveexec_b64 s[8:9], vcc
	s_cbranch_execz .LBB0_1151
	s_add_i32 s2, s10, s78
	v_add_u32_e32 v66, s2, v82
	v_ashrrev_i32_e32 v67, 31, v66
	s_waitcnt lgkmcnt(0)
	v_add_f32_e32 v0, v0, v70
	v_lshl_add_u64 v[66:67], v[66:67], 2, s[40:41]
	global_store_dword v[66:67], v0, off sc1
.LBB0_1151:
	s_or_b64 exec, exec, s[8:9]
	v_add_u32_e32 v66, 0x80, v150
	v_lshlrev_b32_e32 v0, 10, v66
	v_lshl_add_u64 v[68:69], v[0:1], 1, s[6:7]
	v_mul_f32_e32 v0, v63, v63
	v_lshl_add_u64 v[72:73], v[142:143], 1, v[68:69]
	v_cvt_pk_bf16_f32 v68, v62, v63
	v_fmac_f32_e32 v0, v62, v62
	v_mul_f32_e32 v62, v65, v65
	v_fmac_f32_e32 v62, v64, v64
	v_add_f32_e32 v0, v0, v62
	v_mul_f32_e32 v62, v59, v59
	v_mul_f32_e32 v63, v61, v61
	v_fmac_f32_e32 v62, v58, v58
	v_fmac_f32_e32 v63, v60, v60
	v_add_f32_e32 v62, v62, v63
	v_add_f32_e32 v0, v0, v62
	v_mul_f32_e32 v62, v55, v55
	v_mul_f32_e32 v63, v57, v57
	v_fmac_f32_e32 v62, v54, v54
	v_fmac_f32_e32 v63, v56, v56
	v_cvt_pk_bf16_f32 v69, v64, v65
	v_add_f32_e32 v62, v62, v63
	v_mul_f32_e32 v63, v51, v51
	v_mul_f32_e32 v64, v53, v53
	v_fmac_f32_e32 v63, v50, v50
	v_fmac_f32_e32 v64, v52, v52
	v_add_f32_e32 v63, v63, v64
	v_add_f32_e32 v62, v62, v63
	v_add_f32_e32 v0, v0, v62
	ds_bpermute_b32 v62, v149, v0
	s_waitcnt lgkmcnt(0)
	v_cvt_pk_bf16_f32 v70, v58, v59
	v_cvt_pk_bf16_f32 v58, v54, v55
	v_cvt_pk_bf16_f32 v71, v60, v61
	v_cvt_pk_bf16_f32 v59, v56, v57
	v_add_f32_e32 v0, v0, v62
	ds_bpermute_b32 v54, v148, v0
	v_cvt_pk_bf16_f32 v60, v50, v51
	v_cvt_pk_bf16_f32 v61, v52, v53
	global_store_dwordx4 v[72:73], v[68:71], off sc1
	global_store_dwordx4 v[72:73], v[58:61], off offset:256 sc1
	s_and_saveexec_b64 s[8:9], vcc
	s_cbranch_execz .LBB0_1153
	s_add_i32 s2, s10, s78
	v_add_u32_e32 v50, s2, v66
	v_ashrrev_i32_e32 v51, 31, v50
	s_waitcnt lgkmcnt(0)
	v_add_f32_e32 v0, v0, v54
	v_lshl_add_u64 v[50:51], v[50:51], 2, s[40:41]
	global_store_dword v[50:51], v0, off sc1
; __device__ __forceinline__ void st8(bf16_t* p, f32x4 a, f32x4 b) { u32x4 w; w.x = pk2(a[0], a[1]); w.y = pk2(a[2], a[3]); w.z = pk2(b[0], b[1]); w.w = pk2(b[2], b[3]); *(u32x4*)p = w; }
; __device__ __forceinline__ float dot4(f32x4 a) { return (a[0] * a[0] + a[1] * a[1]) + (a[2] * a[2] + a[3] * a[3]); }
;     __device__ __forceinline__ void operator()(ACC_T, const pg8::Unit& u, int wr, int wc, int fr, int fq) const {
;     ...
;             for (int m = 0; m < 4; ++m) { const int row = row0 + ai * 128 + m * 16; float s = 0.f;
; #pragma unroll
;                 for (int bj = 0; bj < 2; ++bj) { const f32x4 v0 = acc[ai][bj][m][0], v1 = acc[ai][bj][m][1]; st8(O + (unsigned)row * (unsigned)ldc + col0 + bj * 128, v0, v1); s += dot4(v0) + dot4(v1); }
;                 s += __shfl_xor(s, 16); s += __shfl_xor(s, 32);
;                 if (fq == 0) ssq[(u.pn * 4 + wc) * TT + tbase + row] = s; }
.LBB0_1153:
	s_or_b64 exec, exec, s[8:9]
	v_add_u32_e32 v50, 0x90, v150
	v_lshlrev_b32_e32 v0, 10, v50
	v_lshl_add_u64 v[52:53], v[0:1], 1, s[6:7]
	v_mul_f32_e32 v0, v47, v47
	v_lshl_add_u64 v[56:57], v[142:143], 1, v[52:53]
	v_cvt_pk_bf16_f32 v52, v46, v47
	v_fmac_f32_e32 v0, v46, v46
	v_mul_f32_e32 v46, v49, v49
	v_fmac_f32_e32 v46, v48, v48
	v_add_f32_e32 v0, v0, v46
	v_mul_f32_e32 v46, v43, v43
	v_mul_f32_e32 v47, v45, v45
	v_fmac_f32_e32 v46, v42, v42
	v_fmac_f32_e32 v47, v44, v44
	v_add_f32_e32 v46, v46, v47
	v_add_f32_e32 v0, v0, v46
	v_mul_f32_e32 v46, v39, v39
	v_mul_f32_e32 v47, v41, v41
	v_fmac_f32_e32 v46, v38, v38
	v_fmac_f32_e32 v47, v40, v40
	v_cvt_pk_bf16_f32 v53, v48, v49
	v_add_f32_e32 v46, v46, v47
	v_mul_f32_e32 v47, v35, v35
	v_mul_f32_e32 v48, v37, v37
	v_fmac_f32_e32 v47, v34, v34
	v_fmac_f32_e32 v48, v36, v36
	v_add_f32_e32 v47, v47, v48
	v_add_f32_e32 v46, v46, v47
	v_add_f32_e32 v0, v0, v46
	ds_bpermute_b32 v46, v149, v0
	s_waitcnt lgkmcnt(0)
	v_cvt_pk_bf16_f32 v54, v42, v43
	v_cvt_pk_bf16_f32 v42, v38, v39
	v_cvt_pk_bf16_f32 v55, v44, v45
	v_cvt_pk_bf16_f32 v43, v40, v41
	v_add_f32_e32 v0, v0, v46
	ds_bpermute_b32 v38, v148, v0
	v_cvt_pk_bf16_f32 v44, v34, v35
	v_cvt_pk_bf16_f32 v45, v36, v37
	global_store_dwordx4 v[56:57], v[52:55], off sc1
	global_store_dwordx4 v[56:57], v[42:45], off offset:256 sc1
	s_and_saveexec_b64 s[8:9], vcc
	s_cbranch_execz .LBB0_1155
	s_add_i32 s2, s10, s78
	v_add_u32_e32 v34, s2, v50
	v_ashrrev_i32_e32 v35, 31, v34
	s_waitcnt lgkmcnt(0)
	v_add_f32_e32 v0, v0, v38
	v_lshl_add_u64 v[34:35], v[34:35], 2, s[40:41]
	global_store_dword v[34:35], v0, off sc1
.LBB0_1155:
	s_or_b64 exec, exec, s[8:9]
	v_add_u32_e32 v34, 0xa0, v150
	v_lshlrev_b32_e32 v0, 10, v34
	v_lshl_add_u64 v[36:37], v[0:1], 1, s[6:7]
	v_mul_f32_e32 v0, v31, v31
	v_lshl_add_u64 v[40:41], v[142:143], 1, v[36:37]
	v_cvt_pk_bf16_f32 v36, v30, v31
	v_fmac_f32_e32 v0, v30, v30
	v_mul_f32_e32 v30, v33, v33
	v_fmac_f32_e32 v30, v32, v32
	v_add_f32_e32 v0, v0, v30
	v_mul_f32_e32 v30, v27, v27
	v_mul_f32_e32 v31, v29, v29
	v_fmac_f32_e32 v30, v26, v26
	v_fmac_f32_e32 v31, v28, v28
	v_add_f32_e32 v30, v30, v31
	v_add_f32_e32 v0, v0, v30
	v_mul_f32_e32 v30, v23, v23
	v_mul_f32_e32 v31, v25, v25
	v_fmac_f32_e32 v30, v22, v22
	v_fmac_f32_e32 v31, v24, v24
	v_cvt_pk_bf16_f32 v37, v32, v33
	v_add_f32_e32 v30, v30, v31
	v_mul_f32_e32 v31, v19, v19
	v_mul_f32_e32 v32, v21, v21
	v_fmac_f32_e32 v31, v18, v18
	v_fmac_f32_e32 v32, v20, v20
	v_add_f32_e32 v31, v31, v32
	v_add_f32_e32 v30, v30, v31
	v_add_f32_e32 v0, v0, v30
	ds_bpermute_b32 v30, v149, v0
	s_waitcnt lgkmcnt(0)
	v_cvt_pk_bf16_f32 v38, v26, v27
	v_cvt_pk_bf16_f32 v26, v22, v23
	v_cvt_pk_bf16_f32 v39, v28, v29
	v_cvt_pk_bf16_f32 v27, v24, v25
	v_add_f32_e32 v0, v0, v30
	ds_bpermute_b32 v22, v148, v0
	v_cvt_pk_bf16_f32 v28, v18, v19
	v_cvt_pk_bf16_f32 v29, v20, v21
	global_store_dwordx4 v[40:41], v[36:39], off sc1
	global_store_dwordx4 v[40:41], v[26:29], off offset:256 sc1
	s_and_saveexec_b64 s[8:9], vcc
	s_cbranch_execz .LBB0_1157
	s_add_i32 s2, s10, s78
	v_add_u32_e32 v18, s2, v34
	v_ashrrev_i32_e32 v19, 31, v18
	s_waitcnt lgkmcnt(0)
	v_add_f32_e32 v0, v0, v22
	v_lshl_add_u64 v[18:19], v[18:19], 2, s[40:41]
	global_store_dword v[18:19], v0, off sc1
.LBB0_1157:
	s_or_b64 exec, exec, s[8:9]
	v_add_u32_e32 v18, 0xb0, v150
	v_lshlrev_b32_e32 v0, 10, v18
	v_lshl_add_u64 v[20:21], v[0:1], 1, s[6:7]
	v_mul_f32_e32 v0, v15, v15
	v_lshl_add_u64 v[24:25], v[142:143], 1, v[20:21]
	v_cvt_pk_bf16_f32 v20, v14, v15
	v_fmac_f32_e32 v0, v14, v14
	v_mul_f32_e32 v14, v17, v17
	v_fmac_f32_e32 v14, v16, v16
	v_add_f32_e32 v0, v0, v14
	v_mul_f32_e32 v14, v11, v11
	v_mul_f32_e32 v15, v13, v13
	v_fmac_f32_e32 v14, v10, v10
	v_fmac_f32_e32 v15, v12, v12
	v_add_f32_e32 v14, v14, v15
	v_add_f32_e32 v0, v0, v14
	v_mul_f32_e32 v14, v7, v7
	v_mul_f32_e32 v15, v9, v9
	v_fmac_f32_e32 v14, v6, v6
	v_fmac_f32_e32 v15, v8, v8
	v_cvt_pk_bf16_f32 v21, v16, v17
	v_add_f32_e32 v14, v14, v15
	v_mul_f32_e32 v15, v3, v3
	v_mul_f32_e32 v16, v5, v5
	v_fmac_f32_e32 v15, v2, v2
	v_fmac_f32_e32 v16, v4, v4
	v_add_f32_e32 v15, v15, v16
	v_add_f32_e32 v14, v14, v15
	v_add_f32_e32 v0, v0, v14
	ds_bpermute_b32 v14, v149, v0
	s_waitcnt lgkmcnt(0)
	v_cvt_pk_bf16_f32 v22, v10, v11
	v_cvt_pk_bf16_f32 v10, v6, v7
	v_cvt_pk_bf16_f32 v23, v12, v13
	v_cvt_pk_bf16_f32 v11, v8, v9
	v_add_f32_e32 v0, v0, v14
	ds_bpermute_b32 v6, v148, v0
	v_cvt_pk_bf16_f32 v12, v2, v3
	v_cvt_pk_bf16_f32 v13, v4, v5
	global_store_dwordx4 v[24:25], v[20:23], off sc1
	global_store_dwordx4 v[24:25], v[10:13], off offset:256 sc1
	s_and_saveexec_b64 s[8:9], vcc
	s_cbranch_execz .LBB0_1159
	s_add_i32 s10, s10, s78
	v_add_u32_e32 v2, s10, v18
	v_ashrrev_i32_e32 v3, 31, v2
	s_waitcnt lgkmcnt(0)
	v_add_f32_e32 v0, v0, v6
	v_lshl_add_u64 v[2:3], v[2:3], 2, s[40:41]
	global_store_dword v[2:3], v0, off sc1

; __device__ __forceinline__ void st8(bf16_t* p, f32x4 a, f32x4 b) { u32x4 w; w.x = pk2(a[0], a[1]); w.y = pk2(a[2], a[3]); w.z = pk2(b[0], b[1]); w.w = pk2(b[2], b[3]); *(u32x4*)p = w; }
;     __device__ __forceinline__ void operator()(ACC_T, const pg8::Unit& u, int wr, int wc, int fr, int fq) const {
;         const int row0 = u.pm * 256 + wr * 64 + fr, col0 = u.pn * 256 + wc * 32 + 8 * fq;
; #pragma unroll
;         for (int ai = 0; ai < 2; ++ai)
; #pragma unroll
;             for (int m = 0; m < 4; ++m) { const int row = row0 + ai * 128 + m * 16;
; #pragma unroll
;                 for (int bj = 0; bj < 2; ++bj) { f32x4 v0 = acc[ai][bj][m][0], v1 = acc[ai][bj][m][1];
; #pragma unroll
;                     for (int e = 0; e < 4; ++e) { const float a = fmaxf(v0[e], 0.f), b = fmaxf(v1[e], 0.f); v0[e] = a * a; v1[e] = b * b; }
;                     st8(O + (unsigned)row * (unsigned)ldc + col0 + bj * 128, v0, v1); } }
;     }
.LBB0_1292:
	v_max_f32_e32 v122, v122, v122
	v_max_f32_e32 v123, v123, v123
	v_mov_b32_e32 v0, v142
	v_mov_b32_e32 v146, v143
	s_lshl_b32 s8, s68, 8
	v_max_f32_e32 v122, 0, v122
	v_max_f32_e32 v123, 0, v123
	s_lshl_b32 s2, s82, 8
	s_or_b32 s8, s8, s45
	v_pk_mul_f32 v[148:149], v[122:123], v[122:123]
	v_max_f32_e32 v123, v124, v124
	s_add_i32 s2, s2, s44
	v_lshl_add_u32 v146, v146, 3, s8
	v_max_f32_e32 v126, v126, v126
	v_max_f32_e32 v127, v127, v127
	v_max_f32_e32 v122, v128, v128
	v_max_f32_e32 v124, 0, v123
	v_max_f32_e32 v123, v129, v129
	v_max_f32_e32 v125, v125, v125
	v_ashrrev_i32_e32 v147, 31, v146
	v_max_f32_e32 v126, 0, v126
	v_max_f32_e32 v127, 0, v127
	v_max_f32_e32 v122, 0, v122
	v_max_f32_e32 v123, 0, v123
	v_max_f32_e32 v125, 0, v125
	v_add_lshl_u32 v0, s2, v0, 12
	v_pk_mul_f32 v[126:127], v[126:127], v[126:127]
	v_pk_mul_f32 v[128:129], v[122:123], v[122:123]
	v_pk_mul_f32 v[150:151], v[124:125], v[124:125]
	v_lshl_add_u64 v[124:125], v[0:1], 1, s[6:7]
	v_lshlrev_b64 v[122:123], 1, v[146:147]
	v_max_f32_e32 v114, v114, v114
	v_max_f32_e32 v115, v115, v115
	v_lshl_add_u64 v[146:147], v[124:125], 0, v[122:123]
	v_cvt_pk_bf16_f32 v124, v126, v127
	v_cvt_pk_bf16_f32 v125, v128, v129
	v_cvt_pk_bf16_f32 v126, v148, v149
	v_cvt_pk_bf16_f32 v127, v150, v151
	v_max_f32_e32 v114, 0, v114
	v_max_f32_e32 v115, 0, v115
	global_store_dwordx4 v[146:147], v[124:127], off sc1
	v_max_f32_e32 v118, v118, v118
	v_max_f32_e32 v119, v119, v119
	v_pk_mul_f32 v[124:125], v[114:115], v[114:115]
	v_max_f32_e32 v115, v116, v116
	v_max_f32_e32 v114, v120, v120
	v_max_f32_e32 v116, 0, v115
	v_max_f32_e32 v115, v121, v121
	v_max_f32_e32 v117, v117, v117
	v_max_f32_e32 v118, 0, v118
	v_max_f32_e32 v119, 0, v119
	v_max_f32_e32 v114, 0, v114
	v_max_f32_e32 v115, 0, v115
	v_max_f32_e32 v117, 0, v117
	v_pk_mul_f32 v[118:119], v[118:119], v[118:119]
	v_pk_mul_f32 v[120:121], v[114:115], v[114:115]
	v_pk_mul_f32 v[126:127], v[116:117], v[116:117]
	v_max_f32_e32 v106, v106, v106
	v_max_f32_e32 v107, v107, v107
	v_cvt_pk_bf16_f32 v114, v118, v119
	v_cvt_pk_bf16_f32 v115, v120, v121
	v_cvt_pk_bf16_f32 v116, v124, v125
	v_cvt_pk_bf16_f32 v117, v126, v127
	v_max_f32_e32 v106, 0, v106
	v_max_f32_e32 v107, 0, v107
	global_store_dwordx4 v[146:147], v[114:117], off offset:256 sc1
	v_max_f32_e32 v110, v110, v110
	v_max_f32_e32 v111, v111, v111
	v_pk_mul_f32 v[114:115], v[106:107], v[106:107]
	v_max_f32_e32 v107, v108, v108
	v_max_f32_e32 v106, v112, v112
	v_max_f32_e32 v108, 0, v107
	v_max_f32_e32 v107, v113, v113
	v_max_f32_e32 v106, 0, v106
	v_max_f32_e32 v107, 0, v107
	v_max_f32_e32 v109, v109, v109
	v_max_f32_e32 v110, 0, v110
	v_max_f32_e32 v111, 0, v111
	v_max_f32_e32 v109, 0, v109
	v_pk_mul_f32 v[112:113], v[106:107], v[106:107]
	v_add_u32_e32 v106, 0x10000, v0
	v_mov_b32_e32 v107, v1
	v_pk_mul_f32 v[110:111], v[110:111], v[110:111]
	v_pk_mul_f32 v[116:117], v[108:109], v[108:109]
	v_lshl_add_u64 v[106:107], v[106:107], 1, s[6:7]
	v_max_f32_e32 v98, v98, v98
	v_max_f32_e32 v99, v99, v99
	v_lshl_add_u64 v[118:119], v[106:107], 0, v[122:123]
	v_cvt_pk_bf16_f32 v106, v110, v111
	v_cvt_pk_bf16_f32 v107, v112, v113
	v_cvt_pk_bf16_f32 v108, v114, v115
	v_cvt_pk_bf16_f32 v109, v116, v117
	v_max_f32_e32 v98, 0, v98
	v_max_f32_e32 v99, 0, v99
	global_store_dwordx4 v[118:119], v[106:109], off sc1
	v_max_f32_e32 v102, v102, v102
	v_max_f32_e32 v103, v103, v103
	v_pk_mul_f32 v[106:107], v[98:99], v[98:99]
	v_max_f32_e32 v99, v100, v100
	v_max_f32_e32 v98, v104, v104
	v_max_f32_e32 v100, 0, v99
	v_max_f32_e32 v99, v105, v105
	v_max_f32_e32 v101, v101, v101
	v_max_f32_e32 v102, 0, v102
	v_max_f32_e32 v103, 0, v103
	v_max_f32_e32 v98, 0, v98
	v_max_f32_e32 v99, 0, v99
	v_max_f32_e32 v101, 0, v101
	v_pk_mul_f32 v[102:103], v[102:103], v[102:103]
	v_pk_mul_f32 v[104:105], v[98:99], v[98:99]
	v_pk_mul_f32 v[108:109], v[100:101], v[100:101]
	v_max_f32_e32 v90, v90, v90
	v_max_f32_e32 v91, v91, v91
	v_cvt_pk_bf16_f32 v98, v102, v103
	v_cvt_pk_bf16_f32 v99, v104, v105
	v_cvt_pk_bf16_f32 v100, v106, v107
	v_cvt_pk_bf16_f32 v101, v108, v109
	v_max_f32_e32 v90, 0, v90
	v_max_f32_e32 v91, 0, v91
	global_store_dwordx4 v[118:119], v[98:101], off offset:256 sc1
	v_max_f32_e32 v94, v94, v94
	v_max_f32_e32 v95, v95, v95
	v_pk_mul_f32 v[98:99], v[90:91], v[90:91]
	v_max_f32_e32 v91, v92, v92
	v_max_f32_e32 v90, v96, v96
	v_max_f32_e32 v92, 0, v91
	v_max_f32_e32 v91, v97, v97
	v_max_f32_e32 v90, 0, v90
	v_max_f32_e32 v91, 0, v91
	v_max_f32_e32 v93, v93, v93
	v_max_f32_e32 v94, 0, v94
	v_max_f32_e32 v95, 0, v95
	v_max_f32_e32 v93, 0, v93
	v_pk_mul_f32 v[96:97], v[90:91], v[90:91]
	v_add_u32_e32 v90, 0x20000, v0
	v_mov_b32_e32 v91, v1
	v_pk_mul_f32 v[94:95], v[94:95], v[94:95]
	v_pk_mul_f32 v[100:101], v[92:93], v[92:93]
	v_lshl_add_u64 v[90:91], v[90:91], 1, s[6:7]
	v_max_f32_e32 v82, v82, v82
	v_max_f32_e32 v83, v83, v83
	v_lshl_add_u64 v[102:103], v[90:91], 0, v[122:123]
	v_cvt_pk_bf16_f32 v90, v94, v95
	v_cvt_pk_bf16_f32 v91, v96, v97
	v_cvt_pk_bf16_f32 v92, v98, v99
	v_cvt_pk_bf16_f32 v93, v100, v101
	v_max_f32_e32 v82, 0, v82
	v_max_f32_e32 v83, 0, v83
	global_store_dwordx4 v[102:103], v[90:93], off sc1
	v_max_f32_e32 v86, v86, v86
	v_max_f32_e32 v87, v87, v87
	v_pk_mul_f32 v[90:91], v[82:83], v[82:83]
	v_max_f32_e32 v83, v84, v84
	v_max_f32_e32 v82, v88, v88
	v_max_f32_e32 v84, 0, v83
	v_max_f32_e32 v83, v89, v89
	v_max_f32_e32 v85, v85, v85
	v_max_f32_e32 v86, 0, v86
	v_max_f32_e32 v87, 0, v87
	v_max_f32_e32 v82, 0, v82
	v_max_f32_e32 v83, 0, v83
	v_max_f32_e32 v85, 0, v85
	v_pk_mul_f32 v[86:87], v[86:87], v[86:87]
	v_pk_mul_f32 v[88:89], v[82:83], v[82:83]
	v_pk_mul_f32 v[92:93], v[84:85], v[84:85]
; __device__ __forceinline__ void st8(bf16_t* p, f32x4 a, f32x4 b) { u32x4 w; w.x = pk2(a[0], a[1]); w.y = pk2(a[2], a[3]); w.z = pk2(b[0], b[1]); w.w = pk2(b[2], b[3]); *(u32x4*)p = w; }
;     __device__ __forceinline__ void operator()(ACC_T, const pg8::Unit& u, int wr, int wc, int fr, int fq) const {
;         const int row0 = u.pm * 256 + wr * 64 + fr, col0 = u.pn * 256 + wc * 32 + 8 * fq;
; #pragma unroll
;         for (int ai = 0; ai < 2; ++ai)
; #pragma unroll
;             for (int m = 0; m < 4; ++m) { const int row = row0 + ai * 128 + m * 16;
; #pragma unroll
;                 for (int bj = 0; bj < 2; ++bj) { f32x4 v0 = acc[ai][bj][m][0], v1 = acc[ai][bj][m][1];
; #pragma unroll
;                     for (int e = 0; e < 4; ++e) { const float a = fmaxf(v0[e], 0.f), b = fmaxf(v1[e], 0.f); v0[e] = a * a; v1[e] = b * b; }
;                     st8(O + (unsigned)row * (unsigned)ldc + col0 + bj * 128, v0, v1); } }
;     }
	v_max_f32_e32 v74, v74, v74
	v_max_f32_e32 v75, v75, v75
	v_cvt_pk_bf16_f32 v82, v86, v87
	v_cvt_pk_bf16_f32 v83, v88, v89
	v_cvt_pk_bf16_f32 v84, v90, v91
	v_cvt_pk_bf16_f32 v85, v92, v93
	v_max_f32_e32 v74, 0, v74
	v_max_f32_e32 v75, 0, v75
	global_store_dwordx4 v[102:103], v[82:85], off offset:256 sc1
	v_max_f32_e32 v78, v78, v78
	v_max_f32_e32 v79, v79, v79
	v_pk_mul_f32 v[82:83], v[74:75], v[74:75]
	v_max_f32_e32 v75, v76, v76
	v_max_f32_e32 v74, v80, v80
	v_max_f32_e32 v76, 0, v75
	v_max_f32_e32 v75, v81, v81
	v_max_f32_e32 v74, 0, v74
	v_max_f32_e32 v75, 0, v75
	v_max_f32_e32 v77, v77, v77
	v_max_f32_e32 v78, 0, v78
	v_max_f32_e32 v79, 0, v79
	v_max_f32_e32 v77, 0, v77
	v_pk_mul_f32 v[80:81], v[74:75], v[74:75]
	v_add_u32_e32 v74, 0x30000, v0
	v_mov_b32_e32 v75, v1
	v_pk_mul_f32 v[78:79], v[78:79], v[78:79]
	v_pk_mul_f32 v[84:85], v[76:77], v[76:77]
	v_lshl_add_u64 v[74:75], v[74:75], 1, s[6:7]
	v_max_f32_e32 v66, v66, v66
	v_max_f32_e32 v67, v67, v67
	v_lshl_add_u64 v[86:87], v[74:75], 0, v[122:123]
	v_cvt_pk_bf16_f32 v74, v78, v79
	v_cvt_pk_bf16_f32 v75, v80, v81
	v_cvt_pk_bf16_f32 v76, v82, v83
	v_cvt_pk_bf16_f32 v77, v84, v85
	v_max_f32_e32 v66, 0, v66
	v_max_f32_e32 v67, 0, v67
	global_store_dwordx4 v[86:87], v[74:77], off sc1
	v_max_f32_e32 v70, v70, v70
	v_max_f32_e32 v71, v71, v71
	v_pk_mul_f32 v[74:75], v[66:67], v[66:67]
	v_max_f32_e32 v67, v68, v68
	v_max_f32_e32 v66, v72, v72
	v_max_f32_e32 v68, 0, v67
	v_max_f32_e32 v67, v73, v73
	v_max_f32_e32 v69, v69, v69
	v_max_f32_e32 v70, 0, v70
	v_max_f32_e32 v71, 0, v71
	v_max_f32_e32 v66, 0, v66
	v_max_f32_e32 v67, 0, v67
	v_max_f32_e32 v69, 0, v69
	v_pk_mul_f32 v[70:71], v[70:71], v[70:71]
	v_pk_mul_f32 v[72:73], v[66:67], v[66:67]
	v_pk_mul_f32 v[76:77], v[68:69], v[68:69]
	v_max_f32_e32 v58, v58, v58
	v_max_f32_e32 v59, v59, v59
	v_cvt_pk_bf16_f32 v66, v70, v71
	v_cvt_pk_bf16_f32 v67, v72, v73
	v_cvt_pk_bf16_f32 v68, v74, v75
	v_cvt_pk_bf16_f32 v69, v76, v77
	v_max_f32_e32 v58, 0, v58
	v_max_f32_e32 v59, 0, v59
	global_store_dwordx4 v[86:87], v[66:69], off offset:256 sc1
	v_max_f32_e32 v62, v62, v62
	v_max_f32_e32 v63, v63, v63
	v_pk_mul_f32 v[66:67], v[58:59], v[58:59]
	v_max_f32_e32 v59, v60, v60
	v_max_f32_e32 v58, v64, v64
	v_max_f32_e32 v60, 0, v59
	v_max_f32_e32 v59, v65, v65
	v_max_f32_e32 v58, 0, v58
	v_max_f32_e32 v59, 0, v59
	v_max_f32_e32 v61, v61, v61
	v_max_f32_e32 v62, 0, v62
	v_max_f32_e32 v63, 0, v63
	v_max_f32_e32 v61, 0, v61
	v_pk_mul_f32 v[64:65], v[58:59], v[58:59]
	v_add_u32_e32 v58, 0x80000, v0
	v_mov_b32_e32 v59, v1
	v_pk_mul_f32 v[62:63], v[62:63], v[62:63]
	v_pk_mul_f32 v[68:69], v[60:61], v[60:61]
	v_lshl_add_u64 v[58:59], v[58:59], 1, s[6:7]
	v_max_f32_e32 v50, v50, v50
	v_max_f32_e32 v51, v51, v51
	v_lshl_add_u64 v[70:71], v[58:59], 0, v[122:123]
	v_cvt_pk_bf16_f32 v58, v62, v63
	v_cvt_pk_bf16_f32 v59, v64, v65
	v_cvt_pk_bf16_f32 v60, v66, v67
	v_cvt_pk_bf16_f32 v61, v68, v69
	v_max_f32_e32 v50, 0, v50
	v_max_f32_e32 v51, 0, v51
	global_store_dwordx4 v[70:71], v[58:61], off sc1
	v_max_f32_e32 v54, v54, v54
	v_max_f32_e32 v55, v55, v55
	v_pk_mul_f32 v[58:59], v[50:51], v[50:51]
	v_max_f32_e32 v51, v52, v52
	v_max_f32_e32 v50, v56, v56
	v_max_f32_e32 v52, 0, v51
	v_max_f32_e32 v51, v57, v57
	v_max_f32_e32 v53, v53, v53
	v_max_f32_e32 v54, 0, v54
	v_max_f32_e32 v55, 0, v55
	v_max_f32_e32 v50, 0, v50
	v_max_f32_e32 v51, 0, v51
	v_max_f32_e32 v53, 0, v53
	v_pk_mul_f32 v[54:55], v[54:55], v[54:55]
	v_pk_mul_f32 v[56:57], v[50:51], v[50:51]
	v_pk_mul_f32 v[60:61], v[52:53], v[52:53]
	v_max_f32_e32 v42, v42, v42
	v_max_f32_e32 v43, v43, v43
	v_cvt_pk_bf16_f32 v50, v54, v55
	v_cvt_pk_bf16_f32 v51, v56, v57
	v_cvt_pk_bf16_f32 v52, v58, v59
	v_cvt_pk_bf16_f32 v53, v60, v61
	v_max_f32_e32 v42, 0, v42
	v_max_f32_e32 v43, 0, v43
	global_store_dwordx4 v[70:71], v[50:53], off offset:256 sc1
	v_max_f32_e32 v46, v46, v46
	v_max_f32_e32 v47, v47, v47
	v_pk_mul_f32 v[50:51], v[42:43], v[42:43]
	v_max_f32_e32 v43, v44, v44
	v_max_f32_e32 v42, v48, v48
	v_max_f32_e32 v44, 0, v43
	v_max_f32_e32 v43, v49, v49
	v_max_f32_e32 v42, 0, v42
	v_max_f32_e32 v43, 0, v43
	v_max_f32_e32 v45, v45, v45
	v_max_f32_e32 v46, 0, v46
	v_max_f32_e32 v47, 0, v47
	v_max_f32_e32 v45, 0, v45
	v_pk_mul_f32 v[48:49], v[42:43], v[42:43]
	v_add_u32_e32 v42, 0x90000, v0
	v_mov_b32_e32 v43, v1
	v_pk_mul_f32 v[46:47], v[46:47], v[46:47]
	v_pk_mul_f32 v[52:53], v[44:45], v[44:45]
	v_lshl_add_u64 v[42:43], v[42:43], 1, s[6:7]
	v_max_f32_e32 v34, v34, v34
	v_max_f32_e32 v35, v35, v35
	v_lshl_add_u64 v[54:55], v[42:43], 0, v[122:123]
; __device__ __forceinline__ void st8(bf16_t* p, f32x4 a, f32x4 b) { u32x4 w; w.x = pk2(a[0], a[1]); w.y = pk2(a[2], a[3]); w.z = pk2(b[0], b[1]); w.w = pk2(b[2], b[3]); *(u32x4*)p = w; }
;     __device__ __forceinline__ void operator()(ACC_T, const pg8::Unit& u, int wr, int wc, int fr, int fq) const {
;         const int row0 = u.pm * 256 + wr * 64 + fr, col0 = u.pn * 256 + wc * 32 + 8 * fq;
; #pragma unroll
;         for (int ai = 0; ai < 2; ++ai)
; #pragma unroll
;             for (int m = 0; m < 4; ++m) { const int row = row0 + ai * 128 + m * 16;
; #pragma unroll
;                 for (int bj = 0; bj < 2; ++bj) { f32x4 v0 = acc[ai][bj][m][0], v1 = acc[ai][bj][m][1];
; #pragma unroll
;                     for (int e = 0; e < 4; ++e) { const float a = fmaxf(v0[e], 0.f), b = fmaxf(v1[e], 0.f); v0[e] = a * a; v1[e] = b * b; }
;                     st8(O + (unsigned)row * (unsigned)ldc + col0 + bj * 128, v0, v1); } }
;     }
	v_cvt_pk_bf16_f32 v42, v46, v47
	v_cvt_pk_bf16_f32 v43, v48, v49
	v_cvt_pk_bf16_f32 v44, v50, v51
	v_cvt_pk_bf16_f32 v45, v52, v53
	v_max_f32_e32 v34, 0, v34
	v_max_f32_e32 v35, 0, v35
	global_store_dwordx4 v[54:55], v[42:45], off sc1
	v_max_f32_e32 v38, v38, v38
	v_max_f32_e32 v39, v39, v39
	v_pk_mul_f32 v[42:43], v[34:35], v[34:35]
	v_max_f32_e32 v35, v36, v36
	v_max_f32_e32 v34, v40, v40
	v_max_f32_e32 v36, 0, v35
	v_max_f32_e32 v35, v41, v41
	v_max_f32_e32 v37, v37, v37
	v_max_f32_e32 v38, 0, v38
	v_max_f32_e32 v39, 0, v39
	v_max_f32_e32 v34, 0, v34
	v_max_f32_e32 v35, 0, v35
	v_max_f32_e32 v37, 0, v37
	v_pk_mul_f32 v[38:39], v[38:39], v[38:39]
	v_pk_mul_f32 v[40:41], v[34:35], v[34:35]
	v_pk_mul_f32 v[44:45], v[36:37], v[36:37]
	v_max_f32_e32 v26, v26, v26
	v_max_f32_e32 v27, v27, v27
	v_cvt_pk_bf16_f32 v34, v38, v39
	v_cvt_pk_bf16_f32 v35, v40, v41
	v_cvt_pk_bf16_f32 v36, v42, v43
	v_cvt_pk_bf16_f32 v37, v44, v45
	v_max_f32_e32 v26, 0, v26
	v_max_f32_e32 v27, 0, v27
	global_store_dwordx4 v[54:55], v[34:37], off offset:256 sc1
	v_max_f32_e32 v30, v30, v30
	v_max_f32_e32 v31, v31, v31
	v_pk_mul_f32 v[34:35], v[26:27], v[26:27]
	v_max_f32_e32 v27, v28, v28
	v_max_f32_e32 v26, v32, v32
	v_max_f32_e32 v28, 0, v27
	v_max_f32_e32 v27, v33, v33
	v_max_f32_e32 v26, 0, v26
	v_max_f32_e32 v27, 0, v27
	v_max_f32_e32 v29, v29, v29
	v_max_f32_e32 v30, 0, v30
	v_max_f32_e32 v31, 0, v31
	v_max_f32_e32 v29, 0, v29
	v_pk_mul_f32 v[32:33], v[26:27], v[26:27]
	v_add_u32_e32 v26, 0xa0000, v0
	v_mov_b32_e32 v27, v1
	v_pk_mul_f32 v[30:31], v[30:31], v[30:31]
	v_pk_mul_f32 v[36:37], v[28:29], v[28:29]
	v_lshl_add_u64 v[26:27], v[26:27], 1, s[6:7]
	v_max_f32_e32 v18, v18, v18
	v_max_f32_e32 v19, v19, v19
	v_lshl_add_u64 v[38:39], v[26:27], 0, v[122:123]
	v_cvt_pk_bf16_f32 v26, v30, v31
	v_cvt_pk_bf16_f32 v27, v32, v33
	v_cvt_pk_bf16_f32 v28, v34, v35
	v_cvt_pk_bf16_f32 v29, v36, v37
	v_max_f32_e32 v18, 0, v18
	v_max_f32_e32 v19, 0, v19
	global_store_dwordx4 v[38:39], v[26:29], off sc1
	v_max_f32_e32 v22, v22, v22
	v_max_f32_e32 v23, v23, v23
	v_pk_mul_f32 v[26:27], v[18:19], v[18:19]
	v_max_f32_e32 v19, v20, v20
	v_max_f32_e32 v18, v24, v24
	v_max_f32_e32 v20, 0, v19
	v_max_f32_e32 v19, v25, v25
	v_max_f32_e32 v21, v21, v21
	v_max_f32_e32 v22, 0, v22
	v_max_f32_e32 v23, 0, v23
	v_max_f32_e32 v18, 0, v18
	v_max_f32_e32 v19, 0, v19
	v_max_f32_e32 v21, 0, v21
	v_pk_mul_f32 v[22:23], v[22:23], v[22:23]
	v_pk_mul_f32 v[24:25], v[18:19], v[18:19]
	v_pk_mul_f32 v[28:29], v[20:21], v[20:21]
	v_max_f32_e32 v10, v10, v10
	v_max_f32_e32 v11, v11, v11
	v_cvt_pk_bf16_f32 v18, v22, v23
	v_cvt_pk_bf16_f32 v19, v24, v25
	v_cvt_pk_bf16_f32 v20, v26, v27
	v_cvt_pk_bf16_f32 v21, v28, v29
	v_max_f32_e32 v10, 0, v10
	v_max_f32_e32 v11, 0, v11
	global_store_dwordx4 v[38:39], v[18:21], off offset:256 sc1
	v_add_u32_e32 v0, 0xb0000, v0
	v_max_f32_e32 v14, v14, v14
	v_pk_mul_f32 v[18:19], v[10:11], v[10:11]
	v_max_f32_e32 v11, v12, v12
	v_max_f32_e32 v10, v16, v16
	v_max_f32_e32 v12, 0, v11
	v_max_f32_e32 v11, v17, v17
	v_max_f32_e32 v10, 0, v10
	v_max_f32_e32 v11, 0, v11
	v_pk_mul_f32 v[16:17], v[10:11], v[10:11]
	v_lshl_add_u64 v[10:11], v[0:1], 1, s[6:7]
	v_max_f32_e32 v0, v6, v6
	v_max_f32_e32 v15, v15, v15
	v_max_f32_e32 v13, v13, v13
	v_max_f32_e32 v6, 0, v0
	v_max_f32_e32 v0, v2, v2
	v_max_f32_e32 v14, 0, v14
	v_max_f32_e32 v15, 0, v15
	v_max_f32_e32 v13, 0, v13
	v_max_f32_e32 v2, 0, v0
	v_max_f32_e32 v0, v7, v7
	v_pk_mul_f32 v[14:15], v[14:15], v[14:15]
	v_pk_mul_f32 v[20:21], v[12:13], v[12:13]
	v_max_f32_e32 v7, 0, v0
	v_max_f32_e32 v0, v3, v3
	v_lshl_add_u64 v[22:23], v[10:11], 0, v[122:123]
	v_cvt_pk_bf16_f32 v10, v14, v15
	v_cvt_pk_bf16_f32 v11, v16, v17
	v_cvt_pk_bf16_f32 v12, v18, v19
	v_cvt_pk_bf16_f32 v13, v20, v21
	v_max_f32_e32 v3, 0, v0
	v_max_f32_e32 v0, v8, v8
	global_store_dwordx4 v[22:23], v[10:13], off sc1
	v_pk_mul_f32 v[6:7], v[6:7], v[6:7]
	s_nop 0
	v_pk_mul_f32 v[10:11], v[2:3], v[2:3]
	v_max_f32_e32 v2, 0, v0
	v_max_f32_e32 v0, v4, v4
	v_max_f32_e32 v4, 0, v0
	v_max_f32_e32 v0, v9, v9
	v_max_f32_e32 v3, 0, v0
	v_max_f32_e32 v0, v5, v5
	v_max_f32_e32 v5, 0, v0
	v_pk_mul_f32 v[8:9], v[2:3], v[2:3]
	v_pk_mul_f32 v[12:13], v[4:5], v[4:5]
	v_cvt_pk_bf16_f32 v2, v6, v7
	v_cvt_pk_bf16_f32 v3, v8, v9
	v_cvt_pk_bf16_f32 v4, v10, v11
	v_cvt_pk_bf16_f32 v5, v12, v13
	global_store_dwordx4 v[22:23], v[2:5], off offset:256 sc1
	s_andn2_b64 vcc, exec, s[38:39]
	s_mov_b64 s[8:9], -1
	s_cbranch_vccnz .LBB0_1281
	s_andn2_b64 vcc, exec, s[4:5]
	s_cbranch_vccnz .LBB0_1280
	s_barrier
	s_branch .LBB0_1280
